# stack1 + removed back-to-back s_setprio 0 / s_setprio 1 pairs between the two MFMA groups of each GEMM super-phase
# baseline (speedup 1.0000x reference)
; #define PG8_STAGE(bufoff, gbase, voff) do { _Pragma("unroll") for (int _i = 0; _i < 2; ++_i) \
;         __builtin_amdgcn_global_load_lds((const unsigned*)((const char*)(gbase) + (voff)[_i]), (PG8_LAS unsigned*)(lds + (bufoff) + ldsw + _i * 8192), 16, 0, 0); } while (0)
; #define PG8_LDA(dst, b, h) do { _Pragma("unroll") for (int m = 0; m < 4; ++m) _Pragma("unroll") for (int k = 0; k < 2; ++k) dst[m][k] = *(const PG8_LAS bf16x8*)(lds + PG8_SA(b, h) + aoff + m * 2048 + k * 1024); } while (0)
; #define PG8_LDB(dst, b, h) do { _Pragma("unroll") for (int n = 0; n < 2; ++n) _Pragma("unroll") for (int k = 0; k < 2; ++k) dst[n][k] = *(const PG8_LAS bf16x8*)(lds + PG8_SB(b, h) + boff + n * 2048 + k * 1024); } while (0)
; #define PG8_MMA(ai, bj, At, Bt) do { __builtin_amdgcn_s_setprio(1); _Pragma("unroll") for (int m = 0; m < 4; ++m) _Pragma("unroll") for (int n = 0; n < 2; ++n) _Pragma("unroll") for (int k = 0; k < 2; ++k) \
;         acc[ai][bj][m][n] = __builtin_amdgcn_mfma_f32_16x16x32_bf16(Bt[n][k], At[m][k], acc[ai][bj][m][n], 0, 0, 0); __builtin_amdgcn_s_setprio(0); } while (0)
; #define PG8_WAIT_V(n) asm volatile("s_waitcnt vmcnt(" #n ")" ::: "memory")
; #define PG8_WAIT_L(n) asm volatile("s_waitcnt lgkmcnt(" #n ")" ::: "memory")
; #define PG8_BAR __builtin_amdgcn_s_barrier()
; #define PG8_SCHED __builtin_amdgcn_sched_barrier(0)
; template <class Epi, class Sched, bool ALIGN_EPI = false, bool SP2 = false>
; __device__ __forceinline__ void gemm_phase(PG8_LAS unsigned char* lds, const Gemm g, const Sched& S, const Epi& E) {
;     ...
;         for (int t = 0; t < nt; t += 2) {
;             const bool last = (t == nt - 2);
;             const char* a1 = cA + (size_t)(t + 1) * kstep;
;             const char* a2 = last ? nA : cA + (size_t)(t + 2) * kstep; const char* b2 = last ? nB : cB + (size_t)(t + 2) * kstep;
;             const char* a3 = a2 + kstep; const char* b3 = b2 + kstep;
;             if (last && has_next) S.a_ready(nxt);
;             if constexpr (SP2) {
;             PG8_LDB(B0, 0, 0); PG8_LDB(B1, 0, 1); PG8_SCHED; PG8_LDA(At, 0, 0); PG8_STAGE(PG8_SA(1, 1), a1 + hstep, voffA);
;             PG8_WAIT_V(8); PG8_WAIT_L(0); PG8_BAR; PG8_MMA(0, 0, At, B0); PG8_MMA(0, 1, At, B1); PG8_BAR; PG8_SCHED;
;             PG8_LDA(At, 0, 1); PG8_STAGE(PG8_SB(0, 0), b2, voffB); PG8_STAGE(PG8_SB(0, 1), b2 + hstep, voffB); PG8_STAGE(PG8_SA(0, 0), a2, voffA);
.LBB0_304:
	v_add_u32_e32 v166, s54, v169
	v_add_u32_e32 v168, s55, v169
	ds_read_b128 v[162:165], v166
	ds_read_b128 v[182:185], v166 offset:1024
	ds_read_b128 v[186:189], v166 offset:2048
	ds_read_b128 v[190:193], v166 offset:3072
	ds_read_b128 v[194:197], v168
	ds_read_b128 v[198:201], v168 offset:1024
	ds_read_b128 v[202:205], v168 offset:2048
	ds_read_b128 v[206:209], v168 offset:3072
	s_cmp_eq_u32 s53, s10
	v_lshl_add_u64 v[172:173], v[160:161], 0, s[22:23]
	s_cselect_b64 vcc, -1, 0
	s_add_i32 s10, s10, 2
	v_cndmask_b32_e32 v173, v173, v153, vcc
	v_cndmask_b32_e32 v172, v172, v152, vcc
	v_cndmask_b32_e32 v245, v159, v155, vcc
	v_cndmask_b32_e32 v244, v158, v154, vcc
	s_mov_b32 m0, s56
	v_lshl_add_u64 v[246:247], v[160:161], 0, v[148:149]
	ds_read_b128 v[210:213], v179
	ds_read_b128 v[216:219], v179 offset:1024
	ds_read_b128 v[220:223], v179 offset:2048
	ds_read_b128 v[224:227], v179 offset:3072
	ds_read_b128 v[228:231], v179 offset:4096
	ds_read_b128 v[232:235], v179 offset:5120
	ds_read_b128 v[236:239], v179 offset:6144
	ds_read_b128 v[240:243], v179 offset:7168
	global_load_lds_dwordx4 v[246:247], off
	v_lshl_add_u64 v[246:247], v[160:161], 0, v[146:147]
	s_mov_b32 m0, s57
	s_nop 0
	global_load_lds_dwordx4 v[246:247], off
	s_waitcnt vmcnt(8)
	s_waitcnt lgkmcnt(0)
	s_barrier
	s_setprio 1
	s_waitcnt lgkmcnt(0)
	v_mfma_f32_16x16x32_bf16 v[124:127], v[162:165], v[210:213], v[124:127]
	v_mfma_f32_16x16x32_bf16 v[116:119], v[186:189], v[210:213], v[116:119]
	v_mfma_f32_16x16x32_bf16 v[108:111], v[162:165], v[220:223], v[108:111]
	v_mfma_f32_16x16x32_bf16 v[100:103], v[186:189], v[220:223], v[100:103]
	v_mfma_f32_16x16x32_bf16 v[92:95], v[162:165], v[228:231], v[92:95]
	v_mfma_f32_16x16x32_bf16 v[84:87], v[186:189], v[228:231], v[84:87]
	v_mfma_f32_16x16x32_bf16 v[76:79], v[162:165], v[236:239], v[76:79]
	v_mfma_f32_16x16x32_bf16 v[68:71], v[186:189], v[236:239], v[68:71]
	v_mfma_f32_16x16x32_bf16 v[124:127], v[182:185], v[216:219], v[124:127]
	v_mfma_f32_16x16x32_bf16 v[116:119], v[190:193], v[216:219], v[116:119]
	v_mfma_f32_16x16x32_bf16 v[108:111], v[182:185], v[224:227], v[108:111]
	v_mfma_f32_16x16x32_bf16 v[100:103], v[190:193], v[224:227], v[100:103]
	v_mfma_f32_16x16x32_bf16 v[92:95], v[182:185], v[232:235], v[92:95]
	v_mfma_f32_16x16x32_bf16 v[84:87], v[190:193], v[232:235], v[84:87]
	v_mfma_f32_16x16x32_bf16 v[76:79], v[182:185], v[240:243], v[76:79]
	v_mfma_f32_16x16x32_bf16 v[68:71], v[190:193], v[240:243], v[68:71]
	v_mfma_f32_16x16x32_bf16 v[120:123], v[194:197], v[210:213], v[120:123]
	v_mfma_f32_16x16x32_bf16 v[112:115], v[202:205], v[210:213], v[112:115]
	v_mfma_f32_16x16x32_bf16 v[104:107], v[194:197], v[220:223], v[104:107]
	v_mfma_f32_16x16x32_bf16 v[96:99], v[202:205], v[220:223], v[96:99]
	v_mfma_f32_16x16x32_bf16 v[88:91], v[194:197], v[228:231], v[88:91]
	v_mfma_f32_16x16x32_bf16 v[80:83], v[202:205], v[228:231], v[80:83]
	v_mfma_f32_16x16x32_bf16 v[72:75], v[194:197], v[236:239], v[72:75]
	v_mfma_f32_16x16x32_bf16 v[64:67], v[202:205], v[236:239], v[64:67]
	v_mfma_f32_16x16x32_bf16 v[120:123], v[198:201], v[216:219], v[120:123]
	v_mfma_f32_16x16x32_bf16 v[112:115], v[206:209], v[216:219], v[112:115]
	v_mfma_f32_16x16x32_bf16 v[104:107], v[198:201], v[224:227], v[104:107]
	v_mfma_f32_16x16x32_bf16 v[96:99], v[206:209], v[224:227], v[96:99]
	v_mfma_f32_16x16x32_bf16 v[88:91], v[198:201], v[232:235], v[88:91]
	v_mfma_f32_16x16x32_bf16 v[80:83], v[206:209], v[232:235], v[80:83]
	v_mfma_f32_16x16x32_bf16 v[72:75], v[198:201], v[240:243], v[72:75]
	v_mfma_f32_16x16x32_bf16 v[64:67], v[206:209], v[240:243], v[64:67]
	s_setprio 0
	s_barrier
	s_mov_b32 m0, s60
	v_lshl_add_u64 v[246:247], v[244:245], 0, v[138:139]
	ds_read_b128 v[210:213], v179 offset:16384
	ds_read_b128 v[216:219], v179 offset:17408
	ds_read_b128 v[220:223], v179 offset:18432
	ds_read_b128 v[224:227], v179 offset:19456
	ds_read_b128 v[228:231], v179 offset:20480
	ds_read_b128 v[232:235], v179 offset:21504
	ds_read_b128 v[236:239], v179 offset:22528
	ds_read_b128 v[240:243], v179 offset:23552
	global_load_lds_dwordx4 v[246:247], off
	v_lshl_add_u64 v[248:249], v[244:245], 0, v[134:135]
	s_mov_b32 m0, s61
	v_lshl_add_u64 v[244:245], v[244:245], 0, s[14:15]
	global_load_lds_dwordx4 v[248:249], off
	v_lshl_add_u64 v[250:251], v[244:245], 0, v[138:139]
	s_mov_b32 m0, s62
	v_lshl_add_u64 v[244:245], v[244:245], 0, v[134:135]
	global_load_lds_dwordx4 v[250:251], off
	s_add_i32 m0, s62, 0x2000
	v_lshl_add_u64 v[252:253], v[172:173], 0, v[140:141]
	global_load_lds_dwordx4 v[244:245], off
	s_mov_b32 m0, s46
	v_lshl_add_u64 v[214:215], v[172:173], 0, v[136:137]
	global_load_lds_dwordx4 v[252:253], off
	s_mov_b32 m0, s47
	s_nop 0
	global_load_lds_dwordx4 v[214:215], off
	s_waitcnt vmcnt(8)
	s_waitcnt lgkmcnt(0)
	s_barrier
; #define PG8_STAGE(bufoff, gbase, voff) do { _Pragma("unroll") for (int _i = 0; _i < 2; ++_i) \
;         __builtin_amdgcn_global_load_lds((const unsigned*)((const char*)(gbase) + (voff)[_i]), (PG8_LAS unsigned*)(lds + (bufoff) + ldsw + _i * 8192), 16, 0, 0); } while (0)
; #define PG8_LDA(dst, b, h) do { _Pragma("unroll") for (int m = 0; m < 4; ++m) _Pragma("unroll") for (int k = 0; k < 2; ++k) dst[m][k] = *(const PG8_LAS bf16x8*)(lds + PG8_SA(b, h) + aoff + m * 2048 + k * 1024); } while (0)
; #define PG8_LDB(dst, b, h) do { _Pragma("unroll") for (int n = 0; n < 2; ++n) _Pragma("unroll") for (int k = 0; k < 2; ++k) dst[n][k] = *(const PG8_LAS bf16x8*)(lds + PG8_SB(b, h) + boff + n * 2048 + k * 1024); } while (0)
; #define PG8_MMA(ai, bj, At, Bt) do { __builtin_amdgcn_s_setprio(1); _Pragma("unroll") for (int m = 0; m < 4; ++m) _Pragma("unroll") for (int n = 0; n < 2; ++n) _Pragma("unroll") for (int k = 0; k < 2; ++k) \
;         acc[ai][bj][m][n] = __builtin_amdgcn_mfma_f32_16x16x32_bf16(Bt[n][k], At[m][k], acc[ai][bj][m][n], 0, 0, 0); __builtin_amdgcn_s_setprio(0); } while (0)
; #define PG8_WAIT_V(n) asm volatile("s_waitcnt vmcnt(" #n ")" ::: "memory")
; #define PG8_WAIT_L(n) asm volatile("s_waitcnt lgkmcnt(" #n ")" ::: "memory")
; #define PG8_BAR __builtin_amdgcn_s_barrier()
; #define PG8_SCHED __builtin_amdgcn_sched_barrier(0)
; template <class Epi, class Sched, bool ALIGN_EPI = false, bool SP2 = false>
; __device__ __forceinline__ void gemm_phase(PG8_LAS unsigned char* lds, const Gemm g, const Sched& S, const Epi& E) {
;     ...
;             PG8_WAIT_V(8); PG8_WAIT_L(0); PG8_BAR; PG8_MMA(1, 0, At, B0); PG8_MMA(1, 1, At, B1); PG8_BAR; PG8_SCHED;
;             PG8_LDB(B0, 1, 0); PG8_LDB(B1, 1, 1); PG8_SCHED; PG8_LDA(At, 1, 0); PG8_STAGE(PG8_SA(0, 1), a2 + hstep, voffA);
;             PG8_WAIT_V(8); PG8_WAIT_L(0); PG8_BAR; PG8_MMA(0, 0, At, B0); PG8_MMA(0, 1, At, B1); PG8_BAR; PG8_SCHED;
	s_setprio 1
	s_waitcnt lgkmcnt(0)
	v_mfma_f32_16x16x32_bf16 v[60:63], v[162:165], v[210:213], v[60:63]
	v_mfma_f32_16x16x32_bf16 v[52:55], v[186:189], v[210:213], v[52:55]
	v_mfma_f32_16x16x32_bf16 v[44:47], v[162:165], v[220:223], v[44:47]
	v_mfma_f32_16x16x32_bf16 v[36:39], v[186:189], v[220:223], v[36:39]
	v_mfma_f32_16x16x32_bf16 v[28:31], v[162:165], v[228:231], v[28:31]
	v_mfma_f32_16x16x32_bf16 v[20:23], v[186:189], v[228:231], v[20:23]
	v_mfma_f32_16x16x32_bf16 v[12:15], v[162:165], v[236:239], v[12:15]
	v_mfma_f32_16x16x32_bf16 v[4:7], v[186:189], v[236:239], v[4:7]
	v_mfma_f32_16x16x32_bf16 v[60:63], v[182:185], v[216:219], v[60:63]
	v_mfma_f32_16x16x32_bf16 v[52:55], v[190:193], v[216:219], v[52:55]
	v_mfma_f32_16x16x32_bf16 v[44:47], v[182:185], v[224:227], v[44:47]
	v_mfma_f32_16x16x32_bf16 v[36:39], v[190:193], v[224:227], v[36:39]
	v_mfma_f32_16x16x32_bf16 v[28:31], v[182:185], v[232:235], v[28:31]
	v_mfma_f32_16x16x32_bf16 v[20:23], v[190:193], v[232:235], v[20:23]
	v_mfma_f32_16x16x32_bf16 v[12:15], v[182:185], v[240:243], v[12:15]
	v_mfma_f32_16x16x32_bf16 v[4:7], v[190:193], v[240:243], v[4:7]
	v_mfma_f32_16x16x32_bf16 v[56:59], v[194:197], v[210:213], v[56:59]
	v_mfma_f32_16x16x32_bf16 v[48:51], v[202:205], v[210:213], v[48:51]
	v_mfma_f32_16x16x32_bf16 v[40:43], v[194:197], v[220:223], v[40:43]
	v_mfma_f32_16x16x32_bf16 v[32:35], v[202:205], v[220:223], v[32:35]
	v_mfma_f32_16x16x32_bf16 v[24:27], v[194:197], v[228:231], v[24:27]
	v_mfma_f32_16x16x32_bf16 v[16:19], v[202:205], v[228:231], v[16:19]
	v_mfma_f32_16x16x32_bf16 v[8:11], v[194:197], v[236:239], v[8:11]
	v_mfma_f32_16x16x32_bf16 v[0:3], v[202:205], v[236:239], v[0:3]
	v_mfma_f32_16x16x32_bf16 v[56:59], v[198:201], v[216:219], v[56:59]
	v_mfma_f32_16x16x32_bf16 v[48:51], v[206:209], v[216:219], v[48:51]
	v_mfma_f32_16x16x32_bf16 v[40:43], v[198:201], v[224:227], v[40:43]
	v_mfma_f32_16x16x32_bf16 v[32:35], v[206:209], v[224:227], v[32:35]
	v_mfma_f32_16x16x32_bf16 v[24:27], v[198:201], v[232:235], v[24:27]
	v_mfma_f32_16x16x32_bf16 v[16:19], v[206:209], v[232:235], v[16:19]
	v_mfma_f32_16x16x32_bf16 v[8:11], v[198:201], v[240:243], v[8:11]
	v_mfma_f32_16x16x32_bf16 v[0:3], v[206:209], v[240:243], v[0:3]
	s_setprio 0
	s_barrier
	s_add_i32 s11, 0, 0x18000
	v_add_u32_e32 v166, s11, v169
	s_add_i32 s13, 0, 0x1c000
	ds_read_b128 v[162:165], v166
	ds_read_b128 v[182:185], v166 offset:1024
	ds_read_b128 v[186:189], v166 offset:2048
	ds_read_b128 v[190:193], v166 offset:3072
	v_add_u32_e32 v166, s13, v169
	ds_read_b128 v[194:197], v166
	ds_read_b128 v[198:201], v166 offset:1024
	ds_read_b128 v[202:205], v166 offset:2048
	ds_read_b128 v[206:209], v166 offset:3072
	v_lshl_add_u64 v[172:173], v[172:173], 0, s[14:15]
	s_mov_b32 m0, s48
	v_lshl_add_u64 v[170:171], v[172:173], 0, v[140:141]
	ds_read_b128 v[210:213], v179 offset:32768
	ds_read_b128 v[216:219], v179 offset:33792
	ds_read_b128 v[220:223], v179 offset:34816
	ds_read_b128 v[224:227], v179 offset:35840
	ds_read_b128 v[228:231], v179 offset:36864
	ds_read_b128 v[232:235], v179 offset:37888
	ds_read_b128 v[236:239], v179 offset:38912
	ds_read_b128 v[240:243], v179 offset:39936
	global_load_lds_dwordx4 v[170:171], off
	v_lshl_add_u64 v[170:171], v[172:173], 0, v[136:137]
	s_mov_b32 m0, s49
	s_nop 0
	global_load_lds_dwordx4 v[170:171], off
	s_waitcnt vmcnt(8)
	s_waitcnt lgkmcnt(0)
	s_barrier
	s_setprio 1
	s_waitcnt lgkmcnt(0)
	v_mfma_f32_16x16x32_bf16 v[124:127], v[162:165], v[210:213], v[124:127]
	v_mfma_f32_16x16x32_bf16 v[116:119], v[186:189], v[210:213], v[116:119]
	v_mfma_f32_16x16x32_bf16 v[108:111], v[162:165], v[220:223], v[108:111]
	v_mfma_f32_16x16x32_bf16 v[100:103], v[186:189], v[220:223], v[100:103]
	v_mfma_f32_16x16x32_bf16 v[92:95], v[162:165], v[228:231], v[92:95]
	v_mfma_f32_16x16x32_bf16 v[84:87], v[186:189], v[228:231], v[84:87]
	v_mfma_f32_16x16x32_bf16 v[76:79], v[162:165], v[236:239], v[76:79]
	v_mfma_f32_16x16x32_bf16 v[68:71], v[186:189], v[236:239], v[68:71]
	v_mfma_f32_16x16x32_bf16 v[124:127], v[182:185], v[216:219], v[124:127]
	v_mfma_f32_16x16x32_bf16 v[116:119], v[190:193], v[216:219], v[116:119]
	v_mfma_f32_16x16x32_bf16 v[108:111], v[182:185], v[224:227], v[108:111]
	v_mfma_f32_16x16x32_bf16 v[100:103], v[190:193], v[224:227], v[100:103]
	v_mfma_f32_16x16x32_bf16 v[92:95], v[182:185], v[232:235], v[92:95]
	v_mfma_f32_16x16x32_bf16 v[84:87], v[190:193], v[232:235], v[84:87]
	v_mfma_f32_16x16x32_bf16 v[76:79], v[182:185], v[240:243], v[76:79]
	v_mfma_f32_16x16x32_bf16 v[68:71], v[190:193], v[240:243], v[68:71]
	v_mfma_f32_16x16x32_bf16 v[120:123], v[194:197], v[210:213], v[120:123]
	v_mfma_f32_16x16x32_bf16 v[112:115], v[202:205], v[210:213], v[112:115]
	v_mfma_f32_16x16x32_bf16 v[104:107], v[194:197], v[220:223], v[104:107]
	v_mfma_f32_16x16x32_bf16 v[96:99], v[202:205], v[220:223], v[96:99]
	v_mfma_f32_16x16x32_bf16 v[88:91], v[194:197], v[228:231], v[88:91]
	v_mfma_f32_16x16x32_bf16 v[80:83], v[202:205], v[228:231], v[80:83]
	v_mfma_f32_16x16x32_bf16 v[72:75], v[194:197], v[236:239], v[72:75]
	v_mfma_f32_16x16x32_bf16 v[64:67], v[202:205], v[236:239], v[64:67]
	v_mfma_f32_16x16x32_bf16 v[120:123], v[198:201], v[216:219], v[120:123]
	v_mfma_f32_16x16x32_bf16 v[112:115], v[206:209], v[216:219], v[112:115]
	v_mfma_f32_16x16x32_bf16 v[104:107], v[198:201], v[224:227], v[104:107]
	v_mfma_f32_16x16x32_bf16 v[96:99], v[206:209], v[224:227], v[96:99]
	v_mfma_f32_16x16x32_bf16 v[88:91], v[198:201], v[232:235], v[88:91]
	v_mfma_f32_16x16x32_bf16 v[80:83], v[206:209], v[232:235], v[80:83]
	v_mfma_f32_16x16x32_bf16 v[72:75], v[198:201], v[240:243], v[72:75]
	v_mfma_f32_16x16x32_bf16 v[64:67], v[206:209], v[240:243], v[64:67]
	s_setprio 0
	s_barrier
; #define PG8_STAGE(bufoff, gbase, voff) do { _Pragma("unroll") for (int _i = 0; _i < 2; ++_i) \
;         __builtin_amdgcn_global_load_lds((const unsigned*)((const char*)(gbase) + (voff)[_i]), (PG8_LAS unsigned*)(lds + (bufoff) + ldsw + _i * 8192), 16, 0, 0); } while (0)
; #define PG8_LDA(dst, b, h) do { _Pragma("unroll") for (int m = 0; m < 4; ++m) _Pragma("unroll") for (int k = 0; k < 2; ++k) dst[m][k] = *(const PG8_LAS bf16x8*)(lds + PG8_SA(b, h) + aoff + m * 2048 + k * 1024); } while (0)
; #define PG8_MMA(ai, bj, At, Bt) do { __builtin_amdgcn_s_setprio(1); _Pragma("unroll") for (int m = 0; m < 4; ++m) _Pragma("unroll") for (int n = 0; n < 2; ++n) _Pragma("unroll") for (int k = 0; k < 2; ++k) \
;         acc[ai][bj][m][n] = __builtin_amdgcn_mfma_f32_16x16x32_bf16(Bt[n][k], At[m][k], acc[ai][bj][m][n], 0, 0, 0); __builtin_amdgcn_s_setprio(0); } while (0)
; #define PG8_WAIT_V(n) asm volatile("s_waitcnt vmcnt(" #n ")" ::: "memory")
; #define PG8_WAIT_L(n) asm volatile("s_waitcnt lgkmcnt(" #n ")" ::: "memory")
; #define PG8_BAR __builtin_amdgcn_s_barrier()
; #define PG8_SCHED __builtin_amdgcn_sched_barrier(0)
; template <class Epi, class Sched, bool ALIGN_EPI = false, bool SP2 = false>
; __device__ __forceinline__ void gemm_phase(PG8_LAS unsigned char* lds, const Gemm g, const Sched& S, const Epi& E) {
;     ...
;             PG8_LDA(At, 1, 1); PG8_STAGE(PG8_SB(1, 0), b3, voffB); PG8_STAGE(PG8_SB(1, 1), b3 + hstep, voffB); PG8_STAGE(PG8_SA(1, 0), a3, voffA);
;             PG8_WAIT_V(8); PG8_WAIT_L(0); PG8_BAR; PG8_MMA(1, 0, At, B0); PG8_MMA(1, 1, At, B1); PG8_BAR; PG8_SCHED;
	s_add_i32 s11, s11, s29
	v_lshl_add_u64 v[170:171], v[246:247], 0, s[22:23]
	s_mov_b32 m0, s11
	ds_read_b128 v[210:213], v179 offset:49152
	ds_read_b128 v[216:219], v179 offset:50176
	ds_read_b128 v[220:223], v179 offset:51200
	ds_read_b128 v[224:227], v179 offset:52224
	ds_read_b128 v[228:231], v179 offset:53248
	ds_read_b128 v[232:235], v179 offset:54272
	ds_read_b128 v[236:239], v179 offset:55296
	ds_read_b128 v[240:243], v179 offset:56320
	global_load_lds_dwordx4 v[170:171], off
	v_lshl_add_u64 v[170:171], v[248:249], 0, s[22:23]
	s_add_i32 m0, s11, 0x2000
	s_add_i32 s11, s13, s29
	global_load_lds_dwordx4 v[170:171], off
	v_lshl_add_u64 v[170:171], v[250:251], 0, s[22:23]
	s_mov_b32 m0, s11
	s_nop 0
	global_load_lds_dwordx4 v[170:171], off
	v_lshl_add_u64 v[170:171], v[244:245], 0, s[22:23]
	s_add_i32 m0, s11, 0x2000
	s_nop 0
	global_load_lds_dwordx4 v[170:171], off
	v_lshl_add_u64 v[170:171], v[252:253], 0, s[22:23]
	s_mov_b32 m0, s50
	s_nop 0
	global_load_lds_dwordx4 v[170:171], off
	v_lshl_add_u64 v[170:171], v[214:215], 0, s[22:23]
	s_mov_b32 m0, s51
	s_nop 0
	global_load_lds_dwordx4 v[170:171], off
	s_waitcnt vmcnt(8)
	s_waitcnt lgkmcnt(0)
	s_barrier
	s_setprio 1
	s_waitcnt lgkmcnt(0)
	v_mfma_f32_16x16x32_bf16 v[60:63], v[162:165], v[210:213], v[60:63]
	v_mfma_f32_16x16x32_bf16 v[52:55], v[186:189], v[210:213], v[52:55]
	v_mfma_f32_16x16x32_bf16 v[44:47], v[162:165], v[220:223], v[44:47]
	v_mfma_f32_16x16x32_bf16 v[36:39], v[186:189], v[220:223], v[36:39]
	v_mfma_f32_16x16x32_bf16 v[28:31], v[162:165], v[228:231], v[28:31]
	v_mfma_f32_16x16x32_bf16 v[20:23], v[186:189], v[228:231], v[20:23]
	v_mfma_f32_16x16x32_bf16 v[12:15], v[162:165], v[236:239], v[12:15]
	v_mfma_f32_16x16x32_bf16 v[4:7], v[186:189], v[236:239], v[4:7]
	v_mfma_f32_16x16x32_bf16 v[60:63], v[182:185], v[216:219], v[60:63]
	v_mfma_f32_16x16x32_bf16 v[52:55], v[190:193], v[216:219], v[52:55]
	v_mfma_f32_16x16x32_bf16 v[44:47], v[182:185], v[224:227], v[44:47]
	v_mfma_f32_16x16x32_bf16 v[36:39], v[190:193], v[224:227], v[36:39]
	v_mfma_f32_16x16x32_bf16 v[28:31], v[182:185], v[232:235], v[28:31]
	v_mfma_f32_16x16x32_bf16 v[20:23], v[190:193], v[232:235], v[20:23]
	v_mfma_f32_16x16x32_bf16 v[12:15], v[182:185], v[240:243], v[12:15]
	v_mfma_f32_16x16x32_bf16 v[4:7], v[190:193], v[240:243], v[4:7]
	v_mfma_f32_16x16x32_bf16 v[56:59], v[194:197], v[210:213], v[56:59]
	v_mfma_f32_16x16x32_bf16 v[48:51], v[202:205], v[210:213], v[48:51]
	v_mfma_f32_16x16x32_bf16 v[40:43], v[194:197], v[220:223], v[40:43]
	v_mfma_f32_16x16x32_bf16 v[32:35], v[202:205], v[220:223], v[32:35]
	v_mfma_f32_16x16x32_bf16 v[24:27], v[194:197], v[228:231], v[24:27]
	v_mfma_f32_16x16x32_bf16 v[16:19], v[202:205], v[228:231], v[16:19]
	v_mfma_f32_16x16x32_bf16 v[8:11], v[194:197], v[236:239], v[8:11]
	v_mfma_f32_16x16x32_bf16 v[0:3], v[202:205], v[236:239], v[0:3]
	v_mfma_f32_16x16x32_bf16 v[56:59], v[198:201], v[216:219], v[56:59]
	v_mfma_f32_16x16x32_bf16 v[48:51], v[206:209], v[216:219], v[48:51]
	v_mfma_f32_16x16x32_bf16 v[40:43], v[198:201], v[224:227], v[40:43]
	v_mfma_f32_16x16x32_bf16 v[32:35], v[206:209], v[224:227], v[32:35]
	v_mfma_f32_16x16x32_bf16 v[24:27], v[198:201], v[232:235], v[24:27]
	v_mfma_f32_16x16x32_bf16 v[16:19], v[206:209], v[232:235], v[16:19]
	v_mfma_f32_16x16x32_bf16 v[8:11], v[198:201], v[240:243], v[8:11]
	v_mfma_f32_16x16x32_bf16 v[0:3], v[206:209], v[240:243], v[0:3]
	s_setprio 0
	s_barrier
	v_lshl_add_u64 v[158:159], v[158:159], 0, s[26:27]
	s_cmp_ge_i32 s10, s52
	v_lshl_add_u64 v[160:161], v[160:161], 0, s[26:27]
	s_cbranch_scc0 .LBB0_304

; #define PG8_STAGE(bufoff, gbase, voff) do { _Pragma("unroll") for (int _i = 0; _i < 2; ++_i) \
;         __builtin_amdgcn_global_load_lds((const unsigned*)((const char*)(gbase) + (voff)[_i]), (PG8_LAS unsigned*)(lds + (bufoff) + ldsw + _i * 8192), 16, 0, 0); } while (0)
; #define PG8_LDA(dst, b, h) do { _Pragma("unroll") for (int m = 0; m < 4; ++m) _Pragma("unroll") for (int k = 0; k < 2; ++k) dst[m][k] = *(const PG8_LAS bf16x8*)(lds + PG8_SA(b, h) + aoff + m * 2048 + k * 1024); } while (0)
; #define PG8_LDB(dst, b, h) do { _Pragma("unroll") for (int n = 0; n < 2; ++n) _Pragma("unroll") for (int k = 0; k < 2; ++k) dst[n][k] = *(const PG8_LAS bf16x8*)(lds + PG8_SB(b, h) + boff + n * 2048 + k * 1024); } while (0)
; #define PG8_MMA(ai, bj, At, Bt) do { __builtin_amdgcn_s_setprio(1); _Pragma("unroll") for (int m = 0; m < 4; ++m) _Pragma("unroll") for (int n = 0; n < 2; ++n) _Pragma("unroll") for (int k = 0; k < 2; ++k) \
;         acc[ai][bj][m][n] = __builtin_amdgcn_mfma_f32_16x16x32_bf16(Bt[n][k], At[m][k], acc[ai][bj][m][n], 0, 0, 0); __builtin_amdgcn_s_setprio(0); } while (0)
; #define PG8_WAIT_V(n) asm volatile("s_waitcnt vmcnt(" #n ")" ::: "memory")
; #define PG8_WAIT_L(n) asm volatile("s_waitcnt lgkmcnt(" #n ")" ::: "memory")
; #define PG8_BAR __builtin_amdgcn_s_barrier()
; #define PG8_SCHED __builtin_amdgcn_sched_barrier(0)
; template <class Epi, class Sched, bool ALIGN_EPI = false, bool SP2 = false>
; __device__ __forceinline__ void gemm_phase(PG8_LAS unsigned char* lds, const Gemm g, const Sched& S, const Epi& E) {
;     ...
;         for (int t = 0; t < nt; t += 2) {
;             const bool last = (t == nt - 2);
;             const char* a1 = cA + (size_t)(t + 1) * kstep;
;             const char* a2 = last ? nA : cA + (size_t)(t + 2) * kstep; const char* b2 = last ? nB : cB + (size_t)(t + 2) * kstep;
;             const char* a3 = a2 + kstep; const char* b3 = b2 + kstep;
;             if (last && has_next) S.a_ready(nxt);
;             if constexpr (SP2) {
;             PG8_LDB(B0, 0, 0); PG8_LDB(B1, 0, 1); PG8_SCHED; PG8_LDA(At, 0, 0); PG8_STAGE(PG8_SA(1, 1), a1 + hstep, voffA);
;             PG8_WAIT_V(8); PG8_WAIT_L(0); PG8_BAR; PG8_MMA(0, 0, At, B0); PG8_MMA(0, 1, At, B1); PG8_BAR; PG8_SCHED;
;             PG8_LDA(At, 0, 1); PG8_STAGE(PG8_SB(0, 0), b2, voffB); PG8_STAGE(PG8_SB(0, 1), b2 + hstep, voffB); PG8_STAGE(PG8_SA(0, 0), a2, voffA);
.LBB0_371:
	v_add_u32_e32 v148, s54, v201
	v_add_u32_e32 v190, s55, v201
	ds_read_b128 v[136:139], v148
	ds_read_b128 v[140:143], v148 offset:1024
	ds_read_b128 v[144:147], v148 offset:2048
	ds_read_b128 v[148:151], v148 offset:3072
	ds_read_b128 v[152:155], v190
	ds_read_b128 v[182:185], v190 offset:1024
	ds_read_b128 v[186:189], v190 offset:2048
	ds_read_b128 v[190:193], v190 offset:3072
	s_cmp_eq_u32 s48, s12
	v_lshl_add_u64 v[194:195], v[134:135], 0, s[22:23]
	s_cselect_b64 vcc, -1, 0
	s_add_i32 s12, s12, 2
	v_cndmask_b32_e32 v199, v195, v179, vcc
	v_cndmask_b32_e32 v198, v194, v178, vcc
	v_cndmask_b32_e32 v215, v133, v181, vcc
	v_cndmask_b32_e32 v214, v132, v180, vcc
	s_mov_b32 m0, s56
	v_lshl_add_u64 v[236:237], v[134:135], 0, v[174:175]
	ds_read_b128 v[194:197], v203
	ds_read_b128 v[206:209], v203 offset:1024
	ds_read_b128 v[210:213], v203 offset:2048
	ds_read_b128 v[216:219], v203 offset:3072
	ds_read_b128 v[220:223], v203 offset:4096
	ds_read_b128 v[224:227], v203 offset:5120
	ds_read_b128 v[228:231], v203 offset:6144
	ds_read_b128 v[232:235], v203 offset:7168
	global_load_lds_dwordx4 v[236:237], off
	v_lshl_add_u64 v[236:237], v[134:135], 0, v[172:173]
	s_mov_b32 m0, s57
	s_nop 0
	global_load_lds_dwordx4 v[236:237], off
	s_waitcnt vmcnt(8)
	s_waitcnt lgkmcnt(0)
	s_barrier
	s_setprio 1
	s_waitcnt lgkmcnt(0)
	v_mfma_f32_16x16x32_bf16 v[124:127], v[136:139], v[194:197], v[124:127]
	v_mfma_f32_16x16x32_bf16 v[128:131], v[144:147], v[194:197], v[128:131]
	v_mfma_f32_16x16x32_bf16 v[112:115], v[136:139], v[210:213], v[112:115]
	v_mfma_f32_16x16x32_bf16 v[108:111], v[144:147], v[210:213], v[108:111]
	v_mfma_f32_16x16x32_bf16 v[96:99], v[136:139], v[220:223], v[96:99]
	v_mfma_f32_16x16x32_bf16 v[92:95], v[144:147], v[220:223], v[92:95]
	v_mfma_f32_16x16x32_bf16 v[80:83], v[136:139], v[228:231], v[80:83]
	v_mfma_f32_16x16x32_bf16 v[76:79], v[144:147], v[228:231], v[76:79]
	v_mfma_f32_16x16x32_bf16 v[124:127], v[140:143], v[206:209], v[124:127]
	v_mfma_f32_16x16x32_bf16 v[128:131], v[148:151], v[206:209], v[128:131]
	v_mfma_f32_16x16x32_bf16 v[112:115], v[140:143], v[216:219], v[112:115]
	v_mfma_f32_16x16x32_bf16 v[108:111], v[148:151], v[216:219], v[108:111]
	v_mfma_f32_16x16x32_bf16 v[96:99], v[140:143], v[224:227], v[96:99]
	v_mfma_f32_16x16x32_bf16 v[92:95], v[148:151], v[224:227], v[92:95]
	v_mfma_f32_16x16x32_bf16 v[80:83], v[140:143], v[232:235], v[80:83]
	v_mfma_f32_16x16x32_bf16 v[76:79], v[148:151], v[232:235], v[76:79]
	v_mfma_f32_16x16x32_bf16 v[120:123], v[152:155], v[194:197], v[120:123]
	v_mfma_f32_16x16x32_bf16 v[116:119], v[186:189], v[194:197], v[116:119]
	v_mfma_f32_16x16x32_bf16 v[104:107], v[152:155], v[210:213], v[104:107]
	v_mfma_f32_16x16x32_bf16 v[100:103], v[186:189], v[210:213], v[100:103]
	v_mfma_f32_16x16x32_bf16 v[88:91], v[152:155], v[220:223], v[88:91]
	v_mfma_f32_16x16x32_bf16 v[84:87], v[186:189], v[220:223], v[84:87]
	v_mfma_f32_16x16x32_bf16 v[72:75], v[152:155], v[228:231], v[72:75]
	v_mfma_f32_16x16x32_bf16 v[68:71], v[186:189], v[228:231], v[68:71]
	v_mfma_f32_16x16x32_bf16 v[120:123], v[182:185], v[206:209], v[120:123]
	v_mfma_f32_16x16x32_bf16 v[116:119], v[190:193], v[206:209], v[116:119]
	v_mfma_f32_16x16x32_bf16 v[104:107], v[182:185], v[216:219], v[104:107]
	v_mfma_f32_16x16x32_bf16 v[100:103], v[190:193], v[216:219], v[100:103]
	v_mfma_f32_16x16x32_bf16 v[88:91], v[182:185], v[224:227], v[88:91]
	v_mfma_f32_16x16x32_bf16 v[84:87], v[190:193], v[224:227], v[84:87]
	v_mfma_f32_16x16x32_bf16 v[72:75], v[182:185], v[232:235], v[72:75]
	v_mfma_f32_16x16x32_bf16 v[68:71], v[190:193], v[232:235], v[68:71]
	s_setprio 0
	s_barrier
	s_mov_b32 m0, s58
	v_lshl_add_u64 v[236:237], v[214:215], 0, v[166:167]
	ds_read_b128 v[194:197], v203 offset:16384
	ds_read_b128 v[206:209], v203 offset:17408
	ds_read_b128 v[210:213], v203 offset:18432
	ds_read_b128 v[216:219], v203 offset:19456
	ds_read_b128 v[220:223], v203 offset:20480
	ds_read_b128 v[224:227], v203 offset:21504
	ds_read_b128 v[228:231], v203 offset:22528
	ds_read_b128 v[232:235], v203 offset:23552
	global_load_lds_dwordx4 v[236:237], off
	v_lshl_add_u64 v[238:239], v[214:215], 0, v[170:171]
	s_mov_b32 m0, s59
	v_lshl_add_u64 v[214:215], v[214:215], 0, s[14:15]
	s_add_i32 s13, s55, s30
	global_load_lds_dwordx4 v[238:239], off
	v_lshl_add_u64 v[240:241], v[214:215], 0, v[166:167]
	s_mov_b32 m0, s13
	v_lshl_add_u64 v[214:215], v[214:215], 0, v[170:171]
	global_load_lds_dwordx4 v[240:241], off
	s_add_i32 m0, s13, 0x2000
	v_lshl_add_u64 v[242:243], v[198:199], 0, v[164:165]
	global_load_lds_dwordx4 v[214:215], off
	s_mov_b32 m0, s31
	v_lshl_add_u64 v[244:245], v[198:199], 0, v[168:169]
	global_load_lds_dwordx4 v[242:243], off
	s_mov_b32 m0, s34
	s_nop 0
	global_load_lds_dwordx4 v[244:245], off
	s_waitcnt vmcnt(8)
	s_waitcnt lgkmcnt(0)
	s_barrier
; #define PG8_STAGE(bufoff, gbase, voff) do { _Pragma("unroll") for (int _i = 0; _i < 2; ++_i) \
;         __builtin_amdgcn_global_load_lds((const unsigned*)((const char*)(gbase) + (voff)[_i]), (PG8_LAS unsigned*)(lds + (bufoff) + ldsw + _i * 8192), 16, 0, 0); } while (0)
; #define PG8_LDA(dst, b, h) do { _Pragma("unroll") for (int m = 0; m < 4; ++m) _Pragma("unroll") for (int k = 0; k < 2; ++k) dst[m][k] = *(const PG8_LAS bf16x8*)(lds + PG8_SA(b, h) + aoff + m * 2048 + k * 1024); } while (0)
; #define PG8_LDB(dst, b, h) do { _Pragma("unroll") for (int n = 0; n < 2; ++n) _Pragma("unroll") for (int k = 0; k < 2; ++k) dst[n][k] = *(const PG8_LAS bf16x8*)(lds + PG8_SB(b, h) + boff + n * 2048 + k * 1024); } while (0)
; #define PG8_MMA(ai, bj, At, Bt) do { __builtin_amdgcn_s_setprio(1); _Pragma("unroll") for (int m = 0; m < 4; ++m) _Pragma("unroll") for (int n = 0; n < 2; ++n) _Pragma("unroll") for (int k = 0; k < 2; ++k) \
;         acc[ai][bj][m][n] = __builtin_amdgcn_mfma_f32_16x16x32_bf16(Bt[n][k], At[m][k], acc[ai][bj][m][n], 0, 0, 0); __builtin_amdgcn_s_setprio(0); } while (0)
; #define PG8_WAIT_V(n) asm volatile("s_waitcnt vmcnt(" #n ")" ::: "memory")
; #define PG8_WAIT_L(n) asm volatile("s_waitcnt lgkmcnt(" #n ")" ::: "memory")
; #define PG8_BAR __builtin_amdgcn_s_barrier()
; #define PG8_SCHED __builtin_amdgcn_sched_barrier(0)
; template <class Epi, class Sched, bool ALIGN_EPI = false, bool SP2 = false>
; __device__ __forceinline__ void gemm_phase(PG8_LAS unsigned char* lds, const Gemm g, const Sched& S, const Epi& E) {
;     ...
;             PG8_WAIT_V(8); PG8_WAIT_L(0); PG8_BAR; PG8_MMA(1, 0, At, B0); PG8_MMA(1, 1, At, B1); PG8_BAR; PG8_SCHED;
;             PG8_LDB(B0, 1, 0); PG8_LDB(B1, 1, 1); PG8_SCHED; PG8_LDA(At, 1, 0); PG8_STAGE(PG8_SA(0, 1), a2 + hstep, voffA);
;             PG8_WAIT_V(8); PG8_WAIT_L(0); PG8_BAR; PG8_MMA(0, 0, At, B0); PG8_MMA(0, 1, At, B1); PG8_BAR; PG8_SCHED;
	s_setprio 1
	s_waitcnt lgkmcnt(0)
	v_mfma_f32_16x16x32_bf16 v[64:67], v[136:139], v[194:197], v[64:67]
	v_mfma_f32_16x16x32_bf16 v[60:63], v[144:147], v[194:197], v[60:63]
	v_mfma_f32_16x16x32_bf16 v[48:51], v[136:139], v[210:213], v[48:51]
	v_mfma_f32_16x16x32_bf16 v[44:47], v[144:147], v[210:213], v[44:47]
	v_mfma_f32_16x16x32_bf16 v[32:35], v[136:139], v[220:223], v[32:35]
	v_mfma_f32_16x16x32_bf16 v[28:31], v[144:147], v[220:223], v[28:31]
	v_mfma_f32_16x16x32_bf16 v[16:19], v[136:139], v[228:231], v[16:19]
	v_mfma_f32_16x16x32_bf16 v[12:15], v[144:147], v[228:231], v[12:15]
	v_mfma_f32_16x16x32_bf16 v[64:67], v[140:143], v[206:209], v[64:67]
	v_mfma_f32_16x16x32_bf16 v[60:63], v[148:151], v[206:209], v[60:63]
	v_mfma_f32_16x16x32_bf16 v[48:51], v[140:143], v[216:219], v[48:51]
	v_mfma_f32_16x16x32_bf16 v[44:47], v[148:151], v[216:219], v[44:47]
	v_mfma_f32_16x16x32_bf16 v[32:35], v[140:143], v[224:227], v[32:35]
	v_mfma_f32_16x16x32_bf16 v[28:31], v[148:151], v[224:227], v[28:31]
	v_mfma_f32_16x16x32_bf16 v[16:19], v[140:143], v[232:235], v[16:19]
	v_mfma_f32_16x16x32_bf16 v[12:15], v[148:151], v[232:235], v[12:15]
	v_mfma_f32_16x16x32_bf16 v[56:59], v[152:155], v[194:197], v[56:59]
	v_mfma_f32_16x16x32_bf16 v[52:55], v[186:189], v[194:197], v[52:55]
	v_mfma_f32_16x16x32_bf16 v[40:43], v[152:155], v[210:213], v[40:43]
	v_mfma_f32_16x16x32_bf16 v[36:39], v[186:189], v[210:213], v[36:39]
	v_mfma_f32_16x16x32_bf16 v[24:27], v[152:155], v[220:223], v[24:27]
	v_mfma_f32_16x16x32_bf16 v[20:23], v[186:189], v[220:223], v[20:23]
	v_mfma_f32_16x16x32_bf16 v[8:11], v[152:155], v[228:231], v[8:11]
	v_mfma_f32_16x16x32_bf16 v[4:7], v[186:189], v[228:231], v[4:7]
	v_mfma_f32_16x16x32_bf16 v[56:59], v[182:185], v[206:209], v[56:59]
	v_mfma_f32_16x16x32_bf16 v[52:55], v[190:193], v[206:209], v[52:55]
	v_mfma_f32_16x16x32_bf16 v[40:43], v[182:185], v[216:219], v[40:43]
	v_mfma_f32_16x16x32_bf16 v[36:39], v[190:193], v[216:219], v[36:39]
	v_mfma_f32_16x16x32_bf16 v[24:27], v[182:185], v[224:227], v[24:27]
	v_mfma_f32_16x16x32_bf16 v[20:23], v[190:193], v[224:227], v[20:23]
	v_mfma_f32_16x16x32_bf16 v[8:11], v[182:185], v[232:235], v[8:11]
	v_mfma_f32_16x16x32_bf16 v[4:7], v[190:193], v[232:235], v[4:7]
	s_setprio 0
	s_barrier
	s_add_i32 s13, 0, 0x18000
	s_add_i32 s29, 0, 0x1c000
	v_add_u32_e32 v148, s13, v201
	v_add_u32_e32 v190, s29, v201
	ds_read_b128 v[136:139], v148
	ds_read_b128 v[140:143], v148 offset:1024
	ds_read_b128 v[144:147], v148 offset:2048
	ds_read_b128 v[148:151], v148 offset:3072
	ds_read_b128 v[152:155], v190
	ds_read_b128 v[182:185], v190 offset:1024
	ds_read_b128 v[186:189], v190 offset:2048
	ds_read_b128 v[190:193], v190 offset:3072
	v_lshl_add_u64 v[198:199], v[198:199], 0, s[14:15]
	s_mov_b32 m0, s35
	v_lshl_add_u64 v[246:247], v[198:199], 0, v[164:165]
	ds_read_b128 v[194:197], v203 offset:32768
	ds_read_b128 v[206:209], v203 offset:33792
	ds_read_b128 v[210:213], v203 offset:34816
	ds_read_b128 v[216:219], v203 offset:35840
	ds_read_b128 v[220:223], v203 offset:36864
	ds_read_b128 v[224:227], v203 offset:37888
	ds_read_b128 v[228:231], v203 offset:38912
	ds_read_b128 v[232:235], v203 offset:39936
	global_load_lds_dwordx4 v[246:247], off
	v_lshl_add_u64 v[198:199], v[198:199], 0, v[168:169]
	s_mov_b32 m0, s36
	s_nop 0
	global_load_lds_dwordx4 v[198:199], off
	s_waitcnt vmcnt(8)
	s_waitcnt lgkmcnt(0)
	s_barrier
	s_setprio 1
	s_waitcnt lgkmcnt(0)
	v_mfma_f32_16x16x32_bf16 v[124:127], v[136:139], v[194:197], v[124:127]
	v_mfma_f32_16x16x32_bf16 v[128:131], v[144:147], v[194:197], v[128:131]
	v_mfma_f32_16x16x32_bf16 v[112:115], v[136:139], v[210:213], v[112:115]
	v_mfma_f32_16x16x32_bf16 v[108:111], v[144:147], v[210:213], v[108:111]
	v_mfma_f32_16x16x32_bf16 v[96:99], v[136:139], v[220:223], v[96:99]
	v_mfma_f32_16x16x32_bf16 v[92:95], v[144:147], v[220:223], v[92:95]
	v_mfma_f32_16x16x32_bf16 v[80:83], v[136:139], v[228:231], v[80:83]
	v_mfma_f32_16x16x32_bf16 v[76:79], v[144:147], v[228:231], v[76:79]
	v_mfma_f32_16x16x32_bf16 v[124:127], v[140:143], v[206:209], v[124:127]
	v_mfma_f32_16x16x32_bf16 v[128:131], v[148:151], v[206:209], v[128:131]
	v_mfma_f32_16x16x32_bf16 v[112:115], v[140:143], v[216:219], v[112:115]
	v_mfma_f32_16x16x32_bf16 v[108:111], v[148:151], v[216:219], v[108:111]
	v_mfma_f32_16x16x32_bf16 v[96:99], v[140:143], v[224:227], v[96:99]
	v_mfma_f32_16x16x32_bf16 v[92:95], v[148:151], v[224:227], v[92:95]
	v_mfma_f32_16x16x32_bf16 v[80:83], v[140:143], v[232:235], v[80:83]
	v_mfma_f32_16x16x32_bf16 v[76:79], v[148:151], v[232:235], v[76:79]
	v_mfma_f32_16x16x32_bf16 v[120:123], v[152:155], v[194:197], v[120:123]
	v_mfma_f32_16x16x32_bf16 v[116:119], v[186:189], v[194:197], v[116:119]
	v_mfma_f32_16x16x32_bf16 v[104:107], v[152:155], v[210:213], v[104:107]
	v_mfma_f32_16x16x32_bf16 v[100:103], v[186:189], v[210:213], v[100:103]
	v_mfma_f32_16x16x32_bf16 v[88:91], v[152:155], v[220:223], v[88:91]
	v_mfma_f32_16x16x32_bf16 v[84:87], v[186:189], v[220:223], v[84:87]
	v_mfma_f32_16x16x32_bf16 v[72:75], v[152:155], v[228:231], v[72:75]
	v_mfma_f32_16x16x32_bf16 v[68:71], v[186:189], v[228:231], v[68:71]
	v_mfma_f32_16x16x32_bf16 v[120:123], v[182:185], v[206:209], v[120:123]
	v_mfma_f32_16x16x32_bf16 v[116:119], v[190:193], v[206:209], v[116:119]
	v_mfma_f32_16x16x32_bf16 v[104:107], v[182:185], v[216:219], v[104:107]
	v_mfma_f32_16x16x32_bf16 v[100:103], v[190:193], v[216:219], v[100:103]
	v_mfma_f32_16x16x32_bf16 v[88:91], v[182:185], v[224:227], v[88:91]
	v_mfma_f32_16x16x32_bf16 v[84:87], v[190:193], v[224:227], v[84:87]
	v_mfma_f32_16x16x32_bf16 v[72:75], v[182:185], v[232:235], v[72:75]
	v_mfma_f32_16x16x32_bf16 v[68:71], v[190:193], v[232:235], v[68:71]
	s_setprio 0
	s_barrier
; #define PG8_STAGE(bufoff, gbase, voff) do { _Pragma("unroll") for (int _i = 0; _i < 2; ++_i) \
;         __builtin_amdgcn_global_load_lds((const unsigned*)((const char*)(gbase) + (voff)[_i]), (PG8_LAS unsigned*)(lds + (bufoff) + ldsw + _i * 8192), 16, 0, 0); } while (0)
; #define PG8_LDA(dst, b, h) do { _Pragma("unroll") for (int m = 0; m < 4; ++m) _Pragma("unroll") for (int k = 0; k < 2; ++k) dst[m][k] = *(const PG8_LAS bf16x8*)(lds + PG8_SA(b, h) + aoff + m * 2048 + k * 1024); } while (0)
; #define PG8_MMA(ai, bj, At, Bt) do { __builtin_amdgcn_s_setprio(1); _Pragma("unroll") for (int m = 0; m < 4; ++m) _Pragma("unroll") for (int n = 0; n < 2; ++n) _Pragma("unroll") for (int k = 0; k < 2; ++k) \
;         acc[ai][bj][m][n] = __builtin_amdgcn_mfma_f32_16x16x32_bf16(Bt[n][k], At[m][k], acc[ai][bj][m][n], 0, 0, 0); __builtin_amdgcn_s_setprio(0); } while (0)
; #define PG8_WAIT_V(n) asm volatile("s_waitcnt vmcnt(" #n ")" ::: "memory")
; #define PG8_WAIT_L(n) asm volatile("s_waitcnt lgkmcnt(" #n ")" ::: "memory")
; #define PG8_BAR __builtin_amdgcn_s_barrier()
; #define PG8_SCHED __builtin_amdgcn_sched_barrier(0)
; template <class Epi, class Sched, bool ALIGN_EPI = false, bool SP2 = false>
; __device__ __forceinline__ void gemm_phase(PG8_LAS unsigned char* lds, const Gemm g, const Sched& S, const Epi& E) {
;     ...
;             PG8_LDA(At, 1, 1); PG8_STAGE(PG8_SB(1, 0), b3, voffB); PG8_STAGE(PG8_SB(1, 1), b3 + hstep, voffB); PG8_STAGE(PG8_SA(1, 0), a3, voffA);
;             PG8_WAIT_V(8); PG8_WAIT_L(0); PG8_BAR; PG8_MMA(1, 0, At, B0); PG8_MMA(1, 1, At, B1); PG8_BAR; PG8_SCHED;
	s_add_i32 s13, s13, s30
	v_lshl_add_u64 v[198:199], v[236:237], 0, s[22:23]
	s_mov_b32 m0, s13
	ds_read_b128 v[194:197], v203 offset:49152
	ds_read_b128 v[206:209], v203 offset:50176
	ds_read_b128 v[210:213], v203 offset:51200
	ds_read_b128 v[216:219], v203 offset:52224
	ds_read_b128 v[220:223], v203 offset:53248
	ds_read_b128 v[224:227], v203 offset:54272
	ds_read_b128 v[228:231], v203 offset:55296
	ds_read_b128 v[232:235], v203 offset:56320
	global_load_lds_dwordx4 v[198:199], off
	v_lshl_add_u64 v[198:199], v[238:239], 0, s[22:23]
	s_add_i32 m0, s13, 0x2000
	s_add_i32 s13, s29, s30
	global_load_lds_dwordx4 v[198:199], off
	v_lshl_add_u64 v[198:199], v[240:241], 0, s[22:23]
	s_mov_b32 m0, s13
	s_nop 0
	global_load_lds_dwordx4 v[198:199], off
	v_lshl_add_u64 v[198:199], v[214:215], 0, s[22:23]
	s_add_i32 m0, s13, 0x2000
	s_nop 0
	global_load_lds_dwordx4 v[198:199], off
	v_lshl_add_u64 v[198:199], v[242:243], 0, s[22:23]
	s_mov_b32 m0, s37
	s_nop 0
	global_load_lds_dwordx4 v[198:199], off
	v_lshl_add_u64 v[198:199], v[244:245], 0, s[22:23]
	s_mov_b32 m0, s41
	s_nop 0
	global_load_lds_dwordx4 v[198:199], off
	s_waitcnt vmcnt(8)
	s_waitcnt lgkmcnt(0)
	s_barrier
	s_setprio 1
	s_waitcnt lgkmcnt(0)
	v_mfma_f32_16x16x32_bf16 v[64:67], v[136:139], v[194:197], v[64:67]
	v_mfma_f32_16x16x32_bf16 v[60:63], v[144:147], v[194:197], v[60:63]
	v_mfma_f32_16x16x32_bf16 v[48:51], v[136:139], v[210:213], v[48:51]
	v_mfma_f32_16x16x32_bf16 v[44:47], v[144:147], v[210:213], v[44:47]
	v_mfma_f32_16x16x32_bf16 v[32:35], v[136:139], v[220:223], v[32:35]
	v_mfma_f32_16x16x32_bf16 v[28:31], v[144:147], v[220:223], v[28:31]
	v_mfma_f32_16x16x32_bf16 v[16:19], v[136:139], v[228:231], v[16:19]
	v_mfma_f32_16x16x32_bf16 v[12:15], v[144:147], v[228:231], v[12:15]
	v_mfma_f32_16x16x32_bf16 v[64:67], v[140:143], v[206:209], v[64:67]
	v_mfma_f32_16x16x32_bf16 v[60:63], v[148:151], v[206:209], v[60:63]
	v_mfma_f32_16x16x32_bf16 v[48:51], v[140:143], v[216:219], v[48:51]
	v_mfma_f32_16x16x32_bf16 v[44:47], v[148:151], v[216:219], v[44:47]
	v_mfma_f32_16x16x32_bf16 v[32:35], v[140:143], v[224:227], v[32:35]
	v_mfma_f32_16x16x32_bf16 v[28:31], v[148:151], v[224:227], v[28:31]
	v_mfma_f32_16x16x32_bf16 v[16:19], v[140:143], v[232:235], v[16:19]
	v_mfma_f32_16x16x32_bf16 v[12:15], v[148:151], v[232:235], v[12:15]
	v_mfma_f32_16x16x32_bf16 v[56:59], v[152:155], v[194:197], v[56:59]
	v_mfma_f32_16x16x32_bf16 v[52:55], v[186:189], v[194:197], v[52:55]
	v_mfma_f32_16x16x32_bf16 v[40:43], v[152:155], v[210:213], v[40:43]
	v_mfma_f32_16x16x32_bf16 v[36:39], v[186:189], v[210:213], v[36:39]
	v_mfma_f32_16x16x32_bf16 v[24:27], v[152:155], v[220:223], v[24:27]
	v_mfma_f32_16x16x32_bf16 v[20:23], v[186:189], v[220:223], v[20:23]
	v_mfma_f32_16x16x32_bf16 v[8:11], v[152:155], v[228:231], v[8:11]
	v_mfma_f32_16x16x32_bf16 v[4:7], v[186:189], v[228:231], v[4:7]
	v_mfma_f32_16x16x32_bf16 v[56:59], v[182:185], v[206:209], v[56:59]
	v_mfma_f32_16x16x32_bf16 v[52:55], v[190:193], v[206:209], v[52:55]
	v_mfma_f32_16x16x32_bf16 v[40:43], v[182:185], v[216:219], v[40:43]
	v_mfma_f32_16x16x32_bf16 v[36:39], v[190:193], v[216:219], v[36:39]
	v_mfma_f32_16x16x32_bf16 v[24:27], v[182:185], v[224:227], v[24:27]
	v_mfma_f32_16x16x32_bf16 v[20:23], v[190:193], v[224:227], v[20:23]
	v_mfma_f32_16x16x32_bf16 v[8:11], v[182:185], v[232:235], v[8:11]
	v_mfma_f32_16x16x32_bf16 v[4:7], v[190:193], v[232:235], v[4:7]
	s_setprio 0
	s_barrier
	v_lshl_add_u64 v[132:133], v[132:133], 0, s[26:27]
	s_cmp_ge_i32 s12, s47
	v_lshl_add_u64 v[134:135], v[134:135], 0, s[26:27]
	s_cbranch_scc0 .LBB0_371

; #define PG8_STAGE(bufoff, gbase, voff) do { _Pragma("unroll") for (int _i = 0; _i < 2; ++_i) \
;         __builtin_amdgcn_global_load_lds((const unsigned*)((const char*)(gbase) + (voff)[_i]), (PG8_LAS unsigned*)(lds + (bufoff) + ldsw + _i * 8192), 16, 0, 0); } while (0)
; #define PG8_LDA(dst, b, h) do { _Pragma("unroll") for (int m = 0; m < 4; ++m) _Pragma("unroll") for (int k = 0; k < 2; ++k) dst[m][k] = *(const PG8_LAS bf16x8*)(lds + PG8_SA(b, h) + aoff + m * 2048 + k * 1024); } while (0)
; #define PG8_LDB(dst, b, h) do { _Pragma("unroll") for (int n = 0; n < 2; ++n) _Pragma("unroll") for (int k = 0; k < 2; ++k) dst[n][k] = *(const PG8_LAS bf16x8*)(lds + PG8_SB(b, h) + boff + n * 2048 + k * 1024); } while (0)
; #define PG8_MMA(ai, bj, At, Bt) do { __builtin_amdgcn_s_setprio(1); _Pragma("unroll") for (int m = 0; m < 4; ++m) _Pragma("unroll") for (int n = 0; n < 2; ++n) _Pragma("unroll") for (int k = 0; k < 2; ++k) \
;         acc[ai][bj][m][n] = __builtin_amdgcn_mfma_f32_16x16x32_bf16(Bt[n][k], At[m][k], acc[ai][bj][m][n], 0, 0, 0); __builtin_amdgcn_s_setprio(0); } while (0)
; #define PG8_WAIT_V(n) asm volatile("s_waitcnt vmcnt(" #n ")" ::: "memory")
; #define PG8_WAIT_L(n) asm volatile("s_waitcnt lgkmcnt(" #n ")" ::: "memory")
; #define PG8_BAR __builtin_amdgcn_s_barrier()
; #define PG8_SCHED __builtin_amdgcn_sched_barrier(0)
; template <class Epi, class Sched, bool ALIGN_EPI = false, bool SP2 = false>
; __device__ __forceinline__ void gemm_phase(PG8_LAS unsigned char* lds, const Gemm g, const Sched& S, const Epi& E) {
;     ...
;         for (int t = 0; t < nt; t += 2) {
;             const bool last = (t == nt - 2);
;             const char* a1 = cA + (size_t)(t + 1) * kstep;
;             const char* a2 = last ? nA : cA + (size_t)(t + 2) * kstep; const char* b2 = last ? nB : cB + (size_t)(t + 2) * kstep;
;             const char* a3 = a2 + kstep; const char* b3 = b2 + kstep;
;             if (last && has_next) S.a_ready(nxt);
;             if constexpr (SP2) {
;             PG8_LDB(B0, 0, 0); PG8_LDB(B1, 0, 1); PG8_SCHED; PG8_LDA(At, 0, 0); PG8_STAGE(PG8_SA(1, 1), a1 + hstep, voffA);
;             PG8_WAIT_V(8); PG8_WAIT_L(0); PG8_BAR; PG8_MMA(0, 0, At, B0); PG8_MMA(0, 1, At, B1); PG8_BAR; PG8_SCHED;
;             PG8_LDA(At, 0, 1); PG8_STAGE(PG8_SB(0, 0), b2, voffB); PG8_STAGE(PG8_SB(0, 1), b2 + hstep, voffB); PG8_STAGE(PG8_SA(0, 0), a2, voffA);
.LBB0_454:
	v_add_u32_e32 v165, s69, v171
	v_add_u32_e32 v167, s70, v171
	ds_read_b128 v[132:135], v165
	ds_read_b128 v[136:139], v165 offset:1024
	ds_read_b128 v[176:179], v165 offset:2048
	ds_read_b128 v[180:183], v165 offset:3072
	ds_read_b128 v[184:187], v167
	ds_read_b128 v[188:191], v167 offset:1024
	ds_read_b128 v[192:195], v167 offset:2048
	ds_read_b128 v[196:199], v167 offset:3072
	s_cmp_eq_u32 s62, s12
	v_lshl_add_u64 v[200:201], v[130:131], 0, s[24:25]
	s_cselect_b64 vcc, -1, 0
	s_add_i32 s12, s12, 2
	v_cndmask_b32_e32 v209, v201, v173, vcc
	v_cndmask_b32_e32 v208, v200, v172, vcc
	v_cndmask_b32_e32 v213, v129, v175, vcc
	v_cndmask_b32_e32 v212, v128, v174, vcc
	v_lshl_add_u64 v[214:215], v[130:131], 0, v[160:161]
	s_add_i32 m0, s41, 0xc000
	ds_read_b128 v[200:203], v216
	ds_read_b128 v[204:207], v216 offset:1024
	ds_read_b128 v[218:221], v216 offset:2048
	ds_read_b128 v[222:225], v216 offset:3072
	ds_read_b128 v[226:229], v216 offset:4096
	ds_read_b128 v[230:233], v216 offset:5120
	ds_read_b128 v[234:237], v216 offset:6144
	ds_read_b128 v[238:241], v216 offset:7168
	global_load_lds_dwordx4 v[214:215], off
	v_lshl_add_u64 v[214:215], v[130:131], 0, v[158:159]
	s_add_i32 m0, s41, 0xe000
	s_nop 0
	global_load_lds_dwordx4 v[214:215], off
	s_waitcnt vmcnt(8)
	s_waitcnt lgkmcnt(0)
	s_barrier
	s_setprio 1
	s_waitcnt lgkmcnt(0)
	v_mfma_f32_16x16x32_bf16 v[124:127], v[132:135], v[200:203], v[124:127]
	v_mfma_f32_16x16x32_bf16 v[120:123], v[176:179], v[200:203], v[120:123]
	v_mfma_f32_16x16x32_bf16 v[108:111], v[132:135], v[218:221], v[108:111]
	v_mfma_f32_16x16x32_bf16 v[104:107], v[176:179], v[218:221], v[104:107]
	v_mfma_f32_16x16x32_bf16 v[92:95], v[132:135], v[226:229], v[92:95]
	v_mfma_f32_16x16x32_bf16 v[88:91], v[176:179], v[226:229], v[88:91]
	v_mfma_f32_16x16x32_bf16 v[76:79], v[132:135], v[234:237], v[76:79]
	v_mfma_f32_16x16x32_bf16 v[72:75], v[176:179], v[234:237], v[72:75]
	v_mfma_f32_16x16x32_bf16 v[124:127], v[136:139], v[204:207], v[124:127]
	v_mfma_f32_16x16x32_bf16 v[120:123], v[180:183], v[204:207], v[120:123]
	v_mfma_f32_16x16x32_bf16 v[108:111], v[136:139], v[222:225], v[108:111]
	v_mfma_f32_16x16x32_bf16 v[104:107], v[180:183], v[222:225], v[104:107]
	v_mfma_f32_16x16x32_bf16 v[92:95], v[136:139], v[230:233], v[92:95]
	v_mfma_f32_16x16x32_bf16 v[88:91], v[180:183], v[230:233], v[88:91]
	v_mfma_f32_16x16x32_bf16 v[76:79], v[136:139], v[238:241], v[76:79]
	v_mfma_f32_16x16x32_bf16 v[72:75], v[180:183], v[238:241], v[72:75]
	v_mfma_f32_16x16x32_bf16 v[116:119], v[184:187], v[200:203], v[116:119]
	v_mfma_f32_16x16x32_bf16 v[112:115], v[192:195], v[200:203], v[112:115]
	v_mfma_f32_16x16x32_bf16 v[100:103], v[184:187], v[218:221], v[100:103]
	v_mfma_f32_16x16x32_bf16 v[96:99], v[192:195], v[218:221], v[96:99]
	v_mfma_f32_16x16x32_bf16 v[84:87], v[184:187], v[226:229], v[84:87]
	v_mfma_f32_16x16x32_bf16 v[80:83], v[192:195], v[226:229], v[80:83]
	v_mfma_f32_16x16x32_bf16 v[68:71], v[184:187], v[234:237], v[68:71]
	v_mfma_f32_16x16x32_bf16 v[64:67], v[192:195], v[234:237], v[64:67]
	v_mfma_f32_16x16x32_bf16 v[116:119], v[188:191], v[204:207], v[116:119]
	v_mfma_f32_16x16x32_bf16 v[112:115], v[196:199], v[204:207], v[112:115]
	v_mfma_f32_16x16x32_bf16 v[100:103], v[188:191], v[222:225], v[100:103]
	v_mfma_f32_16x16x32_bf16 v[96:99], v[196:199], v[222:225], v[96:99]
	v_mfma_f32_16x16x32_bf16 v[84:87], v[188:191], v[230:233], v[84:87]
	v_mfma_f32_16x16x32_bf16 v[80:83], v[196:199], v[230:233], v[80:83]
	v_mfma_f32_16x16x32_bf16 v[68:71], v[188:191], v[238:241], v[68:71]
	v_mfma_f32_16x16x32_bf16 v[64:67], v[196:199], v[238:241], v[64:67]
	s_setprio 0
	s_barrier
	s_add_i32 s13, s69, s37
	v_lshl_add_u64 v[214:215], v[212:213], 0, v[146:147]
	s_mov_b32 m0, s13
	ds_read_b128 v[200:203], v216 offset:16384
	ds_read_b128 v[204:207], v216 offset:17408
	ds_read_b128 v[218:221], v216 offset:18432
	ds_read_b128 v[222:225], v216 offset:19456
	ds_read_b128 v[226:229], v216 offset:20480
	ds_read_b128 v[230:233], v216 offset:21504
	ds_read_b128 v[234:237], v216 offset:22528
	ds_read_b128 v[238:241], v216 offset:23552
	global_load_lds_dwordx4 v[214:215], off
	v_lshl_add_u64 v[242:243], v[212:213], 0, v[150:151]
	s_add_i32 m0, s13, 0x2000
	v_lshl_add_u64 v[212:213], v[212:213], 0, s[16:17]
	s_add_i32 s13, s70, s37
	global_load_lds_dwordx4 v[242:243], off
	v_lshl_add_u64 v[244:245], v[212:213], 0, v[146:147]
	s_mov_b32 m0, s13
	v_lshl_add_u64 v[212:213], v[212:213], 0, v[150:151]
	global_load_lds_dwordx4 v[244:245], off
	s_add_i32 m0, s13, 0x2000
	v_lshl_add_u64 v[246:247], v[208:209], 0, v[144:145]
	global_load_lds_dwordx4 v[212:213], off
	s_mov_b32 m0, s41
	v_lshl_add_u64 v[248:249], v[208:209], 0, v[148:149]
	global_load_lds_dwordx4 v[246:247], off
	s_mov_b32 m0, s50
	s_nop 0
	global_load_lds_dwordx4 v[248:249], off
	s_waitcnt vmcnt(8)
	s_waitcnt lgkmcnt(0)
	s_barrier
; #define PG8_STAGE(bufoff, gbase, voff) do { _Pragma("unroll") for (int _i = 0; _i < 2; ++_i) \
;         __builtin_amdgcn_global_load_lds((const unsigned*)((const char*)(gbase) + (voff)[_i]), (PG8_LAS unsigned*)(lds + (bufoff) + ldsw + _i * 8192), 16, 0, 0); } while (0)
; #define PG8_LDA(dst, b, h) do { _Pragma("unroll") for (int m = 0; m < 4; ++m) _Pragma("unroll") for (int k = 0; k < 2; ++k) dst[m][k] = *(const PG8_LAS bf16x8*)(lds + PG8_SA(b, h) + aoff + m * 2048 + k * 1024); } while (0)
; #define PG8_LDB(dst, b, h) do { _Pragma("unroll") for (int n = 0; n < 2; ++n) _Pragma("unroll") for (int k = 0; k < 2; ++k) dst[n][k] = *(const PG8_LAS bf16x8*)(lds + PG8_SB(b, h) + boff + n * 2048 + k * 1024); } while (0)
; #define PG8_MMA(ai, bj, At, Bt) do { __builtin_amdgcn_s_setprio(1); _Pragma("unroll") for (int m = 0; m < 4; ++m) _Pragma("unroll") for (int n = 0; n < 2; ++n) _Pragma("unroll") for (int k = 0; k < 2; ++k) \
;         acc[ai][bj][m][n] = __builtin_amdgcn_mfma_f32_16x16x32_bf16(Bt[n][k], At[m][k], acc[ai][bj][m][n], 0, 0, 0); __builtin_amdgcn_s_setprio(0); } while (0)
; #define PG8_WAIT_V(n) asm volatile("s_waitcnt vmcnt(" #n ")" ::: "memory")
; #define PG8_WAIT_L(n) asm volatile("s_waitcnt lgkmcnt(" #n ")" ::: "memory")
; #define PG8_BAR __builtin_amdgcn_s_barrier()
; #define PG8_SCHED __builtin_amdgcn_sched_barrier(0)
; template <class Epi, class Sched, bool ALIGN_EPI = false, bool SP2 = false>
; __device__ __forceinline__ void gemm_phase(PG8_LAS unsigned char* lds, const Gemm g, const Sched& S, const Epi& E) {
;     ...
;             PG8_WAIT_V(8); PG8_WAIT_L(0); PG8_BAR; PG8_MMA(1, 0, At, B0); PG8_MMA(1, 1, At, B1); PG8_BAR; PG8_SCHED;
;             PG8_LDB(B0, 1, 0); PG8_LDB(B1, 1, 1); PG8_SCHED; PG8_LDA(At, 1, 0); PG8_STAGE(PG8_SA(0, 1), a2 + hstep, voffA);
;             PG8_WAIT_V(8); PG8_WAIT_L(0); PG8_BAR; PG8_MMA(0, 0, At, B0); PG8_MMA(0, 1, At, B1); PG8_BAR; PG8_SCHED;
	s_setprio 1
	s_waitcnt lgkmcnt(0)
	v_mfma_f32_16x16x32_bf16 v[60:63], v[132:135], v[200:203], v[60:63]
	v_mfma_f32_16x16x32_bf16 v[56:59], v[176:179], v[200:203], v[56:59]
	v_mfma_f32_16x16x32_bf16 v[44:47], v[132:135], v[218:221], v[44:47]
	v_mfma_f32_16x16x32_bf16 v[40:43], v[176:179], v[218:221], v[40:43]
	v_mfma_f32_16x16x32_bf16 v[28:31], v[132:135], v[226:229], v[28:31]
	v_mfma_f32_16x16x32_bf16 v[24:27], v[176:179], v[226:229], v[24:27]
	v_mfma_f32_16x16x32_bf16 v[12:15], v[132:135], v[234:237], v[12:15]
	v_mfma_f32_16x16x32_bf16 v[8:11], v[176:179], v[234:237], v[8:11]
	v_mfma_f32_16x16x32_bf16 v[60:63], v[136:139], v[204:207], v[60:63]
	v_mfma_f32_16x16x32_bf16 v[56:59], v[180:183], v[204:207], v[56:59]
	v_mfma_f32_16x16x32_bf16 v[44:47], v[136:139], v[222:225], v[44:47]
	v_mfma_f32_16x16x32_bf16 v[40:43], v[180:183], v[222:225], v[40:43]
	v_mfma_f32_16x16x32_bf16 v[28:31], v[136:139], v[230:233], v[28:31]
	v_mfma_f32_16x16x32_bf16 v[24:27], v[180:183], v[230:233], v[24:27]
	v_mfma_f32_16x16x32_bf16 v[12:15], v[136:139], v[238:241], v[12:15]
	v_mfma_f32_16x16x32_bf16 v[8:11], v[180:183], v[238:241], v[8:11]
	v_mfma_f32_16x16x32_bf16 v[52:55], v[184:187], v[200:203], v[52:55]
	v_mfma_f32_16x16x32_bf16 v[48:51], v[192:195], v[200:203], v[48:51]
	v_mfma_f32_16x16x32_bf16 v[36:39], v[184:187], v[218:221], v[36:39]
	v_mfma_f32_16x16x32_bf16 v[32:35], v[192:195], v[218:221], v[32:35]
	v_mfma_f32_16x16x32_bf16 v[20:23], v[184:187], v[226:229], v[20:23]
	v_mfma_f32_16x16x32_bf16 v[16:19], v[192:195], v[226:229], v[16:19]
	v_mfma_f32_16x16x32_bf16 v[4:7], v[184:187], v[234:237], v[4:7]
	v_mfma_f32_16x16x32_bf16 v[0:3], v[192:195], v[234:237], v[0:3]
	v_mfma_f32_16x16x32_bf16 v[52:55], v[188:191], v[204:207], v[52:55]
	v_mfma_f32_16x16x32_bf16 v[48:51], v[196:199], v[204:207], v[48:51]
	v_mfma_f32_16x16x32_bf16 v[36:39], v[188:191], v[222:225], v[36:39]
	v_mfma_f32_16x16x32_bf16 v[32:35], v[196:199], v[222:225], v[32:35]
	v_mfma_f32_16x16x32_bf16 v[20:23], v[188:191], v[230:233], v[20:23]
	v_mfma_f32_16x16x32_bf16 v[16:19], v[196:199], v[230:233], v[16:19]
	v_mfma_f32_16x16x32_bf16 v[4:7], v[188:191], v[238:241], v[4:7]
	v_mfma_f32_16x16x32_bf16 v[0:3], v[196:199], v[238:241], v[0:3]
	s_setprio 0
	s_barrier
	s_add_i32 s13, 0, 0x18000
	v_add_u32_e32 v165, s13, v171
	s_add_i32 s15, 0, 0x1c000
	ds_read_b128 v[132:135], v165
	ds_read_b128 v[136:139], v165 offset:1024
	ds_read_b128 v[176:179], v165 offset:2048
	ds_read_b128 v[180:183], v165 offset:3072
	v_add_u32_e32 v165, s15, v171
	ds_read_b128 v[184:187], v165
	ds_read_b128 v[188:191], v165 offset:1024
	ds_read_b128 v[192:195], v165 offset:2048
	ds_read_b128 v[196:199], v165 offset:3072
	v_lshl_add_u64 v[208:209], v[208:209], 0, s[16:17]
	s_mov_b32 m0, s52
	v_lshl_add_u64 v[250:251], v[208:209], 0, v[144:145]
	ds_read_b128 v[200:203], v216 offset:32768
	ds_read_b128 v[204:207], v216 offset:33792
	ds_read_b128 v[218:221], v216 offset:34816
	ds_read_b128 v[222:225], v216 offset:35840
	ds_read_b128 v[226:229], v216 offset:36864
	ds_read_b128 v[230:233], v216 offset:37888
	ds_read_b128 v[234:237], v216 offset:38912
	ds_read_b128 v[238:241], v216 offset:39936
	global_load_lds_dwordx4 v[250:251], off
	v_lshl_add_u64 v[208:209], v[208:209], 0, v[148:149]
	s_mov_b32 m0, s53
	s_nop 0
	global_load_lds_dwordx4 v[208:209], off
	s_waitcnt vmcnt(8)
	s_waitcnt lgkmcnt(0)
	s_barrier
	s_setprio 1
	s_waitcnt lgkmcnt(0)
	v_mfma_f32_16x16x32_bf16 v[124:127], v[132:135], v[200:203], v[124:127]
	v_mfma_f32_16x16x32_bf16 v[120:123], v[176:179], v[200:203], v[120:123]
	v_mfma_f32_16x16x32_bf16 v[108:111], v[132:135], v[218:221], v[108:111]
	v_mfma_f32_16x16x32_bf16 v[104:107], v[176:179], v[218:221], v[104:107]
	v_mfma_f32_16x16x32_bf16 v[92:95], v[132:135], v[226:229], v[92:95]
	v_mfma_f32_16x16x32_bf16 v[88:91], v[176:179], v[226:229], v[88:91]
	v_mfma_f32_16x16x32_bf16 v[76:79], v[132:135], v[234:237], v[76:79]
	v_mfma_f32_16x16x32_bf16 v[72:75], v[176:179], v[234:237], v[72:75]
	v_mfma_f32_16x16x32_bf16 v[124:127], v[136:139], v[204:207], v[124:127]
	v_mfma_f32_16x16x32_bf16 v[120:123], v[180:183], v[204:207], v[120:123]
	v_mfma_f32_16x16x32_bf16 v[108:111], v[136:139], v[222:225], v[108:111]
	v_mfma_f32_16x16x32_bf16 v[104:107], v[180:183], v[222:225], v[104:107]
	v_mfma_f32_16x16x32_bf16 v[92:95], v[136:139], v[230:233], v[92:95]
	v_mfma_f32_16x16x32_bf16 v[88:91], v[180:183], v[230:233], v[88:91]
	v_mfma_f32_16x16x32_bf16 v[76:79], v[136:139], v[238:241], v[76:79]
	v_mfma_f32_16x16x32_bf16 v[72:75], v[180:183], v[238:241], v[72:75]
	v_mfma_f32_16x16x32_bf16 v[116:119], v[184:187], v[200:203], v[116:119]
	v_mfma_f32_16x16x32_bf16 v[112:115], v[192:195], v[200:203], v[112:115]
	v_mfma_f32_16x16x32_bf16 v[100:103], v[184:187], v[218:221], v[100:103]
	v_mfma_f32_16x16x32_bf16 v[96:99], v[192:195], v[218:221], v[96:99]
	v_mfma_f32_16x16x32_bf16 v[84:87], v[184:187], v[226:229], v[84:87]
	v_mfma_f32_16x16x32_bf16 v[80:83], v[192:195], v[226:229], v[80:83]
	v_mfma_f32_16x16x32_bf16 v[68:71], v[184:187], v[234:237], v[68:71]
	v_mfma_f32_16x16x32_bf16 v[64:67], v[192:195], v[234:237], v[64:67]
	v_mfma_f32_16x16x32_bf16 v[116:119], v[188:191], v[204:207], v[116:119]
	v_mfma_f32_16x16x32_bf16 v[112:115], v[196:199], v[204:207], v[112:115]
	v_mfma_f32_16x16x32_bf16 v[100:103], v[188:191], v[222:225], v[100:103]
	v_mfma_f32_16x16x32_bf16 v[96:99], v[196:199], v[222:225], v[96:99]
	v_mfma_f32_16x16x32_bf16 v[84:87], v[188:191], v[230:233], v[84:87]
	v_mfma_f32_16x16x32_bf16 v[80:83], v[196:199], v[230:233], v[80:83]
	v_mfma_f32_16x16x32_bf16 v[68:71], v[188:191], v[238:241], v[68:71]
	v_mfma_f32_16x16x32_bf16 v[64:67], v[196:199], v[238:241], v[64:67]
	s_setprio 0
	s_barrier
; #define PG8_STAGE(bufoff, gbase, voff) do { _Pragma("unroll") for (int _i = 0; _i < 2; ++_i) \
;         __builtin_amdgcn_global_load_lds((const unsigned*)((const char*)(gbase) + (voff)[_i]), (PG8_LAS unsigned*)(lds + (bufoff) + ldsw + _i * 8192), 16, 0, 0); } while (0)
; #define PG8_LDA(dst, b, h) do { _Pragma("unroll") for (int m = 0; m < 4; ++m) _Pragma("unroll") for (int k = 0; k < 2; ++k) dst[m][k] = *(const PG8_LAS bf16x8*)(lds + PG8_SA(b, h) + aoff + m * 2048 + k * 1024); } while (0)
; #define PG8_MMA(ai, bj, At, Bt) do { __builtin_amdgcn_s_setprio(1); _Pragma("unroll") for (int m = 0; m < 4; ++m) _Pragma("unroll") for (int n = 0; n < 2; ++n) _Pragma("unroll") for (int k = 0; k < 2; ++k) \
;         acc[ai][bj][m][n] = __builtin_amdgcn_mfma_f32_16x16x32_bf16(Bt[n][k], At[m][k], acc[ai][bj][m][n], 0, 0, 0); __builtin_amdgcn_s_setprio(0); } while (0)
; #define PG8_WAIT_V(n) asm volatile("s_waitcnt vmcnt(" #n ")" ::: "memory")
; #define PG8_WAIT_L(n) asm volatile("s_waitcnt lgkmcnt(" #n ")" ::: "memory")
; #define PG8_BAR __builtin_amdgcn_s_barrier()
; #define PG8_SCHED __builtin_amdgcn_sched_barrier(0)
; template <class Epi, class Sched, bool ALIGN_EPI = false, bool SP2 = false>
; __device__ __forceinline__ void gemm_phase(PG8_LAS unsigned char* lds, const Gemm g, const Sched& S, const Epi& E) {
;     ...
;             PG8_LDA(At, 1, 1); PG8_STAGE(PG8_SB(1, 0), b3, voffB); PG8_STAGE(PG8_SB(1, 1), b3 + hstep, voffB); PG8_STAGE(PG8_SA(1, 0), a3, voffA);
;             PG8_WAIT_V(8); PG8_WAIT_L(0); PG8_BAR; PG8_MMA(1, 0, At, B0); PG8_MMA(1, 1, At, B1); PG8_BAR; PG8_SCHED;
	s_add_i32 s13, s13, s37
	v_lshl_add_u64 v[208:209], v[214:215], 0, s[24:25]
	s_mov_b32 m0, s13
	ds_read_b128 v[200:203], v216 offset:49152
	ds_read_b128 v[204:207], v216 offset:50176
	ds_read_b128 v[218:221], v216 offset:51200
	ds_read_b128 v[222:225], v216 offset:52224
	ds_read_b128 v[226:229], v216 offset:53248
	ds_read_b128 v[230:233], v216 offset:54272
	ds_read_b128 v[234:237], v216 offset:55296
	ds_read_b128 v[238:241], v216 offset:56320
	global_load_lds_dwordx4 v[208:209], off
	v_lshl_add_u64 v[208:209], v[242:243], 0, s[24:25]
	s_add_i32 m0, s13, 0x2000
	s_add_i32 s13, s15, s37
	global_load_lds_dwordx4 v[208:209], off
	v_lshl_add_u64 v[208:209], v[244:245], 0, s[24:25]
	s_mov_b32 m0, s13
	s_nop 0
	global_load_lds_dwordx4 v[208:209], off
	v_lshl_add_u64 v[208:209], v[212:213], 0, s[24:25]
	s_add_i32 m0, s13, 0x2000
	s_nop 0
	global_load_lds_dwordx4 v[208:209], off
	v_lshl_add_u64 v[208:209], v[246:247], 0, s[24:25]
	s_mov_b32 m0, s56
	s_nop 0
	global_load_lds_dwordx4 v[208:209], off
	v_lshl_add_u64 v[208:209], v[248:249], 0, s[24:25]
	s_mov_b32 m0, s57
	s_nop 0
	global_load_lds_dwordx4 v[208:209], off
	s_waitcnt vmcnt(8)
	s_waitcnt lgkmcnt(0)
	s_barrier
	s_setprio 1
	s_waitcnt lgkmcnt(0)
	v_mfma_f32_16x16x32_bf16 v[60:63], v[132:135], v[200:203], v[60:63]
	v_mfma_f32_16x16x32_bf16 v[56:59], v[176:179], v[200:203], v[56:59]
	v_mfma_f32_16x16x32_bf16 v[44:47], v[132:135], v[218:221], v[44:47]
	v_mfma_f32_16x16x32_bf16 v[40:43], v[176:179], v[218:221], v[40:43]
	v_mfma_f32_16x16x32_bf16 v[28:31], v[132:135], v[226:229], v[28:31]
	v_mfma_f32_16x16x32_bf16 v[24:27], v[176:179], v[226:229], v[24:27]
	v_mfma_f32_16x16x32_bf16 v[12:15], v[132:135], v[234:237], v[12:15]
	v_mfma_f32_16x16x32_bf16 v[8:11], v[176:179], v[234:237], v[8:11]
	v_mfma_f32_16x16x32_bf16 v[60:63], v[136:139], v[204:207], v[60:63]
	v_mfma_f32_16x16x32_bf16 v[56:59], v[180:183], v[204:207], v[56:59]
	v_mfma_f32_16x16x32_bf16 v[44:47], v[136:139], v[222:225], v[44:47]
	v_mfma_f32_16x16x32_bf16 v[40:43], v[180:183], v[222:225], v[40:43]
	v_mfma_f32_16x16x32_bf16 v[28:31], v[136:139], v[230:233], v[28:31]
	v_mfma_f32_16x16x32_bf16 v[24:27], v[180:183], v[230:233], v[24:27]
	v_mfma_f32_16x16x32_bf16 v[12:15], v[136:139], v[238:241], v[12:15]
	v_mfma_f32_16x16x32_bf16 v[8:11], v[180:183], v[238:241], v[8:11]
	v_mfma_f32_16x16x32_bf16 v[52:55], v[184:187], v[200:203], v[52:55]
	v_mfma_f32_16x16x32_bf16 v[48:51], v[192:195], v[200:203], v[48:51]
	v_mfma_f32_16x16x32_bf16 v[36:39], v[184:187], v[218:221], v[36:39]
	v_mfma_f32_16x16x32_bf16 v[32:35], v[192:195], v[218:221], v[32:35]
	v_mfma_f32_16x16x32_bf16 v[20:23], v[184:187], v[226:229], v[20:23]
	v_mfma_f32_16x16x32_bf16 v[16:19], v[192:195], v[226:229], v[16:19]
	v_mfma_f32_16x16x32_bf16 v[4:7], v[184:187], v[234:237], v[4:7]
	v_mfma_f32_16x16x32_bf16 v[0:3], v[192:195], v[234:237], v[0:3]
	v_mfma_f32_16x16x32_bf16 v[52:55], v[188:191], v[204:207], v[52:55]
	v_mfma_f32_16x16x32_bf16 v[48:51], v[196:199], v[204:207], v[48:51]
	v_mfma_f32_16x16x32_bf16 v[36:39], v[188:191], v[222:225], v[36:39]
	v_mfma_f32_16x16x32_bf16 v[32:35], v[196:199], v[222:225], v[32:35]
	v_mfma_f32_16x16x32_bf16 v[20:23], v[188:191], v[230:233], v[20:23]
	v_mfma_f32_16x16x32_bf16 v[16:19], v[196:199], v[230:233], v[16:19]
	v_mfma_f32_16x16x32_bf16 v[4:7], v[188:191], v[238:241], v[4:7]
	v_mfma_f32_16x16x32_bf16 v[0:3], v[196:199], v[238:241], v[0:3]
	s_setprio 0
	s_barrier
	v_lshl_add_u64 v[128:129], v[128:129], 0, s[34:35]
	s_cmp_ge_i32 s12, s58
	v_lshl_add_u64 v[130:131], v[130:131], 0, s[34:35]
	s_cbranch_scc0 .LBB0_454

; #define PG8_STAGE(bufoff, gbase, voff) do { _Pragma("unroll") for (int _i = 0; _i < 2; ++_i) \
;         __builtin_amdgcn_global_load_lds((const unsigned*)((const char*)(gbase) + (voff)[_i]), (PG8_LAS unsigned*)(lds + (bufoff) + ldsw + _i * 8192), 16, 0, 0); } while (0)
; #define PG8_LDA(dst, b, h) do { _Pragma("unroll") for (int m = 0; m < 4; ++m) _Pragma("unroll") for (int k = 0; k < 2; ++k) dst[m][k] = *(const PG8_LAS bf16x8*)(lds + PG8_SA(b, h) + aoff + m * 2048 + k * 1024); } while (0)
; #define PG8_LDB(dst, b, h) do { _Pragma("unroll") for (int n = 0; n < 2; ++n) _Pragma("unroll") for (int k = 0; k < 2; ++k) dst[n][k] = *(const PG8_LAS bf16x8*)(lds + PG8_SB(b, h) + boff + n * 2048 + k * 1024); } while (0)
; #define PG8_MMA(ai, bj, At, Bt) do { __builtin_amdgcn_s_setprio(1); _Pragma("unroll") for (int m = 0; m < 4; ++m) _Pragma("unroll") for (int n = 0; n < 2; ++n) _Pragma("unroll") for (int k = 0; k < 2; ++k) \
;         acc[ai][bj][m][n] = __builtin_amdgcn_mfma_f32_16x16x32_bf16(Bt[n][k], At[m][k], acc[ai][bj][m][n], 0, 0, 0); __builtin_amdgcn_s_setprio(0); } while (0)
; #define PG8_WAIT_V(n) asm volatile("s_waitcnt vmcnt(" #n ")" ::: "memory")
; #define PG8_WAIT_L(n) asm volatile("s_waitcnt lgkmcnt(" #n ")" ::: "memory")
; #define PG8_BAR __builtin_amdgcn_s_barrier()
; #define PG8_SCHED __builtin_amdgcn_sched_barrier(0)
; template <class Epi, class Sched, bool ALIGN_EPI = false, bool SP2 = false>
; __device__ __forceinline__ void gemm_phase(PG8_LAS unsigned char* lds, const Gemm g, const Sched& S, const Epi& E) {
;     ...
;         for (int t = 0; t < nt; t += 2) {
;             const bool last = (t == nt - 2);
;             const char* a1 = cA + (size_t)(t + 1) * kstep;
;             const char* a2 = last ? nA : cA + (size_t)(t + 2) * kstep; const char* b2 = last ? nB : cB + (size_t)(t + 2) * kstep;
;             const char* a3 = a2 + kstep; const char* b3 = b2 + kstep;
;             if (last && has_next) S.a_ready(nxt);
;             if constexpr (SP2) {
;             PG8_LDB(B0, 0, 0); PG8_LDB(B1, 0, 1); PG8_SCHED; PG8_LDA(At, 0, 0); PG8_STAGE(PG8_SA(1, 1), a1 + hstep, voffA);
;             PG8_WAIT_V(8); PG8_WAIT_L(0); PG8_BAR; PG8_MMA(0, 0, At, B0); PG8_MMA(0, 1, At, B1); PG8_BAR; PG8_SCHED;
;             PG8_LDA(At, 0, 1); PG8_STAGE(PG8_SB(0, 0), b2, voffB); PG8_STAGE(PG8_SB(0, 1), b2 + hstep, voffB); PG8_STAGE(PG8_SA(0, 0), a2, voffA);
.LBB0_635:
	v_add_u32_e32 v144, s64, v209
	v_add_u32_e32 v194, s65, v209
	ds_read_b128 v[92:95], v144
	ds_read_b128 v[128:131], v144 offset:1024
	ds_read_b128 v[132:135], v144 offset:2048
	ds_read_b128 v[144:147], v144 offset:3072
	ds_read_b128 v[148:151], v194
	ds_read_b128 v[152:155], v194 offset:1024
	ds_read_b128 v[190:193], v194 offset:2048
	ds_read_b128 v[194:197], v194 offset:3072
	s_cmp_eq_u32 s58, s10
	v_lshl_add_u64 v[198:199], v[90:91], 0, s[24:25]
	s_cselect_b64 vcc, -1, 0
	s_add_i32 s10, s10, 2
	v_cndmask_b32_e32 v207, v199, v187, vcc
	v_cndmask_b32_e32 v206, v198, v186, vcc
	v_cndmask_b32_e32 v215, v89, v189, vcc
	v_cndmask_b32_e32 v214, v88, v188, vcc
	v_lshl_add_u64 v[238:239], v[90:91], 0, v[180:181]
	s_add_i32 m0, s41, 0xc000
	ds_read_b128 v[198:201], v216
	ds_read_b128 v[202:205], v216 offset:1024
	ds_read_b128 v[210:213], v216 offset:2048
	ds_read_b128 v[218:221], v216 offset:3072
	ds_read_b128 v[222:225], v216 offset:4096
	ds_read_b128 v[226:229], v216 offset:5120
	ds_read_b128 v[230:233], v216 offset:6144
	ds_read_b128 v[234:237], v216 offset:7168
	global_load_lds_dwordx4 v[238:239], off
	v_lshl_add_u64 v[238:239], v[90:91], 0, v[178:179]
	s_add_i32 m0, s41, 0xe000
	s_nop 0
	global_load_lds_dwordx4 v[238:239], off
	s_waitcnt vmcnt(8)
	s_waitcnt lgkmcnt(0)
	s_barrier
	s_setprio 1
	s_waitcnt lgkmcnt(0)
	v_mfma_f32_16x16x32_bf16 v[140:143], v[92:95], v[198:201], v[140:143]
	v_mfma_f32_16x16x32_bf16 v[136:139], v[132:135], v[198:201], v[136:139]
	v_mfma_f32_16x16x32_bf16 v[116:119], v[92:95], v[210:213], v[116:119]
	v_mfma_f32_16x16x32_bf16 v[112:115], v[132:135], v[210:213], v[112:115]
	v_mfma_f32_16x16x32_bf16 v[100:103], v[92:95], v[222:225], v[100:103]
	v_mfma_f32_16x16x32_bf16 v[96:99], v[132:135], v[222:225], v[96:99]
	v_mfma_f32_16x16x32_bf16 v[76:79], v[92:95], v[230:233], v[76:79]
	v_mfma_f32_16x16x32_bf16 v[72:75], v[132:135], v[230:233], v[72:75]
	v_mfma_f32_16x16x32_bf16 v[140:143], v[128:131], v[202:205], v[140:143]
	v_mfma_f32_16x16x32_bf16 v[136:139], v[144:147], v[202:205], v[136:139]
	v_mfma_f32_16x16x32_bf16 v[116:119], v[128:131], v[218:221], v[116:119]
	v_mfma_f32_16x16x32_bf16 v[112:115], v[144:147], v[218:221], v[112:115]
	v_mfma_f32_16x16x32_bf16 v[100:103], v[128:131], v[226:229], v[100:103]
	v_mfma_f32_16x16x32_bf16 v[96:99], v[144:147], v[226:229], v[96:99]
	v_mfma_f32_16x16x32_bf16 v[76:79], v[128:131], v[234:237], v[76:79]
	v_mfma_f32_16x16x32_bf16 v[72:75], v[144:147], v[234:237], v[72:75]
	v_mfma_f32_16x16x32_bf16 v[124:127], v[148:151], v[198:201], v[124:127]
	v_mfma_f32_16x16x32_bf16 v[120:123], v[190:193], v[198:201], v[120:123]
	v_mfma_f32_16x16x32_bf16 v[108:111], v[148:151], v[210:213], v[108:111]
	v_mfma_f32_16x16x32_bf16 v[104:107], v[190:193], v[210:213], v[104:107]
	v_mfma_f32_16x16x32_bf16 v[84:87], v[148:151], v[222:225], v[84:87]
	v_mfma_f32_16x16x32_bf16 v[80:83], v[190:193], v[222:225], v[80:83]
	v_mfma_f32_16x16x32_bf16 v[68:71], v[148:151], v[230:233], v[68:71]
	v_mfma_f32_16x16x32_bf16 v[64:67], v[190:193], v[230:233], v[64:67]
	v_mfma_f32_16x16x32_bf16 v[124:127], v[152:155], v[202:205], v[124:127]
	v_mfma_f32_16x16x32_bf16 v[120:123], v[194:197], v[202:205], v[120:123]
	v_mfma_f32_16x16x32_bf16 v[108:111], v[152:155], v[218:221], v[108:111]
	v_mfma_f32_16x16x32_bf16 v[104:107], v[194:197], v[218:221], v[104:107]
	v_mfma_f32_16x16x32_bf16 v[84:87], v[152:155], v[226:229], v[84:87]
	v_mfma_f32_16x16x32_bf16 v[80:83], v[194:197], v[226:229], v[80:83]
	v_mfma_f32_16x16x32_bf16 v[68:71], v[152:155], v[234:237], v[68:71]
	v_mfma_f32_16x16x32_bf16 v[64:67], v[194:197], v[234:237], v[64:67]
	s_setprio 0
	s_barrier
	s_add_i32 s11, s64, s35
	v_lshl_add_u64 v[238:239], v[214:215], 0, v[168:169]
	s_mov_b32 m0, s11
	ds_read_b128 v[198:201], v216 offset:16384
	ds_read_b128 v[202:205], v216 offset:17408
	ds_read_b128 v[210:213], v216 offset:18432
	ds_read_b128 v[218:221], v216 offset:19456
	ds_read_b128 v[222:225], v216 offset:20480
	ds_read_b128 v[226:229], v216 offset:21504
	ds_read_b128 v[230:233], v216 offset:22528
	ds_read_b128 v[234:237], v216 offset:23552
	global_load_lds_dwordx4 v[238:239], off
	v_lshl_add_u64 v[240:241], v[214:215], 0, v[172:173]
	s_add_i32 m0, s11, 0x2000
	v_lshl_add_u64 v[214:215], v[214:215], 0, s[18:19]
	s_add_i32 s11, s65, s35
	global_load_lds_dwordx4 v[240:241], off
	v_lshl_add_u64 v[242:243], v[214:215], 0, v[168:169]
	s_mov_b32 m0, s11
	v_lshl_add_u64 v[214:215], v[214:215], 0, v[172:173]
	global_load_lds_dwordx4 v[242:243], off
	s_add_i32 m0, s11, 0x2000
	v_lshl_add_u64 v[244:245], v[206:207], 0, v[166:167]
	global_load_lds_dwordx4 v[214:215], off
	s_mov_b32 m0, s41
	v_lshl_add_u64 v[246:247], v[206:207], 0, v[170:171]
	global_load_lds_dwordx4 v[244:245], off
	s_mov_b32 m0, s50
	s_nop 0
	global_load_lds_dwordx4 v[246:247], off
	s_waitcnt vmcnt(8)
	s_waitcnt lgkmcnt(0)
	s_barrier
; #define PG8_STAGE(bufoff, gbase, voff) do { _Pragma("unroll") for (int _i = 0; _i < 2; ++_i) \
;         __builtin_amdgcn_global_load_lds((const unsigned*)((const char*)(gbase) + (voff)[_i]), (PG8_LAS unsigned*)(lds + (bufoff) + ldsw + _i * 8192), 16, 0, 0); } while (0)
; #define PG8_LDA(dst, b, h) do { _Pragma("unroll") for (int m = 0; m < 4; ++m) _Pragma("unroll") for (int k = 0; k < 2; ++k) dst[m][k] = *(const PG8_LAS bf16x8*)(lds + PG8_SA(b, h) + aoff + m * 2048 + k * 1024); } while (0)
; #define PG8_LDB(dst, b, h) do { _Pragma("unroll") for (int n = 0; n < 2; ++n) _Pragma("unroll") for (int k = 0; k < 2; ++k) dst[n][k] = *(const PG8_LAS bf16x8*)(lds + PG8_SB(b, h) + boff + n * 2048 + k * 1024); } while (0)
; #define PG8_MMA(ai, bj, At, Bt) do { __builtin_amdgcn_s_setprio(1); _Pragma("unroll") for (int m = 0; m < 4; ++m) _Pragma("unroll") for (int n = 0; n < 2; ++n) _Pragma("unroll") for (int k = 0; k < 2; ++k) \
;         acc[ai][bj][m][n] = __builtin_amdgcn_mfma_f32_16x16x32_bf16(Bt[n][k], At[m][k], acc[ai][bj][m][n], 0, 0, 0); __builtin_amdgcn_s_setprio(0); } while (0)
; #define PG8_WAIT_V(n) asm volatile("s_waitcnt vmcnt(" #n ")" ::: "memory")
; #define PG8_WAIT_L(n) asm volatile("s_waitcnt lgkmcnt(" #n ")" ::: "memory")
; #define PG8_BAR __builtin_amdgcn_s_barrier()
; #define PG8_SCHED __builtin_amdgcn_sched_barrier(0)
; template <class Epi, class Sched, bool ALIGN_EPI = false, bool SP2 = false>
; __device__ __forceinline__ void gemm_phase(PG8_LAS unsigned char* lds, const Gemm g, const Sched& S, const Epi& E) {
;     ...
;             PG8_WAIT_V(8); PG8_WAIT_L(0); PG8_BAR; PG8_MMA(1, 0, At, B0); PG8_MMA(1, 1, At, B1); PG8_BAR; PG8_SCHED;
;             PG8_LDB(B0, 1, 0); PG8_LDB(B1, 1, 1); PG8_SCHED; PG8_LDA(At, 1, 0); PG8_STAGE(PG8_SA(0, 1), a2 + hstep, voffA);
;             PG8_WAIT_V(8); PG8_WAIT_L(0); PG8_BAR; PG8_MMA(0, 0, At, B0); PG8_MMA(0, 1, At, B1); PG8_BAR; PG8_SCHED;
	s_setprio 1
	s_waitcnt lgkmcnt(0)
	v_mfma_f32_16x16x32_bf16 v[60:63], v[92:95], v[198:201], v[60:63]
	v_mfma_f32_16x16x32_bf16 v[56:59], v[132:135], v[198:201], v[56:59]
	v_mfma_f32_16x16x32_bf16 v[44:47], v[92:95], v[210:213], v[44:47]
	v_mfma_f32_16x16x32_bf16 v[40:43], v[132:135], v[210:213], v[40:43]
	v_mfma_f32_16x16x32_bf16 v[28:31], v[92:95], v[222:225], v[28:31]
	v_mfma_f32_16x16x32_bf16 v[24:27], v[132:135], v[222:225], v[24:27]
	v_mfma_f32_16x16x32_bf16 v[12:15], v[92:95], v[230:233], v[12:15]
	v_mfma_f32_16x16x32_bf16 v[8:11], v[132:135], v[230:233], v[8:11]
	v_mfma_f32_16x16x32_bf16 v[60:63], v[128:131], v[202:205], v[60:63]
	v_mfma_f32_16x16x32_bf16 v[56:59], v[144:147], v[202:205], v[56:59]
	v_mfma_f32_16x16x32_bf16 v[44:47], v[128:131], v[218:221], v[44:47]
	v_mfma_f32_16x16x32_bf16 v[40:43], v[144:147], v[218:221], v[40:43]
	v_mfma_f32_16x16x32_bf16 v[28:31], v[128:131], v[226:229], v[28:31]
	v_mfma_f32_16x16x32_bf16 v[24:27], v[144:147], v[226:229], v[24:27]
	v_mfma_f32_16x16x32_bf16 v[12:15], v[128:131], v[234:237], v[12:15]
	v_mfma_f32_16x16x32_bf16 v[8:11], v[144:147], v[234:237], v[8:11]
	v_mfma_f32_16x16x32_bf16 v[52:55], v[148:151], v[198:201], v[52:55]
	v_mfma_f32_16x16x32_bf16 v[48:51], v[190:193], v[198:201], v[48:51]
	v_mfma_f32_16x16x32_bf16 v[36:39], v[148:151], v[210:213], v[36:39]
	v_mfma_f32_16x16x32_bf16 v[32:35], v[190:193], v[210:213], v[32:35]
	v_mfma_f32_16x16x32_bf16 v[20:23], v[148:151], v[222:225], v[20:23]
	v_mfma_f32_16x16x32_bf16 v[16:19], v[190:193], v[222:225], v[16:19]
	v_mfma_f32_16x16x32_bf16 v[4:7], v[148:151], v[230:233], v[4:7]
	v_mfma_f32_16x16x32_bf16 v[0:3], v[190:193], v[230:233], v[0:3]
	v_mfma_f32_16x16x32_bf16 v[52:55], v[152:155], v[202:205], v[52:55]
	v_mfma_f32_16x16x32_bf16 v[48:51], v[194:197], v[202:205], v[48:51]
	v_mfma_f32_16x16x32_bf16 v[36:39], v[152:155], v[218:221], v[36:39]
	v_mfma_f32_16x16x32_bf16 v[32:35], v[194:197], v[218:221], v[32:35]
	v_mfma_f32_16x16x32_bf16 v[20:23], v[152:155], v[226:229], v[20:23]
	v_mfma_f32_16x16x32_bf16 v[16:19], v[194:197], v[226:229], v[16:19]
	v_mfma_f32_16x16x32_bf16 v[4:7], v[152:155], v[234:237], v[4:7]
	v_mfma_f32_16x16x32_bf16 v[0:3], v[194:197], v[234:237], v[0:3]
	s_setprio 0
	s_barrier
	s_add_i32 s11, 0, 0x18000
	s_add_i32 s14, 0, 0x1c000
	v_add_u32_e32 v144, s11, v209
	v_add_u32_e32 v194, s14, v209
	ds_read_b128 v[92:95], v144
	ds_read_b128 v[128:131], v144 offset:1024
	ds_read_b128 v[132:135], v144 offset:2048
	ds_read_b128 v[144:147], v144 offset:3072
	ds_read_b128 v[148:151], v194
	ds_read_b128 v[152:155], v194 offset:1024
	ds_read_b128 v[190:193], v194 offset:2048
	ds_read_b128 v[194:197], v194 offset:3072
	v_lshl_add_u64 v[206:207], v[206:207], 0, s[18:19]
	s_mov_b32 m0, s51
	v_lshl_add_u64 v[248:249], v[206:207], 0, v[166:167]
	ds_read_b128 v[198:201], v216 offset:32768
	ds_read_b128 v[202:205], v216 offset:33792
	ds_read_b128 v[210:213], v216 offset:34816
	ds_read_b128 v[218:221], v216 offset:35840
	ds_read_b128 v[222:225], v216 offset:36864
	ds_read_b128 v[226:229], v216 offset:37888
	ds_read_b128 v[230:233], v216 offset:38912
	ds_read_b128 v[234:237], v216 offset:39936
	global_load_lds_dwordx4 v[248:249], off
	v_lshl_add_u64 v[206:207], v[206:207], 0, v[170:171]
	s_mov_b32 m0, s52
	s_nop 0
	global_load_lds_dwordx4 v[206:207], off
	s_waitcnt vmcnt(8)
	s_waitcnt lgkmcnt(0)
	s_barrier
	s_setprio 1
	s_waitcnt lgkmcnt(0)
	v_mfma_f32_16x16x32_bf16 v[140:143], v[92:95], v[198:201], v[140:143]
	v_mfma_f32_16x16x32_bf16 v[136:139], v[132:135], v[198:201], v[136:139]
	v_mfma_f32_16x16x32_bf16 v[116:119], v[92:95], v[210:213], v[116:119]
	v_mfma_f32_16x16x32_bf16 v[112:115], v[132:135], v[210:213], v[112:115]
	v_mfma_f32_16x16x32_bf16 v[100:103], v[92:95], v[222:225], v[100:103]
	v_mfma_f32_16x16x32_bf16 v[96:99], v[132:135], v[222:225], v[96:99]
	v_mfma_f32_16x16x32_bf16 v[76:79], v[92:95], v[230:233], v[76:79]
	v_mfma_f32_16x16x32_bf16 v[72:75], v[132:135], v[230:233], v[72:75]
	v_mfma_f32_16x16x32_bf16 v[140:143], v[128:131], v[202:205], v[140:143]
	v_mfma_f32_16x16x32_bf16 v[136:139], v[144:147], v[202:205], v[136:139]
	v_mfma_f32_16x16x32_bf16 v[116:119], v[128:131], v[218:221], v[116:119]
	v_mfma_f32_16x16x32_bf16 v[112:115], v[144:147], v[218:221], v[112:115]
	v_mfma_f32_16x16x32_bf16 v[100:103], v[128:131], v[226:229], v[100:103]
	v_mfma_f32_16x16x32_bf16 v[96:99], v[144:147], v[226:229], v[96:99]
	v_mfma_f32_16x16x32_bf16 v[76:79], v[128:131], v[234:237], v[76:79]
	v_mfma_f32_16x16x32_bf16 v[72:75], v[144:147], v[234:237], v[72:75]
	v_mfma_f32_16x16x32_bf16 v[124:127], v[148:151], v[198:201], v[124:127]
	v_mfma_f32_16x16x32_bf16 v[120:123], v[190:193], v[198:201], v[120:123]
	v_mfma_f32_16x16x32_bf16 v[108:111], v[148:151], v[210:213], v[108:111]
	v_mfma_f32_16x16x32_bf16 v[104:107], v[190:193], v[210:213], v[104:107]
	v_mfma_f32_16x16x32_bf16 v[84:87], v[148:151], v[222:225], v[84:87]
	v_mfma_f32_16x16x32_bf16 v[80:83], v[190:193], v[222:225], v[80:83]
	v_mfma_f32_16x16x32_bf16 v[68:71], v[148:151], v[230:233], v[68:71]
	v_mfma_f32_16x16x32_bf16 v[64:67], v[190:193], v[230:233], v[64:67]
	v_mfma_f32_16x16x32_bf16 v[124:127], v[152:155], v[202:205], v[124:127]
	v_mfma_f32_16x16x32_bf16 v[120:123], v[194:197], v[202:205], v[120:123]
	v_mfma_f32_16x16x32_bf16 v[108:111], v[152:155], v[218:221], v[108:111]
	v_mfma_f32_16x16x32_bf16 v[104:107], v[194:197], v[218:221], v[104:107]
	v_mfma_f32_16x16x32_bf16 v[84:87], v[152:155], v[226:229], v[84:87]
	v_mfma_f32_16x16x32_bf16 v[80:83], v[194:197], v[226:229], v[80:83]
	v_mfma_f32_16x16x32_bf16 v[68:71], v[152:155], v[234:237], v[68:71]
	v_mfma_f32_16x16x32_bf16 v[64:67], v[194:197], v[234:237], v[64:67]
	s_setprio 0
	s_barrier
; #define PG8_STAGE(bufoff, gbase, voff) do { _Pragma("unroll") for (int _i = 0; _i < 2; ++_i) \
;         __builtin_amdgcn_global_load_lds((const unsigned*)((const char*)(gbase) + (voff)[_i]), (PG8_LAS unsigned*)(lds + (bufoff) + ldsw + _i * 8192), 16, 0, 0); } while (0)
; #define PG8_LDA(dst, b, h) do { _Pragma("unroll") for (int m = 0; m < 4; ++m) _Pragma("unroll") for (int k = 0; k < 2; ++k) dst[m][k] = *(const PG8_LAS bf16x8*)(lds + PG8_SA(b, h) + aoff + m * 2048 + k * 1024); } while (0)
; #define PG8_MMA(ai, bj, At, Bt) do { __builtin_amdgcn_s_setprio(1); _Pragma("unroll") for (int m = 0; m < 4; ++m) _Pragma("unroll") for (int n = 0; n < 2; ++n) _Pragma("unroll") for (int k = 0; k < 2; ++k) \
;         acc[ai][bj][m][n] = __builtin_amdgcn_mfma_f32_16x16x32_bf16(Bt[n][k], At[m][k], acc[ai][bj][m][n], 0, 0, 0); __builtin_amdgcn_s_setprio(0); } while (0)
; #define PG8_WAIT_V(n) asm volatile("s_waitcnt vmcnt(" #n ")" ::: "memory")
; #define PG8_WAIT_L(n) asm volatile("s_waitcnt lgkmcnt(" #n ")" ::: "memory")
; #define PG8_BAR __builtin_amdgcn_s_barrier()
; #define PG8_SCHED __builtin_amdgcn_sched_barrier(0)
; template <class Epi, class Sched, bool ALIGN_EPI = false, bool SP2 = false>
; __device__ __forceinline__ void gemm_phase(PG8_LAS unsigned char* lds, const Gemm g, const Sched& S, const Epi& E) {
;     ...
;             PG8_LDA(At, 1, 1); PG8_STAGE(PG8_SB(1, 0), b3, voffB); PG8_STAGE(PG8_SB(1, 1), b3 + hstep, voffB); PG8_STAGE(PG8_SA(1, 0), a3, voffA);
;             PG8_WAIT_V(8); PG8_WAIT_L(0); PG8_BAR; PG8_MMA(1, 0, At, B0); PG8_MMA(1, 1, At, B1); PG8_BAR; PG8_SCHED;
	s_add_i32 s11, s11, s35
	v_lshl_add_u64 v[206:207], v[238:239], 0, s[24:25]
	s_mov_b32 m0, s11
	ds_read_b128 v[198:201], v216 offset:49152
	ds_read_b128 v[202:205], v216 offset:50176
	ds_read_b128 v[210:213], v216 offset:51200
	ds_read_b128 v[218:221], v216 offset:52224
	ds_read_b128 v[222:225], v216 offset:53248
	ds_read_b128 v[226:229], v216 offset:54272
	ds_read_b128 v[230:233], v216 offset:55296
	ds_read_b128 v[234:237], v216 offset:56320
	global_load_lds_dwordx4 v[206:207], off
	v_lshl_add_u64 v[206:207], v[240:241], 0, s[24:25]
	s_add_i32 m0, s11, 0x2000
	s_add_i32 s11, s14, s35
	global_load_lds_dwordx4 v[206:207], off
	v_lshl_add_u64 v[206:207], v[242:243], 0, s[24:25]
	s_mov_b32 m0, s11
	s_nop 0
	global_load_lds_dwordx4 v[206:207], off
	v_lshl_add_u64 v[206:207], v[214:215], 0, s[24:25]
	s_add_i32 m0, s11, 0x2000
	s_nop 0
	global_load_lds_dwordx4 v[206:207], off
	v_lshl_add_u64 v[206:207], v[244:245], 0, s[24:25]
	s_mov_b32 m0, s54
	s_nop 0
	global_load_lds_dwordx4 v[206:207], off
	v_lshl_add_u64 v[206:207], v[246:247], 0, s[24:25]
	s_mov_b32 m0, s55
	s_nop 0
	global_load_lds_dwordx4 v[206:207], off
	s_waitcnt vmcnt(8)
	s_waitcnt lgkmcnt(0)
	s_barrier
	s_setprio 1
	s_waitcnt lgkmcnt(0)
	v_mfma_f32_16x16x32_bf16 v[60:63], v[92:95], v[198:201], v[60:63]
	v_mfma_f32_16x16x32_bf16 v[56:59], v[132:135], v[198:201], v[56:59]
	v_mfma_f32_16x16x32_bf16 v[44:47], v[92:95], v[210:213], v[44:47]
	v_mfma_f32_16x16x32_bf16 v[40:43], v[132:135], v[210:213], v[40:43]
	v_mfma_f32_16x16x32_bf16 v[28:31], v[92:95], v[222:225], v[28:31]
	v_mfma_f32_16x16x32_bf16 v[24:27], v[132:135], v[222:225], v[24:27]
	v_mfma_f32_16x16x32_bf16 v[12:15], v[92:95], v[230:233], v[12:15]
	v_mfma_f32_16x16x32_bf16 v[8:11], v[132:135], v[230:233], v[8:11]
	v_mfma_f32_16x16x32_bf16 v[60:63], v[128:131], v[202:205], v[60:63]
	v_mfma_f32_16x16x32_bf16 v[56:59], v[144:147], v[202:205], v[56:59]
	v_mfma_f32_16x16x32_bf16 v[44:47], v[128:131], v[218:221], v[44:47]
	v_mfma_f32_16x16x32_bf16 v[40:43], v[144:147], v[218:221], v[40:43]
	v_mfma_f32_16x16x32_bf16 v[28:31], v[128:131], v[226:229], v[28:31]
	v_mfma_f32_16x16x32_bf16 v[24:27], v[144:147], v[226:229], v[24:27]
	v_mfma_f32_16x16x32_bf16 v[12:15], v[128:131], v[234:237], v[12:15]
	v_mfma_f32_16x16x32_bf16 v[8:11], v[144:147], v[234:237], v[8:11]
	v_mfma_f32_16x16x32_bf16 v[52:55], v[148:151], v[198:201], v[52:55]
	v_mfma_f32_16x16x32_bf16 v[48:51], v[190:193], v[198:201], v[48:51]
	v_mfma_f32_16x16x32_bf16 v[36:39], v[148:151], v[210:213], v[36:39]
	v_mfma_f32_16x16x32_bf16 v[32:35], v[190:193], v[210:213], v[32:35]
	v_mfma_f32_16x16x32_bf16 v[20:23], v[148:151], v[222:225], v[20:23]
	v_mfma_f32_16x16x32_bf16 v[16:19], v[190:193], v[222:225], v[16:19]
	v_mfma_f32_16x16x32_bf16 v[4:7], v[148:151], v[230:233], v[4:7]
	v_mfma_f32_16x16x32_bf16 v[0:3], v[190:193], v[230:233], v[0:3]
	v_mfma_f32_16x16x32_bf16 v[52:55], v[152:155], v[202:205], v[52:55]
	v_mfma_f32_16x16x32_bf16 v[48:51], v[194:197], v[202:205], v[48:51]
	v_mfma_f32_16x16x32_bf16 v[36:39], v[152:155], v[218:221], v[36:39]
	v_mfma_f32_16x16x32_bf16 v[32:35], v[194:197], v[218:221], v[32:35]
	v_mfma_f32_16x16x32_bf16 v[20:23], v[152:155], v[226:229], v[20:23]
	v_mfma_f32_16x16x32_bf16 v[16:19], v[194:197], v[226:229], v[16:19]
	v_mfma_f32_16x16x32_bf16 v[4:7], v[152:155], v[234:237], v[4:7]
	v_mfma_f32_16x16x32_bf16 v[0:3], v[194:197], v[234:237], v[0:3]
	s_setprio 0
	s_barrier
	v_lshl_add_u64 v[88:89], v[88:89], 0, s[30:31]
	s_cmp_ge_i32 s10, s57
	v_lshl_add_u64 v[90:91], v[90:91], 0, s[30:31]
	s_cbranch_scc0 .LBB0_635

; #define PG8_STAGE(bufoff, gbase, voff) do { _Pragma("unroll") for (int _i = 0; _i < 2; ++_i) \
;         __builtin_amdgcn_global_load_lds((const unsigned*)((const char*)(gbase) + (voff)[_i]), (PG8_LAS unsigned*)(lds + (bufoff) + ldsw + _i * 8192), 16, 0, 0); } while (0)
; #define PG8_LDA(dst, b, h) do { _Pragma("unroll") for (int m = 0; m < 4; ++m) _Pragma("unroll") for (int k = 0; k < 2; ++k) dst[m][k] = *(const PG8_LAS bf16x8*)(lds + PG8_SA(b, h) + aoff + m * 2048 + k * 1024); } while (0)
; #define PG8_LDB(dst, b, h) do { _Pragma("unroll") for (int n = 0; n < 2; ++n) _Pragma("unroll") for (int k = 0; k < 2; ++k) dst[n][k] = *(const PG8_LAS bf16x8*)(lds + PG8_SB(b, h) + boff + n * 2048 + k * 1024); } while (0)
; #define PG8_MMA(ai, bj, At, Bt) do { __builtin_amdgcn_s_setprio(1); _Pragma("unroll") for (int m = 0; m < 4; ++m) _Pragma("unroll") for (int n = 0; n < 2; ++n) _Pragma("unroll") for (int k = 0; k < 2; ++k) \
;         acc[ai][bj][m][n] = __builtin_amdgcn_mfma_f32_16x16x32_bf16(Bt[n][k], At[m][k], acc[ai][bj][m][n], 0, 0, 0); __builtin_amdgcn_s_setprio(0); } while (0)
; #define PG8_WAIT_V(n) asm volatile("s_waitcnt vmcnt(" #n ")" ::: "memory")
; #define PG8_WAIT_L(n) asm volatile("s_waitcnt lgkmcnt(" #n ")" ::: "memory")
; #define PG8_BAR __builtin_amdgcn_s_barrier()
; #define PG8_SCHED __builtin_amdgcn_sched_barrier(0)
; template <class Epi, class Sched, bool ALIGN_EPI = false, bool SP2 = false>
; __device__ __forceinline__ void gemm_phase(PG8_LAS unsigned char* lds, const Gemm g, const Sched& S, const Epi& E) {
;     ...
;         for (int t = 0; t < nt; t += 2) {
;             const bool last = (t == nt - 2);
;             const char* a1 = cA + (size_t)(t + 1) * kstep;
;             const char* a2 = last ? nA : cA + (size_t)(t + 2) * kstep; const char* b2 = last ? nB : cB + (size_t)(t + 2) * kstep;
;             const char* a3 = a2 + kstep; const char* b3 = b2 + kstep;
;             if (last && has_next) S.a_ready(nxt);
;             if constexpr (SP2) {
;             PG8_LDB(B0, 0, 0); PG8_LDB(B1, 0, 1); PG8_SCHED; PG8_LDA(At, 0, 0); PG8_STAGE(PG8_SA(1, 1), a1 + hstep, voffA);
;             PG8_WAIT_V(8); PG8_WAIT_L(0); PG8_BAR; PG8_MMA(0, 0, At, B0); PG8_MMA(0, 1, At, B1); PG8_BAR; PG8_SCHED;
;             PG8_LDA(At, 0, 1); PG8_STAGE(PG8_SB(0, 0), b2, voffB); PG8_STAGE(PG8_SB(0, 1), b2 + hstep, voffB); PG8_STAGE(PG8_SA(0, 0), a2, voffA);
.LBB0_722:
	v_add_u32_e32 v144, s59, v183
	v_add_u32_e32 v170, s60, v183
	ds_read_b128 v[116:119], v144
	ds_read_b128 v[136:139], v144 offset:1024
	ds_read_b128 v[140:143], v144 offset:2048
	ds_read_b128 v[144:147], v144 offset:3072
	ds_read_b128 v[148:151], v170
	ds_read_b128 v[188:191], v170 offset:1024
	ds_read_b128 v[192:195], v170 offset:2048
	ds_read_b128 v[198:201], v170 offset:3072
	s_cmp_eq_u32 s53, s8
	v_lshl_add_u64 v[204:205], v[114:115], 0, s[18:19]
	s_cselect_b64 vcc, -1, 0
	s_add_i32 s8, s8, 2
	v_cndmask_b32_e32 v213, v205, v185, vcc
	v_cndmask_b32_e32 v212, v204, v184, vcc
	v_cndmask_b32_e32 v215, v113, v187, vcc
	v_cndmask_b32_e32 v214, v112, v186, vcc
	v_lshl_add_u64 v[240:241], v[114:115], 0, v[178:179]
	s_add_i32 m0, s34, 0xc000
	ds_read_b128 v[204:207], v202
	ds_read_b128 v[208:211], v202 offset:1024
	ds_read_b128 v[216:219], v202 offset:2048
	ds_read_b128 v[220:223], v202 offset:3072
	ds_read_b128 v[224:227], v202 offset:4096
	ds_read_b128 v[228:231], v202 offset:5120
	ds_read_b128 v[232:235], v202 offset:6144
	ds_read_b128 v[236:239], v202 offset:7168
	global_load_lds_dwordx4 v[240:241], off
	v_lshl_add_u64 v[240:241], v[114:115], 0, v[176:177]
	s_add_i32 m0, s34, 0xe000
	s_nop 0
	global_load_lds_dwordx4 v[240:241], off
	s_waitcnt vmcnt(8)
	s_waitcnt lgkmcnt(0)
	s_barrier
	s_setprio 1
	s_waitcnt lgkmcnt(0)
	v_mfma_f32_16x16x32_bf16 v[132:135], v[116:119], v[204:207], v[132:135]
	v_mfma_f32_16x16x32_bf16 v[128:131], v[140:143], v[204:207], v[128:131]
	v_mfma_f32_16x16x32_bf16 v[108:111], v[116:119], v[216:219], v[108:111]
	v_mfma_f32_16x16x32_bf16 v[104:107], v[140:143], v[216:219], v[104:107]
	v_mfma_f32_16x16x32_bf16 v[92:95], v[116:119], v[224:227], v[92:95]
	v_mfma_f32_16x16x32_bf16 v[88:91], v[140:143], v[224:227], v[88:91]
	v_mfma_f32_16x16x32_bf16 v[76:79], v[116:119], v[232:235], v[76:79]
	v_mfma_f32_16x16x32_bf16 v[72:75], v[140:143], v[232:235], v[72:75]
	v_mfma_f32_16x16x32_bf16 v[132:135], v[136:139], v[208:211], v[132:135]
	v_mfma_f32_16x16x32_bf16 v[128:131], v[144:147], v[208:211], v[128:131]
	v_mfma_f32_16x16x32_bf16 v[108:111], v[136:139], v[220:223], v[108:111]
	v_mfma_f32_16x16x32_bf16 v[104:107], v[144:147], v[220:223], v[104:107]
	v_mfma_f32_16x16x32_bf16 v[92:95], v[136:139], v[228:231], v[92:95]
	v_mfma_f32_16x16x32_bf16 v[88:91], v[144:147], v[228:231], v[88:91]
	v_mfma_f32_16x16x32_bf16 v[76:79], v[136:139], v[236:239], v[76:79]
	v_mfma_f32_16x16x32_bf16 v[72:75], v[144:147], v[236:239], v[72:75]
	v_mfma_f32_16x16x32_bf16 v[124:127], v[148:151], v[204:207], v[124:127]
	v_mfma_f32_16x16x32_bf16 v[120:123], v[192:195], v[204:207], v[120:123]
	v_mfma_f32_16x16x32_bf16 v[100:103], v[148:151], v[216:219], v[100:103]
	v_mfma_f32_16x16x32_bf16 v[96:99], v[192:195], v[216:219], v[96:99]
	v_mfma_f32_16x16x32_bf16 v[84:87], v[148:151], v[224:227], v[84:87]
	v_mfma_f32_16x16x32_bf16 v[80:83], v[192:195], v[224:227], v[80:83]
	v_mfma_f32_16x16x32_bf16 v[68:71], v[148:151], v[232:235], v[68:71]
	v_mfma_f32_16x16x32_bf16 v[64:67], v[192:195], v[232:235], v[64:67]
	v_mfma_f32_16x16x32_bf16 v[124:127], v[188:191], v[208:211], v[124:127]
	v_mfma_f32_16x16x32_bf16 v[120:123], v[198:201], v[208:211], v[120:123]
	v_mfma_f32_16x16x32_bf16 v[100:103], v[188:191], v[220:223], v[100:103]
	v_mfma_f32_16x16x32_bf16 v[96:99], v[198:201], v[220:223], v[96:99]
	v_mfma_f32_16x16x32_bf16 v[84:87], v[188:191], v[228:231], v[84:87]
	v_mfma_f32_16x16x32_bf16 v[80:83], v[198:201], v[228:231], v[80:83]
	v_mfma_f32_16x16x32_bf16 v[68:71], v[188:191], v[236:239], v[68:71]
	v_mfma_f32_16x16x32_bf16 v[64:67], v[198:201], v[236:239], v[64:67]
	s_setprio 0
	s_barrier
	s_add_i32 s9, s59, s29
	v_lshl_add_u64 v[240:241], v[214:215], 0, v[164:165]
	s_mov_b32 m0, s9
	ds_read_b128 v[204:207], v202 offset:16384
	ds_read_b128 v[208:211], v202 offset:17408
	ds_read_b128 v[216:219], v202 offset:18432
	ds_read_b128 v[220:223], v202 offset:19456
	ds_read_b128 v[224:227], v202 offset:20480
	ds_read_b128 v[228:231], v202 offset:21504
	ds_read_b128 v[232:235], v202 offset:22528
	ds_read_b128 v[236:239], v202 offset:23552
	global_load_lds_dwordx4 v[240:241], off
	v_lshl_add_u64 v[242:243], v[214:215], 0, v[168:169]
	s_add_i32 m0, s9, 0x2000
	v_lshl_add_u64 v[214:215], v[214:215], 0, s[12:13]
	s_add_i32 s9, s60, s29
	global_load_lds_dwordx4 v[242:243], off
	v_lshl_add_u64 v[244:245], v[214:215], 0, v[164:165]
	s_mov_b32 m0, s9
	v_lshl_add_u64 v[214:215], v[214:215], 0, v[168:169]
	global_load_lds_dwordx4 v[244:245], off
	s_add_i32 m0, s9, 0x2000
	v_lshl_add_u64 v[246:247], v[212:213], 0, v[162:163]
	global_load_lds_dwordx4 v[214:215], off
	s_mov_b32 m0, s34
	v_lshl_add_u64 v[248:249], v[212:213], 0, v[166:167]
	global_load_lds_dwordx4 v[246:247], off
	s_mov_b32 m0, s36
	s_nop 0
	global_load_lds_dwordx4 v[248:249], off
	s_waitcnt vmcnt(8)
	s_waitcnt lgkmcnt(0)
	s_barrier
; #define PG8_STAGE(bufoff, gbase, voff) do { _Pragma("unroll") for (int _i = 0; _i < 2; ++_i) \
;         __builtin_amdgcn_global_load_lds((const unsigned*)((const char*)(gbase) + (voff)[_i]), (PG8_LAS unsigned*)(lds + (bufoff) + ldsw + _i * 8192), 16, 0, 0); } while (0)
; #define PG8_LDA(dst, b, h) do { _Pragma("unroll") for (int m = 0; m < 4; ++m) _Pragma("unroll") for (int k = 0; k < 2; ++k) dst[m][k] = *(const PG8_LAS bf16x8*)(lds + PG8_SA(b, h) + aoff + m * 2048 + k * 1024); } while (0)
; #define PG8_LDB(dst, b, h) do { _Pragma("unroll") for (int n = 0; n < 2; ++n) _Pragma("unroll") for (int k = 0; k < 2; ++k) dst[n][k] = *(const PG8_LAS bf16x8*)(lds + PG8_SB(b, h) + boff + n * 2048 + k * 1024); } while (0)
; #define PG8_MMA(ai, bj, At, Bt) do { __builtin_amdgcn_s_setprio(1); _Pragma("unroll") for (int m = 0; m < 4; ++m) _Pragma("unroll") for (int n = 0; n < 2; ++n) _Pragma("unroll") for (int k = 0; k < 2; ++k) \
;         acc[ai][bj][m][n] = __builtin_amdgcn_mfma_f32_16x16x32_bf16(Bt[n][k], At[m][k], acc[ai][bj][m][n], 0, 0, 0); __builtin_amdgcn_s_setprio(0); } while (0)
; #define PG8_WAIT_V(n) asm volatile("s_waitcnt vmcnt(" #n ")" ::: "memory")
; #define PG8_WAIT_L(n) asm volatile("s_waitcnt lgkmcnt(" #n ")" ::: "memory")
; #define PG8_BAR __builtin_amdgcn_s_barrier()
; #define PG8_SCHED __builtin_amdgcn_sched_barrier(0)
; template <class Epi, class Sched, bool ALIGN_EPI = false, bool SP2 = false>
; __device__ __forceinline__ void gemm_phase(PG8_LAS unsigned char* lds, const Gemm g, const Sched& S, const Epi& E) {
;     ...
;             PG8_WAIT_V(8); PG8_WAIT_L(0); PG8_BAR; PG8_MMA(1, 0, At, B0); PG8_MMA(1, 1, At, B1); PG8_BAR; PG8_SCHED;
;             PG8_LDB(B0, 1, 0); PG8_LDB(B1, 1, 1); PG8_SCHED; PG8_LDA(At, 1, 0); PG8_STAGE(PG8_SA(0, 1), a2 + hstep, voffA);
;             PG8_WAIT_V(8); PG8_WAIT_L(0); PG8_BAR; PG8_MMA(0, 0, At, B0); PG8_MMA(0, 1, At, B1); PG8_BAR; PG8_SCHED;
	s_setprio 1
	s_waitcnt lgkmcnt(0)
	v_mfma_f32_16x16x32_bf16 v[60:63], v[116:119], v[204:207], v[60:63]
	v_mfma_f32_16x16x32_bf16 v[56:59], v[140:143], v[204:207], v[56:59]
	v_mfma_f32_16x16x32_bf16 v[44:47], v[116:119], v[216:219], v[44:47]
	v_mfma_f32_16x16x32_bf16 v[40:43], v[140:143], v[216:219], v[40:43]
	v_mfma_f32_16x16x32_bf16 v[28:31], v[116:119], v[224:227], v[28:31]
	v_mfma_f32_16x16x32_bf16 v[24:27], v[140:143], v[224:227], v[24:27]
	v_mfma_f32_16x16x32_bf16 v[12:15], v[116:119], v[232:235], v[12:15]
	v_mfma_f32_16x16x32_bf16 v[8:11], v[140:143], v[232:235], v[8:11]
	v_mfma_f32_16x16x32_bf16 v[60:63], v[136:139], v[208:211], v[60:63]
	v_mfma_f32_16x16x32_bf16 v[56:59], v[144:147], v[208:211], v[56:59]
	v_mfma_f32_16x16x32_bf16 v[44:47], v[136:139], v[220:223], v[44:47]
	v_mfma_f32_16x16x32_bf16 v[40:43], v[144:147], v[220:223], v[40:43]
	v_mfma_f32_16x16x32_bf16 v[28:31], v[136:139], v[228:231], v[28:31]
	v_mfma_f32_16x16x32_bf16 v[24:27], v[144:147], v[228:231], v[24:27]
	v_mfma_f32_16x16x32_bf16 v[12:15], v[136:139], v[236:239], v[12:15]
	v_mfma_f32_16x16x32_bf16 v[8:11], v[144:147], v[236:239], v[8:11]
	v_mfma_f32_16x16x32_bf16 v[52:55], v[148:151], v[204:207], v[52:55]
	v_mfma_f32_16x16x32_bf16 v[48:51], v[192:195], v[204:207], v[48:51]
	v_mfma_f32_16x16x32_bf16 v[36:39], v[148:151], v[216:219], v[36:39]
	v_mfma_f32_16x16x32_bf16 v[32:35], v[192:195], v[216:219], v[32:35]
	v_mfma_f32_16x16x32_bf16 v[20:23], v[148:151], v[224:227], v[20:23]
	v_mfma_f32_16x16x32_bf16 v[16:19], v[192:195], v[224:227], v[16:19]
	v_mfma_f32_16x16x32_bf16 v[4:7], v[148:151], v[232:235], v[4:7]
	v_mfma_f32_16x16x32_bf16 v[0:3], v[192:195], v[232:235], v[0:3]
	v_mfma_f32_16x16x32_bf16 v[52:55], v[188:191], v[208:211], v[52:55]
	v_mfma_f32_16x16x32_bf16 v[48:51], v[198:201], v[208:211], v[48:51]
	v_mfma_f32_16x16x32_bf16 v[36:39], v[188:191], v[220:223], v[36:39]
	v_mfma_f32_16x16x32_bf16 v[32:35], v[198:201], v[220:223], v[32:35]
	v_mfma_f32_16x16x32_bf16 v[20:23], v[188:191], v[228:231], v[20:23]
	v_mfma_f32_16x16x32_bf16 v[16:19], v[198:201], v[228:231], v[16:19]
	v_mfma_f32_16x16x32_bf16 v[4:7], v[188:191], v[236:239], v[4:7]
	v_mfma_f32_16x16x32_bf16 v[0:3], v[198:201], v[236:239], v[0:3]
	s_setprio 0
	s_barrier
	s_add_i32 s9, 0, 0x18000
	s_add_i32 s10, 0, 0x1c000
	v_add_u32_e32 v144, s9, v183
	v_add_u32_e32 v170, s10, v183
	ds_read_b128 v[116:119], v144
	ds_read_b128 v[136:139], v144 offset:1024
	ds_read_b128 v[140:143], v144 offset:2048
	ds_read_b128 v[144:147], v144 offset:3072
	ds_read_b128 v[148:151], v170
	ds_read_b128 v[188:191], v170 offset:1024
	ds_read_b128 v[192:195], v170 offset:2048
	ds_read_b128 v[198:201], v170 offset:3072
	v_lshl_add_u64 v[212:213], v[212:213], 0, s[12:13]
	s_mov_b32 m0, s37
	v_lshl_add_u64 v[250:251], v[212:213], 0, v[162:163]
	ds_read_b128 v[204:207], v202 offset:32768
	ds_read_b128 v[208:211], v202 offset:33792
	ds_read_b128 v[216:219], v202 offset:34816
	ds_read_b128 v[220:223], v202 offset:35840
	ds_read_b128 v[224:227], v202 offset:36864
	ds_read_b128 v[228:231], v202 offset:37888
	ds_read_b128 v[232:235], v202 offset:38912
	ds_read_b128 v[236:239], v202 offset:39936
	global_load_lds_dwordx4 v[250:251], off
	v_lshl_add_u64 v[212:213], v[212:213], 0, v[166:167]
	s_mov_b32 m0, s41
	s_nop 0
	global_load_lds_dwordx4 v[212:213], off
	s_waitcnt vmcnt(8)
	s_waitcnt lgkmcnt(0)
	s_barrier
	s_setprio 1
	s_waitcnt lgkmcnt(0)
	v_mfma_f32_16x16x32_bf16 v[132:135], v[116:119], v[204:207], v[132:135]
	v_mfma_f32_16x16x32_bf16 v[128:131], v[140:143], v[204:207], v[128:131]
	v_mfma_f32_16x16x32_bf16 v[108:111], v[116:119], v[216:219], v[108:111]
	v_mfma_f32_16x16x32_bf16 v[104:107], v[140:143], v[216:219], v[104:107]
	v_mfma_f32_16x16x32_bf16 v[92:95], v[116:119], v[224:227], v[92:95]
	v_mfma_f32_16x16x32_bf16 v[88:91], v[140:143], v[224:227], v[88:91]
	v_mfma_f32_16x16x32_bf16 v[76:79], v[116:119], v[232:235], v[76:79]
	v_mfma_f32_16x16x32_bf16 v[72:75], v[140:143], v[232:235], v[72:75]
	v_mfma_f32_16x16x32_bf16 v[132:135], v[136:139], v[208:211], v[132:135]
	v_mfma_f32_16x16x32_bf16 v[128:131], v[144:147], v[208:211], v[128:131]
	v_mfma_f32_16x16x32_bf16 v[108:111], v[136:139], v[220:223], v[108:111]
	v_mfma_f32_16x16x32_bf16 v[104:107], v[144:147], v[220:223], v[104:107]
	v_mfma_f32_16x16x32_bf16 v[92:95], v[136:139], v[228:231], v[92:95]
	v_mfma_f32_16x16x32_bf16 v[88:91], v[144:147], v[228:231], v[88:91]
	v_mfma_f32_16x16x32_bf16 v[76:79], v[136:139], v[236:239], v[76:79]
	v_mfma_f32_16x16x32_bf16 v[72:75], v[144:147], v[236:239], v[72:75]
	v_mfma_f32_16x16x32_bf16 v[124:127], v[148:151], v[204:207], v[124:127]
	v_mfma_f32_16x16x32_bf16 v[120:123], v[192:195], v[204:207], v[120:123]
	v_mfma_f32_16x16x32_bf16 v[100:103], v[148:151], v[216:219], v[100:103]
	v_mfma_f32_16x16x32_bf16 v[96:99], v[192:195], v[216:219], v[96:99]
	v_mfma_f32_16x16x32_bf16 v[84:87], v[148:151], v[224:227], v[84:87]
	v_mfma_f32_16x16x32_bf16 v[80:83], v[192:195], v[224:227], v[80:83]
	v_mfma_f32_16x16x32_bf16 v[68:71], v[148:151], v[232:235], v[68:71]
	v_mfma_f32_16x16x32_bf16 v[64:67], v[192:195], v[232:235], v[64:67]
	v_mfma_f32_16x16x32_bf16 v[124:127], v[188:191], v[208:211], v[124:127]
	v_mfma_f32_16x16x32_bf16 v[120:123], v[198:201], v[208:211], v[120:123]
	v_mfma_f32_16x16x32_bf16 v[100:103], v[188:191], v[220:223], v[100:103]
	v_mfma_f32_16x16x32_bf16 v[96:99], v[198:201], v[220:223], v[96:99]
	v_mfma_f32_16x16x32_bf16 v[84:87], v[188:191], v[228:231], v[84:87]
	v_mfma_f32_16x16x32_bf16 v[80:83], v[198:201], v[228:231], v[80:83]
	v_mfma_f32_16x16x32_bf16 v[68:71], v[188:191], v[236:239], v[68:71]
	v_mfma_f32_16x16x32_bf16 v[64:67], v[198:201], v[236:239], v[64:67]
	s_setprio 0
	s_barrier
; #define PG8_STAGE(bufoff, gbase, voff) do { _Pragma("unroll") for (int _i = 0; _i < 2; ++_i) \
;         __builtin_amdgcn_global_load_lds((const unsigned*)((const char*)(gbase) + (voff)[_i]), (PG8_LAS unsigned*)(lds + (bufoff) + ldsw + _i * 8192), 16, 0, 0); } while (0)
; #define PG8_LDA(dst, b, h) do { _Pragma("unroll") for (int m = 0; m < 4; ++m) _Pragma("unroll") for (int k = 0; k < 2; ++k) dst[m][k] = *(const PG8_LAS bf16x8*)(lds + PG8_SA(b, h) + aoff + m * 2048 + k * 1024); } while (0)
; #define PG8_MMA(ai, bj, At, Bt) do { __builtin_amdgcn_s_setprio(1); _Pragma("unroll") for (int m = 0; m < 4; ++m) _Pragma("unroll") for (int n = 0; n < 2; ++n) _Pragma("unroll") for (int k = 0; k < 2; ++k) \
;         acc[ai][bj][m][n] = __builtin_amdgcn_mfma_f32_16x16x32_bf16(Bt[n][k], At[m][k], acc[ai][bj][m][n], 0, 0, 0); __builtin_amdgcn_s_setprio(0); } while (0)
; #define PG8_WAIT_V(n) asm volatile("s_waitcnt vmcnt(" #n ")" ::: "memory")
; #define PG8_WAIT_L(n) asm volatile("s_waitcnt lgkmcnt(" #n ")" ::: "memory")
; #define PG8_BAR __builtin_amdgcn_s_barrier()
; #define PG8_SCHED __builtin_amdgcn_sched_barrier(0)
; template <class Epi, class Sched, bool ALIGN_EPI = false, bool SP2 = false>
; __device__ __forceinline__ void gemm_phase(PG8_LAS unsigned char* lds, const Gemm g, const Sched& S, const Epi& E) {
;     ...
;             PG8_LDA(At, 1, 1); PG8_STAGE(PG8_SB(1, 0), b3, voffB); PG8_STAGE(PG8_SB(1, 1), b3 + hstep, voffB); PG8_STAGE(PG8_SA(1, 0), a3, voffA);
;             PG8_WAIT_V(8); PG8_WAIT_L(0); PG8_BAR; PG8_MMA(1, 0, At, B0); PG8_MMA(1, 1, At, B1); PG8_BAR; PG8_SCHED;
	s_add_i32 s9, s9, s29
	v_lshl_add_u64 v[212:213], v[240:241], 0, s[18:19]
	s_mov_b32 m0, s9
	ds_read_b128 v[204:207], v202 offset:49152
	ds_read_b128 v[208:211], v202 offset:50176
	ds_read_b128 v[216:219], v202 offset:51200
	ds_read_b128 v[220:223], v202 offset:52224
	ds_read_b128 v[224:227], v202 offset:53248
	ds_read_b128 v[228:231], v202 offset:54272
	ds_read_b128 v[232:235], v202 offset:55296
	ds_read_b128 v[236:239], v202 offset:56320
	global_load_lds_dwordx4 v[212:213], off
	v_lshl_add_u64 v[212:213], v[242:243], 0, s[18:19]
	s_add_i32 m0, s9, 0x2000
	s_add_i32 s9, s10, s29
	global_load_lds_dwordx4 v[212:213], off
	v_lshl_add_u64 v[212:213], v[244:245], 0, s[18:19]
	s_mov_b32 m0, s9
	s_nop 0
	global_load_lds_dwordx4 v[212:213], off
	v_lshl_add_u64 v[212:213], v[214:215], 0, s[18:19]
	s_add_i32 m0, s9, 0x2000
	s_nop 0
	global_load_lds_dwordx4 v[212:213], off
	v_lshl_add_u64 v[212:213], v[246:247], 0, s[18:19]
	s_mov_b32 m0, s49
	s_nop 0
	global_load_lds_dwordx4 v[212:213], off
	v_lshl_add_u64 v[212:213], v[248:249], 0, s[18:19]
	s_mov_b32 m0, s50
	s_nop 0
	global_load_lds_dwordx4 v[212:213], off
	s_waitcnt vmcnt(8)
	s_waitcnt lgkmcnt(0)
	s_barrier
	s_setprio 1
	s_waitcnt lgkmcnt(0)
	v_mfma_f32_16x16x32_bf16 v[60:63], v[116:119], v[204:207], v[60:63]
	v_mfma_f32_16x16x32_bf16 v[56:59], v[140:143], v[204:207], v[56:59]
	v_mfma_f32_16x16x32_bf16 v[44:47], v[116:119], v[216:219], v[44:47]
	v_mfma_f32_16x16x32_bf16 v[40:43], v[140:143], v[216:219], v[40:43]
	v_mfma_f32_16x16x32_bf16 v[28:31], v[116:119], v[224:227], v[28:31]
	v_mfma_f32_16x16x32_bf16 v[24:27], v[140:143], v[224:227], v[24:27]
	v_mfma_f32_16x16x32_bf16 v[12:15], v[116:119], v[232:235], v[12:15]
	v_mfma_f32_16x16x32_bf16 v[8:11], v[140:143], v[232:235], v[8:11]
	v_mfma_f32_16x16x32_bf16 v[60:63], v[136:139], v[208:211], v[60:63]
	v_mfma_f32_16x16x32_bf16 v[56:59], v[144:147], v[208:211], v[56:59]
	v_mfma_f32_16x16x32_bf16 v[44:47], v[136:139], v[220:223], v[44:47]
	v_mfma_f32_16x16x32_bf16 v[40:43], v[144:147], v[220:223], v[40:43]
	v_mfma_f32_16x16x32_bf16 v[28:31], v[136:139], v[228:231], v[28:31]
	v_mfma_f32_16x16x32_bf16 v[24:27], v[144:147], v[228:231], v[24:27]
	v_mfma_f32_16x16x32_bf16 v[12:15], v[136:139], v[236:239], v[12:15]
	v_mfma_f32_16x16x32_bf16 v[8:11], v[144:147], v[236:239], v[8:11]
	v_mfma_f32_16x16x32_bf16 v[52:55], v[148:151], v[204:207], v[52:55]
	v_mfma_f32_16x16x32_bf16 v[48:51], v[192:195], v[204:207], v[48:51]
	v_mfma_f32_16x16x32_bf16 v[36:39], v[148:151], v[216:219], v[36:39]
	v_mfma_f32_16x16x32_bf16 v[32:35], v[192:195], v[216:219], v[32:35]
	v_mfma_f32_16x16x32_bf16 v[20:23], v[148:151], v[224:227], v[20:23]
	v_mfma_f32_16x16x32_bf16 v[16:19], v[192:195], v[224:227], v[16:19]
	v_mfma_f32_16x16x32_bf16 v[4:7], v[148:151], v[232:235], v[4:7]
	v_mfma_f32_16x16x32_bf16 v[0:3], v[192:195], v[232:235], v[0:3]
	v_mfma_f32_16x16x32_bf16 v[52:55], v[188:191], v[208:211], v[52:55]
	v_mfma_f32_16x16x32_bf16 v[48:51], v[198:201], v[208:211], v[48:51]
	v_mfma_f32_16x16x32_bf16 v[36:39], v[188:191], v[220:223], v[36:39]
	v_mfma_f32_16x16x32_bf16 v[32:35], v[198:201], v[220:223], v[32:35]
	v_mfma_f32_16x16x32_bf16 v[20:23], v[188:191], v[228:231], v[20:23]
	v_mfma_f32_16x16x32_bf16 v[16:19], v[198:201], v[228:231], v[16:19]
	v_mfma_f32_16x16x32_bf16 v[4:7], v[188:191], v[236:239], v[4:7]
	v_mfma_f32_16x16x32_bf16 v[0:3], v[198:201], v[236:239], v[0:3]
	s_setprio 0
	s_barrier
	v_lshl_add_u64 v[112:113], v[112:113], 0, s[26:27]
	s_cmp_ge_i32 s8, s51
	v_lshl_add_u64 v[114:115], v[114:115], 0, s[26:27]
	s_cbranch_scc0 .LBB0_722

; #define PG8_STAGE(bufoff, gbase, voff) do { _Pragma("unroll") for (int _i = 0; _i < 2; ++_i) \
;         __builtin_amdgcn_global_load_lds((const unsigned*)((const char*)(gbase) + (voff)[_i]), (PG8_LAS unsigned*)(lds + (bufoff) + ldsw + _i * 8192), 16, 0, 0); } while (0)
; #define PG8_LDA(dst, b, h) do { _Pragma("unroll") for (int m = 0; m < 4; ++m) _Pragma("unroll") for (int k = 0; k < 2; ++k) dst[m][k] = *(const PG8_LAS bf16x8*)(lds + PG8_SA(b, h) + aoff + m * 2048 + k * 1024); } while (0)
; #define PG8_LDB(dst, b, h) do { _Pragma("unroll") for (int n = 0; n < 2; ++n) _Pragma("unroll") for (int k = 0; k < 2; ++k) dst[n][k] = *(const PG8_LAS bf16x8*)(lds + PG8_SB(b, h) + boff + n * 2048 + k * 1024); } while (0)
; #define PG8_MMA(ai, bj, At, Bt) do { __builtin_amdgcn_s_setprio(1); _Pragma("unroll") for (int m = 0; m < 4; ++m) _Pragma("unroll") for (int n = 0; n < 2; ++n) _Pragma("unroll") for (int k = 0; k < 2; ++k) \
;         acc[ai][bj][m][n] = __builtin_amdgcn_mfma_f32_16x16x32_bf16(Bt[n][k], At[m][k], acc[ai][bj][m][n], 0, 0, 0); __builtin_amdgcn_s_setprio(0); } while (0)
; #define PG8_WAIT_V(n) asm volatile("s_waitcnt vmcnt(" #n ")" ::: "memory")
; #define PG8_WAIT_L(n) asm volatile("s_waitcnt lgkmcnt(" #n ")" ::: "memory")
; #define PG8_BAR __builtin_amdgcn_s_barrier()
; #define PG8_SCHED __builtin_amdgcn_sched_barrier(0)
; template <class Epi, class Sched, bool ALIGN_EPI = false, bool SP2 = false>
; __device__ __forceinline__ void gemm_phase(PG8_LAS unsigned char* lds, const Gemm g, const Sched& S, const Epi& E) {
;     ...
;         for (int t = 0; t < nt; t += 2) {
;             const bool last = (t == nt - 2);
;             const char* a1 = cA + (size_t)(t + 1) * kstep;
;             const char* a2 = last ? nA : cA + (size_t)(t + 2) * kstep; const char* b2 = last ? nB : cB + (size_t)(t + 2) * kstep;
;             const char* a3 = a2 + kstep; const char* b3 = b2 + kstep;
;             if (last && has_next) S.a_ready(nxt);
;             if constexpr (SP2) {
;             PG8_LDB(B0, 0, 0); PG8_LDB(B1, 0, 1); PG8_SCHED; PG8_LDA(At, 0, 0); PG8_STAGE(PG8_SA(1, 1), a1 + hstep, voffA);
;             PG8_WAIT_V(8); PG8_WAIT_L(0); PG8_BAR; PG8_MMA(0, 0, At, B0); PG8_MMA(0, 1, At, B1); PG8_BAR; PG8_SCHED;
;             PG8_LDA(At, 0, 1); PG8_STAGE(PG8_SB(0, 0), b2, voffB); PG8_STAGE(PG8_SB(0, 1), b2 + hstep, voffB); PG8_STAGE(PG8_SA(0, 0), a2, voffA);
.LBB0_940:
	v_add_u32_e32 v188, s55, v199
	ds_read_b128 v[132:135], v201
	ds_read_b128 v[136:139], v201 offset:1024
	ds_read_b128 v[140:143], v201 offset:2048
	ds_read_b128 v[144:147], v201 offset:3072
	ds_read_b128 v[148:151], v188
	ds_read_b128 v[180:183], v188 offset:1024
	ds_read_b128 v[184:187], v188 offset:2048
	ds_read_b128 v[188:191], v188 offset:3072
	s_cmp_eq_u32 s48, s12
	v_lshl_add_u64 v[192:193], v[130:131], 0, s[22:23]
	s_cselect_b64 vcc, -1, 0
	s_add_i32 s12, s12, 2
	v_cndmask_b32_e32 v197, v193, v177, vcc
	v_cndmask_b32_e32 v196, v192, v176, vcc
	v_cndmask_b32_e32 v213, v129, v179, vcc
	v_cndmask_b32_e32 v212, v128, v178, vcc
	s_mov_b32 m0, s56
	v_lshl_add_u64 v[214:215], v[130:131], 0, v[172:173]
	ds_read_b128 v[192:195], v202
	ds_read_b128 v[204:207], v202 offset:1024
	ds_read_b128 v[208:211], v202 offset:2048
	ds_read_b128 v[216:219], v202 offset:3072
	ds_read_b128 v[220:223], v202 offset:4096
	ds_read_b128 v[224:227], v202 offset:5120
	ds_read_b128 v[228:231], v202 offset:6144
	ds_read_b128 v[232:235], v202 offset:7168
	global_load_lds_dwordx4 v[214:215], off
	v_lshl_add_u64 v[214:215], v[130:131], 0, v[170:171]
	s_mov_b32 m0, s57
	s_nop 0
	global_load_lds_dwordx4 v[214:215], off
	s_waitcnt vmcnt(8)
	s_waitcnt lgkmcnt(0)
	s_barrier
	s_setprio 1
	s_waitcnt lgkmcnt(0)
	v_mfma_f32_16x16x32_bf16 v[120:123], v[132:135], v[192:195], v[120:123]
	v_mfma_f32_16x16x32_bf16 v[124:127], v[140:143], v[192:195], v[124:127]
	v_mfma_f32_16x16x32_bf16 v[108:111], v[132:135], v[208:211], v[108:111]
	v_mfma_f32_16x16x32_bf16 v[104:107], v[140:143], v[208:211], v[104:107]
	v_mfma_f32_16x16x32_bf16 v[92:95], v[132:135], v[220:223], v[92:95]
	v_mfma_f32_16x16x32_bf16 v[88:91], v[140:143], v[220:223], v[88:91]
	v_mfma_f32_16x16x32_bf16 v[76:79], v[132:135], v[228:231], v[76:79]
	v_mfma_f32_16x16x32_bf16 v[72:75], v[140:143], v[228:231], v[72:75]
	v_mfma_f32_16x16x32_bf16 v[120:123], v[136:139], v[204:207], v[120:123]
	v_mfma_f32_16x16x32_bf16 v[124:127], v[144:147], v[204:207], v[124:127]
	v_mfma_f32_16x16x32_bf16 v[108:111], v[136:139], v[216:219], v[108:111]
	v_mfma_f32_16x16x32_bf16 v[104:107], v[144:147], v[216:219], v[104:107]
	v_mfma_f32_16x16x32_bf16 v[92:95], v[136:139], v[224:227], v[92:95]
	v_mfma_f32_16x16x32_bf16 v[88:91], v[144:147], v[224:227], v[88:91]
	v_mfma_f32_16x16x32_bf16 v[76:79], v[136:139], v[232:235], v[76:79]
	v_mfma_f32_16x16x32_bf16 v[72:75], v[144:147], v[232:235], v[72:75]
	v_mfma_f32_16x16x32_bf16 v[116:119], v[148:151], v[192:195], v[116:119]
	v_mfma_f32_16x16x32_bf16 v[112:115], v[184:187], v[192:195], v[112:115]
	v_mfma_f32_16x16x32_bf16 v[100:103], v[148:151], v[208:211], v[100:103]
	v_mfma_f32_16x16x32_bf16 v[96:99], v[184:187], v[208:211], v[96:99]
	v_mfma_f32_16x16x32_bf16 v[84:87], v[148:151], v[220:223], v[84:87]
	v_mfma_f32_16x16x32_bf16 v[80:83], v[184:187], v[220:223], v[80:83]
	v_mfma_f32_16x16x32_bf16 v[68:71], v[148:151], v[228:231], v[68:71]
	v_mfma_f32_16x16x32_bf16 v[64:67], v[184:187], v[228:231], v[64:67]
	v_mfma_f32_16x16x32_bf16 v[116:119], v[180:183], v[204:207], v[116:119]
	v_mfma_f32_16x16x32_bf16 v[112:115], v[188:191], v[204:207], v[112:115]
	v_mfma_f32_16x16x32_bf16 v[100:103], v[180:183], v[216:219], v[100:103]
	v_mfma_f32_16x16x32_bf16 v[96:99], v[188:191], v[216:219], v[96:99]
	v_mfma_f32_16x16x32_bf16 v[84:87], v[180:183], v[224:227], v[84:87]
	v_mfma_f32_16x16x32_bf16 v[80:83], v[188:191], v[224:227], v[80:83]
	v_mfma_f32_16x16x32_bf16 v[68:71], v[180:183], v[232:235], v[68:71]
	v_mfma_f32_16x16x32_bf16 v[64:67], v[188:191], v[232:235], v[64:67]
	s_setprio 0
	s_barrier
	s_mov_b32 m0, s58
	v_lshl_add_u64 v[214:215], v[212:213], 0, v[164:165]
	ds_read_b128 v[192:195], v202 offset:16384
	ds_read_b128 v[204:207], v202 offset:17408
	ds_read_b128 v[208:211], v202 offset:18432
	ds_read_b128 v[216:219], v202 offset:19456
	ds_read_b128 v[220:223], v202 offset:20480
	ds_read_b128 v[224:227], v202 offset:21504
	ds_read_b128 v[228:231], v202 offset:22528
	ds_read_b128 v[232:235], v202 offset:23552
	global_load_lds_dwordx4 v[214:215], off
	v_lshl_add_u64 v[236:237], v[212:213], 0, v[168:169]
	s_mov_b32 m0, s59
	v_lshl_add_u64 v[212:213], v[212:213], 0, s[14:15]
	s_add_i32 s13, s55, s30
	global_load_lds_dwordx4 v[236:237], off
	v_lshl_add_u64 v[238:239], v[212:213], 0, v[164:165]
	s_mov_b32 m0, s13
	v_lshl_add_u64 v[212:213], v[212:213], 0, v[168:169]
	global_load_lds_dwordx4 v[238:239], off
	s_add_i32 m0, s13, 0x2000
	v_lshl_add_u64 v[240:241], v[196:197], 0, v[162:163]
	global_load_lds_dwordx4 v[212:213], off
	s_mov_b32 m0, s31
	v_lshl_add_u64 v[242:243], v[196:197], 0, v[166:167]
	global_load_lds_dwordx4 v[240:241], off
	s_mov_b32 m0, s34
	s_nop 0
	global_load_lds_dwordx4 v[242:243], off
	s_waitcnt vmcnt(8)
	s_waitcnt lgkmcnt(0)
	s_barrier
; #define PG8_STAGE(bufoff, gbase, voff) do { _Pragma("unroll") for (int _i = 0; _i < 2; ++_i) \
;         __builtin_amdgcn_global_load_lds((const unsigned*)((const char*)(gbase) + (voff)[_i]), (PG8_LAS unsigned*)(lds + (bufoff) + ldsw + _i * 8192), 16, 0, 0); } while (0)
; #define PG8_LDA(dst, b, h) do { _Pragma("unroll") for (int m = 0; m < 4; ++m) _Pragma("unroll") for (int k = 0; k < 2; ++k) dst[m][k] = *(const PG8_LAS bf16x8*)(lds + PG8_SA(b, h) + aoff + m * 2048 + k * 1024); } while (0)
; #define PG8_LDB(dst, b, h) do { _Pragma("unroll") for (int n = 0; n < 2; ++n) _Pragma("unroll") for (int k = 0; k < 2; ++k) dst[n][k] = *(const PG8_LAS bf16x8*)(lds + PG8_SB(b, h) + boff + n * 2048 + k * 1024); } while (0)
; #define PG8_MMA(ai, bj, At, Bt) do { __builtin_amdgcn_s_setprio(1); _Pragma("unroll") for (int m = 0; m < 4; ++m) _Pragma("unroll") for (int n = 0; n < 2; ++n) _Pragma("unroll") for (int k = 0; k < 2; ++k) \
;         acc[ai][bj][m][n] = __builtin_amdgcn_mfma_f32_16x16x32_bf16(Bt[n][k], At[m][k], acc[ai][bj][m][n], 0, 0, 0); __builtin_amdgcn_s_setprio(0); } while (0)
; #define PG8_WAIT_V(n) asm volatile("s_waitcnt vmcnt(" #n ")" ::: "memory")
; #define PG8_WAIT_L(n) asm volatile("s_waitcnt lgkmcnt(" #n ")" ::: "memory")
; #define PG8_BAR __builtin_amdgcn_s_barrier()
; #define PG8_SCHED __builtin_amdgcn_sched_barrier(0)
; template <class Epi, class Sched, bool ALIGN_EPI = false, bool SP2 = false>
; __device__ __forceinline__ void gemm_phase(PG8_LAS unsigned char* lds, const Gemm g, const Sched& S, const Epi& E) {
;     ...
;             PG8_WAIT_V(8); PG8_WAIT_L(0); PG8_BAR; PG8_MMA(1, 0, At, B0); PG8_MMA(1, 1, At, B1); PG8_BAR; PG8_SCHED;
;             PG8_LDB(B0, 1, 0); PG8_LDB(B1, 1, 1); PG8_SCHED; PG8_LDA(At, 1, 0); PG8_STAGE(PG8_SA(0, 1), a2 + hstep, voffA);
;             PG8_WAIT_V(8); PG8_WAIT_L(0); PG8_BAR; PG8_MMA(0, 0, At, B0); PG8_MMA(0, 1, At, B1); PG8_BAR; PG8_SCHED;
	s_setprio 1
	s_waitcnt lgkmcnt(0)
	v_mfma_f32_16x16x32_bf16 v[60:63], v[132:135], v[192:195], v[60:63]
	v_mfma_f32_16x16x32_bf16 v[56:59], v[140:143], v[192:195], v[56:59]
	v_mfma_f32_16x16x32_bf16 v[44:47], v[132:135], v[208:211], v[44:47]
	v_mfma_f32_16x16x32_bf16 v[40:43], v[140:143], v[208:211], v[40:43]
	v_mfma_f32_16x16x32_bf16 v[28:31], v[132:135], v[220:223], v[28:31]
	v_mfma_f32_16x16x32_bf16 v[24:27], v[140:143], v[220:223], v[24:27]
	v_mfma_f32_16x16x32_bf16 v[12:15], v[132:135], v[228:231], v[12:15]
	v_mfma_f32_16x16x32_bf16 v[8:11], v[140:143], v[228:231], v[8:11]
	v_mfma_f32_16x16x32_bf16 v[60:63], v[136:139], v[204:207], v[60:63]
	v_mfma_f32_16x16x32_bf16 v[56:59], v[144:147], v[204:207], v[56:59]
	v_mfma_f32_16x16x32_bf16 v[44:47], v[136:139], v[216:219], v[44:47]
	v_mfma_f32_16x16x32_bf16 v[40:43], v[144:147], v[216:219], v[40:43]
	v_mfma_f32_16x16x32_bf16 v[28:31], v[136:139], v[224:227], v[28:31]
	v_mfma_f32_16x16x32_bf16 v[24:27], v[144:147], v[224:227], v[24:27]
	v_mfma_f32_16x16x32_bf16 v[12:15], v[136:139], v[232:235], v[12:15]
	v_mfma_f32_16x16x32_bf16 v[8:11], v[144:147], v[232:235], v[8:11]
	v_mfma_f32_16x16x32_bf16 v[52:55], v[148:151], v[192:195], v[52:55]
	v_mfma_f32_16x16x32_bf16 v[48:51], v[184:187], v[192:195], v[48:51]
	v_mfma_f32_16x16x32_bf16 v[36:39], v[148:151], v[208:211], v[36:39]
	v_mfma_f32_16x16x32_bf16 v[32:35], v[184:187], v[208:211], v[32:35]
	v_mfma_f32_16x16x32_bf16 v[20:23], v[148:151], v[220:223], v[20:23]
	v_mfma_f32_16x16x32_bf16 v[16:19], v[184:187], v[220:223], v[16:19]
	v_mfma_f32_16x16x32_bf16 v[4:7], v[148:151], v[228:231], v[4:7]
	v_mfma_f32_16x16x32_bf16 v[0:3], v[184:187], v[228:231], v[0:3]
	v_mfma_f32_16x16x32_bf16 v[52:55], v[180:183], v[204:207], v[52:55]
	v_mfma_f32_16x16x32_bf16 v[48:51], v[188:191], v[204:207], v[48:51]
	v_mfma_f32_16x16x32_bf16 v[36:39], v[180:183], v[216:219], v[36:39]
	v_mfma_f32_16x16x32_bf16 v[32:35], v[188:191], v[216:219], v[32:35]
	v_mfma_f32_16x16x32_bf16 v[20:23], v[180:183], v[224:227], v[20:23]
	v_mfma_f32_16x16x32_bf16 v[16:19], v[188:191], v[224:227], v[16:19]
	v_mfma_f32_16x16x32_bf16 v[4:7], v[180:183], v[232:235], v[4:7]
	v_mfma_f32_16x16x32_bf16 v[0:3], v[188:191], v[232:235], v[0:3]
	s_setprio 0
	s_barrier
	s_add_i32 s13, 0, 0x18000
	s_add_i32 s29, 0, 0x1c000
	v_add_u32_e32 v144, s13, v199
	v_add_u32_e32 v188, s29, v199
	ds_read_b128 v[132:135], v144
	ds_read_b128 v[136:139], v144 offset:1024
	ds_read_b128 v[140:143], v144 offset:2048
	ds_read_b128 v[144:147], v144 offset:3072
	ds_read_b128 v[148:151], v188
	ds_read_b128 v[180:183], v188 offset:1024
	ds_read_b128 v[184:187], v188 offset:2048
	ds_read_b128 v[188:191], v188 offset:3072
	v_lshl_add_u64 v[196:197], v[196:197], 0, s[14:15]
	s_mov_b32 m0, s35
	v_lshl_add_u64 v[244:245], v[196:197], 0, v[162:163]
	ds_read_b128 v[192:195], v202 offset:32768
	ds_read_b128 v[204:207], v202 offset:33792
	ds_read_b128 v[208:211], v202 offset:34816
	ds_read_b128 v[216:219], v202 offset:35840
	ds_read_b128 v[220:223], v202 offset:36864
	ds_read_b128 v[224:227], v202 offset:37888
	ds_read_b128 v[228:231], v202 offset:38912
	ds_read_b128 v[232:235], v202 offset:39936
	global_load_lds_dwordx4 v[244:245], off
	v_lshl_add_u64 v[196:197], v[196:197], 0, v[166:167]
	s_mov_b32 m0, s36
	s_nop 0
	global_load_lds_dwordx4 v[196:197], off
	s_waitcnt vmcnt(8)
	s_waitcnt lgkmcnt(0)
	s_barrier
	s_setprio 1
	s_waitcnt lgkmcnt(0)
	v_mfma_f32_16x16x32_bf16 v[120:123], v[132:135], v[192:195], v[120:123]
	v_mfma_f32_16x16x32_bf16 v[124:127], v[140:143], v[192:195], v[124:127]
	v_mfma_f32_16x16x32_bf16 v[108:111], v[132:135], v[208:211], v[108:111]
	v_mfma_f32_16x16x32_bf16 v[104:107], v[140:143], v[208:211], v[104:107]
	v_mfma_f32_16x16x32_bf16 v[92:95], v[132:135], v[220:223], v[92:95]
	v_mfma_f32_16x16x32_bf16 v[88:91], v[140:143], v[220:223], v[88:91]
	v_mfma_f32_16x16x32_bf16 v[76:79], v[132:135], v[228:231], v[76:79]
	v_mfma_f32_16x16x32_bf16 v[72:75], v[140:143], v[228:231], v[72:75]
	v_mfma_f32_16x16x32_bf16 v[120:123], v[136:139], v[204:207], v[120:123]
	v_mfma_f32_16x16x32_bf16 v[124:127], v[144:147], v[204:207], v[124:127]
	v_mfma_f32_16x16x32_bf16 v[108:111], v[136:139], v[216:219], v[108:111]
	v_mfma_f32_16x16x32_bf16 v[104:107], v[144:147], v[216:219], v[104:107]
	v_mfma_f32_16x16x32_bf16 v[92:95], v[136:139], v[224:227], v[92:95]
	v_mfma_f32_16x16x32_bf16 v[88:91], v[144:147], v[224:227], v[88:91]
	v_mfma_f32_16x16x32_bf16 v[76:79], v[136:139], v[232:235], v[76:79]
	v_mfma_f32_16x16x32_bf16 v[72:75], v[144:147], v[232:235], v[72:75]
	v_mfma_f32_16x16x32_bf16 v[116:119], v[148:151], v[192:195], v[116:119]
	v_mfma_f32_16x16x32_bf16 v[112:115], v[184:187], v[192:195], v[112:115]
	v_mfma_f32_16x16x32_bf16 v[100:103], v[148:151], v[208:211], v[100:103]
	v_mfma_f32_16x16x32_bf16 v[96:99], v[184:187], v[208:211], v[96:99]
	v_mfma_f32_16x16x32_bf16 v[84:87], v[148:151], v[220:223], v[84:87]
	v_mfma_f32_16x16x32_bf16 v[80:83], v[184:187], v[220:223], v[80:83]
	v_mfma_f32_16x16x32_bf16 v[68:71], v[148:151], v[228:231], v[68:71]
	v_mfma_f32_16x16x32_bf16 v[64:67], v[184:187], v[228:231], v[64:67]
	v_mfma_f32_16x16x32_bf16 v[116:119], v[180:183], v[204:207], v[116:119]
	v_mfma_f32_16x16x32_bf16 v[112:115], v[188:191], v[204:207], v[112:115]
	v_mfma_f32_16x16x32_bf16 v[100:103], v[180:183], v[216:219], v[100:103]
	v_mfma_f32_16x16x32_bf16 v[96:99], v[188:191], v[216:219], v[96:99]
	v_mfma_f32_16x16x32_bf16 v[84:87], v[180:183], v[224:227], v[84:87]
	v_mfma_f32_16x16x32_bf16 v[80:83], v[188:191], v[224:227], v[80:83]
	v_mfma_f32_16x16x32_bf16 v[68:71], v[180:183], v[232:235], v[68:71]
	v_mfma_f32_16x16x32_bf16 v[64:67], v[188:191], v[232:235], v[64:67]
	s_setprio 0
	s_barrier
; #define PG8_STAGE(bufoff, gbase, voff) do { _Pragma("unroll") for (int _i = 0; _i < 2; ++_i) \
;         __builtin_amdgcn_global_load_lds((const unsigned*)((const char*)(gbase) + (voff)[_i]), (PG8_LAS unsigned*)(lds + (bufoff) + ldsw + _i * 8192), 16, 0, 0); } while (0)
; #define PG8_LDA(dst, b, h) do { _Pragma("unroll") for (int m = 0; m < 4; ++m) _Pragma("unroll") for (int k = 0; k < 2; ++k) dst[m][k] = *(const PG8_LAS bf16x8*)(lds + PG8_SA(b, h) + aoff + m * 2048 + k * 1024); } while (0)
; #define PG8_MMA(ai, bj, At, Bt) do { __builtin_amdgcn_s_setprio(1); _Pragma("unroll") for (int m = 0; m < 4; ++m) _Pragma("unroll") for (int n = 0; n < 2; ++n) _Pragma("unroll") for (int k = 0; k < 2; ++k) \
;         acc[ai][bj][m][n] = __builtin_amdgcn_mfma_f32_16x16x32_bf16(Bt[n][k], At[m][k], acc[ai][bj][m][n], 0, 0, 0); __builtin_amdgcn_s_setprio(0); } while (0)
; #define PG8_WAIT_V(n) asm volatile("s_waitcnt vmcnt(" #n ")" ::: "memory")
; #define PG8_WAIT_L(n) asm volatile("s_waitcnt lgkmcnt(" #n ")" ::: "memory")
; #define PG8_BAR __builtin_amdgcn_s_barrier()
; #define PG8_SCHED __builtin_amdgcn_sched_barrier(0)
; template <class Epi, class Sched, bool ALIGN_EPI = false, bool SP2 = false>
; __device__ __forceinline__ void gemm_phase(PG8_LAS unsigned char* lds, const Gemm g, const Sched& S, const Epi& E) {
;     ...
;             PG8_LDA(At, 1, 1); PG8_STAGE(PG8_SB(1, 0), b3, voffB); PG8_STAGE(PG8_SB(1, 1), b3 + hstep, voffB); PG8_STAGE(PG8_SA(1, 0), a3, voffA);
;             PG8_WAIT_V(8); PG8_WAIT_L(0); PG8_BAR; PG8_MMA(1, 0, At, B0); PG8_MMA(1, 1, At, B1); PG8_BAR; PG8_SCHED;
	s_add_i32 s13, s13, s30
	v_lshl_add_u64 v[196:197], v[214:215], 0, s[22:23]
	s_mov_b32 m0, s13
	ds_read_b128 v[192:195], v202 offset:49152
	ds_read_b128 v[204:207], v202 offset:50176
	ds_read_b128 v[208:211], v202 offset:51200
	ds_read_b128 v[216:219], v202 offset:52224
	ds_read_b128 v[220:223], v202 offset:53248
	ds_read_b128 v[224:227], v202 offset:54272
	ds_read_b128 v[228:231], v202 offset:55296
	ds_read_b128 v[232:235], v202 offset:56320
	global_load_lds_dwordx4 v[196:197], off
	v_lshl_add_u64 v[196:197], v[236:237], 0, s[22:23]
	s_add_i32 m0, s13, 0x2000
	s_add_i32 s13, s29, s30
	global_load_lds_dwordx4 v[196:197], off
	v_lshl_add_u64 v[196:197], v[238:239], 0, s[22:23]
	s_mov_b32 m0, s13
	s_nop 0
	global_load_lds_dwordx4 v[196:197], off
	v_lshl_add_u64 v[196:197], v[212:213], 0, s[22:23]
	s_add_i32 m0, s13, 0x2000
	s_nop 0
	global_load_lds_dwordx4 v[196:197], off
	v_lshl_add_u64 v[196:197], v[240:241], 0, s[22:23]
	s_mov_b32 m0, s37
	s_nop 0
	global_load_lds_dwordx4 v[196:197], off
	v_lshl_add_u64 v[196:197], v[242:243], 0, s[22:23]
	s_mov_b32 m0, s41
	s_nop 0
	global_load_lds_dwordx4 v[196:197], off
	s_waitcnt vmcnt(8)
	s_waitcnt lgkmcnt(0)
	s_barrier
	s_setprio 1
	s_waitcnt lgkmcnt(0)
	v_mfma_f32_16x16x32_bf16 v[60:63], v[132:135], v[192:195], v[60:63]
	v_mfma_f32_16x16x32_bf16 v[56:59], v[140:143], v[192:195], v[56:59]
	v_mfma_f32_16x16x32_bf16 v[44:47], v[132:135], v[208:211], v[44:47]
	v_mfma_f32_16x16x32_bf16 v[40:43], v[140:143], v[208:211], v[40:43]
	v_mfma_f32_16x16x32_bf16 v[28:31], v[132:135], v[220:223], v[28:31]
	v_mfma_f32_16x16x32_bf16 v[24:27], v[140:143], v[220:223], v[24:27]
	v_mfma_f32_16x16x32_bf16 v[12:15], v[132:135], v[228:231], v[12:15]
	v_mfma_f32_16x16x32_bf16 v[8:11], v[140:143], v[228:231], v[8:11]
	v_mfma_f32_16x16x32_bf16 v[60:63], v[136:139], v[204:207], v[60:63]
	v_mfma_f32_16x16x32_bf16 v[56:59], v[144:147], v[204:207], v[56:59]
	v_mfma_f32_16x16x32_bf16 v[44:47], v[136:139], v[216:219], v[44:47]
	v_mfma_f32_16x16x32_bf16 v[40:43], v[144:147], v[216:219], v[40:43]
	v_mfma_f32_16x16x32_bf16 v[28:31], v[136:139], v[224:227], v[28:31]
	v_mfma_f32_16x16x32_bf16 v[24:27], v[144:147], v[224:227], v[24:27]
	v_mfma_f32_16x16x32_bf16 v[12:15], v[136:139], v[232:235], v[12:15]
	v_mfma_f32_16x16x32_bf16 v[8:11], v[144:147], v[232:235], v[8:11]
	v_mfma_f32_16x16x32_bf16 v[52:55], v[148:151], v[192:195], v[52:55]
	v_mfma_f32_16x16x32_bf16 v[48:51], v[184:187], v[192:195], v[48:51]
	v_mfma_f32_16x16x32_bf16 v[36:39], v[148:151], v[208:211], v[36:39]
	v_mfma_f32_16x16x32_bf16 v[32:35], v[184:187], v[208:211], v[32:35]
	v_mfma_f32_16x16x32_bf16 v[20:23], v[148:151], v[220:223], v[20:23]
	v_mfma_f32_16x16x32_bf16 v[16:19], v[184:187], v[220:223], v[16:19]
	v_mfma_f32_16x16x32_bf16 v[4:7], v[148:151], v[228:231], v[4:7]
	v_mfma_f32_16x16x32_bf16 v[0:3], v[184:187], v[228:231], v[0:3]
	v_mfma_f32_16x16x32_bf16 v[52:55], v[180:183], v[204:207], v[52:55]
	v_mfma_f32_16x16x32_bf16 v[48:51], v[188:191], v[204:207], v[48:51]
	v_mfma_f32_16x16x32_bf16 v[36:39], v[180:183], v[216:219], v[36:39]
	v_mfma_f32_16x16x32_bf16 v[32:35], v[188:191], v[216:219], v[32:35]
	v_mfma_f32_16x16x32_bf16 v[20:23], v[180:183], v[224:227], v[20:23]
	v_mfma_f32_16x16x32_bf16 v[16:19], v[188:191], v[224:227], v[16:19]
	v_mfma_f32_16x16x32_bf16 v[4:7], v[180:183], v[232:235], v[4:7]
	v_mfma_f32_16x16x32_bf16 v[0:3], v[188:191], v[232:235], v[0:3]
	s_setprio 0
	s_barrier
	v_lshl_add_u64 v[128:129], v[128:129], 0, s[26:27]
	s_cmp_ge_i32 s12, s47
	v_lshl_add_u64 v[130:131], v[130:131], 0, s[26:27]
	s_cbranch_scc0 .LBB0_940

; #define PG8_STAGE(bufoff, gbase, voff) do { _Pragma("unroll") for (int _i = 0; _i < 2; ++_i) \
;         __builtin_amdgcn_global_load_lds((const unsigned*)((const char*)(gbase) + (voff)[_i]), (PG8_LAS unsigned*)(lds + (bufoff) + ldsw + _i * 8192), 16, 0, 0); } while (0)
; #define PG8_LDA(dst, b, h) do { _Pragma("unroll") for (int m = 0; m < 4; ++m) _Pragma("unroll") for (int k = 0; k < 2; ++k) dst[m][k] = *(const PG8_LAS bf16x8*)(lds + PG8_SA(b, h) + aoff + m * 2048 + k * 1024); } while (0)
; #define PG8_LDB(dst, b, h) do { _Pragma("unroll") for (int n = 0; n < 2; ++n) _Pragma("unroll") for (int k = 0; k < 2; ++k) dst[n][k] = *(const PG8_LAS bf16x8*)(lds + PG8_SB(b, h) + boff + n * 2048 + k * 1024); } while (0)
; #define PG8_MMA(ai, bj, At, Bt) do { __builtin_amdgcn_s_setprio(1); _Pragma("unroll") for (int m = 0; m < 4; ++m) _Pragma("unroll") for (int n = 0; n < 2; ++n) _Pragma("unroll") for (int k = 0; k < 2; ++k) \
;         acc[ai][bj][m][n] = __builtin_amdgcn_mfma_f32_16x16x32_bf16(Bt[n][k], At[m][k], acc[ai][bj][m][n], 0, 0, 0); __builtin_amdgcn_s_setprio(0); } while (0)
; #define PG8_WAIT_V(n) asm volatile("s_waitcnt vmcnt(" #n ")" ::: "memory")
; #define PG8_WAIT_L(n) asm volatile("s_waitcnt lgkmcnt(" #n ")" ::: "memory")
; #define PG8_BAR __builtin_amdgcn_s_barrier()
; #define PG8_SCHED __builtin_amdgcn_sched_barrier(0)
; template <class Epi, class Sched, bool ALIGN_EPI = false, bool SP2 = false>
; __device__ __forceinline__ void gemm_phase(PG8_LAS unsigned char* lds, const Gemm g, const Sched& S, const Epi& E) {
;     ...
;         for (int t = 0; t < nt; t += 2) {
;             const bool last = (t == nt - 2);
;             const char* a1 = cA + (size_t)(t + 1) * kstep;
;             const char* a2 = last ? nA : cA + (size_t)(t + 2) * kstep; const char* b2 = last ? nB : cB + (size_t)(t + 2) * kstep;
;             const char* a3 = a2 + kstep; const char* b3 = b2 + kstep;
;             if (last && has_next) S.a_ready(nxt);
;             if constexpr (SP2) {
;             PG8_LDB(B0, 0, 0); PG8_LDB(B1, 0, 1); PG8_SCHED; PG8_LDA(At, 0, 0); PG8_STAGE(PG8_SA(1, 1), a1 + hstep, voffA);
;             PG8_WAIT_V(8); PG8_WAIT_L(0); PG8_BAR; PG8_MMA(0, 0, At, B0); PG8_MMA(0, 1, At, B1); PG8_BAR; PG8_SCHED;
;             PG8_LDA(At, 0, 1); PG8_STAGE(PG8_SB(0, 0), b2, voffB); PG8_STAGE(PG8_SB(0, 1), b2 + hstep, voffB); PG8_STAGE(PG8_SA(0, 0), a2, voffA);
.LBB0_1021:
	v_add_u32_e32 v166, s55, v169
	v_add_u32_e32 v168, s56, v169
	ds_read_b128 v[162:165], v166
	ds_read_b128 v[182:185], v166 offset:1024
	ds_read_b128 v[186:189], v166 offset:2048
	ds_read_b128 v[190:193], v166 offset:3072
	ds_read_b128 v[194:197], v168
	ds_read_b128 v[198:201], v168 offset:1024
	ds_read_b128 v[202:205], v168 offset:2048
	ds_read_b128 v[206:209], v168 offset:3072
	s_cmp_eq_u32 s54, s10
	v_lshl_add_u64 v[172:173], v[160:161], 0, s[22:23]
	s_cselect_b64 vcc, -1, 0
	s_add_i32 s10, s10, 2
	v_cndmask_b32_e32 v173, v173, v153, vcc
	v_cndmask_b32_e32 v172, v172, v152, vcc
	v_cndmask_b32_e32 v215, v159, v155, vcc
	v_cndmask_b32_e32 v214, v158, v154, vcc
	s_mov_b32 m0, s57
	v_lshl_add_u64 v[244:245], v[160:161], 0, v[148:149]
	ds_read_b128 v[210:213], v179
	ds_read_b128 v[216:219], v179 offset:1024
	ds_read_b128 v[220:223], v179 offset:2048
	ds_read_b128 v[224:227], v179 offset:3072
	ds_read_b128 v[228:231], v179 offset:4096
	ds_read_b128 v[232:235], v179 offset:5120
	ds_read_b128 v[236:239], v179 offset:6144
	ds_read_b128 v[240:243], v179 offset:7168
	global_load_lds_dwordx4 v[244:245], off
	v_lshl_add_u64 v[244:245], v[160:161], 0, v[146:147]
	s_mov_b32 m0, s58
	s_nop 0
	global_load_lds_dwordx4 v[244:245], off
	s_waitcnt vmcnt(8)
	s_waitcnt lgkmcnt(0)
	s_barrier
	s_setprio 1
	s_waitcnt lgkmcnt(0)
	v_mfma_f32_16x16x32_bf16 v[124:127], v[162:165], v[210:213], v[124:127]
	v_mfma_f32_16x16x32_bf16 v[116:119], v[186:189], v[210:213], v[116:119]
	v_mfma_f32_16x16x32_bf16 v[108:111], v[162:165], v[220:223], v[108:111]
	v_mfma_f32_16x16x32_bf16 v[100:103], v[186:189], v[220:223], v[100:103]
	v_mfma_f32_16x16x32_bf16 v[92:95], v[162:165], v[228:231], v[92:95]
	v_mfma_f32_16x16x32_bf16 v[84:87], v[186:189], v[228:231], v[84:87]
	v_mfma_f32_16x16x32_bf16 v[76:79], v[162:165], v[236:239], v[76:79]
	v_mfma_f32_16x16x32_bf16 v[68:71], v[186:189], v[236:239], v[68:71]
	v_mfma_f32_16x16x32_bf16 v[124:127], v[182:185], v[216:219], v[124:127]
	v_mfma_f32_16x16x32_bf16 v[116:119], v[190:193], v[216:219], v[116:119]
	v_mfma_f32_16x16x32_bf16 v[108:111], v[182:185], v[224:227], v[108:111]
	v_mfma_f32_16x16x32_bf16 v[100:103], v[190:193], v[224:227], v[100:103]
	v_mfma_f32_16x16x32_bf16 v[92:95], v[182:185], v[232:235], v[92:95]
	v_mfma_f32_16x16x32_bf16 v[84:87], v[190:193], v[232:235], v[84:87]
	v_mfma_f32_16x16x32_bf16 v[76:79], v[182:185], v[240:243], v[76:79]
	v_mfma_f32_16x16x32_bf16 v[68:71], v[190:193], v[240:243], v[68:71]
	v_mfma_f32_16x16x32_bf16 v[120:123], v[194:197], v[210:213], v[120:123]
	v_mfma_f32_16x16x32_bf16 v[112:115], v[202:205], v[210:213], v[112:115]
	v_mfma_f32_16x16x32_bf16 v[104:107], v[194:197], v[220:223], v[104:107]
	v_mfma_f32_16x16x32_bf16 v[96:99], v[202:205], v[220:223], v[96:99]
	v_mfma_f32_16x16x32_bf16 v[88:91], v[194:197], v[228:231], v[88:91]
	v_mfma_f32_16x16x32_bf16 v[80:83], v[202:205], v[228:231], v[80:83]
	v_mfma_f32_16x16x32_bf16 v[72:75], v[194:197], v[236:239], v[72:75]
	v_mfma_f32_16x16x32_bf16 v[64:67], v[202:205], v[236:239], v[64:67]
	v_mfma_f32_16x16x32_bf16 v[120:123], v[198:201], v[216:219], v[120:123]
	v_mfma_f32_16x16x32_bf16 v[112:115], v[206:209], v[216:219], v[112:115]
	v_mfma_f32_16x16x32_bf16 v[104:107], v[198:201], v[224:227], v[104:107]
	v_mfma_f32_16x16x32_bf16 v[96:99], v[206:209], v[224:227], v[96:99]
	v_mfma_f32_16x16x32_bf16 v[88:91], v[198:201], v[232:235], v[88:91]
	v_mfma_f32_16x16x32_bf16 v[80:83], v[206:209], v[232:235], v[80:83]
	v_mfma_f32_16x16x32_bf16 v[72:75], v[198:201], v[240:243], v[72:75]
	v_mfma_f32_16x16x32_bf16 v[64:67], v[206:209], v[240:243], v[64:67]
	s_setprio 0
	s_barrier
	s_mov_b32 m0, s61
	v_lshl_add_u64 v[244:245], v[214:215], 0, v[138:139]
	ds_read_b128 v[210:213], v179 offset:16384
	ds_read_b128 v[216:219], v179 offset:17408
	ds_read_b128 v[220:223], v179 offset:18432
	ds_read_b128 v[224:227], v179 offset:19456
	ds_read_b128 v[228:231], v179 offset:20480
	ds_read_b128 v[232:235], v179 offset:21504
	ds_read_b128 v[236:239], v179 offset:22528
	ds_read_b128 v[240:243], v179 offset:23552
	global_load_lds_dwordx4 v[244:245], off
	v_lshl_add_u64 v[246:247], v[214:215], 0, v[134:135]
	s_mov_b32 m0, s62
	v_lshl_add_u64 v[214:215], v[214:215], 0, s[14:15]
	global_load_lds_dwordx4 v[246:247], off
	v_lshl_add_u64 v[248:249], v[214:215], 0, v[138:139]
	s_mov_b32 m0, s63
	v_lshl_add_u64 v[214:215], v[214:215], 0, v[134:135]
	global_load_lds_dwordx4 v[248:249], off
	s_add_i32 m0, s63, 0x2000
	v_lshl_add_u64 v[250:251], v[172:173], 0, v[140:141]
	global_load_lds_dwordx4 v[214:215], off
	s_mov_b32 m0, s46
	v_lshl_add_u64 v[252:253], v[172:173], 0, v[136:137]
	global_load_lds_dwordx4 v[250:251], off
	s_mov_b32 m0, s47
	s_nop 0
	global_load_lds_dwordx4 v[252:253], off
	s_waitcnt vmcnt(8)
	s_waitcnt lgkmcnt(0)
	s_barrier
; #define PG8_STAGE(bufoff, gbase, voff) do { _Pragma("unroll") for (int _i = 0; _i < 2; ++_i) \
;         __builtin_amdgcn_global_load_lds((const unsigned*)((const char*)(gbase) + (voff)[_i]), (PG8_LAS unsigned*)(lds + (bufoff) + ldsw + _i * 8192), 16, 0, 0); } while (0)
; #define PG8_LDA(dst, b, h) do { _Pragma("unroll") for (int m = 0; m < 4; ++m) _Pragma("unroll") for (int k = 0; k < 2; ++k) dst[m][k] = *(const PG8_LAS bf16x8*)(lds + PG8_SA(b, h) + aoff + m * 2048 + k * 1024); } while (0)
; #define PG8_LDB(dst, b, h) do { _Pragma("unroll") for (int n = 0; n < 2; ++n) _Pragma("unroll") for (int k = 0; k < 2; ++k) dst[n][k] = *(const PG8_LAS bf16x8*)(lds + PG8_SB(b, h) + boff + n * 2048 + k * 1024); } while (0)
; #define PG8_MMA(ai, bj, At, Bt) do { __builtin_amdgcn_s_setprio(1); _Pragma("unroll") for (int m = 0; m < 4; ++m) _Pragma("unroll") for (int n = 0; n < 2; ++n) _Pragma("unroll") for (int k = 0; k < 2; ++k) \
;         acc[ai][bj][m][n] = __builtin_amdgcn_mfma_f32_16x16x32_bf16(Bt[n][k], At[m][k], acc[ai][bj][m][n], 0, 0, 0); __builtin_amdgcn_s_setprio(0); } while (0)
; #define PG8_WAIT_V(n) asm volatile("s_waitcnt vmcnt(" #n ")" ::: "memory")
; #define PG8_WAIT_L(n) asm volatile("s_waitcnt lgkmcnt(" #n ")" ::: "memory")
; #define PG8_BAR __builtin_amdgcn_s_barrier()
; #define PG8_SCHED __builtin_amdgcn_sched_barrier(0)
; template <class Epi, class Sched, bool ALIGN_EPI = false, bool SP2 = false>
; __device__ __forceinline__ void gemm_phase(PG8_LAS unsigned char* lds, const Gemm g, const Sched& S, const Epi& E) {
;     ...
;             PG8_WAIT_V(8); PG8_WAIT_L(0); PG8_BAR; PG8_MMA(1, 0, At, B0); PG8_MMA(1, 1, At, B1); PG8_BAR; PG8_SCHED;
;             PG8_LDB(B0, 1, 0); PG8_LDB(B1, 1, 1); PG8_SCHED; PG8_LDA(At, 1, 0); PG8_STAGE(PG8_SA(0, 1), a2 + hstep, voffA);
;             PG8_WAIT_V(8); PG8_WAIT_L(0); PG8_BAR; PG8_MMA(0, 0, At, B0); PG8_MMA(0, 1, At, B1); PG8_BAR; PG8_SCHED;
	s_setprio 1
	s_waitcnt lgkmcnt(0)
	v_mfma_f32_16x16x32_bf16 v[60:63], v[162:165], v[210:213], v[60:63]
	v_mfma_f32_16x16x32_bf16 v[52:55], v[186:189], v[210:213], v[52:55]
	v_mfma_f32_16x16x32_bf16 v[44:47], v[162:165], v[220:223], v[44:47]
	v_mfma_f32_16x16x32_bf16 v[36:39], v[186:189], v[220:223], v[36:39]
	v_mfma_f32_16x16x32_bf16 v[28:31], v[162:165], v[228:231], v[28:31]
	v_mfma_f32_16x16x32_bf16 v[20:23], v[186:189], v[228:231], v[20:23]
	v_mfma_f32_16x16x32_bf16 v[12:15], v[162:165], v[236:239], v[12:15]
	v_mfma_f32_16x16x32_bf16 v[4:7], v[186:189], v[236:239], v[4:7]
	v_mfma_f32_16x16x32_bf16 v[60:63], v[182:185], v[216:219], v[60:63]
	v_mfma_f32_16x16x32_bf16 v[52:55], v[190:193], v[216:219], v[52:55]
	v_mfma_f32_16x16x32_bf16 v[44:47], v[182:185], v[224:227], v[44:47]
	v_mfma_f32_16x16x32_bf16 v[36:39], v[190:193], v[224:227], v[36:39]
	v_mfma_f32_16x16x32_bf16 v[28:31], v[182:185], v[232:235], v[28:31]
	v_mfma_f32_16x16x32_bf16 v[20:23], v[190:193], v[232:235], v[20:23]
	v_mfma_f32_16x16x32_bf16 v[12:15], v[182:185], v[240:243], v[12:15]
	v_mfma_f32_16x16x32_bf16 v[4:7], v[190:193], v[240:243], v[4:7]
	v_mfma_f32_16x16x32_bf16 v[56:59], v[194:197], v[210:213], v[56:59]
	v_mfma_f32_16x16x32_bf16 v[48:51], v[202:205], v[210:213], v[48:51]
	v_mfma_f32_16x16x32_bf16 v[40:43], v[194:197], v[220:223], v[40:43]
	v_mfma_f32_16x16x32_bf16 v[32:35], v[202:205], v[220:223], v[32:35]
	v_mfma_f32_16x16x32_bf16 v[24:27], v[194:197], v[228:231], v[24:27]
	v_mfma_f32_16x16x32_bf16 v[16:19], v[202:205], v[228:231], v[16:19]
	v_mfma_f32_16x16x32_bf16 v[8:11], v[194:197], v[236:239], v[8:11]
	v_mfma_f32_16x16x32_bf16 v[0:3], v[202:205], v[236:239], v[0:3]
	v_mfma_f32_16x16x32_bf16 v[56:59], v[198:201], v[216:219], v[56:59]
	v_mfma_f32_16x16x32_bf16 v[48:51], v[206:209], v[216:219], v[48:51]
	v_mfma_f32_16x16x32_bf16 v[40:43], v[198:201], v[224:227], v[40:43]
	v_mfma_f32_16x16x32_bf16 v[32:35], v[206:209], v[224:227], v[32:35]
	v_mfma_f32_16x16x32_bf16 v[24:27], v[198:201], v[232:235], v[24:27]
	v_mfma_f32_16x16x32_bf16 v[16:19], v[206:209], v[232:235], v[16:19]
	v_mfma_f32_16x16x32_bf16 v[8:11], v[198:201], v[240:243], v[8:11]
	v_mfma_f32_16x16x32_bf16 v[0:3], v[206:209], v[240:243], v[0:3]
	s_setprio 0
	s_barrier
	s_add_i32 s11, 0, 0x18000
	v_add_u32_e32 v166, s11, v169
	s_add_i32 s13, 0, 0x1c000
	ds_read_b128 v[162:165], v166
	ds_read_b128 v[182:185], v166 offset:1024
	ds_read_b128 v[186:189], v166 offset:2048
	ds_read_b128 v[190:193], v166 offset:3072
	v_add_u32_e32 v166, s13, v169
	ds_read_b128 v[194:197], v166
	ds_read_b128 v[198:201], v166 offset:1024
	ds_read_b128 v[202:205], v166 offset:2048
	ds_read_b128 v[206:209], v166 offset:3072
	v_lshl_add_u64 v[172:173], v[172:173], 0, s[14:15]
	s_mov_b32 m0, s48
	v_lshl_add_u64 v[170:171], v[172:173], 0, v[140:141]
	ds_read_b128 v[210:213], v179 offset:32768
	ds_read_b128 v[216:219], v179 offset:33792
	ds_read_b128 v[220:223], v179 offset:34816
	ds_read_b128 v[224:227], v179 offset:35840
	ds_read_b128 v[228:231], v179 offset:36864
	ds_read_b128 v[232:235], v179 offset:37888
	ds_read_b128 v[236:239], v179 offset:38912
	ds_read_b128 v[240:243], v179 offset:39936
	global_load_lds_dwordx4 v[170:171], off
	v_lshl_add_u64 v[170:171], v[172:173], 0, v[136:137]
	s_mov_b32 m0, s49
	s_nop 0
	global_load_lds_dwordx4 v[170:171], off
	s_waitcnt vmcnt(8)
	s_waitcnt lgkmcnt(0)
	s_barrier
	s_setprio 1
	s_waitcnt lgkmcnt(0)
	v_mfma_f32_16x16x32_bf16 v[124:127], v[162:165], v[210:213], v[124:127]
	v_mfma_f32_16x16x32_bf16 v[116:119], v[186:189], v[210:213], v[116:119]
	v_mfma_f32_16x16x32_bf16 v[108:111], v[162:165], v[220:223], v[108:111]
	v_mfma_f32_16x16x32_bf16 v[100:103], v[186:189], v[220:223], v[100:103]
	v_mfma_f32_16x16x32_bf16 v[92:95], v[162:165], v[228:231], v[92:95]
	v_mfma_f32_16x16x32_bf16 v[84:87], v[186:189], v[228:231], v[84:87]
	v_mfma_f32_16x16x32_bf16 v[76:79], v[162:165], v[236:239], v[76:79]
	v_mfma_f32_16x16x32_bf16 v[68:71], v[186:189], v[236:239], v[68:71]
	v_mfma_f32_16x16x32_bf16 v[124:127], v[182:185], v[216:219], v[124:127]
	v_mfma_f32_16x16x32_bf16 v[116:119], v[190:193], v[216:219], v[116:119]
	v_mfma_f32_16x16x32_bf16 v[108:111], v[182:185], v[224:227], v[108:111]
	v_mfma_f32_16x16x32_bf16 v[100:103], v[190:193], v[224:227], v[100:103]
	v_mfma_f32_16x16x32_bf16 v[92:95], v[182:185], v[232:235], v[92:95]
	v_mfma_f32_16x16x32_bf16 v[84:87], v[190:193], v[232:235], v[84:87]
	v_mfma_f32_16x16x32_bf16 v[76:79], v[182:185], v[240:243], v[76:79]
	v_mfma_f32_16x16x32_bf16 v[68:71], v[190:193], v[240:243], v[68:71]
	v_mfma_f32_16x16x32_bf16 v[120:123], v[194:197], v[210:213], v[120:123]
	v_mfma_f32_16x16x32_bf16 v[112:115], v[202:205], v[210:213], v[112:115]
	v_mfma_f32_16x16x32_bf16 v[104:107], v[194:197], v[220:223], v[104:107]
	v_mfma_f32_16x16x32_bf16 v[96:99], v[202:205], v[220:223], v[96:99]
	v_mfma_f32_16x16x32_bf16 v[88:91], v[194:197], v[228:231], v[88:91]
	v_mfma_f32_16x16x32_bf16 v[80:83], v[202:205], v[228:231], v[80:83]
	v_mfma_f32_16x16x32_bf16 v[72:75], v[194:197], v[236:239], v[72:75]
	v_mfma_f32_16x16x32_bf16 v[64:67], v[202:205], v[236:239], v[64:67]
	v_mfma_f32_16x16x32_bf16 v[120:123], v[198:201], v[216:219], v[120:123]
	v_mfma_f32_16x16x32_bf16 v[112:115], v[206:209], v[216:219], v[112:115]
	v_mfma_f32_16x16x32_bf16 v[104:107], v[198:201], v[224:227], v[104:107]
	v_mfma_f32_16x16x32_bf16 v[96:99], v[206:209], v[224:227], v[96:99]
	v_mfma_f32_16x16x32_bf16 v[88:91], v[198:201], v[232:235], v[88:91]
	v_mfma_f32_16x16x32_bf16 v[80:83], v[206:209], v[232:235], v[80:83]
	v_mfma_f32_16x16x32_bf16 v[72:75], v[198:201], v[240:243], v[72:75]
	v_mfma_f32_16x16x32_bf16 v[64:67], v[206:209], v[240:243], v[64:67]
	s_setprio 0
	s_barrier
; #define PG8_STAGE(bufoff, gbase, voff) do { _Pragma("unroll") for (int _i = 0; _i < 2; ++_i) \
;         __builtin_amdgcn_global_load_lds((const unsigned*)((const char*)(gbase) + (voff)[_i]), (PG8_LAS unsigned*)(lds + (bufoff) + ldsw + _i * 8192), 16, 0, 0); } while (0)
; #define PG8_LDA(dst, b, h) do { _Pragma("unroll") for (int m = 0; m < 4; ++m) _Pragma("unroll") for (int k = 0; k < 2; ++k) dst[m][k] = *(const PG8_LAS bf16x8*)(lds + PG8_SA(b, h) + aoff + m * 2048 + k * 1024); } while (0)
; #define PG8_MMA(ai, bj, At, Bt) do { __builtin_amdgcn_s_setprio(1); _Pragma("unroll") for (int m = 0; m < 4; ++m) _Pragma("unroll") for (int n = 0; n < 2; ++n) _Pragma("unroll") for (int k = 0; k < 2; ++k) \
;         acc[ai][bj][m][n] = __builtin_amdgcn_mfma_f32_16x16x32_bf16(Bt[n][k], At[m][k], acc[ai][bj][m][n], 0, 0, 0); __builtin_amdgcn_s_setprio(0); } while (0)
; #define PG8_WAIT_V(n) asm volatile("s_waitcnt vmcnt(" #n ")" ::: "memory")
; #define PG8_WAIT_L(n) asm volatile("s_waitcnt lgkmcnt(" #n ")" ::: "memory")
; #define PG8_BAR __builtin_amdgcn_s_barrier()
; #define PG8_SCHED __builtin_amdgcn_sched_barrier(0)
; template <class Epi, class Sched, bool ALIGN_EPI = false, bool SP2 = false>
; __device__ __forceinline__ void gemm_phase(PG8_LAS unsigned char* lds, const Gemm g, const Sched& S, const Epi& E) {
;     ...
;             PG8_LDA(At, 1, 1); PG8_STAGE(PG8_SB(1, 0), b3, voffB); PG8_STAGE(PG8_SB(1, 1), b3 + hstep, voffB); PG8_STAGE(PG8_SA(1, 0), a3, voffA);
;             PG8_WAIT_V(8); PG8_WAIT_L(0); PG8_BAR; PG8_MMA(1, 0, At, B0); PG8_MMA(1, 1, At, B1); PG8_BAR; PG8_SCHED;
	s_add_i32 s11, s11, s29
	v_lshl_add_u64 v[170:171], v[244:245], 0, s[22:23]
	s_mov_b32 m0, s11
	ds_read_b128 v[210:213], v179 offset:49152
	ds_read_b128 v[216:219], v179 offset:50176
	ds_read_b128 v[220:223], v179 offset:51200
	ds_read_b128 v[224:227], v179 offset:52224
	ds_read_b128 v[228:231], v179 offset:53248
	ds_read_b128 v[232:235], v179 offset:54272
	ds_read_b128 v[236:239], v179 offset:55296
	ds_read_b128 v[240:243], v179 offset:56320
	global_load_lds_dwordx4 v[170:171], off
	v_lshl_add_u64 v[170:171], v[246:247], 0, s[22:23]
	s_add_i32 m0, s11, 0x2000
	s_add_i32 s11, s13, s29
	global_load_lds_dwordx4 v[170:171], off
	v_lshl_add_u64 v[170:171], v[248:249], 0, s[22:23]
	s_mov_b32 m0, s11
	s_nop 0
	global_load_lds_dwordx4 v[170:171], off
	v_lshl_add_u64 v[170:171], v[214:215], 0, s[22:23]
	s_add_i32 m0, s11, 0x2000
	s_nop 0
	global_load_lds_dwordx4 v[170:171], off
	v_lshl_add_u64 v[170:171], v[250:251], 0, s[22:23]
	s_mov_b32 m0, s50
	s_nop 0
	global_load_lds_dwordx4 v[170:171], off
	v_lshl_add_u64 v[170:171], v[252:253], 0, s[22:23]
	s_mov_b32 m0, s51
	s_nop 0
	global_load_lds_dwordx4 v[170:171], off
	s_waitcnt vmcnt(8)
	s_waitcnt lgkmcnt(0)
	s_barrier
	s_setprio 1
	s_waitcnt lgkmcnt(0)
	v_mfma_f32_16x16x32_bf16 v[60:63], v[162:165], v[210:213], v[60:63]
	v_mfma_f32_16x16x32_bf16 v[52:55], v[186:189], v[210:213], v[52:55]
	v_mfma_f32_16x16x32_bf16 v[44:47], v[162:165], v[220:223], v[44:47]
	v_mfma_f32_16x16x32_bf16 v[36:39], v[186:189], v[220:223], v[36:39]
	v_mfma_f32_16x16x32_bf16 v[28:31], v[162:165], v[228:231], v[28:31]
	v_mfma_f32_16x16x32_bf16 v[20:23], v[186:189], v[228:231], v[20:23]
	v_mfma_f32_16x16x32_bf16 v[12:15], v[162:165], v[236:239], v[12:15]
	v_mfma_f32_16x16x32_bf16 v[4:7], v[186:189], v[236:239], v[4:7]
	v_mfma_f32_16x16x32_bf16 v[60:63], v[182:185], v[216:219], v[60:63]
	v_mfma_f32_16x16x32_bf16 v[52:55], v[190:193], v[216:219], v[52:55]
	v_mfma_f32_16x16x32_bf16 v[44:47], v[182:185], v[224:227], v[44:47]
	v_mfma_f32_16x16x32_bf16 v[36:39], v[190:193], v[224:227], v[36:39]
	v_mfma_f32_16x16x32_bf16 v[28:31], v[182:185], v[232:235], v[28:31]
	v_mfma_f32_16x16x32_bf16 v[20:23], v[190:193], v[232:235], v[20:23]
	v_mfma_f32_16x16x32_bf16 v[12:15], v[182:185], v[240:243], v[12:15]
	v_mfma_f32_16x16x32_bf16 v[4:7], v[190:193], v[240:243], v[4:7]
	v_mfma_f32_16x16x32_bf16 v[56:59], v[194:197], v[210:213], v[56:59]
	v_mfma_f32_16x16x32_bf16 v[48:51], v[202:205], v[210:213], v[48:51]
	v_mfma_f32_16x16x32_bf16 v[40:43], v[194:197], v[220:223], v[40:43]
	v_mfma_f32_16x16x32_bf16 v[32:35], v[202:205], v[220:223], v[32:35]
	v_mfma_f32_16x16x32_bf16 v[24:27], v[194:197], v[228:231], v[24:27]
	v_mfma_f32_16x16x32_bf16 v[16:19], v[202:205], v[228:231], v[16:19]
	v_mfma_f32_16x16x32_bf16 v[8:11], v[194:197], v[236:239], v[8:11]
	v_mfma_f32_16x16x32_bf16 v[0:3], v[202:205], v[236:239], v[0:3]
	v_mfma_f32_16x16x32_bf16 v[56:59], v[198:201], v[216:219], v[56:59]
	v_mfma_f32_16x16x32_bf16 v[48:51], v[206:209], v[216:219], v[48:51]
	v_mfma_f32_16x16x32_bf16 v[40:43], v[198:201], v[224:227], v[40:43]
	v_mfma_f32_16x16x32_bf16 v[32:35], v[206:209], v[224:227], v[32:35]
	v_mfma_f32_16x16x32_bf16 v[24:27], v[198:201], v[232:235], v[24:27]
	v_mfma_f32_16x16x32_bf16 v[16:19], v[206:209], v[232:235], v[16:19]
	v_mfma_f32_16x16x32_bf16 v[8:11], v[198:201], v[240:243], v[8:11]
	v_mfma_f32_16x16x32_bf16 v[0:3], v[206:209], v[240:243], v[0:3]
	s_setprio 0
	s_barrier
	v_lshl_add_u64 v[158:159], v[158:159], 0, s[26:27]
	s_cmp_ge_i32 s10, s52
	v_lshl_add_u64 v[160:161], v[160:161], 0, s[26:27]
	s_cbranch_scc0 .LBB0_1021

; #define PG8_STAGE(bufoff, gbase, voff) do { _Pragma("unroll") for (int _i = 0; _i < 2; ++_i) \
;         __builtin_amdgcn_global_load_lds((const unsigned*)((const char*)(gbase) + (voff)[_i]), (PG8_LAS unsigned*)(lds + (bufoff) + ldsw + _i * 8192), 16, 0, 0); } while (0)
; #define PG8_LDA(dst, b, h) do { _Pragma("unroll") for (int m = 0; m < 4; ++m) _Pragma("unroll") for (int k = 0; k < 2; ++k) dst[m][k] = *(const PG8_LAS bf16x8*)(lds + PG8_SA(b, h) + aoff + m * 2048 + k * 1024); } while (0)
; #define PG8_LDB(dst, b, h) do { _Pragma("unroll") for (int n = 0; n < 2; ++n) _Pragma("unroll") for (int k = 0; k < 2; ++k) dst[n][k] = *(const PG8_LAS bf16x8*)(lds + PG8_SB(b, h) + boff + n * 2048 + k * 1024); } while (0)
; #define PG8_MMA(ai, bj, At, Bt) do { __builtin_amdgcn_s_setprio(1); _Pragma("unroll") for (int m = 0; m < 4; ++m) _Pragma("unroll") for (int n = 0; n < 2; ++n) _Pragma("unroll") for (int k = 0; k < 2; ++k) \
;         acc[ai][bj][m][n] = __builtin_amdgcn_mfma_f32_16x16x32_bf16(Bt[n][k], At[m][k], acc[ai][bj][m][n], 0, 0, 0); __builtin_amdgcn_s_setprio(0); } while (0)
; #define PG8_WAIT_V(n) asm volatile("s_waitcnt vmcnt(" #n ")" ::: "memory")
; #define PG8_WAIT_L(n) asm volatile("s_waitcnt lgkmcnt(" #n ")" ::: "memory")
; #define PG8_BAR __builtin_amdgcn_s_barrier()
; #define PG8_SCHED __builtin_amdgcn_sched_barrier(0)
; template <class Epi, class Sched, bool ALIGN_EPI = false, bool SP2 = false>
; __device__ __forceinline__ void gemm_phase(PG8_LAS unsigned char* lds, const Gemm g, const Sched& S, const Epi& E) {
;     ...
;         for (int t = 0; t < nt; t += 2) {
;             const bool last = (t == nt - 2);
;             const char* a1 = cA + (size_t)(t + 1) * kstep;
;             const char* a2 = last ? nA : cA + (size_t)(t + 2) * kstep; const char* b2 = last ? nB : cB + (size_t)(t + 2) * kstep;
;             const char* a3 = a2 + kstep; const char* b3 = b2 + kstep;
;             if (last && has_next) S.a_ready(nxt);
;             if constexpr (SP2) {
;             PG8_LDB(B0, 0, 0); PG8_LDB(B1, 0, 1); PG8_SCHED; PG8_LDA(At, 0, 0); PG8_STAGE(PG8_SA(1, 1), a1 + hstep, voffA);
;             PG8_WAIT_V(8); PG8_WAIT_L(0); PG8_BAR; PG8_MMA(0, 0, At, B0); PG8_MMA(0, 1, At, B1); PG8_BAR; PG8_SCHED;
;             PG8_LDA(At, 0, 1); PG8_STAGE(PG8_SB(0, 0), b2, voffB); PG8_STAGE(PG8_SB(0, 1), b2 + hstep, voffB); PG8_STAGE(PG8_SA(0, 0), a2, voffA);
.LBB0_1169:
	v_add_u32_e32 v192, s52, v161
	ds_read_b128 v[164:167], v162
	ds_read_b128 v[168:171], v162 offset:1024
	ds_read_b128 v[172:175], v162 offset:2048
	ds_read_b128 v[176:179], v162 offset:3072
	ds_read_b128 v[180:183], v192
	ds_read_b128 v[184:187], v192 offset:1024
	ds_read_b128 v[188:191], v192 offset:2048
	ds_read_b128 v[192:195], v192 offset:3072
	s_cmp_eq_u32 s51, s10
	v_lshl_add_u64 v[196:197], v[158:159], 0, s[24:25]
	s_cselect_b64 vcc, -1, 0
	s_add_i32 s10, s10, 2
	v_cndmask_b32_e32 v213, v197, v151, vcc
	v_cndmask_b32_e32 v212, v196, v150, vcc
	v_cndmask_b32_e32 v215, v155, v153, vcc
	v_cndmask_b32_e32 v214, v154, v152, vcc
	s_mov_b32 m0, s54
	v_lshl_add_u64 v[232:233], v[158:159], 0, v[146:147]
	ds_read_b128 v[196:199], v163
	ds_read_b128 v[200:203], v163 offset:1024
	ds_read_b128 v[204:207], v163 offset:2048
	ds_read_b128 v[208:211], v163 offset:3072
	ds_read_b128 v[216:219], v163 offset:4096
	ds_read_b128 v[220:223], v163 offset:5120
	ds_read_b128 v[224:227], v163 offset:6144
	ds_read_b128 v[228:231], v163 offset:7168
	global_load_lds_dwordx4 v[232:233], off
	v_lshl_add_u64 v[232:233], v[158:159], 0, v[144:145]
	s_mov_b32 m0, s55
	s_nop 0
	global_load_lds_dwordx4 v[232:233], off
	s_waitcnt vmcnt(8)
	s_waitcnt lgkmcnt(0)
	s_barrier
	s_setprio 1
	s_waitcnt lgkmcnt(0)
	v_mfma_f32_16x16x32_bf16 v[124:127], v[164:167], v[196:199], v[124:127]
	v_mfma_f32_16x16x32_bf16 v[120:123], v[172:175], v[196:199], v[120:123]
	v_mfma_f32_16x16x32_bf16 v[108:111], v[164:167], v[204:207], v[108:111]
	v_mfma_f32_16x16x32_bf16 v[104:107], v[172:175], v[204:207], v[104:107]
	v_mfma_f32_16x16x32_bf16 v[92:95], v[164:167], v[216:219], v[92:95]
	v_mfma_f32_16x16x32_bf16 v[88:91], v[172:175], v[216:219], v[88:91]
	v_mfma_f32_16x16x32_bf16 v[76:79], v[164:167], v[224:227], v[76:79]
	v_mfma_f32_16x16x32_bf16 v[72:75], v[172:175], v[224:227], v[72:75]
	v_mfma_f32_16x16x32_bf16 v[124:127], v[168:171], v[200:203], v[124:127]
	v_mfma_f32_16x16x32_bf16 v[120:123], v[176:179], v[200:203], v[120:123]
	v_mfma_f32_16x16x32_bf16 v[108:111], v[168:171], v[208:211], v[108:111]
	v_mfma_f32_16x16x32_bf16 v[104:107], v[176:179], v[208:211], v[104:107]
	v_mfma_f32_16x16x32_bf16 v[92:95], v[168:171], v[220:223], v[92:95]
	v_mfma_f32_16x16x32_bf16 v[88:91], v[176:179], v[220:223], v[88:91]
	v_mfma_f32_16x16x32_bf16 v[76:79], v[168:171], v[228:231], v[76:79]
	v_mfma_f32_16x16x32_bf16 v[72:75], v[176:179], v[228:231], v[72:75]
	v_mfma_f32_16x16x32_bf16 v[116:119], v[180:183], v[196:199], v[116:119]
	v_mfma_f32_16x16x32_bf16 v[112:115], v[188:191], v[196:199], v[112:115]
	v_mfma_f32_16x16x32_bf16 v[100:103], v[180:183], v[204:207], v[100:103]
	v_mfma_f32_16x16x32_bf16 v[96:99], v[188:191], v[204:207], v[96:99]
	v_mfma_f32_16x16x32_bf16 v[84:87], v[180:183], v[216:219], v[84:87]
	v_mfma_f32_16x16x32_bf16 v[80:83], v[188:191], v[216:219], v[80:83]
	v_mfma_f32_16x16x32_bf16 v[68:71], v[180:183], v[224:227], v[68:71]
	v_mfma_f32_16x16x32_bf16 v[64:67], v[188:191], v[224:227], v[64:67]
	v_mfma_f32_16x16x32_bf16 v[116:119], v[184:187], v[200:203], v[116:119]
	v_mfma_f32_16x16x32_bf16 v[112:115], v[192:195], v[200:203], v[112:115]
	v_mfma_f32_16x16x32_bf16 v[100:103], v[184:187], v[208:211], v[100:103]
	v_mfma_f32_16x16x32_bf16 v[96:99], v[192:195], v[208:211], v[96:99]
	v_mfma_f32_16x16x32_bf16 v[84:87], v[184:187], v[220:223], v[84:87]
	v_mfma_f32_16x16x32_bf16 v[80:83], v[192:195], v[220:223], v[80:83]
	v_mfma_f32_16x16x32_bf16 v[68:71], v[184:187], v[228:231], v[68:71]
	v_mfma_f32_16x16x32_bf16 v[64:67], v[192:195], v[228:231], v[64:67]
	s_setprio 0
	s_barrier
	s_mov_b32 m0, s56
	v_lshl_add_u64 v[232:233], v[214:215], 0, v[138:139]
	ds_read_b128 v[196:199], v163 offset:16384
	ds_read_b128 v[200:203], v163 offset:17408
	ds_read_b128 v[204:207], v163 offset:18432
	ds_read_b128 v[208:211], v163 offset:19456
	ds_read_b128 v[216:219], v163 offset:20480
	ds_read_b128 v[220:223], v163 offset:21504
	ds_read_b128 v[224:227], v163 offset:22528
	ds_read_b128 v[228:231], v163 offset:23552
	global_load_lds_dwordx4 v[232:233], off
	v_lshl_add_u64 v[234:235], v[214:215], 0, v[134:135]
	s_mov_b32 m0, s57
	v_lshl_add_u64 v[214:215], v[214:215], 0, s[14:15]
	global_load_lds_dwordx4 v[234:235], off
	v_lshl_add_u64 v[236:237], v[214:215], 0, v[138:139]
	s_mov_b32 m0, s58
	v_lshl_add_u64 v[214:215], v[214:215], 0, v[134:135]
	global_load_lds_dwordx4 v[236:237], off
	s_mov_b32 m0, s59
	v_lshl_add_u64 v[238:239], v[212:213], 0, v[140:141]
	global_load_lds_dwordx4 v[214:215], off
	s_mov_b32 m0, s37
	v_lshl_add_u64 v[240:241], v[212:213], 0, v[136:137]
	global_load_lds_dwordx4 v[238:239], off
	s_mov_b32 m0, s41
	s_nop 0
	global_load_lds_dwordx4 v[240:241], off
	s_waitcnt vmcnt(8)
	s_waitcnt lgkmcnt(0)
	s_barrier
; #define PG8_STAGE(bufoff, gbase, voff) do { _Pragma("unroll") for (int _i = 0; _i < 2; ++_i) \
;         __builtin_amdgcn_global_load_lds((const unsigned*)((const char*)(gbase) + (voff)[_i]), (PG8_LAS unsigned*)(lds + (bufoff) + ldsw + _i * 8192), 16, 0, 0); } while (0)
; #define PG8_LDA(dst, b, h) do { _Pragma("unroll") for (int m = 0; m < 4; ++m) _Pragma("unroll") for (int k = 0; k < 2; ++k) dst[m][k] = *(const PG8_LAS bf16x8*)(lds + PG8_SA(b, h) + aoff + m * 2048 + k * 1024); } while (0)
; #define PG8_LDB(dst, b, h) do { _Pragma("unroll") for (int n = 0; n < 2; ++n) _Pragma("unroll") for (int k = 0; k < 2; ++k) dst[n][k] = *(const PG8_LAS bf16x8*)(lds + PG8_SB(b, h) + boff + n * 2048 + k * 1024); } while (0)
; #define PG8_MMA(ai, bj, At, Bt) do { __builtin_amdgcn_s_setprio(1); _Pragma("unroll") for (int m = 0; m < 4; ++m) _Pragma("unroll") for (int n = 0; n < 2; ++n) _Pragma("unroll") for (int k = 0; k < 2; ++k) \
;         acc[ai][bj][m][n] = __builtin_amdgcn_mfma_f32_16x16x32_bf16(Bt[n][k], At[m][k], acc[ai][bj][m][n], 0, 0, 0); __builtin_amdgcn_s_setprio(0); } while (0)
; #define PG8_WAIT_V(n) asm volatile("s_waitcnt vmcnt(" #n ")" ::: "memory")
; #define PG8_WAIT_L(n) asm volatile("s_waitcnt lgkmcnt(" #n ")" ::: "memory")
; #define PG8_BAR __builtin_amdgcn_s_barrier()
; #define PG8_SCHED __builtin_amdgcn_sched_barrier(0)
; template <class Epi, class Sched, bool ALIGN_EPI = false, bool SP2 = false>
; __device__ __forceinline__ void gemm_phase(PG8_LAS unsigned char* lds, const Gemm g, const Sched& S, const Epi& E) {
;     ...
;             PG8_WAIT_V(8); PG8_WAIT_L(0); PG8_BAR; PG8_MMA(1, 0, At, B0); PG8_MMA(1, 1, At, B1); PG8_BAR; PG8_SCHED;
;             PG8_LDB(B0, 1, 0); PG8_LDB(B1, 1, 1); PG8_SCHED; PG8_LDA(At, 1, 0); PG8_STAGE(PG8_SA(0, 1), a2 + hstep, voffA);
;             PG8_WAIT_V(8); PG8_WAIT_L(0); PG8_BAR; PG8_MMA(0, 0, At, B0); PG8_MMA(0, 1, At, B1); PG8_BAR; PG8_SCHED;
	s_setprio 1
	s_waitcnt lgkmcnt(0)
	v_mfma_f32_16x16x32_bf16 v[60:63], v[164:167], v[196:199], v[60:63]
	v_mfma_f32_16x16x32_bf16 v[56:59], v[172:175], v[196:199], v[56:59]
	v_mfma_f32_16x16x32_bf16 v[44:47], v[164:167], v[204:207], v[44:47]
	v_mfma_f32_16x16x32_bf16 v[40:43], v[172:175], v[204:207], v[40:43]
	v_mfma_f32_16x16x32_bf16 v[28:31], v[164:167], v[216:219], v[28:31]
	v_mfma_f32_16x16x32_bf16 v[24:27], v[172:175], v[216:219], v[24:27]
	v_mfma_f32_16x16x32_bf16 v[12:15], v[164:167], v[224:227], v[12:15]
	v_mfma_f32_16x16x32_bf16 v[8:11], v[172:175], v[224:227], v[8:11]
	v_mfma_f32_16x16x32_bf16 v[60:63], v[168:171], v[200:203], v[60:63]
	v_mfma_f32_16x16x32_bf16 v[56:59], v[176:179], v[200:203], v[56:59]
	v_mfma_f32_16x16x32_bf16 v[44:47], v[168:171], v[208:211], v[44:47]
	v_mfma_f32_16x16x32_bf16 v[40:43], v[176:179], v[208:211], v[40:43]
	v_mfma_f32_16x16x32_bf16 v[28:31], v[168:171], v[220:223], v[28:31]
	v_mfma_f32_16x16x32_bf16 v[24:27], v[176:179], v[220:223], v[24:27]
	v_mfma_f32_16x16x32_bf16 v[12:15], v[168:171], v[228:231], v[12:15]
	v_mfma_f32_16x16x32_bf16 v[8:11], v[176:179], v[228:231], v[8:11]
	v_mfma_f32_16x16x32_bf16 v[52:55], v[180:183], v[196:199], v[52:55]
	v_mfma_f32_16x16x32_bf16 v[48:51], v[188:191], v[196:199], v[48:51]
	v_mfma_f32_16x16x32_bf16 v[36:39], v[180:183], v[204:207], v[36:39]
	v_mfma_f32_16x16x32_bf16 v[32:35], v[188:191], v[204:207], v[32:35]
	v_mfma_f32_16x16x32_bf16 v[20:23], v[180:183], v[216:219], v[20:23]
	v_mfma_f32_16x16x32_bf16 v[16:19], v[188:191], v[216:219], v[16:19]
	v_mfma_f32_16x16x32_bf16 v[4:7], v[180:183], v[224:227], v[4:7]
	v_mfma_f32_16x16x32_bf16 v[0:3], v[188:191], v[224:227], v[0:3]
	v_mfma_f32_16x16x32_bf16 v[52:55], v[184:187], v[200:203], v[52:55]
	v_mfma_f32_16x16x32_bf16 v[48:51], v[192:195], v[200:203], v[48:51]
	v_mfma_f32_16x16x32_bf16 v[36:39], v[184:187], v[208:211], v[36:39]
	v_mfma_f32_16x16x32_bf16 v[32:35], v[192:195], v[208:211], v[32:35]
	v_mfma_f32_16x16x32_bf16 v[20:23], v[184:187], v[220:223], v[20:23]
	v_mfma_f32_16x16x32_bf16 v[16:19], v[192:195], v[220:223], v[16:19]
	v_mfma_f32_16x16x32_bf16 v[4:7], v[184:187], v[228:231], v[4:7]
	v_mfma_f32_16x16x32_bf16 v[0:3], v[192:195], v[228:231], v[0:3]
	s_setprio 0
	s_barrier
	v_add_u32_e32 v176, s60, v161
	v_add_u32_e32 v192, s61, v161
	ds_read_b128 v[164:167], v176
	ds_read_b128 v[168:171], v176 offset:1024
	ds_read_b128 v[172:175], v176 offset:2048
	ds_read_b128 v[176:179], v176 offset:3072
	ds_read_b128 v[180:183], v192
	ds_read_b128 v[184:187], v192 offset:1024
	ds_read_b128 v[188:191], v192 offset:2048
	ds_read_b128 v[192:195], v192 offset:3072
	v_lshl_add_u64 v[212:213], v[212:213], 0, s[14:15]
	s_mov_b32 m0, s46
	v_lshl_add_u64 v[242:243], v[212:213], 0, v[140:141]
	ds_read_b128 v[196:199], v163 offset:32768
	ds_read_b128 v[200:203], v163 offset:33792
	ds_read_b128 v[204:207], v163 offset:34816
	ds_read_b128 v[208:211], v163 offset:35840
	ds_read_b128 v[216:219], v163 offset:36864
	ds_read_b128 v[220:223], v163 offset:37888
	ds_read_b128 v[224:227], v163 offset:38912
	ds_read_b128 v[228:231], v163 offset:39936
	global_load_lds_dwordx4 v[242:243], off
	v_lshl_add_u64 v[212:213], v[212:213], 0, v[136:137]
	s_mov_b32 m0, s47
	s_nop 0
	global_load_lds_dwordx4 v[212:213], off
	s_waitcnt vmcnt(8)
	s_waitcnt lgkmcnt(0)
	s_barrier
	s_setprio 1
	s_waitcnt lgkmcnt(0)
	v_mfma_f32_16x16x32_bf16 v[124:127], v[164:167], v[196:199], v[124:127]
	v_mfma_f32_16x16x32_bf16 v[120:123], v[172:175], v[196:199], v[120:123]
	v_mfma_f32_16x16x32_bf16 v[108:111], v[164:167], v[204:207], v[108:111]
	v_mfma_f32_16x16x32_bf16 v[104:107], v[172:175], v[204:207], v[104:107]
	v_mfma_f32_16x16x32_bf16 v[92:95], v[164:167], v[216:219], v[92:95]
	v_mfma_f32_16x16x32_bf16 v[88:91], v[172:175], v[216:219], v[88:91]
	v_mfma_f32_16x16x32_bf16 v[76:79], v[164:167], v[224:227], v[76:79]
	v_mfma_f32_16x16x32_bf16 v[72:75], v[172:175], v[224:227], v[72:75]
	v_mfma_f32_16x16x32_bf16 v[124:127], v[168:171], v[200:203], v[124:127]
	v_mfma_f32_16x16x32_bf16 v[120:123], v[176:179], v[200:203], v[120:123]
	v_mfma_f32_16x16x32_bf16 v[108:111], v[168:171], v[208:211], v[108:111]
	v_mfma_f32_16x16x32_bf16 v[104:107], v[176:179], v[208:211], v[104:107]
	v_mfma_f32_16x16x32_bf16 v[92:95], v[168:171], v[220:223], v[92:95]
	v_mfma_f32_16x16x32_bf16 v[88:91], v[176:179], v[220:223], v[88:91]
	v_mfma_f32_16x16x32_bf16 v[76:79], v[168:171], v[228:231], v[76:79]
	v_mfma_f32_16x16x32_bf16 v[72:75], v[176:179], v[228:231], v[72:75]
	v_mfma_f32_16x16x32_bf16 v[116:119], v[180:183], v[196:199], v[116:119]
	v_mfma_f32_16x16x32_bf16 v[112:115], v[188:191], v[196:199], v[112:115]
	v_mfma_f32_16x16x32_bf16 v[100:103], v[180:183], v[204:207], v[100:103]
	v_mfma_f32_16x16x32_bf16 v[96:99], v[188:191], v[204:207], v[96:99]
	v_mfma_f32_16x16x32_bf16 v[84:87], v[180:183], v[216:219], v[84:87]
	v_mfma_f32_16x16x32_bf16 v[80:83], v[188:191], v[216:219], v[80:83]
	v_mfma_f32_16x16x32_bf16 v[68:71], v[180:183], v[224:227], v[68:71]
	v_mfma_f32_16x16x32_bf16 v[64:67], v[188:191], v[224:227], v[64:67]
	v_mfma_f32_16x16x32_bf16 v[116:119], v[184:187], v[200:203], v[116:119]
	v_mfma_f32_16x16x32_bf16 v[112:115], v[192:195], v[200:203], v[112:115]
	v_mfma_f32_16x16x32_bf16 v[100:103], v[184:187], v[208:211], v[100:103]
	v_mfma_f32_16x16x32_bf16 v[96:99], v[192:195], v[208:211], v[96:99]
	v_mfma_f32_16x16x32_bf16 v[84:87], v[184:187], v[220:223], v[84:87]
	v_mfma_f32_16x16x32_bf16 v[80:83], v[192:195], v[220:223], v[80:83]
	v_mfma_f32_16x16x32_bf16 v[68:71], v[184:187], v[228:231], v[68:71]
	v_mfma_f32_16x16x32_bf16 v[64:67], v[192:195], v[228:231], v[64:67]
	s_setprio 0
	s_barrier
; #define PG8_STAGE(bufoff, gbase, voff) do { _Pragma("unroll") for (int _i = 0; _i < 2; ++_i) \
;         __builtin_amdgcn_global_load_lds((const unsigned*)((const char*)(gbase) + (voff)[_i]), (PG8_LAS unsigned*)(lds + (bufoff) + ldsw + _i * 8192), 16, 0, 0); } while (0)
; #define PG8_LDA(dst, b, h) do { _Pragma("unroll") for (int m = 0; m < 4; ++m) _Pragma("unroll") for (int k = 0; k < 2; ++k) dst[m][k] = *(const PG8_LAS bf16x8*)(lds + PG8_SA(b, h) + aoff + m * 2048 + k * 1024); } while (0)
; #define PG8_MMA(ai, bj, At, Bt) do { __builtin_amdgcn_s_setprio(1); _Pragma("unroll") for (int m = 0; m < 4; ++m) _Pragma("unroll") for (int n = 0; n < 2; ++n) _Pragma("unroll") for (int k = 0; k < 2; ++k) \
;         acc[ai][bj][m][n] = __builtin_amdgcn_mfma_f32_16x16x32_bf16(Bt[n][k], At[m][k], acc[ai][bj][m][n], 0, 0, 0); __builtin_amdgcn_s_setprio(0); } while (0)
; #define PG8_WAIT_V(n) asm volatile("s_waitcnt vmcnt(" #n ")" ::: "memory")
; #define PG8_WAIT_L(n) asm volatile("s_waitcnt lgkmcnt(" #n ")" ::: "memory")
; #define PG8_BAR __builtin_amdgcn_s_barrier()
; #define PG8_SCHED __builtin_amdgcn_sched_barrier(0)
; template <class Epi, class Sched, bool ALIGN_EPI = false, bool SP2 = false>
; __device__ __forceinline__ void gemm_phase(PG8_LAS unsigned char* lds, const Gemm g, const Sched& S, const Epi& E) {
;     ...
;             PG8_LDA(At, 1, 1); PG8_STAGE(PG8_SB(1, 0), b3, voffB); PG8_STAGE(PG8_SB(1, 1), b3 + hstep, voffB); PG8_STAGE(PG8_SA(1, 0), a3, voffA);
;             PG8_WAIT_V(8); PG8_WAIT_L(0); PG8_BAR; PG8_MMA(1, 0, At, B0); PG8_MMA(1, 1, At, B1); PG8_BAR; PG8_SCHED;
	s_mov_b32 m0, s62
	v_lshl_add_u64 v[212:213], v[232:233], 0, s[24:25]
	ds_read_b128 v[196:199], v163 offset:49152
	ds_read_b128 v[200:203], v163 offset:50176
	ds_read_b128 v[204:207], v163 offset:51200
	ds_read_b128 v[208:211], v163 offset:52224
	ds_read_b128 v[216:219], v163 offset:53248
	ds_read_b128 v[220:223], v163 offset:54272
	ds_read_b128 v[224:227], v163 offset:55296
	ds_read_b128 v[228:231], v163 offset:56320
	global_load_lds_dwordx4 v[212:213], off
	v_lshl_add_u64 v[212:213], v[234:235], 0, s[24:25]
	s_mov_b32 m0, s63
	s_nop 0
	global_load_lds_dwordx4 v[212:213], off
	v_lshl_add_u64 v[212:213], v[236:237], 0, s[24:25]
	s_mov_b32 m0, s64
	s_nop 0
	global_load_lds_dwordx4 v[212:213], off
	v_lshl_add_u64 v[212:213], v[214:215], 0, s[24:25]
	s_mov_b32 m0, s65
	s_nop 0
	global_load_lds_dwordx4 v[212:213], off
	v_lshl_add_u64 v[212:213], v[238:239], 0, s[24:25]
	s_mov_b32 m0, s48
	s_nop 0
	global_load_lds_dwordx4 v[212:213], off
	v_lshl_add_u64 v[212:213], v[240:241], 0, s[24:25]
	s_mov_b32 m0, s49
	s_nop 0
	global_load_lds_dwordx4 v[212:213], off
	s_waitcnt vmcnt(8)
	s_waitcnt lgkmcnt(0)
	s_barrier
	s_setprio 1
	s_waitcnt lgkmcnt(0)
	v_mfma_f32_16x16x32_bf16 v[60:63], v[164:167], v[196:199], v[60:63]
	v_mfma_f32_16x16x32_bf16 v[56:59], v[172:175], v[196:199], v[56:59]
	v_mfma_f32_16x16x32_bf16 v[44:47], v[164:167], v[204:207], v[44:47]
	v_mfma_f32_16x16x32_bf16 v[40:43], v[172:175], v[204:207], v[40:43]
	v_mfma_f32_16x16x32_bf16 v[28:31], v[164:167], v[216:219], v[28:31]
	v_mfma_f32_16x16x32_bf16 v[24:27], v[172:175], v[216:219], v[24:27]
	v_mfma_f32_16x16x32_bf16 v[12:15], v[164:167], v[224:227], v[12:15]
	v_mfma_f32_16x16x32_bf16 v[8:11], v[172:175], v[224:227], v[8:11]
	v_mfma_f32_16x16x32_bf16 v[60:63], v[168:171], v[200:203], v[60:63]
	v_mfma_f32_16x16x32_bf16 v[56:59], v[176:179], v[200:203], v[56:59]
	v_mfma_f32_16x16x32_bf16 v[44:47], v[168:171], v[208:211], v[44:47]
	v_mfma_f32_16x16x32_bf16 v[40:43], v[176:179], v[208:211], v[40:43]
	v_mfma_f32_16x16x32_bf16 v[28:31], v[168:171], v[220:223], v[28:31]
	v_mfma_f32_16x16x32_bf16 v[24:27], v[176:179], v[220:223], v[24:27]
	v_mfma_f32_16x16x32_bf16 v[12:15], v[168:171], v[228:231], v[12:15]
	v_mfma_f32_16x16x32_bf16 v[8:11], v[176:179], v[228:231], v[8:11]
	v_mfma_f32_16x16x32_bf16 v[52:55], v[180:183], v[196:199], v[52:55]
	v_mfma_f32_16x16x32_bf16 v[48:51], v[188:191], v[196:199], v[48:51]
	v_mfma_f32_16x16x32_bf16 v[36:39], v[180:183], v[204:207], v[36:39]
	v_mfma_f32_16x16x32_bf16 v[32:35], v[188:191], v[204:207], v[32:35]
	v_mfma_f32_16x16x32_bf16 v[20:23], v[180:183], v[216:219], v[20:23]
	v_mfma_f32_16x16x32_bf16 v[16:19], v[188:191], v[216:219], v[16:19]
	v_mfma_f32_16x16x32_bf16 v[4:7], v[180:183], v[224:227], v[4:7]
	v_mfma_f32_16x16x32_bf16 v[0:3], v[188:191], v[224:227], v[0:3]
	v_mfma_f32_16x16x32_bf16 v[52:55], v[184:187], v[200:203], v[52:55]
	v_mfma_f32_16x16x32_bf16 v[48:51], v[192:195], v[200:203], v[48:51]
	v_mfma_f32_16x16x32_bf16 v[36:39], v[184:187], v[208:211], v[36:39]
	v_mfma_f32_16x16x32_bf16 v[32:35], v[192:195], v[208:211], v[32:35]
	v_mfma_f32_16x16x32_bf16 v[20:23], v[184:187], v[220:223], v[20:23]
	v_mfma_f32_16x16x32_bf16 v[16:19], v[192:195], v[220:223], v[16:19]
	v_mfma_f32_16x16x32_bf16 v[4:7], v[184:187], v[228:231], v[4:7]
	v_mfma_f32_16x16x32_bf16 v[0:3], v[192:195], v[228:231], v[0:3]
	s_setprio 0
	s_barrier
	v_lshl_add_u64 v[154:155], v[154:155], 0, s[28:29]
	s_cmp_ge_i32 s10, s50
	v_lshl_add_u64 v[158:159], v[158:159], 0, s[28:29]
	s_cbranch_scc0 .LBB0_1169

; #define PG8_STAGE(bufoff, gbase, voff) do { _Pragma("unroll") for (int _i = 0; _i < 2; ++_i) \
;         __builtin_amdgcn_global_load_lds((const unsigned*)((const char*)(gbase) + (voff)[_i]), (PG8_LAS unsigned*)(lds + (bufoff) + ldsw + _i * 8192), 16, 0, 0); } while (0)
; #define PG8_LDA(dst, b, h) do { _Pragma("unroll") for (int m = 0; m < 4; ++m) _Pragma("unroll") for (int k = 0; k < 2; ++k) dst[m][k] = *(const PG8_LAS bf16x8*)(lds + PG8_SA(b, h) + aoff + m * 2048 + k * 1024); } while (0)
; #define PG8_LDB(dst, b, h) do { _Pragma("unroll") for (int n = 0; n < 2; ++n) _Pragma("unroll") for (int k = 0; k < 2; ++k) dst[n][k] = *(const PG8_LAS bf16x8*)(lds + PG8_SB(b, h) + boff + n * 2048 + k * 1024); } while (0)
; #define PG8_MMA(ai, bj, At, Bt) do { __builtin_amdgcn_s_setprio(1); _Pragma("unroll") for (int m = 0; m < 4; ++m) _Pragma("unroll") for (int n = 0; n < 2; ++n) _Pragma("unroll") for (int k = 0; k < 2; ++k) \
;         acc[ai][bj][m][n] = __builtin_amdgcn_mfma_f32_16x16x32_bf16(Bt[n][k], At[m][k], acc[ai][bj][m][n], 0, 0, 0); __builtin_amdgcn_s_setprio(0); } while (0)
; #define PG8_WAIT_V(n) asm volatile("s_waitcnt vmcnt(" #n ")" ::: "memory")
; #define PG8_WAIT_L(n) asm volatile("s_waitcnt lgkmcnt(" #n ")" ::: "memory")
; #define PG8_BAR __builtin_amdgcn_s_barrier()
; #define PG8_SCHED __builtin_amdgcn_sched_barrier(0)
; template <class Epi, class Sched, bool ALIGN_EPI = false, bool SP2 = false>
; __device__ __forceinline__ void gemm_phase(PG8_LAS unsigned char* lds, const Gemm g, const Sched& S, const Epi& E) {
;     ...
;         for (int t = 0; t < nt; t += 2) {
;             const bool last = (t == nt - 2);
;             const char* a1 = cA + (size_t)(t + 1) * kstep;
;             const char* a2 = last ? nA : cA + (size_t)(t + 2) * kstep; const char* b2 = last ? nB : cB + (size_t)(t + 2) * kstep;
;             const char* a3 = a2 + kstep; const char* b3 = b2 + kstep;
;             if (last && has_next) S.a_ready(nxt);
;             if constexpr (SP2) {
;             PG8_LDB(B0, 0, 0); PG8_LDB(B1, 0, 1); PG8_SCHED; PG8_LDA(At, 0, 0); PG8_STAGE(PG8_SA(1, 1), a1 + hstep, voffA);
;             PG8_WAIT_V(8); PG8_WAIT_L(0); PG8_BAR; PG8_MMA(0, 0, At, B0); PG8_MMA(0, 1, At, B1); PG8_BAR; PG8_SCHED;
;             PG8_LDA(At, 0, 1); PG8_STAGE(PG8_SB(0, 0), b2, voffB); PG8_STAGE(PG8_SB(0, 1), b2 + hstep, voffB); PG8_STAGE(PG8_SA(0, 0), a2, voffA);
.LBB0_1192:
	v_add_u32_e32 v178, s56, v216
	v_add_u32_e32 v194, s57, v216
	ds_read_b128 v[138:141], v178
	ds_read_b128 v[142:145], v178 offset:1024
	ds_read_b128 v[146:149], v178 offset:2048
	ds_read_b128 v[178:181], v178 offset:3072
	ds_read_b128 v[182:185], v194
	ds_read_b128 v[186:189], v194 offset:1024
	ds_read_b128 v[190:193], v194 offset:2048
	ds_read_b128 v[194:197], v194 offset:3072
	s_cmp_eq_u32 s49, s10
	v_lshl_add_u64 v[198:199], v[136:137], 0, s[20:21]
	s_cselect_b64 vcc, -1, 0
	s_add_i32 s10, s10, 2
	v_cndmask_b32_e32 v215, v199, v175, vcc
	v_cndmask_b32_e32 v214, v198, v174, vcc
	v_cndmask_b32_e32 v237, v135, v177, vcc
	v_cndmask_b32_e32 v236, v134, v176, vcc
	v_lshl_add_u64 v[238:239], v[136:137], 0, v[168:169]
	s_add_i32 m0, s34, 0xc000
	ds_read_b128 v[198:201], v218
	ds_read_b128 v[202:205], v218 offset:1024
	ds_read_b128 v[206:209], v218 offset:2048
	ds_read_b128 v[210:213], v218 offset:3072
	ds_read_b128 v[220:223], v218 offset:4096
	ds_read_b128 v[224:227], v218 offset:5120
	ds_read_b128 v[228:231], v218 offset:6144
	ds_read_b128 v[232:235], v218 offset:7168
	global_load_lds_dwordx4 v[238:239], off
	v_lshl_add_u64 v[238:239], v[136:137], 0, v[166:167]
	s_add_i32 m0, s34, 0xe000
	s_nop 0
	global_load_lds_dwordx4 v[238:239], off
	s_waitcnt vmcnt(8)
	s_waitcnt lgkmcnt(0)
	s_barrier
	s_setprio 1
	s_waitcnt lgkmcnt(0)
	v_mfma_f32_16x16x32_bf16 v[130:133], v[138:141], v[198:201], v[130:133]
	v_mfma_f32_16x16x32_bf16 v[126:129], v[146:149], v[198:201], v[126:129]
	v_mfma_f32_16x16x32_bf16 v[114:117], v[138:141], v[206:209], v[114:117]
	v_mfma_f32_16x16x32_bf16 v[110:113], v[146:149], v[206:209], v[110:113]
	v_mfma_f32_16x16x32_bf16 v[98:101], v[138:141], v[220:223], v[98:101]
	v_mfma_f32_16x16x32_bf16 v[94:97], v[146:149], v[220:223], v[94:97]
	v_mfma_f32_16x16x32_bf16 v[82:85], v[138:141], v[228:231], v[82:85]
	v_mfma_f32_16x16x32_bf16 v[78:81], v[146:149], v[228:231], v[78:81]
	v_mfma_f32_16x16x32_bf16 v[130:133], v[142:145], v[202:205], v[130:133]
	v_mfma_f32_16x16x32_bf16 v[126:129], v[178:181], v[202:205], v[126:129]
	v_mfma_f32_16x16x32_bf16 v[114:117], v[142:145], v[210:213], v[114:117]
	v_mfma_f32_16x16x32_bf16 v[110:113], v[178:181], v[210:213], v[110:113]
	v_mfma_f32_16x16x32_bf16 v[98:101], v[142:145], v[224:227], v[98:101]
	v_mfma_f32_16x16x32_bf16 v[94:97], v[178:181], v[224:227], v[94:97]
	v_mfma_f32_16x16x32_bf16 v[82:85], v[142:145], v[232:235], v[82:85]
	v_mfma_f32_16x16x32_bf16 v[78:81], v[178:181], v[232:235], v[78:81]
	v_mfma_f32_16x16x32_bf16 v[122:125], v[182:185], v[198:201], v[122:125]
	v_mfma_f32_16x16x32_bf16 v[118:121], v[190:193], v[198:201], v[118:121]
	v_mfma_f32_16x16x32_bf16 v[106:109], v[182:185], v[206:209], v[106:109]
	v_mfma_f32_16x16x32_bf16 v[102:105], v[190:193], v[206:209], v[102:105]
	v_mfma_f32_16x16x32_bf16 v[90:93], v[182:185], v[220:223], v[90:93]
	v_mfma_f32_16x16x32_bf16 v[86:89], v[190:193], v[220:223], v[86:89]
	v_mfma_f32_16x16x32_bf16 v[74:77], v[182:185], v[228:231], v[74:77]
	v_mfma_f32_16x16x32_bf16 v[70:73], v[190:193], v[228:231], v[70:73]
	v_mfma_f32_16x16x32_bf16 v[122:125], v[186:189], v[202:205], v[122:125]
	v_mfma_f32_16x16x32_bf16 v[118:121], v[194:197], v[202:205], v[118:121]
	v_mfma_f32_16x16x32_bf16 v[106:109], v[186:189], v[210:213], v[106:109]
	v_mfma_f32_16x16x32_bf16 v[102:105], v[194:197], v[210:213], v[102:105]
	v_mfma_f32_16x16x32_bf16 v[90:93], v[186:189], v[224:227], v[90:93]
	v_mfma_f32_16x16x32_bf16 v[86:89], v[194:197], v[224:227], v[86:89]
	v_mfma_f32_16x16x32_bf16 v[74:77], v[186:189], v[232:235], v[74:77]
	v_mfma_f32_16x16x32_bf16 v[70:73], v[194:197], v[232:235], v[70:73]
	s_setprio 0
	s_barrier
	s_add_i32 s11, s56, s29
	v_lshl_add_u64 v[238:239], v[236:237], 0, v[158:159]
	s_mov_b32 m0, s11
	ds_read_b128 v[198:201], v218 offset:16384
	ds_read_b128 v[202:205], v218 offset:17408
	ds_read_b128 v[206:209], v218 offset:18432
	ds_read_b128 v[210:213], v218 offset:19456
	ds_read_b128 v[220:223], v218 offset:20480
	ds_read_b128 v[224:227], v218 offset:21504
	ds_read_b128 v[228:231], v218 offset:22528
	ds_read_b128 v[232:235], v218 offset:23552
	global_load_lds_dwordx4 v[238:239], off
	v_lshl_add_u64 v[240:241], v[236:237], 0, v[162:163]
	s_add_i32 m0, s11, 0x2000
	v_lshl_add_u64 v[236:237], v[236:237], 0, s[12:13]
	s_add_i32 s11, s57, s29
	global_load_lds_dwordx4 v[240:241], off
	v_lshl_add_u64 v[242:243], v[236:237], 0, v[158:159]
	s_mov_b32 m0, s11
	v_lshl_add_u64 v[236:237], v[236:237], 0, v[162:163]
	global_load_lds_dwordx4 v[242:243], off
	s_add_i32 m0, s11, 0x2000
	v_lshl_add_u64 v[244:245], v[214:215], 0, v[154:155]
	global_load_lds_dwordx4 v[236:237], off
	s_mov_b32 m0, s34
	v_lshl_add_u64 v[246:247], v[214:215], 0, v[160:161]
	global_load_lds_dwordx4 v[244:245], off
	s_mov_b32 m0, s35
	s_nop 0
	global_load_lds_dwordx4 v[246:247], off
	s_waitcnt vmcnt(8)
	s_waitcnt lgkmcnt(0)
	s_barrier
; #define PG8_STAGE(bufoff, gbase, voff) do { _Pragma("unroll") for (int _i = 0; _i < 2; ++_i) \
;         __builtin_amdgcn_global_load_lds((const unsigned*)((const char*)(gbase) + (voff)[_i]), (PG8_LAS unsigned*)(lds + (bufoff) + ldsw + _i * 8192), 16, 0, 0); } while (0)
; #define PG8_LDA(dst, b, h) do { _Pragma("unroll") for (int m = 0; m < 4; ++m) _Pragma("unroll") for (int k = 0; k < 2; ++k) dst[m][k] = *(const PG8_LAS bf16x8*)(lds + PG8_SA(b, h) + aoff + m * 2048 + k * 1024); } while (0)
; #define PG8_LDB(dst, b, h) do { _Pragma("unroll") for (int n = 0; n < 2; ++n) _Pragma("unroll") for (int k = 0; k < 2; ++k) dst[n][k] = *(const PG8_LAS bf16x8*)(lds + PG8_SB(b, h) + boff + n * 2048 + k * 1024); } while (0)
; #define PG8_MMA(ai, bj, At, Bt) do { __builtin_amdgcn_s_setprio(1); _Pragma("unroll") for (int m = 0; m < 4; ++m) _Pragma("unroll") for (int n = 0; n < 2; ++n) _Pragma("unroll") for (int k = 0; k < 2; ++k) \
;         acc[ai][bj][m][n] = __builtin_amdgcn_mfma_f32_16x16x32_bf16(Bt[n][k], At[m][k], acc[ai][bj][m][n], 0, 0, 0); __builtin_amdgcn_s_setprio(0); } while (0)
; #define PG8_WAIT_V(n) asm volatile("s_waitcnt vmcnt(" #n ")" ::: "memory")
; #define PG8_WAIT_L(n) asm volatile("s_waitcnt lgkmcnt(" #n ")" ::: "memory")
; #define PG8_BAR __builtin_amdgcn_s_barrier()
; #define PG8_SCHED __builtin_amdgcn_sched_barrier(0)
; template <class Epi, class Sched, bool ALIGN_EPI = false, bool SP2 = false>
; __device__ __forceinline__ void gemm_phase(PG8_LAS unsigned char* lds, const Gemm g, const Sched& S, const Epi& E) {
;     ...
;             PG8_WAIT_V(8); PG8_WAIT_L(0); PG8_BAR; PG8_MMA(1, 0, At, B0); PG8_MMA(1, 1, At, B1); PG8_BAR; PG8_SCHED;
;             PG8_LDB(B0, 1, 0); PG8_LDB(B1, 1, 1); PG8_SCHED; PG8_LDA(At, 1, 0); PG8_STAGE(PG8_SA(0, 1), a2 + hstep, voffA);
;             PG8_WAIT_V(8); PG8_WAIT_L(0); PG8_BAR; PG8_MMA(0, 0, At, B0); PG8_MMA(0, 1, At, B1); PG8_BAR; PG8_SCHED;
	s_setprio 1
	s_waitcnt lgkmcnt(0)
	v_mfma_f32_16x16x32_bf16 v[66:69], v[138:141], v[198:201], v[66:69]
	v_mfma_f32_16x16x32_bf16 v[62:65], v[146:149], v[198:201], v[62:65]
	v_mfma_f32_16x16x32_bf16 v[50:53], v[138:141], v[206:209], v[50:53]
	v_mfma_f32_16x16x32_bf16 v[46:49], v[146:149], v[206:209], v[46:49]
	v_mfma_f32_16x16x32_bf16 v[34:37], v[138:141], v[220:223], v[34:37]
	v_mfma_f32_16x16x32_bf16 v[30:33], v[146:149], v[220:223], v[30:33]
	v_mfma_f32_16x16x32_bf16 v[18:21], v[138:141], v[228:231], v[18:21]
	v_mfma_f32_16x16x32_bf16 v[14:17], v[146:149], v[228:231], v[14:17]
	v_mfma_f32_16x16x32_bf16 v[66:69], v[142:145], v[202:205], v[66:69]
	v_mfma_f32_16x16x32_bf16 v[62:65], v[178:181], v[202:205], v[62:65]
	v_mfma_f32_16x16x32_bf16 v[50:53], v[142:145], v[210:213], v[50:53]
	v_mfma_f32_16x16x32_bf16 v[46:49], v[178:181], v[210:213], v[46:49]
	v_mfma_f32_16x16x32_bf16 v[34:37], v[142:145], v[224:227], v[34:37]
	v_mfma_f32_16x16x32_bf16 v[30:33], v[178:181], v[224:227], v[30:33]
	v_mfma_f32_16x16x32_bf16 v[18:21], v[142:145], v[232:235], v[18:21]
	v_mfma_f32_16x16x32_bf16 v[14:17], v[178:181], v[232:235], v[14:17]
	v_mfma_f32_16x16x32_bf16 v[58:61], v[182:185], v[198:201], v[58:61]
	v_mfma_f32_16x16x32_bf16 v[54:57], v[190:193], v[198:201], v[54:57]
	v_mfma_f32_16x16x32_bf16 v[42:45], v[182:185], v[206:209], v[42:45]
	v_mfma_f32_16x16x32_bf16 v[38:41], v[190:193], v[206:209], v[38:41]
	v_mfma_f32_16x16x32_bf16 v[26:29], v[182:185], v[220:223], v[26:29]
	v_mfma_f32_16x16x32_bf16 v[22:25], v[190:193], v[220:223], v[22:25]
	v_mfma_f32_16x16x32_bf16 v[10:13], v[182:185], v[228:231], v[10:13]
	v_mfma_f32_16x16x32_bf16 v[6:9], v[190:193], v[228:231], v[6:9]
	v_mfma_f32_16x16x32_bf16 v[58:61], v[186:189], v[202:205], v[58:61]
	v_mfma_f32_16x16x32_bf16 v[54:57], v[194:197], v[202:205], v[54:57]
	v_mfma_f32_16x16x32_bf16 v[42:45], v[186:189], v[210:213], v[42:45]
	v_mfma_f32_16x16x32_bf16 v[38:41], v[194:197], v[210:213], v[38:41]
	v_mfma_f32_16x16x32_bf16 v[26:29], v[186:189], v[224:227], v[26:29]
	v_mfma_f32_16x16x32_bf16 v[22:25], v[194:197], v[224:227], v[22:25]
	v_mfma_f32_16x16x32_bf16 v[10:13], v[186:189], v[232:235], v[10:13]
	v_mfma_f32_16x16x32_bf16 v[6:9], v[194:197], v[232:235], v[6:9]
	s_setprio 0
	s_barrier
	s_add_i32 s11, 0, 0x18000
	s_add_i32 s31, 0, 0x1c000
	v_add_u32_e32 v178, s11, v216
	v_add_u32_e32 v194, s31, v216
	ds_read_b128 v[138:141], v178
	ds_read_b128 v[142:145], v178 offset:1024
	ds_read_b128 v[146:149], v178 offset:2048
	ds_read_b128 v[178:181], v178 offset:3072
	ds_read_b128 v[182:185], v194
	ds_read_b128 v[186:189], v194 offset:1024
	ds_read_b128 v[190:193], v194 offset:2048
	ds_read_b128 v[194:197], v194 offset:3072
	v_lshl_add_u64 v[214:215], v[214:215], 0, s[12:13]
	s_mov_b32 m0, s36
	v_lshl_add_u64 v[248:249], v[214:215], 0, v[154:155]
	ds_read_b128 v[198:201], v218 offset:32768
	ds_read_b128 v[202:205], v218 offset:33792
	ds_read_b128 v[206:209], v218 offset:34816
	ds_read_b128 v[210:213], v218 offset:35840
	ds_read_b128 v[220:223], v218 offset:36864
	ds_read_b128 v[224:227], v218 offset:37888
	ds_read_b128 v[228:231], v218 offset:38912
	ds_read_b128 v[232:235], v218 offset:39936
	global_load_lds_dwordx4 v[248:249], off
	v_lshl_add_u64 v[214:215], v[214:215], 0, v[160:161]
	s_mov_b32 m0, s37
	s_nop 0
	global_load_lds_dwordx4 v[214:215], off
	s_waitcnt vmcnt(8)
	s_waitcnt lgkmcnt(0)
	s_barrier
	s_setprio 1
	s_waitcnt lgkmcnt(0)
	v_mfma_f32_16x16x32_bf16 v[130:133], v[138:141], v[198:201], v[130:133]
	v_mfma_f32_16x16x32_bf16 v[126:129], v[146:149], v[198:201], v[126:129]
	v_mfma_f32_16x16x32_bf16 v[114:117], v[138:141], v[206:209], v[114:117]
	v_mfma_f32_16x16x32_bf16 v[110:113], v[146:149], v[206:209], v[110:113]
	v_mfma_f32_16x16x32_bf16 v[98:101], v[138:141], v[220:223], v[98:101]
	v_mfma_f32_16x16x32_bf16 v[94:97], v[146:149], v[220:223], v[94:97]
	v_mfma_f32_16x16x32_bf16 v[82:85], v[138:141], v[228:231], v[82:85]
	v_mfma_f32_16x16x32_bf16 v[78:81], v[146:149], v[228:231], v[78:81]
	v_mfma_f32_16x16x32_bf16 v[130:133], v[142:145], v[202:205], v[130:133]
	v_mfma_f32_16x16x32_bf16 v[126:129], v[178:181], v[202:205], v[126:129]
	v_mfma_f32_16x16x32_bf16 v[114:117], v[142:145], v[210:213], v[114:117]
	v_mfma_f32_16x16x32_bf16 v[110:113], v[178:181], v[210:213], v[110:113]
	v_mfma_f32_16x16x32_bf16 v[98:101], v[142:145], v[224:227], v[98:101]
	v_mfma_f32_16x16x32_bf16 v[94:97], v[178:181], v[224:227], v[94:97]
	v_mfma_f32_16x16x32_bf16 v[82:85], v[142:145], v[232:235], v[82:85]
	v_mfma_f32_16x16x32_bf16 v[78:81], v[178:181], v[232:235], v[78:81]
	v_mfma_f32_16x16x32_bf16 v[122:125], v[182:185], v[198:201], v[122:125]
	v_mfma_f32_16x16x32_bf16 v[118:121], v[190:193], v[198:201], v[118:121]
	v_mfma_f32_16x16x32_bf16 v[106:109], v[182:185], v[206:209], v[106:109]
	v_mfma_f32_16x16x32_bf16 v[102:105], v[190:193], v[206:209], v[102:105]
	v_mfma_f32_16x16x32_bf16 v[90:93], v[182:185], v[220:223], v[90:93]
	v_mfma_f32_16x16x32_bf16 v[86:89], v[190:193], v[220:223], v[86:89]
	v_mfma_f32_16x16x32_bf16 v[74:77], v[182:185], v[228:231], v[74:77]
	v_mfma_f32_16x16x32_bf16 v[70:73], v[190:193], v[228:231], v[70:73]
	v_mfma_f32_16x16x32_bf16 v[122:125], v[186:189], v[202:205], v[122:125]
	v_mfma_f32_16x16x32_bf16 v[118:121], v[194:197], v[202:205], v[118:121]
	v_mfma_f32_16x16x32_bf16 v[106:109], v[186:189], v[210:213], v[106:109]
	v_mfma_f32_16x16x32_bf16 v[102:105], v[194:197], v[210:213], v[102:105]
	v_mfma_f32_16x16x32_bf16 v[90:93], v[186:189], v[224:227], v[90:93]
	v_mfma_f32_16x16x32_bf16 v[86:89], v[194:197], v[224:227], v[86:89]
	v_mfma_f32_16x16x32_bf16 v[74:77], v[186:189], v[232:235], v[74:77]
	v_mfma_f32_16x16x32_bf16 v[70:73], v[194:197], v[232:235], v[70:73]
	s_setprio 0
	s_barrier
; #define PG8_STAGE(bufoff, gbase, voff) do { _Pragma("unroll") for (int _i = 0; _i < 2; ++_i) \
;         __builtin_amdgcn_global_load_lds((const unsigned*)((const char*)(gbase) + (voff)[_i]), (PG8_LAS unsigned*)(lds + (bufoff) + ldsw + _i * 8192), 16, 0, 0); } while (0)
; #define PG8_LDA(dst, b, h) do { _Pragma("unroll") for (int m = 0; m < 4; ++m) _Pragma("unroll") for (int k = 0; k < 2; ++k) dst[m][k] = *(const PG8_LAS bf16x8*)(lds + PG8_SA(b, h) + aoff + m * 2048 + k * 1024); } while (0)
; #define PG8_MMA(ai, bj, At, Bt) do { __builtin_amdgcn_s_setprio(1); _Pragma("unroll") for (int m = 0; m < 4; ++m) _Pragma("unroll") for (int n = 0; n < 2; ++n) _Pragma("unroll") for (int k = 0; k < 2; ++k) \
;         acc[ai][bj][m][n] = __builtin_amdgcn_mfma_f32_16x16x32_bf16(Bt[n][k], At[m][k], acc[ai][bj][m][n], 0, 0, 0); __builtin_amdgcn_s_setprio(0); } while (0)
; #define PG8_WAIT_V(n) asm volatile("s_waitcnt vmcnt(" #n ")" ::: "memory")
; #define PG8_WAIT_L(n) asm volatile("s_waitcnt lgkmcnt(" #n ")" ::: "memory")
; #define PG8_BAR __builtin_amdgcn_s_barrier()
; #define PG8_SCHED __builtin_amdgcn_sched_barrier(0)
; template <class Epi, class Sched, bool ALIGN_EPI = false, bool SP2 = false>
; __device__ __forceinline__ void gemm_phase(PG8_LAS unsigned char* lds, const Gemm g, const Sched& S, const Epi& E) {
;     ...
;             PG8_LDA(At, 1, 1); PG8_STAGE(PG8_SB(1, 0), b3, voffB); PG8_STAGE(PG8_SB(1, 1), b3 + hstep, voffB); PG8_STAGE(PG8_SA(1, 0), a3, voffA);
;             PG8_WAIT_V(8); PG8_WAIT_L(0); PG8_BAR; PG8_MMA(1, 0, At, B0); PG8_MMA(1, 1, At, B1); PG8_BAR; PG8_SCHED;
	s_add_i32 s11, s11, s29
	v_lshl_add_u64 v[214:215], v[238:239], 0, s[20:21]
	s_mov_b32 m0, s11
	ds_read_b128 v[198:201], v218 offset:49152
	ds_read_b128 v[202:205], v218 offset:50176
	ds_read_b128 v[206:209], v218 offset:51200
	ds_read_b128 v[210:213], v218 offset:52224
	ds_read_b128 v[220:223], v218 offset:53248
	ds_read_b128 v[224:227], v218 offset:54272
	ds_read_b128 v[228:231], v218 offset:55296
	ds_read_b128 v[232:235], v218 offset:56320
	global_load_lds_dwordx4 v[214:215], off
	v_lshl_add_u64 v[214:215], v[240:241], 0, s[20:21]
	s_add_i32 m0, s11, 0x2000
	s_add_i32 s11, s31, s29
	global_load_lds_dwordx4 v[214:215], off
	v_lshl_add_u64 v[214:215], v[242:243], 0, s[20:21]
	s_mov_b32 m0, s11
	s_nop 0
	global_load_lds_dwordx4 v[214:215], off
	v_lshl_add_u64 v[214:215], v[236:237], 0, s[20:21]
	s_add_i32 m0, s11, 0x2000
	s_nop 0
	global_load_lds_dwordx4 v[214:215], off
	v_lshl_add_u64 v[214:215], v[244:245], 0, s[20:21]
	s_mov_b32 m0, s41
	s_nop 0
	global_load_lds_dwordx4 v[214:215], off
	v_lshl_add_u64 v[214:215], v[246:247], 0, s[20:21]
	s_mov_b32 m0, s46
	s_nop 0
	global_load_lds_dwordx4 v[214:215], off
	s_waitcnt vmcnt(8)
	s_waitcnt lgkmcnt(0)
	s_barrier
	s_setprio 1
	s_waitcnt lgkmcnt(0)
	v_mfma_f32_16x16x32_bf16 v[66:69], v[138:141], v[198:201], v[66:69]
	v_mfma_f32_16x16x32_bf16 v[62:65], v[146:149], v[198:201], v[62:65]
	v_mfma_f32_16x16x32_bf16 v[50:53], v[138:141], v[206:209], v[50:53]
	v_mfma_f32_16x16x32_bf16 v[46:49], v[146:149], v[206:209], v[46:49]
	v_mfma_f32_16x16x32_bf16 v[34:37], v[138:141], v[220:223], v[34:37]
	v_mfma_f32_16x16x32_bf16 v[30:33], v[146:149], v[220:223], v[30:33]
	v_mfma_f32_16x16x32_bf16 v[18:21], v[138:141], v[228:231], v[18:21]
	v_mfma_f32_16x16x32_bf16 v[14:17], v[146:149], v[228:231], v[14:17]
	v_mfma_f32_16x16x32_bf16 v[66:69], v[142:145], v[202:205], v[66:69]
	v_mfma_f32_16x16x32_bf16 v[62:65], v[178:181], v[202:205], v[62:65]
	v_mfma_f32_16x16x32_bf16 v[50:53], v[142:145], v[210:213], v[50:53]
	v_mfma_f32_16x16x32_bf16 v[46:49], v[178:181], v[210:213], v[46:49]
	v_mfma_f32_16x16x32_bf16 v[34:37], v[142:145], v[224:227], v[34:37]
	v_mfma_f32_16x16x32_bf16 v[30:33], v[178:181], v[224:227], v[30:33]
	v_mfma_f32_16x16x32_bf16 v[18:21], v[142:145], v[232:235], v[18:21]
	v_mfma_f32_16x16x32_bf16 v[14:17], v[178:181], v[232:235], v[14:17]
	v_mfma_f32_16x16x32_bf16 v[58:61], v[182:185], v[198:201], v[58:61]
	v_mfma_f32_16x16x32_bf16 v[54:57], v[190:193], v[198:201], v[54:57]
	v_mfma_f32_16x16x32_bf16 v[42:45], v[182:185], v[206:209], v[42:45]
	v_mfma_f32_16x16x32_bf16 v[38:41], v[190:193], v[206:209], v[38:41]
	v_mfma_f32_16x16x32_bf16 v[26:29], v[182:185], v[220:223], v[26:29]
	v_mfma_f32_16x16x32_bf16 v[22:25], v[190:193], v[220:223], v[22:25]
	v_mfma_f32_16x16x32_bf16 v[10:13], v[182:185], v[228:231], v[10:13]
	v_mfma_f32_16x16x32_bf16 v[6:9], v[190:193], v[228:231], v[6:9]
	v_mfma_f32_16x16x32_bf16 v[58:61], v[186:189], v[202:205], v[58:61]
	v_mfma_f32_16x16x32_bf16 v[54:57], v[194:197], v[202:205], v[54:57]
	v_mfma_f32_16x16x32_bf16 v[42:45], v[186:189], v[210:213], v[42:45]
	v_mfma_f32_16x16x32_bf16 v[38:41], v[194:197], v[210:213], v[38:41]
	v_mfma_f32_16x16x32_bf16 v[26:29], v[186:189], v[224:227], v[26:29]
	v_mfma_f32_16x16x32_bf16 v[22:25], v[194:197], v[224:227], v[22:25]
	v_mfma_f32_16x16x32_bf16 v[10:13], v[186:189], v[232:235], v[10:13]
	v_mfma_f32_16x16x32_bf16 v[6:9], v[194:197], v[232:235], v[6:9]
	s_setprio 0
	s_barrier
	v_lshl_add_u64 v[134:135], v[134:135], 0, s[26:27]
	s_cmp_ge_i32 s10, s48
	v_lshl_add_u64 v[136:137], v[136:137], 0, s[26:27]
	s_cbranch_scc0 .LBB0_1192

; #define PG8_STAGE(bufoff, gbase, voff) do { _Pragma("unroll") for (int _i = 0; _i < 2; ++_i) \
;         __builtin_amdgcn_global_load_lds((const unsigned*)((const char*)(gbase) + (voff)[_i]), (PG8_LAS unsigned*)(lds + (bufoff) + ldsw + _i * 8192), 16, 0, 0); } while (0)
; #define PG8_LDA(dst, b, h) do { _Pragma("unroll") for (int m = 0; m < 4; ++m) _Pragma("unroll") for (int k = 0; k < 2; ++k) dst[m][k] = *(const PG8_LAS bf16x8*)(lds + PG8_SA(b, h) + aoff + m * 2048 + k * 1024); } while (0)
; #define PG8_LDB(dst, b, h) do { _Pragma("unroll") for (int n = 0; n < 2; ++n) _Pragma("unroll") for (int k = 0; k < 2; ++k) dst[n][k] = *(const PG8_LAS bf16x8*)(lds + PG8_SB(b, h) + boff + n * 2048 + k * 1024); } while (0)
; #define PG8_MMA(ai, bj, At, Bt) do { __builtin_amdgcn_s_setprio(1); _Pragma("unroll") for (int m = 0; m < 4; ++m) _Pragma("unroll") for (int n = 0; n < 2; ++n) _Pragma("unroll") for (int k = 0; k < 2; ++k) \
;         acc[ai][bj][m][n] = __builtin_amdgcn_mfma_f32_16x16x32_bf16(Bt[n][k], At[m][k], acc[ai][bj][m][n], 0, 0, 0); __builtin_amdgcn_s_setprio(0); } while (0)
; #define PG8_WAIT_V(n) asm volatile("s_waitcnt vmcnt(" #n ")" ::: "memory")
; #define PG8_WAIT_L(n) asm volatile("s_waitcnt lgkmcnt(" #n ")" ::: "memory")
; #define PG8_BAR __builtin_amdgcn_s_barrier()
; #define PG8_SCHED __builtin_amdgcn_sched_barrier(0)
; template <class Epi, class Sched, bool ALIGN_EPI = false, bool SP2 = false>
; __device__ __forceinline__ void gemm_phase(PG8_LAS unsigned char* lds, const Gemm g, const Sched& S, const Epi& E) {
;     ...
;         for (int t = 0; t < nt; t += 2) {
;             const bool last = (t == nt - 2);
;             const char* a1 = cA + (size_t)(t + 1) * kstep;
;             const char* a2 = last ? nA : cA + (size_t)(t + 2) * kstep; const char* b2 = last ? nB : cB + (size_t)(t + 2) * kstep;
;             const char* a3 = a2 + kstep; const char* b3 = b2 + kstep;
;             if (last && has_next) S.a_ready(nxt);
;             if constexpr (SP2) {
;             PG8_LDB(B0, 0, 0); PG8_LDB(B1, 0, 1); PG8_SCHED; PG8_LDA(At, 0, 0); PG8_STAGE(PG8_SA(1, 1), a1 + hstep, voffA);
;             PG8_WAIT_V(8); PG8_WAIT_L(0); PG8_BAR; PG8_MMA(0, 0, At, B0); PG8_MMA(0, 1, At, B1); PG8_BAR; PG8_SCHED;
;             PG8_LDA(At, 0, 1); PG8_STAGE(PG8_SB(0, 0), b2, voffB); PG8_STAGE(PG8_SB(0, 1), b2 + hstep, voffB); PG8_STAGE(PG8_SA(0, 0), a2, voffA);
.LBB0_1340:
	v_add_u32_e32 v148, s55, v201
	v_add_u32_e32 v190, s56, v201
	ds_read_b128 v[136:139], v148
	ds_read_b128 v[140:143], v148 offset:1024
	ds_read_b128 v[144:147], v148 offset:2048
	ds_read_b128 v[148:151], v148 offset:3072
	ds_read_b128 v[152:155], v190
	ds_read_b128 v[182:185], v190 offset:1024
	ds_read_b128 v[186:189], v190 offset:2048
	ds_read_b128 v[190:193], v190 offset:3072
	s_cmp_eq_u32 s48, s12
	v_lshl_add_u64 v[194:195], v[134:135], 0, s[22:23]
	s_cselect_b64 vcc, -1, 0
	s_add_i32 s12, s12, 2
	v_cndmask_b32_e32 v199, v195, v179, vcc
	v_cndmask_b32_e32 v198, v194, v178, vcc
	v_cndmask_b32_e32 v215, v133, v181, vcc
	v_cndmask_b32_e32 v214, v132, v180, vcc
	s_mov_b32 m0, s57
	v_lshl_add_u64 v[236:237], v[134:135], 0, v[174:175]
	ds_read_b128 v[194:197], v203
	ds_read_b128 v[206:209], v203 offset:1024
	ds_read_b128 v[210:213], v203 offset:2048
	ds_read_b128 v[216:219], v203 offset:3072
	ds_read_b128 v[220:223], v203 offset:4096
	ds_read_b128 v[224:227], v203 offset:5120
	ds_read_b128 v[228:231], v203 offset:6144
	ds_read_b128 v[232:235], v203 offset:7168
	global_load_lds_dwordx4 v[236:237], off
	v_lshl_add_u64 v[236:237], v[134:135], 0, v[172:173]
	s_mov_b32 m0, s58
	s_nop 0
	global_load_lds_dwordx4 v[236:237], off
	s_waitcnt vmcnt(8)
	s_waitcnt lgkmcnt(0)
	s_barrier
	s_setprio 1
	s_waitcnt lgkmcnt(0)
	v_mfma_f32_16x16x32_bf16 v[124:127], v[136:139], v[194:197], v[124:127]
	v_mfma_f32_16x16x32_bf16 v[128:131], v[144:147], v[194:197], v[128:131]
	v_mfma_f32_16x16x32_bf16 v[112:115], v[136:139], v[210:213], v[112:115]
	v_mfma_f32_16x16x32_bf16 v[108:111], v[144:147], v[210:213], v[108:111]
	v_mfma_f32_16x16x32_bf16 v[96:99], v[136:139], v[220:223], v[96:99]
	v_mfma_f32_16x16x32_bf16 v[92:95], v[144:147], v[220:223], v[92:95]
	v_mfma_f32_16x16x32_bf16 v[80:83], v[136:139], v[228:231], v[80:83]
	v_mfma_f32_16x16x32_bf16 v[76:79], v[144:147], v[228:231], v[76:79]
	v_mfma_f32_16x16x32_bf16 v[124:127], v[140:143], v[206:209], v[124:127]
	v_mfma_f32_16x16x32_bf16 v[128:131], v[148:151], v[206:209], v[128:131]
	v_mfma_f32_16x16x32_bf16 v[112:115], v[140:143], v[216:219], v[112:115]
	v_mfma_f32_16x16x32_bf16 v[108:111], v[148:151], v[216:219], v[108:111]
	v_mfma_f32_16x16x32_bf16 v[96:99], v[140:143], v[224:227], v[96:99]
	v_mfma_f32_16x16x32_bf16 v[92:95], v[148:151], v[224:227], v[92:95]
	v_mfma_f32_16x16x32_bf16 v[80:83], v[140:143], v[232:235], v[80:83]
	v_mfma_f32_16x16x32_bf16 v[76:79], v[148:151], v[232:235], v[76:79]
	v_mfma_f32_16x16x32_bf16 v[120:123], v[152:155], v[194:197], v[120:123]
	v_mfma_f32_16x16x32_bf16 v[116:119], v[186:189], v[194:197], v[116:119]
	v_mfma_f32_16x16x32_bf16 v[104:107], v[152:155], v[210:213], v[104:107]
	v_mfma_f32_16x16x32_bf16 v[100:103], v[186:189], v[210:213], v[100:103]
	v_mfma_f32_16x16x32_bf16 v[88:91], v[152:155], v[220:223], v[88:91]
	v_mfma_f32_16x16x32_bf16 v[84:87], v[186:189], v[220:223], v[84:87]
	v_mfma_f32_16x16x32_bf16 v[72:75], v[152:155], v[228:231], v[72:75]
	v_mfma_f32_16x16x32_bf16 v[68:71], v[186:189], v[228:231], v[68:71]
	v_mfma_f32_16x16x32_bf16 v[120:123], v[182:185], v[206:209], v[120:123]
	v_mfma_f32_16x16x32_bf16 v[116:119], v[190:193], v[206:209], v[116:119]
	v_mfma_f32_16x16x32_bf16 v[104:107], v[182:185], v[216:219], v[104:107]
	v_mfma_f32_16x16x32_bf16 v[100:103], v[190:193], v[216:219], v[100:103]
	v_mfma_f32_16x16x32_bf16 v[88:91], v[182:185], v[224:227], v[88:91]
	v_mfma_f32_16x16x32_bf16 v[84:87], v[190:193], v[224:227], v[84:87]
	v_mfma_f32_16x16x32_bf16 v[72:75], v[182:185], v[232:235], v[72:75]
	v_mfma_f32_16x16x32_bf16 v[68:71], v[190:193], v[232:235], v[68:71]
	s_setprio 0
	s_barrier
	s_mov_b32 m0, s59
	v_lshl_add_u64 v[236:237], v[214:215], 0, v[166:167]
	ds_read_b128 v[194:197], v203 offset:16384
	ds_read_b128 v[206:209], v203 offset:17408
	ds_read_b128 v[210:213], v203 offset:18432
	ds_read_b128 v[216:219], v203 offset:19456
	ds_read_b128 v[220:223], v203 offset:20480
	ds_read_b128 v[224:227], v203 offset:21504
	ds_read_b128 v[228:231], v203 offset:22528
	ds_read_b128 v[232:235], v203 offset:23552
	global_load_lds_dwordx4 v[236:237], off
	v_lshl_add_u64 v[238:239], v[214:215], 0, v[170:171]
	s_mov_b32 m0, s60
	v_lshl_add_u64 v[214:215], v[214:215], 0, s[14:15]
	s_add_i32 s13, s56, s30
	global_load_lds_dwordx4 v[238:239], off
	v_lshl_add_u64 v[240:241], v[214:215], 0, v[166:167]
	s_mov_b32 m0, s13
	v_lshl_add_u64 v[214:215], v[214:215], 0, v[170:171]
	global_load_lds_dwordx4 v[240:241], off
	s_add_i32 m0, s13, 0x2000
	v_lshl_add_u64 v[242:243], v[198:199], 0, v[164:165]
	global_load_lds_dwordx4 v[214:215], off
	s_mov_b32 m0, s31
	v_lshl_add_u64 v[244:245], v[198:199], 0, v[168:169]
	global_load_lds_dwordx4 v[242:243], off
	s_mov_b32 m0, s34
	s_nop 0
	global_load_lds_dwordx4 v[244:245], off
	s_waitcnt vmcnt(8)
	s_waitcnt lgkmcnt(0)
	s_barrier
; #define PG8_STAGE(bufoff, gbase, voff) do { _Pragma("unroll") for (int _i = 0; _i < 2; ++_i) \
;         __builtin_amdgcn_global_load_lds((const unsigned*)((const char*)(gbase) + (voff)[_i]), (PG8_LAS unsigned*)(lds + (bufoff) + ldsw + _i * 8192), 16, 0, 0); } while (0)
; #define PG8_LDA(dst, b, h) do { _Pragma("unroll") for (int m = 0; m < 4; ++m) _Pragma("unroll") for (int k = 0; k < 2; ++k) dst[m][k] = *(const PG8_LAS bf16x8*)(lds + PG8_SA(b, h) + aoff + m * 2048 + k * 1024); } while (0)
; #define PG8_LDB(dst, b, h) do { _Pragma("unroll") for (int n = 0; n < 2; ++n) _Pragma("unroll") for (int k = 0; k < 2; ++k) dst[n][k] = *(const PG8_LAS bf16x8*)(lds + PG8_SB(b, h) + boff + n * 2048 + k * 1024); } while (0)
; #define PG8_MMA(ai, bj, At, Bt) do { __builtin_amdgcn_s_setprio(1); _Pragma("unroll") for (int m = 0; m < 4; ++m) _Pragma("unroll") for (int n = 0; n < 2; ++n) _Pragma("unroll") for (int k = 0; k < 2; ++k) \
;         acc[ai][bj][m][n] = __builtin_amdgcn_mfma_f32_16x16x32_bf16(Bt[n][k], At[m][k], acc[ai][bj][m][n], 0, 0, 0); __builtin_amdgcn_s_setprio(0); } while (0)
; #define PG8_WAIT_V(n) asm volatile("s_waitcnt vmcnt(" #n ")" ::: "memory")
; #define PG8_WAIT_L(n) asm volatile("s_waitcnt lgkmcnt(" #n ")" ::: "memory")
; #define PG8_BAR __builtin_amdgcn_s_barrier()
; #define PG8_SCHED __builtin_amdgcn_sched_barrier(0)
; template <class Epi, class Sched, bool ALIGN_EPI = false, bool SP2 = false>
; __device__ __forceinline__ void gemm_phase(PG8_LAS unsigned char* lds, const Gemm g, const Sched& S, const Epi& E) {
;     ...
;             PG8_WAIT_V(8); PG8_WAIT_L(0); PG8_BAR; PG8_MMA(1, 0, At, B0); PG8_MMA(1, 1, At, B1); PG8_BAR; PG8_SCHED;
;             PG8_LDB(B0, 1, 0); PG8_LDB(B1, 1, 1); PG8_SCHED; PG8_LDA(At, 1, 0); PG8_STAGE(PG8_SA(0, 1), a2 + hstep, voffA);
;             PG8_WAIT_V(8); PG8_WAIT_L(0); PG8_BAR; PG8_MMA(0, 0, At, B0); PG8_MMA(0, 1, At, B1); PG8_BAR; PG8_SCHED;
	s_setprio 1
	s_waitcnt lgkmcnt(0)
	v_mfma_f32_16x16x32_bf16 v[64:67], v[136:139], v[194:197], v[64:67]
	v_mfma_f32_16x16x32_bf16 v[60:63], v[144:147], v[194:197], v[60:63]
	v_mfma_f32_16x16x32_bf16 v[48:51], v[136:139], v[210:213], v[48:51]
	v_mfma_f32_16x16x32_bf16 v[44:47], v[144:147], v[210:213], v[44:47]
	v_mfma_f32_16x16x32_bf16 v[32:35], v[136:139], v[220:223], v[32:35]
	v_mfma_f32_16x16x32_bf16 v[28:31], v[144:147], v[220:223], v[28:31]
	v_mfma_f32_16x16x32_bf16 v[16:19], v[136:139], v[228:231], v[16:19]
	v_mfma_f32_16x16x32_bf16 v[12:15], v[144:147], v[228:231], v[12:15]
	v_mfma_f32_16x16x32_bf16 v[64:67], v[140:143], v[206:209], v[64:67]
	v_mfma_f32_16x16x32_bf16 v[60:63], v[148:151], v[206:209], v[60:63]
	v_mfma_f32_16x16x32_bf16 v[48:51], v[140:143], v[216:219], v[48:51]
	v_mfma_f32_16x16x32_bf16 v[44:47], v[148:151], v[216:219], v[44:47]
	v_mfma_f32_16x16x32_bf16 v[32:35], v[140:143], v[224:227], v[32:35]
	v_mfma_f32_16x16x32_bf16 v[28:31], v[148:151], v[224:227], v[28:31]
	v_mfma_f32_16x16x32_bf16 v[16:19], v[140:143], v[232:235], v[16:19]
	v_mfma_f32_16x16x32_bf16 v[12:15], v[148:151], v[232:235], v[12:15]
	v_mfma_f32_16x16x32_bf16 v[56:59], v[152:155], v[194:197], v[56:59]
	v_mfma_f32_16x16x32_bf16 v[52:55], v[186:189], v[194:197], v[52:55]
	v_mfma_f32_16x16x32_bf16 v[40:43], v[152:155], v[210:213], v[40:43]
	v_mfma_f32_16x16x32_bf16 v[36:39], v[186:189], v[210:213], v[36:39]
	v_mfma_f32_16x16x32_bf16 v[24:27], v[152:155], v[220:223], v[24:27]
	v_mfma_f32_16x16x32_bf16 v[20:23], v[186:189], v[220:223], v[20:23]
	v_mfma_f32_16x16x32_bf16 v[8:11], v[152:155], v[228:231], v[8:11]
	v_mfma_f32_16x16x32_bf16 v[4:7], v[186:189], v[228:231], v[4:7]
	v_mfma_f32_16x16x32_bf16 v[56:59], v[182:185], v[206:209], v[56:59]
	v_mfma_f32_16x16x32_bf16 v[52:55], v[190:193], v[206:209], v[52:55]
	v_mfma_f32_16x16x32_bf16 v[40:43], v[182:185], v[216:219], v[40:43]
	v_mfma_f32_16x16x32_bf16 v[36:39], v[190:193], v[216:219], v[36:39]
	v_mfma_f32_16x16x32_bf16 v[24:27], v[182:185], v[224:227], v[24:27]
	v_mfma_f32_16x16x32_bf16 v[20:23], v[190:193], v[224:227], v[20:23]
	v_mfma_f32_16x16x32_bf16 v[8:11], v[182:185], v[232:235], v[8:11]
	v_mfma_f32_16x16x32_bf16 v[4:7], v[190:193], v[232:235], v[4:7]
	s_setprio 0
	s_barrier
	s_add_i32 s13, 0, 0x18000
	s_add_i32 s29, 0, 0x1c000
	v_add_u32_e32 v148, s13, v201
	v_add_u32_e32 v190, s29, v201
	ds_read_b128 v[136:139], v148
	ds_read_b128 v[140:143], v148 offset:1024
	ds_read_b128 v[144:147], v148 offset:2048
	ds_read_b128 v[148:151], v148 offset:3072
	ds_read_b128 v[152:155], v190
	ds_read_b128 v[182:185], v190 offset:1024
	ds_read_b128 v[186:189], v190 offset:2048
	ds_read_b128 v[190:193], v190 offset:3072
	v_lshl_add_u64 v[198:199], v[198:199], 0, s[14:15]
	s_mov_b32 m0, s35
	v_lshl_add_u64 v[246:247], v[198:199], 0, v[164:165]
	ds_read_b128 v[194:197], v203 offset:32768
	ds_read_b128 v[206:209], v203 offset:33792
	ds_read_b128 v[210:213], v203 offset:34816
	ds_read_b128 v[216:219], v203 offset:35840
	ds_read_b128 v[220:223], v203 offset:36864
	ds_read_b128 v[224:227], v203 offset:37888
	ds_read_b128 v[228:231], v203 offset:38912
	ds_read_b128 v[232:235], v203 offset:39936
	global_load_lds_dwordx4 v[246:247], off
	v_lshl_add_u64 v[198:199], v[198:199], 0, v[168:169]
	s_mov_b32 m0, s36
	s_nop 0
	global_load_lds_dwordx4 v[198:199], off
	s_waitcnt vmcnt(8)
	s_waitcnt lgkmcnt(0)
	s_barrier
	s_setprio 1
	s_waitcnt lgkmcnt(0)
	v_mfma_f32_16x16x32_bf16 v[124:127], v[136:139], v[194:197], v[124:127]
	v_mfma_f32_16x16x32_bf16 v[128:131], v[144:147], v[194:197], v[128:131]
	v_mfma_f32_16x16x32_bf16 v[112:115], v[136:139], v[210:213], v[112:115]
	v_mfma_f32_16x16x32_bf16 v[108:111], v[144:147], v[210:213], v[108:111]
	v_mfma_f32_16x16x32_bf16 v[96:99], v[136:139], v[220:223], v[96:99]
	v_mfma_f32_16x16x32_bf16 v[92:95], v[144:147], v[220:223], v[92:95]
	v_mfma_f32_16x16x32_bf16 v[80:83], v[136:139], v[228:231], v[80:83]
	v_mfma_f32_16x16x32_bf16 v[76:79], v[144:147], v[228:231], v[76:79]
	v_mfma_f32_16x16x32_bf16 v[124:127], v[140:143], v[206:209], v[124:127]
	v_mfma_f32_16x16x32_bf16 v[128:131], v[148:151], v[206:209], v[128:131]
	v_mfma_f32_16x16x32_bf16 v[112:115], v[140:143], v[216:219], v[112:115]
	v_mfma_f32_16x16x32_bf16 v[108:111], v[148:151], v[216:219], v[108:111]
	v_mfma_f32_16x16x32_bf16 v[96:99], v[140:143], v[224:227], v[96:99]
	v_mfma_f32_16x16x32_bf16 v[92:95], v[148:151], v[224:227], v[92:95]
	v_mfma_f32_16x16x32_bf16 v[80:83], v[140:143], v[232:235], v[80:83]
	v_mfma_f32_16x16x32_bf16 v[76:79], v[148:151], v[232:235], v[76:79]
	v_mfma_f32_16x16x32_bf16 v[120:123], v[152:155], v[194:197], v[120:123]
	v_mfma_f32_16x16x32_bf16 v[116:119], v[186:189], v[194:197], v[116:119]
	v_mfma_f32_16x16x32_bf16 v[104:107], v[152:155], v[210:213], v[104:107]
	v_mfma_f32_16x16x32_bf16 v[100:103], v[186:189], v[210:213], v[100:103]
	v_mfma_f32_16x16x32_bf16 v[88:91], v[152:155], v[220:223], v[88:91]
	v_mfma_f32_16x16x32_bf16 v[84:87], v[186:189], v[220:223], v[84:87]
	v_mfma_f32_16x16x32_bf16 v[72:75], v[152:155], v[228:231], v[72:75]
	v_mfma_f32_16x16x32_bf16 v[68:71], v[186:189], v[228:231], v[68:71]
	v_mfma_f32_16x16x32_bf16 v[120:123], v[182:185], v[206:209], v[120:123]
	v_mfma_f32_16x16x32_bf16 v[116:119], v[190:193], v[206:209], v[116:119]
	v_mfma_f32_16x16x32_bf16 v[104:107], v[182:185], v[216:219], v[104:107]
	v_mfma_f32_16x16x32_bf16 v[100:103], v[190:193], v[216:219], v[100:103]
	v_mfma_f32_16x16x32_bf16 v[88:91], v[182:185], v[224:227], v[88:91]
	v_mfma_f32_16x16x32_bf16 v[84:87], v[190:193], v[224:227], v[84:87]
	v_mfma_f32_16x16x32_bf16 v[72:75], v[182:185], v[232:235], v[72:75]
	v_mfma_f32_16x16x32_bf16 v[68:71], v[190:193], v[232:235], v[68:71]
	s_setprio 0
	s_barrier
; #define PG8_STAGE(bufoff, gbase, voff) do { _Pragma("unroll") for (int _i = 0; _i < 2; ++_i) \
;         __builtin_amdgcn_global_load_lds((const unsigned*)((const char*)(gbase) + (voff)[_i]), (PG8_LAS unsigned*)(lds + (bufoff) + ldsw + _i * 8192), 16, 0, 0); } while (0)
; #define PG8_LDA(dst, b, h) do { _Pragma("unroll") for (int m = 0; m < 4; ++m) _Pragma("unroll") for (int k = 0; k < 2; ++k) dst[m][k] = *(const PG8_LAS bf16x8*)(lds + PG8_SA(b, h) + aoff + m * 2048 + k * 1024); } while (0)
; #define PG8_MMA(ai, bj, At, Bt) do { __builtin_amdgcn_s_setprio(1); _Pragma("unroll") for (int m = 0; m < 4; ++m) _Pragma("unroll") for (int n = 0; n < 2; ++n) _Pragma("unroll") for (int k = 0; k < 2; ++k) \
;         acc[ai][bj][m][n] = __builtin_amdgcn_mfma_f32_16x16x32_bf16(Bt[n][k], At[m][k], acc[ai][bj][m][n], 0, 0, 0); __builtin_amdgcn_s_setprio(0); } while (0)
; #define PG8_WAIT_V(n) asm volatile("s_waitcnt vmcnt(" #n ")" ::: "memory")
; #define PG8_WAIT_L(n) asm volatile("s_waitcnt lgkmcnt(" #n ")" ::: "memory")
; #define PG8_BAR __builtin_amdgcn_s_barrier()
; #define PG8_SCHED __builtin_amdgcn_sched_barrier(0)
; template <class Epi, class Sched, bool ALIGN_EPI = false, bool SP2 = false>
; __device__ __forceinline__ void gemm_phase(PG8_LAS unsigned char* lds, const Gemm g, const Sched& S, const Epi& E) {
;     ...
;             PG8_LDA(At, 1, 1); PG8_STAGE(PG8_SB(1, 0), b3, voffB); PG8_STAGE(PG8_SB(1, 1), b3 + hstep, voffB); PG8_STAGE(PG8_SA(1, 0), a3, voffA);
;             PG8_WAIT_V(8); PG8_WAIT_L(0); PG8_BAR; PG8_MMA(1, 0, At, B0); PG8_MMA(1, 1, At, B1); PG8_BAR; PG8_SCHED;
	s_add_i32 s13, s13, s30
	v_lshl_add_u64 v[198:199], v[236:237], 0, s[22:23]
	s_mov_b32 m0, s13
	ds_read_b128 v[194:197], v203 offset:49152
	ds_read_b128 v[206:209], v203 offset:50176
	ds_read_b128 v[210:213], v203 offset:51200
	ds_read_b128 v[216:219], v203 offset:52224
	ds_read_b128 v[220:223], v203 offset:53248
	ds_read_b128 v[224:227], v203 offset:54272
	ds_read_b128 v[228:231], v203 offset:55296
	ds_read_b128 v[232:235], v203 offset:56320
	global_load_lds_dwordx4 v[198:199], off
	v_lshl_add_u64 v[198:199], v[238:239], 0, s[22:23]
	s_add_i32 m0, s13, 0x2000
	s_add_i32 s13, s29, s30
	global_load_lds_dwordx4 v[198:199], off
	v_lshl_add_u64 v[198:199], v[240:241], 0, s[22:23]
	s_mov_b32 m0, s13
	s_nop 0
	global_load_lds_dwordx4 v[198:199], off
	v_lshl_add_u64 v[198:199], v[214:215], 0, s[22:23]
	s_add_i32 m0, s13, 0x2000
	s_nop 0
	global_load_lds_dwordx4 v[198:199], off
	v_lshl_add_u64 v[198:199], v[242:243], 0, s[22:23]
	s_mov_b32 m0, s37
	s_nop 0
	global_load_lds_dwordx4 v[198:199], off
	v_lshl_add_u64 v[198:199], v[244:245], 0, s[22:23]
	s_mov_b32 m0, s41
	s_nop 0
	global_load_lds_dwordx4 v[198:199], off
	s_waitcnt vmcnt(8)
	s_waitcnt lgkmcnt(0)
	s_barrier
	s_setprio 1
	s_waitcnt lgkmcnt(0)
	v_mfma_f32_16x16x32_bf16 v[64:67], v[136:139], v[194:197], v[64:67]
	v_mfma_f32_16x16x32_bf16 v[60:63], v[144:147], v[194:197], v[60:63]
	v_mfma_f32_16x16x32_bf16 v[48:51], v[136:139], v[210:213], v[48:51]
	v_mfma_f32_16x16x32_bf16 v[44:47], v[144:147], v[210:213], v[44:47]
	v_mfma_f32_16x16x32_bf16 v[32:35], v[136:139], v[220:223], v[32:35]
	v_mfma_f32_16x16x32_bf16 v[28:31], v[144:147], v[220:223], v[28:31]
	v_mfma_f32_16x16x32_bf16 v[16:19], v[136:139], v[228:231], v[16:19]
	v_mfma_f32_16x16x32_bf16 v[12:15], v[144:147], v[228:231], v[12:15]
	v_mfma_f32_16x16x32_bf16 v[64:67], v[140:143], v[206:209], v[64:67]
	v_mfma_f32_16x16x32_bf16 v[60:63], v[148:151], v[206:209], v[60:63]
	v_mfma_f32_16x16x32_bf16 v[48:51], v[140:143], v[216:219], v[48:51]
	v_mfma_f32_16x16x32_bf16 v[44:47], v[148:151], v[216:219], v[44:47]
	v_mfma_f32_16x16x32_bf16 v[32:35], v[140:143], v[224:227], v[32:35]
	v_mfma_f32_16x16x32_bf16 v[28:31], v[148:151], v[224:227], v[28:31]
	v_mfma_f32_16x16x32_bf16 v[16:19], v[140:143], v[232:235], v[16:19]
	v_mfma_f32_16x16x32_bf16 v[12:15], v[148:151], v[232:235], v[12:15]
	v_mfma_f32_16x16x32_bf16 v[56:59], v[152:155], v[194:197], v[56:59]
	v_mfma_f32_16x16x32_bf16 v[52:55], v[186:189], v[194:197], v[52:55]
	v_mfma_f32_16x16x32_bf16 v[40:43], v[152:155], v[210:213], v[40:43]
	v_mfma_f32_16x16x32_bf16 v[36:39], v[186:189], v[210:213], v[36:39]
	v_mfma_f32_16x16x32_bf16 v[24:27], v[152:155], v[220:223], v[24:27]
	v_mfma_f32_16x16x32_bf16 v[20:23], v[186:189], v[220:223], v[20:23]
	v_mfma_f32_16x16x32_bf16 v[8:11], v[152:155], v[228:231], v[8:11]
	v_mfma_f32_16x16x32_bf16 v[4:7], v[186:189], v[228:231], v[4:7]
	v_mfma_f32_16x16x32_bf16 v[56:59], v[182:185], v[206:209], v[56:59]
	v_mfma_f32_16x16x32_bf16 v[52:55], v[190:193], v[206:209], v[52:55]
	v_mfma_f32_16x16x32_bf16 v[40:43], v[182:185], v[216:219], v[40:43]
	v_mfma_f32_16x16x32_bf16 v[36:39], v[190:193], v[216:219], v[36:39]
	v_mfma_f32_16x16x32_bf16 v[24:27], v[182:185], v[224:227], v[24:27]
	v_mfma_f32_16x16x32_bf16 v[20:23], v[190:193], v[224:227], v[20:23]
	v_mfma_f32_16x16x32_bf16 v[8:11], v[182:185], v[232:235], v[8:11]
	v_mfma_f32_16x16x32_bf16 v[4:7], v[190:193], v[232:235], v[4:7]
	s_setprio 0
	s_barrier
	v_lshl_add_u64 v[132:133], v[132:133], 0, s[26:27]
	s_cmp_ge_i32 s12, s47
	v_lshl_add_u64 v[134:135], v[134:135], 0, s[26:27]
	s_cbranch_scc0 .LBB0_1340

; #define PG8_STAGE(bufoff, gbase, voff) do { _Pragma("unroll") for (int _i = 0; _i < 2; ++_i) \
;         __builtin_amdgcn_global_load_lds((const unsigned*)((const char*)(gbase) + (voff)[_i]), (PG8_LAS unsigned*)(lds + (bufoff) + ldsw + _i * 8192), 16, 0, 0); } while (0)
; #define PG8_LDA(dst, b, h) do { _Pragma("unroll") for (int m = 0; m < 4; ++m) _Pragma("unroll") for (int k = 0; k < 2; ++k) dst[m][k] = *(const PG8_LAS bf16x8*)(lds + PG8_SA(b, h) + aoff + m * 2048 + k * 1024); } while (0)
; #define PG8_LDB(dst, b, h) do { _Pragma("unroll") for (int n = 0; n < 2; ++n) _Pragma("unroll") for (int k = 0; k < 2; ++k) dst[n][k] = *(const PG8_LAS bf16x8*)(lds + PG8_SB(b, h) + boff + n * 2048 + k * 1024); } while (0)
; #define PG8_MMA(ai, bj, At, Bt) do { __builtin_amdgcn_s_setprio(1); _Pragma("unroll") for (int m = 0; m < 4; ++m) _Pragma("unroll") for (int n = 0; n < 2; ++n) _Pragma("unroll") for (int k = 0; k < 2; ++k) \
;         acc[ai][bj][m][n] = __builtin_amdgcn_mfma_f32_16x16x32_bf16(Bt[n][k], At[m][k], acc[ai][bj][m][n], 0, 0, 0); __builtin_amdgcn_s_setprio(0); } while (0)
; #define PG8_WAIT_V(n) asm volatile("s_waitcnt vmcnt(" #n ")" ::: "memory")
; #define PG8_WAIT_L(n) asm volatile("s_waitcnt lgkmcnt(" #n ")" ::: "memory")
; #define PG8_BAR __builtin_amdgcn_s_barrier()
; #define PG8_SCHED __builtin_amdgcn_sched_barrier(0)
; template <class Epi, class Sched, bool ALIGN_EPI = false, bool SP2 = false>
; __device__ __forceinline__ void gemm_phase(PG8_LAS unsigned char* lds, const Gemm g, const Sched& S, const Epi& E) {
;     ...
;         for (int t = 0; t < nt; t += 2) {
;             const bool last = (t == nt - 2);
;             const char* a1 = cA + (size_t)(t + 1) * kstep;
;             const char* a2 = last ? nA : cA + (size_t)(t + 2) * kstep; const char* b2 = last ? nB : cB + (size_t)(t + 2) * kstep;
;             const char* a3 = a2 + kstep; const char* b3 = b2 + kstep;
;             if (last && has_next) S.a_ready(nxt);
;             if constexpr (SP2) {
;             PG8_LDB(B0, 0, 0); PG8_LDB(B1, 0, 1); PG8_SCHED; PG8_LDA(At, 0, 0); PG8_STAGE(PG8_SA(1, 1), a1 + hstep, voffA);
;             PG8_WAIT_V(8); PG8_WAIT_L(0); PG8_BAR; PG8_MMA(0, 0, At, B0); PG8_MMA(0, 1, At, B1); PG8_BAR; PG8_SCHED;
;             PG8_LDA(At, 0, 1); PG8_STAGE(PG8_SB(0, 0), b2, voffB); PG8_STAGE(PG8_SB(0, 1), b2 + hstep, voffB); PG8_STAGE(PG8_SA(0, 0), a2, voffA);
.LBB0_1423:
	v_add_u32_e32 v152, s81, v169
	v_add_u32_e32 v165, s82, v169
	ds_read_b128 v[132:135], v152
	ds_read_b128 v[136:139], v152 offset:1024
	ds_read_b128 v[174:177], v152 offset:2048
	ds_read_b128 v[178:181], v152 offset:3072
	ds_read_b128 v[182:185], v165
	ds_read_b128 v[186:189], v165 offset:1024
	ds_read_b128 v[190:193], v165 offset:2048
	ds_read_b128 v[194:197], v165 offset:3072
	s_cmp_eq_u32 s74, s10
	v_lshl_add_u64 v[198:199], v[130:131], 0, s[26:27]
	s_cselect_b64 vcc, -1, 0
	s_add_i32 s10, s10, 2
	v_cndmask_b32_e32 v211, v199, v171, vcc
	v_cndmask_b32_e32 v210, v198, v170, vcc
	v_cndmask_b32_e32 v215, v129, v173, vcc
	v_cndmask_b32_e32 v214, v128, v172, vcc
	v_lshl_add_u64 v[240:241], v[130:131], 0, v[160:161]
	s_add_i32 m0, s47, 0xc000
	ds_read_b128 v[198:201], v213
	ds_read_b128 v[202:205], v213 offset:1024
	ds_read_b128 v[206:209], v213 offset:2048
	ds_read_b128 v[220:223], v213 offset:3072
	ds_read_b128 v[224:227], v213 offset:4096
	ds_read_b128 v[228:231], v213 offset:5120
	ds_read_b128 v[232:235], v213 offset:6144
	ds_read_b128 v[236:239], v213 offset:7168
	global_load_lds_dwordx4 v[240:241], off
	v_lshl_add_u64 v[240:241], v[130:131], 0, v[158:159]
	s_add_i32 m0, s47, 0xe000
	s_nop 0
	global_load_lds_dwordx4 v[240:241], off
	s_waitcnt vmcnt(8)
	s_waitcnt lgkmcnt(0)
	s_barrier
	s_setprio 1
	s_waitcnt lgkmcnt(0)
	v_mfma_f32_16x16x32_bf16 v[124:127], v[132:135], v[198:201], v[124:127]
	v_mfma_f32_16x16x32_bf16 v[120:123], v[174:177], v[198:201], v[120:123]
	v_mfma_f32_16x16x32_bf16 v[108:111], v[132:135], v[206:209], v[108:111]
	v_mfma_f32_16x16x32_bf16 v[104:107], v[174:177], v[206:209], v[104:107]
	v_mfma_f32_16x16x32_bf16 v[92:95], v[132:135], v[224:227], v[92:95]
	v_mfma_f32_16x16x32_bf16 v[88:91], v[174:177], v[224:227], v[88:91]
	v_mfma_f32_16x16x32_bf16 v[76:79], v[132:135], v[232:235], v[76:79]
	v_mfma_f32_16x16x32_bf16 v[72:75], v[174:177], v[232:235], v[72:75]
	v_mfma_f32_16x16x32_bf16 v[124:127], v[136:139], v[202:205], v[124:127]
	v_mfma_f32_16x16x32_bf16 v[120:123], v[178:181], v[202:205], v[120:123]
	v_mfma_f32_16x16x32_bf16 v[108:111], v[136:139], v[220:223], v[108:111]
	v_mfma_f32_16x16x32_bf16 v[104:107], v[178:181], v[220:223], v[104:107]
	v_mfma_f32_16x16x32_bf16 v[92:95], v[136:139], v[228:231], v[92:95]
	v_mfma_f32_16x16x32_bf16 v[88:91], v[178:181], v[228:231], v[88:91]
	v_mfma_f32_16x16x32_bf16 v[76:79], v[136:139], v[236:239], v[76:79]
	v_mfma_f32_16x16x32_bf16 v[72:75], v[178:181], v[236:239], v[72:75]
	v_mfma_f32_16x16x32_bf16 v[116:119], v[182:185], v[198:201], v[116:119]
	v_mfma_f32_16x16x32_bf16 v[112:115], v[190:193], v[198:201], v[112:115]
	v_mfma_f32_16x16x32_bf16 v[100:103], v[182:185], v[206:209], v[100:103]
	v_mfma_f32_16x16x32_bf16 v[96:99], v[190:193], v[206:209], v[96:99]
	v_mfma_f32_16x16x32_bf16 v[84:87], v[182:185], v[224:227], v[84:87]
	v_mfma_f32_16x16x32_bf16 v[80:83], v[190:193], v[224:227], v[80:83]
	v_mfma_f32_16x16x32_bf16 v[68:71], v[182:185], v[232:235], v[68:71]
	v_mfma_f32_16x16x32_bf16 v[64:67], v[190:193], v[232:235], v[64:67]
	v_mfma_f32_16x16x32_bf16 v[116:119], v[186:189], v[202:205], v[116:119]
	v_mfma_f32_16x16x32_bf16 v[112:115], v[194:197], v[202:205], v[112:115]
	v_mfma_f32_16x16x32_bf16 v[100:103], v[186:189], v[220:223], v[100:103]
	v_mfma_f32_16x16x32_bf16 v[96:99], v[194:197], v[220:223], v[96:99]
	v_mfma_f32_16x16x32_bf16 v[84:87], v[186:189], v[228:231], v[84:87]
	v_mfma_f32_16x16x32_bf16 v[80:83], v[194:197], v[228:231], v[80:83]
	v_mfma_f32_16x16x32_bf16 v[68:71], v[186:189], v[236:239], v[68:71]
	v_mfma_f32_16x16x32_bf16 v[64:67], v[194:197], v[236:239], v[64:67]
	s_setprio 0
	s_barrier
	s_add_i32 s11, s81, s41
	v_lshl_add_u64 v[240:241], v[214:215], 0, v[146:147]
	s_mov_b32 m0, s11
	ds_read_b128 v[198:201], v213 offset:16384
	ds_read_b128 v[202:205], v213 offset:17408
	ds_read_b128 v[206:209], v213 offset:18432
	ds_read_b128 v[220:223], v213 offset:19456
	ds_read_b128 v[224:227], v213 offset:20480
	ds_read_b128 v[228:231], v213 offset:21504
	ds_read_b128 v[232:235], v213 offset:22528
	ds_read_b128 v[236:239], v213 offset:23552
	global_load_lds_dwordx4 v[240:241], off
	v_lshl_add_u64 v[242:243], v[214:215], 0, v[150:151]
	s_add_i32 m0, s11, 0x2000
	v_lshl_add_u64 v[214:215], v[214:215], 0, s[18:19]
	s_add_i32 s11, s82, s41
	global_load_lds_dwordx4 v[242:243], off
	v_lshl_add_u64 v[244:245], v[214:215], 0, v[146:147]
	s_mov_b32 m0, s11
	v_lshl_add_u64 v[214:215], v[214:215], 0, v[150:151]
	global_load_lds_dwordx4 v[244:245], off
	s_add_i32 m0, s11, 0x2000
	v_lshl_add_u64 v[246:247], v[210:211], 0, v[144:145]
	global_load_lds_dwordx4 v[214:215], off
	s_mov_b32 m0, s47
	v_lshl_add_u64 v[248:249], v[210:211], 0, v[148:149]
	global_load_lds_dwordx4 v[246:247], off
	s_mov_b32 m0, s55
	s_nop 0
	global_load_lds_dwordx4 v[248:249], off
	s_waitcnt vmcnt(8)
	s_waitcnt lgkmcnt(0)
	s_barrier
; #define PG8_STAGE(bufoff, gbase, voff) do { _Pragma("unroll") for (int _i = 0; _i < 2; ++_i) \
;         __builtin_amdgcn_global_load_lds((const unsigned*)((const char*)(gbase) + (voff)[_i]), (PG8_LAS unsigned*)(lds + (bufoff) + ldsw + _i * 8192), 16, 0, 0); } while (0)
; #define PG8_LDA(dst, b, h) do { _Pragma("unroll") for (int m = 0; m < 4; ++m) _Pragma("unroll") for (int k = 0; k < 2; ++k) dst[m][k] = *(const PG8_LAS bf16x8*)(lds + PG8_SA(b, h) + aoff + m * 2048 + k * 1024); } while (0)
; #define PG8_LDB(dst, b, h) do { _Pragma("unroll") for (int n = 0; n < 2; ++n) _Pragma("unroll") for (int k = 0; k < 2; ++k) dst[n][k] = *(const PG8_LAS bf16x8*)(lds + PG8_SB(b, h) + boff + n * 2048 + k * 1024); } while (0)
; #define PG8_MMA(ai, bj, At, Bt) do { __builtin_amdgcn_s_setprio(1); _Pragma("unroll") for (int m = 0; m < 4; ++m) _Pragma("unroll") for (int n = 0; n < 2; ++n) _Pragma("unroll") for (int k = 0; k < 2; ++k) \
;         acc[ai][bj][m][n] = __builtin_amdgcn_mfma_f32_16x16x32_bf16(Bt[n][k], At[m][k], acc[ai][bj][m][n], 0, 0, 0); __builtin_amdgcn_s_setprio(0); } while (0)
; #define PG8_WAIT_V(n) asm volatile("s_waitcnt vmcnt(" #n ")" ::: "memory")
; #define PG8_WAIT_L(n) asm volatile("s_waitcnt lgkmcnt(" #n ")" ::: "memory")
; #define PG8_BAR __builtin_amdgcn_s_barrier()
; #define PG8_SCHED __builtin_amdgcn_sched_barrier(0)
; template <class Epi, class Sched, bool ALIGN_EPI = false, bool SP2 = false>
; __device__ __forceinline__ void gemm_phase(PG8_LAS unsigned char* lds, const Gemm g, const Sched& S, const Epi& E) {
;     ...
;             PG8_WAIT_V(8); PG8_WAIT_L(0); PG8_BAR; PG8_MMA(1, 0, At, B0); PG8_MMA(1, 1, At, B1); PG8_BAR; PG8_SCHED;
;             PG8_LDB(B0, 1, 0); PG8_LDB(B1, 1, 1); PG8_SCHED; PG8_LDA(At, 1, 0); PG8_STAGE(PG8_SA(0, 1), a2 + hstep, voffA);
;             PG8_WAIT_V(8); PG8_WAIT_L(0); PG8_BAR; PG8_MMA(0, 0, At, B0); PG8_MMA(0, 1, At, B1); PG8_BAR; PG8_SCHED;
	s_setprio 1
	s_waitcnt lgkmcnt(0)
	v_mfma_f32_16x16x32_bf16 v[60:63], v[132:135], v[198:201], v[60:63]
	v_mfma_f32_16x16x32_bf16 v[56:59], v[174:177], v[198:201], v[56:59]
	v_mfma_f32_16x16x32_bf16 v[44:47], v[132:135], v[206:209], v[44:47]
	v_mfma_f32_16x16x32_bf16 v[40:43], v[174:177], v[206:209], v[40:43]
	v_mfma_f32_16x16x32_bf16 v[28:31], v[132:135], v[224:227], v[28:31]
	v_mfma_f32_16x16x32_bf16 v[24:27], v[174:177], v[224:227], v[24:27]
	v_mfma_f32_16x16x32_bf16 v[12:15], v[132:135], v[232:235], v[12:15]
	v_mfma_f32_16x16x32_bf16 v[8:11], v[174:177], v[232:235], v[8:11]
	v_mfma_f32_16x16x32_bf16 v[60:63], v[136:139], v[202:205], v[60:63]
	v_mfma_f32_16x16x32_bf16 v[56:59], v[178:181], v[202:205], v[56:59]
	v_mfma_f32_16x16x32_bf16 v[44:47], v[136:139], v[220:223], v[44:47]
	v_mfma_f32_16x16x32_bf16 v[40:43], v[178:181], v[220:223], v[40:43]
	v_mfma_f32_16x16x32_bf16 v[28:31], v[136:139], v[228:231], v[28:31]
	v_mfma_f32_16x16x32_bf16 v[24:27], v[178:181], v[228:231], v[24:27]
	v_mfma_f32_16x16x32_bf16 v[12:15], v[136:139], v[236:239], v[12:15]
	v_mfma_f32_16x16x32_bf16 v[8:11], v[178:181], v[236:239], v[8:11]
	v_mfma_f32_16x16x32_bf16 v[52:55], v[182:185], v[198:201], v[52:55]
	v_mfma_f32_16x16x32_bf16 v[48:51], v[190:193], v[198:201], v[48:51]
	v_mfma_f32_16x16x32_bf16 v[36:39], v[182:185], v[206:209], v[36:39]
	v_mfma_f32_16x16x32_bf16 v[32:35], v[190:193], v[206:209], v[32:35]
	v_mfma_f32_16x16x32_bf16 v[20:23], v[182:185], v[224:227], v[20:23]
	v_mfma_f32_16x16x32_bf16 v[16:19], v[190:193], v[224:227], v[16:19]
	v_mfma_f32_16x16x32_bf16 v[4:7], v[182:185], v[232:235], v[4:7]
	v_mfma_f32_16x16x32_bf16 v[0:3], v[190:193], v[232:235], v[0:3]
	v_mfma_f32_16x16x32_bf16 v[52:55], v[186:189], v[202:205], v[52:55]
	v_mfma_f32_16x16x32_bf16 v[48:51], v[194:197], v[202:205], v[48:51]
	v_mfma_f32_16x16x32_bf16 v[36:39], v[186:189], v[220:223], v[36:39]
	v_mfma_f32_16x16x32_bf16 v[32:35], v[194:197], v[220:223], v[32:35]
	v_mfma_f32_16x16x32_bf16 v[20:23], v[186:189], v[228:231], v[20:23]
	v_mfma_f32_16x16x32_bf16 v[16:19], v[194:197], v[228:231], v[16:19]
	v_mfma_f32_16x16x32_bf16 v[4:7], v[186:189], v[236:239], v[4:7]
	v_mfma_f32_16x16x32_bf16 v[0:3], v[194:197], v[236:239], v[0:3]
	s_setprio 0
	s_barrier
	s_add_i32 s11, 0, 0x18000
	v_add_u32_e32 v152, s11, v169
	s_add_i32 s13, 0, 0x1c000
	ds_read_b128 v[132:135], v152
	ds_read_b128 v[136:139], v152 offset:1024
	ds_read_b128 v[174:177], v152 offset:2048
	ds_read_b128 v[178:181], v152 offset:3072
	v_add_u32_e32 v152, s13, v169
	ds_read_b128 v[182:185], v152
	ds_read_b128 v[186:189], v152 offset:1024
	ds_read_b128 v[190:193], v152 offset:2048
	ds_read_b128 v[194:197], v152 offset:3072
	v_lshl_add_u64 v[210:211], v[210:211], 0, s[18:19]
	s_mov_b32 m0, s57
	v_lshl_add_u64 v[250:251], v[210:211], 0, v[144:145]
	ds_read_b128 v[198:201], v213 offset:32768
	ds_read_b128 v[202:205], v213 offset:33792
	ds_read_b128 v[206:209], v213 offset:34816
	ds_read_b128 v[220:223], v213 offset:35840
	ds_read_b128 v[224:227], v213 offset:36864
	ds_read_b128 v[228:231], v213 offset:37888
	ds_read_b128 v[232:235], v213 offset:38912
	ds_read_b128 v[236:239], v213 offset:39936
	global_load_lds_dwordx4 v[250:251], off
	v_lshl_add_u64 v[210:211], v[210:211], 0, v[148:149]
	s_mov_b32 m0, s59
	s_nop 0
	global_load_lds_dwordx4 v[210:211], off
	s_waitcnt vmcnt(8)
	s_waitcnt lgkmcnt(0)
	s_barrier
	s_setprio 1
	s_waitcnt lgkmcnt(0)
	v_mfma_f32_16x16x32_bf16 v[124:127], v[132:135], v[198:201], v[124:127]
	v_mfma_f32_16x16x32_bf16 v[120:123], v[174:177], v[198:201], v[120:123]
	v_mfma_f32_16x16x32_bf16 v[108:111], v[132:135], v[206:209], v[108:111]
	v_mfma_f32_16x16x32_bf16 v[104:107], v[174:177], v[206:209], v[104:107]
	v_mfma_f32_16x16x32_bf16 v[92:95], v[132:135], v[224:227], v[92:95]
	v_mfma_f32_16x16x32_bf16 v[88:91], v[174:177], v[224:227], v[88:91]
	v_mfma_f32_16x16x32_bf16 v[76:79], v[132:135], v[232:235], v[76:79]
	v_mfma_f32_16x16x32_bf16 v[72:75], v[174:177], v[232:235], v[72:75]
	v_mfma_f32_16x16x32_bf16 v[124:127], v[136:139], v[202:205], v[124:127]
	v_mfma_f32_16x16x32_bf16 v[120:123], v[178:181], v[202:205], v[120:123]
	v_mfma_f32_16x16x32_bf16 v[108:111], v[136:139], v[220:223], v[108:111]
	v_mfma_f32_16x16x32_bf16 v[104:107], v[178:181], v[220:223], v[104:107]
	v_mfma_f32_16x16x32_bf16 v[92:95], v[136:139], v[228:231], v[92:95]
	v_mfma_f32_16x16x32_bf16 v[88:91], v[178:181], v[228:231], v[88:91]
	v_mfma_f32_16x16x32_bf16 v[76:79], v[136:139], v[236:239], v[76:79]
	v_mfma_f32_16x16x32_bf16 v[72:75], v[178:181], v[236:239], v[72:75]
	v_mfma_f32_16x16x32_bf16 v[116:119], v[182:185], v[198:201], v[116:119]
	v_mfma_f32_16x16x32_bf16 v[112:115], v[190:193], v[198:201], v[112:115]
	v_mfma_f32_16x16x32_bf16 v[100:103], v[182:185], v[206:209], v[100:103]
	v_mfma_f32_16x16x32_bf16 v[96:99], v[190:193], v[206:209], v[96:99]
	v_mfma_f32_16x16x32_bf16 v[84:87], v[182:185], v[224:227], v[84:87]
	v_mfma_f32_16x16x32_bf16 v[80:83], v[190:193], v[224:227], v[80:83]
	v_mfma_f32_16x16x32_bf16 v[68:71], v[182:185], v[232:235], v[68:71]
	v_mfma_f32_16x16x32_bf16 v[64:67], v[190:193], v[232:235], v[64:67]
	v_mfma_f32_16x16x32_bf16 v[116:119], v[186:189], v[202:205], v[116:119]
	v_mfma_f32_16x16x32_bf16 v[112:115], v[194:197], v[202:205], v[112:115]
	v_mfma_f32_16x16x32_bf16 v[100:103], v[186:189], v[220:223], v[100:103]
	v_mfma_f32_16x16x32_bf16 v[96:99], v[194:197], v[220:223], v[96:99]
	v_mfma_f32_16x16x32_bf16 v[84:87], v[186:189], v[228:231], v[84:87]
	v_mfma_f32_16x16x32_bf16 v[80:83], v[194:197], v[228:231], v[80:83]
	v_mfma_f32_16x16x32_bf16 v[68:71], v[186:189], v[236:239], v[68:71]
	v_mfma_f32_16x16x32_bf16 v[64:67], v[194:197], v[236:239], v[64:67]
	s_setprio 0
	s_barrier
; #define PG8_STAGE(bufoff, gbase, voff) do { _Pragma("unroll") for (int _i = 0; _i < 2; ++_i) \
;         __builtin_amdgcn_global_load_lds((const unsigned*)((const char*)(gbase) + (voff)[_i]), (PG8_LAS unsigned*)(lds + (bufoff) + ldsw + _i * 8192), 16, 0, 0); } while (0)
; #define PG8_LDA(dst, b, h) do { _Pragma("unroll") for (int m = 0; m < 4; ++m) _Pragma("unroll") for (int k = 0; k < 2; ++k) dst[m][k] = *(const PG8_LAS bf16x8*)(lds + PG8_SA(b, h) + aoff + m * 2048 + k * 1024); } while (0)
; #define PG8_MMA(ai, bj, At, Bt) do { __builtin_amdgcn_s_setprio(1); _Pragma("unroll") for (int m = 0; m < 4; ++m) _Pragma("unroll") for (int n = 0; n < 2; ++n) _Pragma("unroll") for (int k = 0; k < 2; ++k) \
;         acc[ai][bj][m][n] = __builtin_amdgcn_mfma_f32_16x16x32_bf16(Bt[n][k], At[m][k], acc[ai][bj][m][n], 0, 0, 0); __builtin_amdgcn_s_setprio(0); } while (0)
; #define PG8_WAIT_V(n) asm volatile("s_waitcnt vmcnt(" #n ")" ::: "memory")
; #define PG8_WAIT_L(n) asm volatile("s_waitcnt lgkmcnt(" #n ")" ::: "memory")
; #define PG8_BAR __builtin_amdgcn_s_barrier()
; #define PG8_SCHED __builtin_amdgcn_sched_barrier(0)
; template <class Epi, class Sched, bool ALIGN_EPI = false, bool SP2 = false>
; __device__ __forceinline__ void gemm_phase(PG8_LAS unsigned char* lds, const Gemm g, const Sched& S, const Epi& E) {
;     ...
;             PG8_LDA(At, 1, 1); PG8_STAGE(PG8_SB(1, 0), b3, voffB); PG8_STAGE(PG8_SB(1, 1), b3 + hstep, voffB); PG8_STAGE(PG8_SA(1, 0), a3, voffA);
;             PG8_WAIT_V(8); PG8_WAIT_L(0); PG8_BAR; PG8_MMA(1, 0, At, B0); PG8_MMA(1, 1, At, B1); PG8_BAR; PG8_SCHED;
	s_add_i32 s11, s11, s41
	v_lshl_add_u64 v[210:211], v[240:241], 0, s[26:27]
	s_mov_b32 m0, s11
	ds_read_b128 v[198:201], v213 offset:49152
	ds_read_b128 v[202:205], v213 offset:50176
	ds_read_b128 v[206:209], v213 offset:51200
	ds_read_b128 v[220:223], v213 offset:52224
	ds_read_b128 v[224:227], v213 offset:53248
	ds_read_b128 v[228:231], v213 offset:54272
	ds_read_b128 v[232:235], v213 offset:55296
	ds_read_b128 v[236:239], v213 offset:56320
	global_load_lds_dwordx4 v[210:211], off
	v_lshl_add_u64 v[210:211], v[242:243], 0, s[26:27]
	s_add_i32 m0, s11, 0x2000
	s_add_i32 s11, s13, s41
	global_load_lds_dwordx4 v[210:211], off
	v_lshl_add_u64 v[210:211], v[244:245], 0, s[26:27]
	s_mov_b32 m0, s11
	s_nop 0
	global_load_lds_dwordx4 v[210:211], off
	v_lshl_add_u64 v[210:211], v[214:215], 0, s[26:27]
	s_add_i32 m0, s11, 0x2000
	s_nop 0
	global_load_lds_dwordx4 v[210:211], off
	v_lshl_add_u64 v[210:211], v[246:247], 0, s[26:27]
	s_mov_b32 m0, s69
	s_nop 0
	global_load_lds_dwordx4 v[210:211], off
	v_lshl_add_u64 v[210:211], v[248:249], 0, s[26:27]
	s_mov_b32 m0, s70
	s_nop 0
	global_load_lds_dwordx4 v[210:211], off
	s_waitcnt vmcnt(8)
	s_waitcnt lgkmcnt(0)
	s_barrier
	s_setprio 1
	s_waitcnt lgkmcnt(0)
	v_mfma_f32_16x16x32_bf16 v[60:63], v[132:135], v[198:201], v[60:63]
	v_mfma_f32_16x16x32_bf16 v[56:59], v[174:177], v[198:201], v[56:59]
	v_mfma_f32_16x16x32_bf16 v[44:47], v[132:135], v[206:209], v[44:47]
	v_mfma_f32_16x16x32_bf16 v[40:43], v[174:177], v[206:209], v[40:43]
	v_mfma_f32_16x16x32_bf16 v[28:31], v[132:135], v[224:227], v[28:31]
	v_mfma_f32_16x16x32_bf16 v[24:27], v[174:177], v[224:227], v[24:27]
	v_mfma_f32_16x16x32_bf16 v[12:15], v[132:135], v[232:235], v[12:15]
	v_mfma_f32_16x16x32_bf16 v[8:11], v[174:177], v[232:235], v[8:11]
	v_mfma_f32_16x16x32_bf16 v[60:63], v[136:139], v[202:205], v[60:63]
	v_mfma_f32_16x16x32_bf16 v[56:59], v[178:181], v[202:205], v[56:59]
	v_mfma_f32_16x16x32_bf16 v[44:47], v[136:139], v[220:223], v[44:47]
	v_mfma_f32_16x16x32_bf16 v[40:43], v[178:181], v[220:223], v[40:43]
	v_mfma_f32_16x16x32_bf16 v[28:31], v[136:139], v[228:231], v[28:31]
	v_mfma_f32_16x16x32_bf16 v[24:27], v[178:181], v[228:231], v[24:27]
	v_mfma_f32_16x16x32_bf16 v[12:15], v[136:139], v[236:239], v[12:15]
	v_mfma_f32_16x16x32_bf16 v[8:11], v[178:181], v[236:239], v[8:11]
	v_mfma_f32_16x16x32_bf16 v[52:55], v[182:185], v[198:201], v[52:55]
	v_mfma_f32_16x16x32_bf16 v[48:51], v[190:193], v[198:201], v[48:51]
	v_mfma_f32_16x16x32_bf16 v[36:39], v[182:185], v[206:209], v[36:39]
	v_mfma_f32_16x16x32_bf16 v[32:35], v[190:193], v[206:209], v[32:35]
	v_mfma_f32_16x16x32_bf16 v[20:23], v[182:185], v[224:227], v[20:23]
	v_mfma_f32_16x16x32_bf16 v[16:19], v[190:193], v[224:227], v[16:19]
	v_mfma_f32_16x16x32_bf16 v[4:7], v[182:185], v[232:235], v[4:7]
	v_mfma_f32_16x16x32_bf16 v[0:3], v[190:193], v[232:235], v[0:3]
	v_mfma_f32_16x16x32_bf16 v[52:55], v[186:189], v[202:205], v[52:55]
	v_mfma_f32_16x16x32_bf16 v[48:51], v[194:197], v[202:205], v[48:51]
	v_mfma_f32_16x16x32_bf16 v[36:39], v[186:189], v[220:223], v[36:39]
	v_mfma_f32_16x16x32_bf16 v[32:35], v[194:197], v[220:223], v[32:35]
	v_mfma_f32_16x16x32_bf16 v[20:23], v[186:189], v[228:231], v[20:23]
	v_mfma_f32_16x16x32_bf16 v[16:19], v[194:197], v[228:231], v[16:19]
	v_mfma_f32_16x16x32_bf16 v[4:7], v[186:189], v[236:239], v[4:7]
	v_mfma_f32_16x16x32_bf16 v[0:3], v[194:197], v[236:239], v[0:3]
	s_setprio 0
	s_barrier
	v_lshl_add_u64 v[128:129], v[128:129], 0, s[36:37]
	s_cmp_ge_i32 s10, s67
	v_lshl_add_u64 v[130:131], v[130:131], 0, s[36:37]
	s_cbranch_scc0 .LBB0_1423

; #define PG8_STAGE(bufoff, gbase, voff) do { _Pragma("unroll") for (int _i = 0; _i < 2; ++_i) \
;         __builtin_amdgcn_global_load_lds((const unsigned*)((const char*)(gbase) + (voff)[_i]), (PG8_LAS unsigned*)(lds + (bufoff) + ldsw + _i * 8192), 16, 0, 0); } while (0)
; #define PG8_LDA(dst, b, h) do { _Pragma("unroll") for (int m = 0; m < 4; ++m) _Pragma("unroll") for (int k = 0; k < 2; ++k) dst[m][k] = *(const PG8_LAS bf16x8*)(lds + PG8_SA(b, h) + aoff + m * 2048 + k * 1024); } while (0)
; #define PG8_LDB(dst, b, h) do { _Pragma("unroll") for (int n = 0; n < 2; ++n) _Pragma("unroll") for (int k = 0; k < 2; ++k) dst[n][k] = *(const PG8_LAS bf16x8*)(lds + PG8_SB(b, h) + boff + n * 2048 + k * 1024); } while (0)
; #define PG8_MMA(ai, bj, At, Bt) do { __builtin_amdgcn_s_setprio(1); _Pragma("unroll") for (int m = 0; m < 4; ++m) _Pragma("unroll") for (int n = 0; n < 2; ++n) _Pragma("unroll") for (int k = 0; k < 2; ++k) \
;         acc[ai][bj][m][n] = __builtin_amdgcn_mfma_f32_16x16x32_bf16(Bt[n][k], At[m][k], acc[ai][bj][m][n], 0, 0, 0); __builtin_amdgcn_s_setprio(0); } while (0)
; #define PG8_WAIT_V(n) asm volatile("s_waitcnt vmcnt(" #n ")" ::: "memory")
; #define PG8_WAIT_L(n) asm volatile("s_waitcnt lgkmcnt(" #n ")" ::: "memory")
; #define PG8_BAR __builtin_amdgcn_s_barrier()
; #define PG8_SCHED __builtin_amdgcn_sched_barrier(0)
; template <class Epi, class Sched, bool ALIGN_EPI = false, bool SP2 = false>
; __device__ __forceinline__ void gemm_phase(PG8_LAS unsigned char* lds, const Gemm g, const Sched& S, const Epi& E) {
;     ...
;         for (int t = 0; t < nt; t += 2) {
;             const bool last = (t == nt - 2);
;             const char* a1 = cA + (size_t)(t + 1) * kstep;
;             const char* a2 = last ? nA : cA + (size_t)(t + 2) * kstep; const char* b2 = last ? nB : cB + (size_t)(t + 2) * kstep;
;             const char* a3 = a2 + kstep; const char* b3 = b2 + kstep;
;             if (last && has_next) S.a_ready(nxt);
;             if constexpr (SP2) {
;             PG8_LDB(B0, 0, 0); PG8_LDB(B1, 0, 1); PG8_SCHED; PG8_LDA(At, 0, 0); PG8_STAGE(PG8_SA(1, 1), a1 + hstep, voffA);
;             PG8_WAIT_V(8); PG8_WAIT_L(0); PG8_BAR; PG8_MMA(0, 0, At, B0); PG8_MMA(0, 1, At, B1); PG8_BAR; PG8_SCHED;
;             PG8_LDA(At, 0, 1); PG8_STAGE(PG8_SB(0, 0), b2, voffB); PG8_STAGE(PG8_SB(0, 1), b2 + hstep, voffB); PG8_STAGE(PG8_SA(0, 0), a2, voffA);
.LBB0_1695:
	v_add_u32_e32 v188, s54, v199
	ds_read_b128 v[132:135], v201
	ds_read_b128 v[136:139], v201 offset:1024
	ds_read_b128 v[140:143], v201 offset:2048
	ds_read_b128 v[144:147], v201 offset:3072
	ds_read_b128 v[148:151], v188
	ds_read_b128 v[180:183], v188 offset:1024
	ds_read_b128 v[184:187], v188 offset:2048
	ds_read_b128 v[188:191], v188 offset:3072
	s_cmp_eq_u32 s48, s12
	v_lshl_add_u64 v[192:193], v[130:131], 0, s[22:23]
	s_cselect_b64 vcc, -1, 0
	s_add_i32 s12, s12, 2
	v_cndmask_b32_e32 v197, v193, v177, vcc
	v_cndmask_b32_e32 v196, v192, v176, vcc
	v_cndmask_b32_e32 v213, v129, v179, vcc
	v_cndmask_b32_e32 v212, v128, v178, vcc
	s_mov_b32 m0, s55
	v_lshl_add_u64 v[214:215], v[130:131], 0, v[172:173]
	ds_read_b128 v[192:195], v202
	ds_read_b128 v[204:207], v202 offset:1024
	ds_read_b128 v[208:211], v202 offset:2048
	ds_read_b128 v[216:219], v202 offset:3072
	ds_read_b128 v[220:223], v202 offset:4096
	ds_read_b128 v[224:227], v202 offset:5120
	ds_read_b128 v[228:231], v202 offset:6144
	ds_read_b128 v[232:235], v202 offset:7168
	global_load_lds_dwordx4 v[214:215], off
	v_lshl_add_u64 v[214:215], v[130:131], 0, v[170:171]
	s_mov_b32 m0, s56
	s_nop 0
	global_load_lds_dwordx4 v[214:215], off
	s_waitcnt vmcnt(8)
	s_waitcnt lgkmcnt(0)
	s_barrier
	s_setprio 1
	s_waitcnt lgkmcnt(0)
	v_mfma_f32_16x16x32_bf16 v[120:123], v[132:135], v[192:195], v[120:123]
	v_mfma_f32_16x16x32_bf16 v[124:127], v[140:143], v[192:195], v[124:127]
	v_mfma_f32_16x16x32_bf16 v[108:111], v[132:135], v[208:211], v[108:111]
	v_mfma_f32_16x16x32_bf16 v[104:107], v[140:143], v[208:211], v[104:107]
	v_mfma_f32_16x16x32_bf16 v[92:95], v[132:135], v[220:223], v[92:95]
	v_mfma_f32_16x16x32_bf16 v[88:91], v[140:143], v[220:223], v[88:91]
	v_mfma_f32_16x16x32_bf16 v[76:79], v[132:135], v[228:231], v[76:79]
	v_mfma_f32_16x16x32_bf16 v[72:75], v[140:143], v[228:231], v[72:75]
	v_mfma_f32_16x16x32_bf16 v[120:123], v[136:139], v[204:207], v[120:123]
	v_mfma_f32_16x16x32_bf16 v[124:127], v[144:147], v[204:207], v[124:127]
	v_mfma_f32_16x16x32_bf16 v[108:111], v[136:139], v[216:219], v[108:111]
	v_mfma_f32_16x16x32_bf16 v[104:107], v[144:147], v[216:219], v[104:107]
	v_mfma_f32_16x16x32_bf16 v[92:95], v[136:139], v[224:227], v[92:95]
	v_mfma_f32_16x16x32_bf16 v[88:91], v[144:147], v[224:227], v[88:91]
	v_mfma_f32_16x16x32_bf16 v[76:79], v[136:139], v[232:235], v[76:79]
	v_mfma_f32_16x16x32_bf16 v[72:75], v[144:147], v[232:235], v[72:75]
	v_mfma_f32_16x16x32_bf16 v[116:119], v[148:151], v[192:195], v[116:119]
	v_mfma_f32_16x16x32_bf16 v[112:115], v[184:187], v[192:195], v[112:115]
	v_mfma_f32_16x16x32_bf16 v[100:103], v[148:151], v[208:211], v[100:103]
	v_mfma_f32_16x16x32_bf16 v[96:99], v[184:187], v[208:211], v[96:99]
	v_mfma_f32_16x16x32_bf16 v[84:87], v[148:151], v[220:223], v[84:87]
	v_mfma_f32_16x16x32_bf16 v[80:83], v[184:187], v[220:223], v[80:83]
	v_mfma_f32_16x16x32_bf16 v[68:71], v[148:151], v[228:231], v[68:71]
	v_mfma_f32_16x16x32_bf16 v[64:67], v[184:187], v[228:231], v[64:67]
	v_mfma_f32_16x16x32_bf16 v[116:119], v[180:183], v[204:207], v[116:119]
	v_mfma_f32_16x16x32_bf16 v[112:115], v[188:191], v[204:207], v[112:115]
	v_mfma_f32_16x16x32_bf16 v[100:103], v[180:183], v[216:219], v[100:103]
	v_mfma_f32_16x16x32_bf16 v[96:99], v[188:191], v[216:219], v[96:99]
	v_mfma_f32_16x16x32_bf16 v[84:87], v[180:183], v[224:227], v[84:87]
	v_mfma_f32_16x16x32_bf16 v[80:83], v[188:191], v[224:227], v[80:83]
	v_mfma_f32_16x16x32_bf16 v[68:71], v[180:183], v[232:235], v[68:71]
	v_mfma_f32_16x16x32_bf16 v[64:67], v[188:191], v[232:235], v[64:67]
	s_setprio 0
	s_barrier
	s_mov_b32 m0, s57
	v_lshl_add_u64 v[214:215], v[212:213], 0, v[164:165]
	ds_read_b128 v[192:195], v202 offset:16384
	ds_read_b128 v[204:207], v202 offset:17408
	ds_read_b128 v[208:211], v202 offset:18432
	ds_read_b128 v[216:219], v202 offset:19456
	ds_read_b128 v[220:223], v202 offset:20480
	ds_read_b128 v[224:227], v202 offset:21504
	ds_read_b128 v[228:231], v202 offset:22528
	ds_read_b128 v[232:235], v202 offset:23552
	global_load_lds_dwordx4 v[214:215], off
	v_lshl_add_u64 v[236:237], v[212:213], 0, v[168:169]
	s_mov_b32 m0, s58
	v_lshl_add_u64 v[212:213], v[212:213], 0, s[14:15]
	s_add_i32 s13, s54, s30
	global_load_lds_dwordx4 v[236:237], off
	v_lshl_add_u64 v[238:239], v[212:213], 0, v[164:165]
	s_mov_b32 m0, s13
	v_lshl_add_u64 v[212:213], v[212:213], 0, v[168:169]
	global_load_lds_dwordx4 v[238:239], off
	s_add_i32 m0, s13, 0x2000
	v_lshl_add_u64 v[240:241], v[196:197], 0, v[162:163]
	global_load_lds_dwordx4 v[212:213], off
	s_mov_b32 m0, s31
	v_lshl_add_u64 v[242:243], v[196:197], 0, v[166:167]
	global_load_lds_dwordx4 v[240:241], off
	s_mov_b32 m0, s34
	s_nop 0
	global_load_lds_dwordx4 v[242:243], off
	s_waitcnt vmcnt(8)
	s_waitcnt lgkmcnt(0)
	s_barrier
; #define PG8_STAGE(bufoff, gbase, voff) do { _Pragma("unroll") for (int _i = 0; _i < 2; ++_i) \
;         __builtin_amdgcn_global_load_lds((const unsigned*)((const char*)(gbase) + (voff)[_i]), (PG8_LAS unsigned*)(lds + (bufoff) + ldsw + _i * 8192), 16, 0, 0); } while (0)
; #define PG8_LDA(dst, b, h) do { _Pragma("unroll") for (int m = 0; m < 4; ++m) _Pragma("unroll") for (int k = 0; k < 2; ++k) dst[m][k] = *(const PG8_LAS bf16x8*)(lds + PG8_SA(b, h) + aoff + m * 2048 + k * 1024); } while (0)
; #define PG8_LDB(dst, b, h) do { _Pragma("unroll") for (int n = 0; n < 2; ++n) _Pragma("unroll") for (int k = 0; k < 2; ++k) dst[n][k] = *(const PG8_LAS bf16x8*)(lds + PG8_SB(b, h) + boff + n * 2048 + k * 1024); } while (0)
; #define PG8_MMA(ai, bj, At, Bt) do { __builtin_amdgcn_s_setprio(1); _Pragma("unroll") for (int m = 0; m < 4; ++m) _Pragma("unroll") for (int n = 0; n < 2; ++n) _Pragma("unroll") for (int k = 0; k < 2; ++k) \
;         acc[ai][bj][m][n] = __builtin_amdgcn_mfma_f32_16x16x32_bf16(Bt[n][k], At[m][k], acc[ai][bj][m][n], 0, 0, 0); __builtin_amdgcn_s_setprio(0); } while (0)
; #define PG8_WAIT_V(n) asm volatile("s_waitcnt vmcnt(" #n ")" ::: "memory")
; #define PG8_WAIT_L(n) asm volatile("s_waitcnt lgkmcnt(" #n ")" ::: "memory")
; #define PG8_BAR __builtin_amdgcn_s_barrier()
; #define PG8_SCHED __builtin_amdgcn_sched_barrier(0)
; template <class Epi, class Sched, bool ALIGN_EPI = false, bool SP2 = false>
; __device__ __forceinline__ void gemm_phase(PG8_LAS unsigned char* lds, const Gemm g, const Sched& S, const Epi& E) {
;     ...
;             PG8_WAIT_V(8); PG8_WAIT_L(0); PG8_BAR; PG8_MMA(1, 0, At, B0); PG8_MMA(1, 1, At, B1); PG8_BAR; PG8_SCHED;
;             PG8_LDB(B0, 1, 0); PG8_LDB(B1, 1, 1); PG8_SCHED; PG8_LDA(At, 1, 0); PG8_STAGE(PG8_SA(0, 1), a2 + hstep, voffA);
;             PG8_WAIT_V(8); PG8_WAIT_L(0); PG8_BAR; PG8_MMA(0, 0, At, B0); PG8_MMA(0, 1, At, B1); PG8_BAR; PG8_SCHED;
	s_setprio 1
	s_waitcnt lgkmcnt(0)
	v_mfma_f32_16x16x32_bf16 v[60:63], v[132:135], v[192:195], v[60:63]
	v_mfma_f32_16x16x32_bf16 v[56:59], v[140:143], v[192:195], v[56:59]
	v_mfma_f32_16x16x32_bf16 v[44:47], v[132:135], v[208:211], v[44:47]
	v_mfma_f32_16x16x32_bf16 v[40:43], v[140:143], v[208:211], v[40:43]
	v_mfma_f32_16x16x32_bf16 v[28:31], v[132:135], v[220:223], v[28:31]
	v_mfma_f32_16x16x32_bf16 v[24:27], v[140:143], v[220:223], v[24:27]
	v_mfma_f32_16x16x32_bf16 v[12:15], v[132:135], v[228:231], v[12:15]
	v_mfma_f32_16x16x32_bf16 v[8:11], v[140:143], v[228:231], v[8:11]
	v_mfma_f32_16x16x32_bf16 v[60:63], v[136:139], v[204:207], v[60:63]
	v_mfma_f32_16x16x32_bf16 v[56:59], v[144:147], v[204:207], v[56:59]
	v_mfma_f32_16x16x32_bf16 v[44:47], v[136:139], v[216:219], v[44:47]
	v_mfma_f32_16x16x32_bf16 v[40:43], v[144:147], v[216:219], v[40:43]
	v_mfma_f32_16x16x32_bf16 v[28:31], v[136:139], v[224:227], v[28:31]
	v_mfma_f32_16x16x32_bf16 v[24:27], v[144:147], v[224:227], v[24:27]
	v_mfma_f32_16x16x32_bf16 v[12:15], v[136:139], v[232:235], v[12:15]
	v_mfma_f32_16x16x32_bf16 v[8:11], v[144:147], v[232:235], v[8:11]
	v_mfma_f32_16x16x32_bf16 v[52:55], v[148:151], v[192:195], v[52:55]
	v_mfma_f32_16x16x32_bf16 v[48:51], v[184:187], v[192:195], v[48:51]
	v_mfma_f32_16x16x32_bf16 v[36:39], v[148:151], v[208:211], v[36:39]
	v_mfma_f32_16x16x32_bf16 v[32:35], v[184:187], v[208:211], v[32:35]
	v_mfma_f32_16x16x32_bf16 v[20:23], v[148:151], v[220:223], v[20:23]
	v_mfma_f32_16x16x32_bf16 v[16:19], v[184:187], v[220:223], v[16:19]
	v_mfma_f32_16x16x32_bf16 v[4:7], v[148:151], v[228:231], v[4:7]
	v_mfma_f32_16x16x32_bf16 v[0:3], v[184:187], v[228:231], v[0:3]
	v_mfma_f32_16x16x32_bf16 v[52:55], v[180:183], v[204:207], v[52:55]
	v_mfma_f32_16x16x32_bf16 v[48:51], v[188:191], v[204:207], v[48:51]
	v_mfma_f32_16x16x32_bf16 v[36:39], v[180:183], v[216:219], v[36:39]
	v_mfma_f32_16x16x32_bf16 v[32:35], v[188:191], v[216:219], v[32:35]
	v_mfma_f32_16x16x32_bf16 v[20:23], v[180:183], v[224:227], v[20:23]
	v_mfma_f32_16x16x32_bf16 v[16:19], v[188:191], v[224:227], v[16:19]
	v_mfma_f32_16x16x32_bf16 v[4:7], v[180:183], v[232:235], v[4:7]
	v_mfma_f32_16x16x32_bf16 v[0:3], v[188:191], v[232:235], v[0:3]
	s_setprio 0
	s_barrier
	s_add_i32 s13, 0, 0x18000
	s_add_i32 s29, 0, 0x1c000
	v_add_u32_e32 v144, s13, v199
	v_add_u32_e32 v188, s29, v199
	ds_read_b128 v[132:135], v144
	ds_read_b128 v[136:139], v144 offset:1024
	ds_read_b128 v[140:143], v144 offset:2048
	ds_read_b128 v[144:147], v144 offset:3072
	ds_read_b128 v[148:151], v188
	ds_read_b128 v[180:183], v188 offset:1024
	ds_read_b128 v[184:187], v188 offset:2048
	ds_read_b128 v[188:191], v188 offset:3072
	v_lshl_add_u64 v[196:197], v[196:197], 0, s[14:15]
	s_mov_b32 m0, s35
	v_lshl_add_u64 v[244:245], v[196:197], 0, v[162:163]
	ds_read_b128 v[192:195], v202 offset:32768
	ds_read_b128 v[204:207], v202 offset:33792
	ds_read_b128 v[208:211], v202 offset:34816
	ds_read_b128 v[216:219], v202 offset:35840
	ds_read_b128 v[220:223], v202 offset:36864
	ds_read_b128 v[224:227], v202 offset:37888
	ds_read_b128 v[228:231], v202 offset:38912
	ds_read_b128 v[232:235], v202 offset:39936
	global_load_lds_dwordx4 v[244:245], off
	v_lshl_add_u64 v[196:197], v[196:197], 0, v[166:167]
	s_mov_b32 m0, s36
	s_nop 0
	global_load_lds_dwordx4 v[196:197], off
	s_waitcnt vmcnt(8)
	s_waitcnt lgkmcnt(0)
	s_barrier
	s_setprio 1
	s_waitcnt lgkmcnt(0)
	v_mfma_f32_16x16x32_bf16 v[120:123], v[132:135], v[192:195], v[120:123]
	v_mfma_f32_16x16x32_bf16 v[124:127], v[140:143], v[192:195], v[124:127]
	v_mfma_f32_16x16x32_bf16 v[108:111], v[132:135], v[208:211], v[108:111]
	v_mfma_f32_16x16x32_bf16 v[104:107], v[140:143], v[208:211], v[104:107]
	v_mfma_f32_16x16x32_bf16 v[92:95], v[132:135], v[220:223], v[92:95]
	v_mfma_f32_16x16x32_bf16 v[88:91], v[140:143], v[220:223], v[88:91]
	v_mfma_f32_16x16x32_bf16 v[76:79], v[132:135], v[228:231], v[76:79]
	v_mfma_f32_16x16x32_bf16 v[72:75], v[140:143], v[228:231], v[72:75]
	v_mfma_f32_16x16x32_bf16 v[120:123], v[136:139], v[204:207], v[120:123]
	v_mfma_f32_16x16x32_bf16 v[124:127], v[144:147], v[204:207], v[124:127]
	v_mfma_f32_16x16x32_bf16 v[108:111], v[136:139], v[216:219], v[108:111]
	v_mfma_f32_16x16x32_bf16 v[104:107], v[144:147], v[216:219], v[104:107]
	v_mfma_f32_16x16x32_bf16 v[92:95], v[136:139], v[224:227], v[92:95]
	v_mfma_f32_16x16x32_bf16 v[88:91], v[144:147], v[224:227], v[88:91]
	v_mfma_f32_16x16x32_bf16 v[76:79], v[136:139], v[232:235], v[76:79]
	v_mfma_f32_16x16x32_bf16 v[72:75], v[144:147], v[232:235], v[72:75]
	v_mfma_f32_16x16x32_bf16 v[116:119], v[148:151], v[192:195], v[116:119]
	v_mfma_f32_16x16x32_bf16 v[112:115], v[184:187], v[192:195], v[112:115]
	v_mfma_f32_16x16x32_bf16 v[100:103], v[148:151], v[208:211], v[100:103]
	v_mfma_f32_16x16x32_bf16 v[96:99], v[184:187], v[208:211], v[96:99]
	v_mfma_f32_16x16x32_bf16 v[84:87], v[148:151], v[220:223], v[84:87]
	v_mfma_f32_16x16x32_bf16 v[80:83], v[184:187], v[220:223], v[80:83]
	v_mfma_f32_16x16x32_bf16 v[68:71], v[148:151], v[228:231], v[68:71]
	v_mfma_f32_16x16x32_bf16 v[64:67], v[184:187], v[228:231], v[64:67]
	v_mfma_f32_16x16x32_bf16 v[116:119], v[180:183], v[204:207], v[116:119]
	v_mfma_f32_16x16x32_bf16 v[112:115], v[188:191], v[204:207], v[112:115]
	v_mfma_f32_16x16x32_bf16 v[100:103], v[180:183], v[216:219], v[100:103]
	v_mfma_f32_16x16x32_bf16 v[96:99], v[188:191], v[216:219], v[96:99]
	v_mfma_f32_16x16x32_bf16 v[84:87], v[180:183], v[224:227], v[84:87]
	v_mfma_f32_16x16x32_bf16 v[80:83], v[188:191], v[224:227], v[80:83]
	v_mfma_f32_16x16x32_bf16 v[68:71], v[180:183], v[232:235], v[68:71]
	v_mfma_f32_16x16x32_bf16 v[64:67], v[188:191], v[232:235], v[64:67]
	s_setprio 0
	s_barrier
; #define PG8_STAGE(bufoff, gbase, voff) do { _Pragma("unroll") for (int _i = 0; _i < 2; ++_i) \
;         __builtin_amdgcn_global_load_lds((const unsigned*)((const char*)(gbase) + (voff)[_i]), (PG8_LAS unsigned*)(lds + (bufoff) + ldsw + _i * 8192), 16, 0, 0); } while (0)
; #define PG8_LDA(dst, b, h) do { _Pragma("unroll") for (int m = 0; m < 4; ++m) _Pragma("unroll") for (int k = 0; k < 2; ++k) dst[m][k] = *(const PG8_LAS bf16x8*)(lds + PG8_SA(b, h) + aoff + m * 2048 + k * 1024); } while (0)
; #define PG8_MMA(ai, bj, At, Bt) do { __builtin_amdgcn_s_setprio(1); _Pragma("unroll") for (int m = 0; m < 4; ++m) _Pragma("unroll") for (int n = 0; n < 2; ++n) _Pragma("unroll") for (int k = 0; k < 2; ++k) \
;         acc[ai][bj][m][n] = __builtin_amdgcn_mfma_f32_16x16x32_bf16(Bt[n][k], At[m][k], acc[ai][bj][m][n], 0, 0, 0); __builtin_amdgcn_s_setprio(0); } while (0)
; #define PG8_WAIT_V(n) asm volatile("s_waitcnt vmcnt(" #n ")" ::: "memory")
; #define PG8_WAIT_L(n) asm volatile("s_waitcnt lgkmcnt(" #n ")" ::: "memory")
; #define PG8_BAR __builtin_amdgcn_s_barrier()
; #define PG8_SCHED __builtin_amdgcn_sched_barrier(0)
; template <class Epi, class Sched, bool ALIGN_EPI = false, bool SP2 = false>
; __device__ __forceinline__ void gemm_phase(PG8_LAS unsigned char* lds, const Gemm g, const Sched& S, const Epi& E) {
;     ...
;             PG8_LDA(At, 1, 1); PG8_STAGE(PG8_SB(1, 0), b3, voffB); PG8_STAGE(PG8_SB(1, 1), b3 + hstep, voffB); PG8_STAGE(PG8_SA(1, 0), a3, voffA);
;             PG8_WAIT_V(8); PG8_WAIT_L(0); PG8_BAR; PG8_MMA(1, 0, At, B0); PG8_MMA(1, 1, At, B1); PG8_BAR; PG8_SCHED;
	s_add_i32 s13, s13, s30
	v_lshl_add_u64 v[196:197], v[214:215], 0, s[22:23]
	s_mov_b32 m0, s13
	ds_read_b128 v[192:195], v202 offset:49152
	ds_read_b128 v[204:207], v202 offset:50176
	ds_read_b128 v[208:211], v202 offset:51200
	ds_read_b128 v[216:219], v202 offset:52224
	ds_read_b128 v[220:223], v202 offset:53248
	ds_read_b128 v[224:227], v202 offset:54272
	ds_read_b128 v[228:231], v202 offset:55296
	ds_read_b128 v[232:235], v202 offset:56320
	global_load_lds_dwordx4 v[196:197], off
	v_lshl_add_u64 v[196:197], v[236:237], 0, s[22:23]
	s_add_i32 m0, s13, 0x2000
	s_add_i32 s13, s29, s30
	global_load_lds_dwordx4 v[196:197], off
	v_lshl_add_u64 v[196:197], v[238:239], 0, s[22:23]
	s_mov_b32 m0, s13
	s_nop 0
	global_load_lds_dwordx4 v[196:197], off
	v_lshl_add_u64 v[196:197], v[212:213], 0, s[22:23]
	s_add_i32 m0, s13, 0x2000
	s_nop 0
	global_load_lds_dwordx4 v[196:197], off
	v_lshl_add_u64 v[196:197], v[240:241], 0, s[22:23]
	s_mov_b32 m0, s37
	s_nop 0
	global_load_lds_dwordx4 v[196:197], off
	v_lshl_add_u64 v[196:197], v[242:243], 0, s[22:23]
	s_mov_b32 m0, s41
	s_nop 0
	global_load_lds_dwordx4 v[196:197], off
	s_waitcnt vmcnt(8)
	s_waitcnt lgkmcnt(0)
	s_barrier
	s_setprio 1
	s_waitcnt lgkmcnt(0)
	v_mfma_f32_16x16x32_bf16 v[60:63], v[132:135], v[192:195], v[60:63]
	v_mfma_f32_16x16x32_bf16 v[56:59], v[140:143], v[192:195], v[56:59]
	v_mfma_f32_16x16x32_bf16 v[44:47], v[132:135], v[208:211], v[44:47]
	v_mfma_f32_16x16x32_bf16 v[40:43], v[140:143], v[208:211], v[40:43]
	v_mfma_f32_16x16x32_bf16 v[28:31], v[132:135], v[220:223], v[28:31]
	v_mfma_f32_16x16x32_bf16 v[24:27], v[140:143], v[220:223], v[24:27]
	v_mfma_f32_16x16x32_bf16 v[12:15], v[132:135], v[228:231], v[12:15]
	v_mfma_f32_16x16x32_bf16 v[8:11], v[140:143], v[228:231], v[8:11]
	v_mfma_f32_16x16x32_bf16 v[60:63], v[136:139], v[204:207], v[60:63]
	v_mfma_f32_16x16x32_bf16 v[56:59], v[144:147], v[204:207], v[56:59]
	v_mfma_f32_16x16x32_bf16 v[44:47], v[136:139], v[216:219], v[44:47]
	v_mfma_f32_16x16x32_bf16 v[40:43], v[144:147], v[216:219], v[40:43]
	v_mfma_f32_16x16x32_bf16 v[28:31], v[136:139], v[224:227], v[28:31]
	v_mfma_f32_16x16x32_bf16 v[24:27], v[144:147], v[224:227], v[24:27]
	v_mfma_f32_16x16x32_bf16 v[12:15], v[136:139], v[232:235], v[12:15]
	v_mfma_f32_16x16x32_bf16 v[8:11], v[144:147], v[232:235], v[8:11]
	v_mfma_f32_16x16x32_bf16 v[52:55], v[148:151], v[192:195], v[52:55]
	v_mfma_f32_16x16x32_bf16 v[48:51], v[184:187], v[192:195], v[48:51]
	v_mfma_f32_16x16x32_bf16 v[36:39], v[148:151], v[208:211], v[36:39]
	v_mfma_f32_16x16x32_bf16 v[32:35], v[184:187], v[208:211], v[32:35]
	v_mfma_f32_16x16x32_bf16 v[20:23], v[148:151], v[220:223], v[20:23]
	v_mfma_f32_16x16x32_bf16 v[16:19], v[184:187], v[220:223], v[16:19]
	v_mfma_f32_16x16x32_bf16 v[4:7], v[148:151], v[228:231], v[4:7]
	v_mfma_f32_16x16x32_bf16 v[0:3], v[184:187], v[228:231], v[0:3]
	v_mfma_f32_16x16x32_bf16 v[52:55], v[180:183], v[204:207], v[52:55]
	v_mfma_f32_16x16x32_bf16 v[48:51], v[188:191], v[204:207], v[48:51]
	v_mfma_f32_16x16x32_bf16 v[36:39], v[180:183], v[216:219], v[36:39]
	v_mfma_f32_16x16x32_bf16 v[32:35], v[188:191], v[216:219], v[32:35]
	v_mfma_f32_16x16x32_bf16 v[20:23], v[180:183], v[224:227], v[20:23]
	v_mfma_f32_16x16x32_bf16 v[16:19], v[188:191], v[224:227], v[16:19]
	v_mfma_f32_16x16x32_bf16 v[4:7], v[180:183], v[232:235], v[4:7]
	v_mfma_f32_16x16x32_bf16 v[0:3], v[188:191], v[232:235], v[0:3]
	s_setprio 0
	s_barrier
	v_lshl_add_u64 v[128:129], v[128:129], 0, s[26:27]
	s_cmp_ge_i32 s12, s47
	v_lshl_add_u64 v[130:131], v[130:131], 0, s[26:27]
	s_cbranch_scc0 .LBB0_1695

; #define PG8_STAGE(bufoff, gbase, voff) do { _Pragma("unroll") for (int _i = 0; _i < 2; ++_i) \
;         __builtin_amdgcn_global_load_lds((const unsigned*)((const char*)(gbase) + (voff)[_i]), (PG8_LAS unsigned*)(lds + (bufoff) + ldsw + _i * 8192), 16, 0, 0); } while (0)
; #define PG8_LDA(dst, b, h) do { _Pragma("unroll") for (int m = 0; m < 4; ++m) _Pragma("unroll") for (int k = 0; k < 2; ++k) dst[m][k] = *(const PG8_LAS bf16x8*)(lds + PG8_SA(b, h) + aoff + m * 2048 + k * 1024); } while (0)
; #define PG8_LDB(dst, b, h) do { _Pragma("unroll") for (int n = 0; n < 2; ++n) _Pragma("unroll") for (int k = 0; k < 2; ++k) dst[n][k] = *(const PG8_LAS bf16x8*)(lds + PG8_SB(b, h) + boff + n * 2048 + k * 1024); } while (0)
; #define PG8_MMA(ai, bj, At, Bt) do { __builtin_amdgcn_s_setprio(1); _Pragma("unroll") for (int m = 0; m < 4; ++m) _Pragma("unroll") for (int n = 0; n < 2; ++n) _Pragma("unroll") for (int k = 0; k < 2; ++k) \
;         acc[ai][bj][m][n] = __builtin_amdgcn_mfma_f32_16x16x32_bf16(Bt[n][k], At[m][k], acc[ai][bj][m][n], 0, 0, 0); __builtin_amdgcn_s_setprio(0); } while (0)
; #define PG8_WAIT_V(n) asm volatile("s_waitcnt vmcnt(" #n ")" ::: "memory")
; #define PG8_WAIT_L(n) asm volatile("s_waitcnt lgkmcnt(" #n ")" ::: "memory")
; #define PG8_BAR __builtin_amdgcn_s_barrier()
; #define PG8_SCHED __builtin_amdgcn_sched_barrier(0)
; template <class Epi, class Sched, bool ALIGN_EPI = false, bool SP2 = false>
; __device__ __forceinline__ void gemm_phase(PG8_LAS unsigned char* lds, const Gemm g, const Sched& S, const Epi& E) {
;     ...
;         for (int t = 0; t < nt; t += 2) {
;             const bool last = (t == nt - 2);
;             const char* a1 = cA + (size_t)(t + 1) * kstep;
;             const char* a2 = last ? nA : cA + (size_t)(t + 2) * kstep; const char* b2 = last ? nB : cB + (size_t)(t + 2) * kstep;
;             const char* a3 = a2 + kstep; const char* b3 = b2 + kstep;
;             if (last && has_next) S.a_ready(nxt);
;             if constexpr (SP2) {
;             PG8_LDB(B0, 0, 0); PG8_LDB(B1, 0, 1); PG8_SCHED; PG8_LDA(At, 0, 0); PG8_STAGE(PG8_SA(1, 1), a1 + hstep, voffA);
;             PG8_WAIT_V(8); PG8_WAIT_L(0); PG8_BAR; PG8_MMA(0, 0, At, B0); PG8_MMA(0, 1, At, B1); PG8_BAR; PG8_SCHED;
;             PG8_LDA(At, 0, 1); PG8_STAGE(PG8_SB(0, 0), b2, voffB); PG8_STAGE(PG8_SB(0, 1), b2 + hstep, voffB); PG8_STAGE(PG8_SA(0, 0), a2, voffA);
.LBB0_1776:
	v_add_u32_e32 v166, s54, v169
	v_add_u32_e32 v168, s55, v169
	ds_read_b128 v[162:165], v166
	ds_read_b128 v[182:185], v166 offset:1024
	ds_read_b128 v[186:189], v166 offset:2048
	ds_read_b128 v[190:193], v166 offset:3072
	ds_read_b128 v[194:197], v168
	ds_read_b128 v[198:201], v168 offset:1024
	ds_read_b128 v[202:205], v168 offset:2048
	ds_read_b128 v[206:209], v168 offset:3072
	s_cmp_eq_u32 s53, s10
	v_lshl_add_u64 v[172:173], v[160:161], 0, s[22:23]
	s_cselect_b64 vcc, -1, 0
	s_add_i32 s10, s10, 2
	v_cndmask_b32_e32 v173, v173, v153, vcc
	v_cndmask_b32_e32 v172, v172, v152, vcc
	v_cndmask_b32_e32 v215, v159, v155, vcc
	v_cndmask_b32_e32 v214, v158, v154, vcc
	s_mov_b32 m0, s56
	v_lshl_add_u64 v[244:245], v[160:161], 0, v[148:149]
	ds_read_b128 v[210:213], v179
	ds_read_b128 v[216:219], v179 offset:1024
	ds_read_b128 v[220:223], v179 offset:2048
	ds_read_b128 v[224:227], v179 offset:3072
	ds_read_b128 v[228:231], v179 offset:4096
	ds_read_b128 v[232:235], v179 offset:5120
	ds_read_b128 v[236:239], v179 offset:6144
	ds_read_b128 v[240:243], v179 offset:7168
	global_load_lds_dwordx4 v[244:245], off
	v_lshl_add_u64 v[244:245], v[160:161], 0, v[146:147]
	s_mov_b32 m0, s57
	s_nop 0
	global_load_lds_dwordx4 v[244:245], off
	s_waitcnt vmcnt(8)
	s_waitcnt lgkmcnt(0)
	s_barrier
	s_setprio 1
	s_waitcnt lgkmcnt(0)
	v_mfma_f32_16x16x32_bf16 v[124:127], v[162:165], v[210:213], v[124:127]
	v_mfma_f32_16x16x32_bf16 v[116:119], v[186:189], v[210:213], v[116:119]
	v_mfma_f32_16x16x32_bf16 v[108:111], v[162:165], v[220:223], v[108:111]
	v_mfma_f32_16x16x32_bf16 v[100:103], v[186:189], v[220:223], v[100:103]
	v_mfma_f32_16x16x32_bf16 v[92:95], v[162:165], v[228:231], v[92:95]
	v_mfma_f32_16x16x32_bf16 v[84:87], v[186:189], v[228:231], v[84:87]
	v_mfma_f32_16x16x32_bf16 v[76:79], v[162:165], v[236:239], v[76:79]
	v_mfma_f32_16x16x32_bf16 v[68:71], v[186:189], v[236:239], v[68:71]
	v_mfma_f32_16x16x32_bf16 v[124:127], v[182:185], v[216:219], v[124:127]
	v_mfma_f32_16x16x32_bf16 v[116:119], v[190:193], v[216:219], v[116:119]
	v_mfma_f32_16x16x32_bf16 v[108:111], v[182:185], v[224:227], v[108:111]
	v_mfma_f32_16x16x32_bf16 v[100:103], v[190:193], v[224:227], v[100:103]
	v_mfma_f32_16x16x32_bf16 v[92:95], v[182:185], v[232:235], v[92:95]
	v_mfma_f32_16x16x32_bf16 v[84:87], v[190:193], v[232:235], v[84:87]
	v_mfma_f32_16x16x32_bf16 v[76:79], v[182:185], v[240:243], v[76:79]
	v_mfma_f32_16x16x32_bf16 v[68:71], v[190:193], v[240:243], v[68:71]
	v_mfma_f32_16x16x32_bf16 v[120:123], v[194:197], v[210:213], v[120:123]
	v_mfma_f32_16x16x32_bf16 v[112:115], v[202:205], v[210:213], v[112:115]
	v_mfma_f32_16x16x32_bf16 v[104:107], v[194:197], v[220:223], v[104:107]
	v_mfma_f32_16x16x32_bf16 v[96:99], v[202:205], v[220:223], v[96:99]
	v_mfma_f32_16x16x32_bf16 v[88:91], v[194:197], v[228:231], v[88:91]
	v_mfma_f32_16x16x32_bf16 v[80:83], v[202:205], v[228:231], v[80:83]
	v_mfma_f32_16x16x32_bf16 v[72:75], v[194:197], v[236:239], v[72:75]
	v_mfma_f32_16x16x32_bf16 v[64:67], v[202:205], v[236:239], v[64:67]
	v_mfma_f32_16x16x32_bf16 v[120:123], v[198:201], v[216:219], v[120:123]
	v_mfma_f32_16x16x32_bf16 v[112:115], v[206:209], v[216:219], v[112:115]
	v_mfma_f32_16x16x32_bf16 v[104:107], v[198:201], v[224:227], v[104:107]
	v_mfma_f32_16x16x32_bf16 v[96:99], v[206:209], v[224:227], v[96:99]
	v_mfma_f32_16x16x32_bf16 v[88:91], v[198:201], v[232:235], v[88:91]
	v_mfma_f32_16x16x32_bf16 v[80:83], v[206:209], v[232:235], v[80:83]
	v_mfma_f32_16x16x32_bf16 v[72:75], v[198:201], v[240:243], v[72:75]
	v_mfma_f32_16x16x32_bf16 v[64:67], v[206:209], v[240:243], v[64:67]
	s_setprio 0
	s_barrier
	s_mov_b32 m0, s60
	v_lshl_add_u64 v[244:245], v[214:215], 0, v[138:139]
	ds_read_b128 v[210:213], v179 offset:16384
	ds_read_b128 v[216:219], v179 offset:17408
	ds_read_b128 v[220:223], v179 offset:18432
	ds_read_b128 v[224:227], v179 offset:19456
	ds_read_b128 v[228:231], v179 offset:20480
	ds_read_b128 v[232:235], v179 offset:21504
	ds_read_b128 v[236:239], v179 offset:22528
	ds_read_b128 v[240:243], v179 offset:23552
	global_load_lds_dwordx4 v[244:245], off
	v_lshl_add_u64 v[246:247], v[214:215], 0, v[134:135]
	s_mov_b32 m0, s61
	v_lshl_add_u64 v[214:215], v[214:215], 0, s[14:15]
	global_load_lds_dwordx4 v[246:247], off
	v_lshl_add_u64 v[248:249], v[214:215], 0, v[138:139]
	s_mov_b32 m0, s62
	v_lshl_add_u64 v[214:215], v[214:215], 0, v[134:135]
	global_load_lds_dwordx4 v[248:249], off
	s_add_i32 m0, s62, 0x2000
	v_lshl_add_u64 v[250:251], v[172:173], 0, v[140:141]
	global_load_lds_dwordx4 v[214:215], off
	s_mov_b32 m0, s46
	v_lshl_add_u64 v[252:253], v[172:173], 0, v[136:137]
	global_load_lds_dwordx4 v[250:251], off
	s_mov_b32 m0, s47
	s_nop 0
	global_load_lds_dwordx4 v[252:253], off
	s_waitcnt vmcnt(8)
	s_waitcnt lgkmcnt(0)
	s_barrier
; #define PG8_STAGE(bufoff, gbase, voff) do { _Pragma("unroll") for (int _i = 0; _i < 2; ++_i) \
;         __builtin_amdgcn_global_load_lds((const unsigned*)((const char*)(gbase) + (voff)[_i]), (PG8_LAS unsigned*)(lds + (bufoff) + ldsw + _i * 8192), 16, 0, 0); } while (0)
; #define PG8_LDA(dst, b, h) do { _Pragma("unroll") for (int m = 0; m < 4; ++m) _Pragma("unroll") for (int k = 0; k < 2; ++k) dst[m][k] = *(const PG8_LAS bf16x8*)(lds + PG8_SA(b, h) + aoff + m * 2048 + k * 1024); } while (0)
; #define PG8_LDB(dst, b, h) do { _Pragma("unroll") for (int n = 0; n < 2; ++n) _Pragma("unroll") for (int k = 0; k < 2; ++k) dst[n][k] = *(const PG8_LAS bf16x8*)(lds + PG8_SB(b, h) + boff + n * 2048 + k * 1024); } while (0)
; #define PG8_MMA(ai, bj, At, Bt) do { __builtin_amdgcn_s_setprio(1); _Pragma("unroll") for (int m = 0; m < 4; ++m) _Pragma("unroll") for (int n = 0; n < 2; ++n) _Pragma("unroll") for (int k = 0; k < 2; ++k) \
;         acc[ai][bj][m][n] = __builtin_amdgcn_mfma_f32_16x16x32_bf16(Bt[n][k], At[m][k], acc[ai][bj][m][n], 0, 0, 0); __builtin_amdgcn_s_setprio(0); } while (0)
; #define PG8_WAIT_V(n) asm volatile("s_waitcnt vmcnt(" #n ")" ::: "memory")
; #define PG8_WAIT_L(n) asm volatile("s_waitcnt lgkmcnt(" #n ")" ::: "memory")
; #define PG8_BAR __builtin_amdgcn_s_barrier()
; #define PG8_SCHED __builtin_amdgcn_sched_barrier(0)
; template <class Epi, class Sched, bool ALIGN_EPI = false, bool SP2 = false>
; __device__ __forceinline__ void gemm_phase(PG8_LAS unsigned char* lds, const Gemm g, const Sched& S, const Epi& E) {
;     ...
;             PG8_WAIT_V(8); PG8_WAIT_L(0); PG8_BAR; PG8_MMA(1, 0, At, B0); PG8_MMA(1, 1, At, B1); PG8_BAR; PG8_SCHED;
;             PG8_LDB(B0, 1, 0); PG8_LDB(B1, 1, 1); PG8_SCHED; PG8_LDA(At, 1, 0); PG8_STAGE(PG8_SA(0, 1), a2 + hstep, voffA);
;             PG8_WAIT_V(8); PG8_WAIT_L(0); PG8_BAR; PG8_MMA(0, 0, At, B0); PG8_MMA(0, 1, At, B1); PG8_BAR; PG8_SCHED;
	s_setprio 1
	s_waitcnt lgkmcnt(0)
	v_mfma_f32_16x16x32_bf16 v[60:63], v[162:165], v[210:213], v[60:63]
	v_mfma_f32_16x16x32_bf16 v[52:55], v[186:189], v[210:213], v[52:55]
	v_mfma_f32_16x16x32_bf16 v[44:47], v[162:165], v[220:223], v[44:47]
	v_mfma_f32_16x16x32_bf16 v[36:39], v[186:189], v[220:223], v[36:39]
	v_mfma_f32_16x16x32_bf16 v[28:31], v[162:165], v[228:231], v[28:31]
	v_mfma_f32_16x16x32_bf16 v[20:23], v[186:189], v[228:231], v[20:23]
	v_mfma_f32_16x16x32_bf16 v[12:15], v[162:165], v[236:239], v[12:15]
	v_mfma_f32_16x16x32_bf16 v[4:7], v[186:189], v[236:239], v[4:7]
	v_mfma_f32_16x16x32_bf16 v[60:63], v[182:185], v[216:219], v[60:63]
	v_mfma_f32_16x16x32_bf16 v[52:55], v[190:193], v[216:219], v[52:55]
	v_mfma_f32_16x16x32_bf16 v[44:47], v[182:185], v[224:227], v[44:47]
	v_mfma_f32_16x16x32_bf16 v[36:39], v[190:193], v[224:227], v[36:39]
	v_mfma_f32_16x16x32_bf16 v[28:31], v[182:185], v[232:235], v[28:31]
	v_mfma_f32_16x16x32_bf16 v[20:23], v[190:193], v[232:235], v[20:23]
	v_mfma_f32_16x16x32_bf16 v[12:15], v[182:185], v[240:243], v[12:15]
	v_mfma_f32_16x16x32_bf16 v[4:7], v[190:193], v[240:243], v[4:7]
	v_mfma_f32_16x16x32_bf16 v[56:59], v[194:197], v[210:213], v[56:59]
	v_mfma_f32_16x16x32_bf16 v[48:51], v[202:205], v[210:213], v[48:51]
	v_mfma_f32_16x16x32_bf16 v[40:43], v[194:197], v[220:223], v[40:43]
	v_mfma_f32_16x16x32_bf16 v[32:35], v[202:205], v[220:223], v[32:35]
	v_mfma_f32_16x16x32_bf16 v[24:27], v[194:197], v[228:231], v[24:27]
	v_mfma_f32_16x16x32_bf16 v[16:19], v[202:205], v[228:231], v[16:19]
	v_mfma_f32_16x16x32_bf16 v[8:11], v[194:197], v[236:239], v[8:11]
	v_mfma_f32_16x16x32_bf16 v[0:3], v[202:205], v[236:239], v[0:3]
	v_mfma_f32_16x16x32_bf16 v[56:59], v[198:201], v[216:219], v[56:59]
	v_mfma_f32_16x16x32_bf16 v[48:51], v[206:209], v[216:219], v[48:51]
	v_mfma_f32_16x16x32_bf16 v[40:43], v[198:201], v[224:227], v[40:43]
	v_mfma_f32_16x16x32_bf16 v[32:35], v[206:209], v[224:227], v[32:35]
	v_mfma_f32_16x16x32_bf16 v[24:27], v[198:201], v[232:235], v[24:27]
	v_mfma_f32_16x16x32_bf16 v[16:19], v[206:209], v[232:235], v[16:19]
	v_mfma_f32_16x16x32_bf16 v[8:11], v[198:201], v[240:243], v[8:11]
	v_mfma_f32_16x16x32_bf16 v[0:3], v[206:209], v[240:243], v[0:3]
	s_setprio 0
	s_barrier
	s_add_i32 s11, 0, 0x18000
	v_add_u32_e32 v166, s11, v169
	s_add_i32 s13, 0, 0x1c000
	ds_read_b128 v[162:165], v166
	ds_read_b128 v[182:185], v166 offset:1024
	ds_read_b128 v[186:189], v166 offset:2048
	ds_read_b128 v[190:193], v166 offset:3072
	v_add_u32_e32 v166, s13, v169
	ds_read_b128 v[194:197], v166
	ds_read_b128 v[198:201], v166 offset:1024
	ds_read_b128 v[202:205], v166 offset:2048
	ds_read_b128 v[206:209], v166 offset:3072
	v_lshl_add_u64 v[172:173], v[172:173], 0, s[14:15]
	s_mov_b32 m0, s48
	v_lshl_add_u64 v[170:171], v[172:173], 0, v[140:141]
	ds_read_b128 v[210:213], v179 offset:32768
	ds_read_b128 v[216:219], v179 offset:33792
	ds_read_b128 v[220:223], v179 offset:34816
	ds_read_b128 v[224:227], v179 offset:35840
	ds_read_b128 v[228:231], v179 offset:36864
	ds_read_b128 v[232:235], v179 offset:37888
	ds_read_b128 v[236:239], v179 offset:38912
	ds_read_b128 v[240:243], v179 offset:39936
	global_load_lds_dwordx4 v[170:171], off
	v_lshl_add_u64 v[170:171], v[172:173], 0, v[136:137]
	s_mov_b32 m0, s49
	s_nop 0
	global_load_lds_dwordx4 v[170:171], off
	s_waitcnt vmcnt(8)
	s_waitcnt lgkmcnt(0)
	s_barrier
	s_setprio 1
	s_waitcnt lgkmcnt(0)
	v_mfma_f32_16x16x32_bf16 v[124:127], v[162:165], v[210:213], v[124:127]
	v_mfma_f32_16x16x32_bf16 v[116:119], v[186:189], v[210:213], v[116:119]
	v_mfma_f32_16x16x32_bf16 v[108:111], v[162:165], v[220:223], v[108:111]
	v_mfma_f32_16x16x32_bf16 v[100:103], v[186:189], v[220:223], v[100:103]
	v_mfma_f32_16x16x32_bf16 v[92:95], v[162:165], v[228:231], v[92:95]
	v_mfma_f32_16x16x32_bf16 v[84:87], v[186:189], v[228:231], v[84:87]
	v_mfma_f32_16x16x32_bf16 v[76:79], v[162:165], v[236:239], v[76:79]
	v_mfma_f32_16x16x32_bf16 v[68:71], v[186:189], v[236:239], v[68:71]
	v_mfma_f32_16x16x32_bf16 v[124:127], v[182:185], v[216:219], v[124:127]
	v_mfma_f32_16x16x32_bf16 v[116:119], v[190:193], v[216:219], v[116:119]
	v_mfma_f32_16x16x32_bf16 v[108:111], v[182:185], v[224:227], v[108:111]
	v_mfma_f32_16x16x32_bf16 v[100:103], v[190:193], v[224:227], v[100:103]
	v_mfma_f32_16x16x32_bf16 v[92:95], v[182:185], v[232:235], v[92:95]
	v_mfma_f32_16x16x32_bf16 v[84:87], v[190:193], v[232:235], v[84:87]
	v_mfma_f32_16x16x32_bf16 v[76:79], v[182:185], v[240:243], v[76:79]
	v_mfma_f32_16x16x32_bf16 v[68:71], v[190:193], v[240:243], v[68:71]
	v_mfma_f32_16x16x32_bf16 v[120:123], v[194:197], v[210:213], v[120:123]
	v_mfma_f32_16x16x32_bf16 v[112:115], v[202:205], v[210:213], v[112:115]
	v_mfma_f32_16x16x32_bf16 v[104:107], v[194:197], v[220:223], v[104:107]
	v_mfma_f32_16x16x32_bf16 v[96:99], v[202:205], v[220:223], v[96:99]
	v_mfma_f32_16x16x32_bf16 v[88:91], v[194:197], v[228:231], v[88:91]
	v_mfma_f32_16x16x32_bf16 v[80:83], v[202:205], v[228:231], v[80:83]
	v_mfma_f32_16x16x32_bf16 v[72:75], v[194:197], v[236:239], v[72:75]
	v_mfma_f32_16x16x32_bf16 v[64:67], v[202:205], v[236:239], v[64:67]
	v_mfma_f32_16x16x32_bf16 v[120:123], v[198:201], v[216:219], v[120:123]
	v_mfma_f32_16x16x32_bf16 v[112:115], v[206:209], v[216:219], v[112:115]
	v_mfma_f32_16x16x32_bf16 v[104:107], v[198:201], v[224:227], v[104:107]
	v_mfma_f32_16x16x32_bf16 v[96:99], v[206:209], v[224:227], v[96:99]
	v_mfma_f32_16x16x32_bf16 v[88:91], v[198:201], v[232:235], v[88:91]
	v_mfma_f32_16x16x32_bf16 v[80:83], v[206:209], v[232:235], v[80:83]
	v_mfma_f32_16x16x32_bf16 v[72:75], v[198:201], v[240:243], v[72:75]
	v_mfma_f32_16x16x32_bf16 v[64:67], v[206:209], v[240:243], v[64:67]
	s_setprio 0
	s_barrier
; #define PG8_STAGE(bufoff, gbase, voff) do { _Pragma("unroll") for (int _i = 0; _i < 2; ++_i) \
;         __builtin_amdgcn_global_load_lds((const unsigned*)((const char*)(gbase) + (voff)[_i]), (PG8_LAS unsigned*)(lds + (bufoff) + ldsw + _i * 8192), 16, 0, 0); } while (0)
; #define PG8_LDA(dst, b, h) do { _Pragma("unroll") for (int m = 0; m < 4; ++m) _Pragma("unroll") for (int k = 0; k < 2; ++k) dst[m][k] = *(const PG8_LAS bf16x8*)(lds + PG8_SA(b, h) + aoff + m * 2048 + k * 1024); } while (0)
; #define PG8_MMA(ai, bj, At, Bt) do { __builtin_amdgcn_s_setprio(1); _Pragma("unroll") for (int m = 0; m < 4; ++m) _Pragma("unroll") for (int n = 0; n < 2; ++n) _Pragma("unroll") for (int k = 0; k < 2; ++k) \
;         acc[ai][bj][m][n] = __builtin_amdgcn_mfma_f32_16x16x32_bf16(Bt[n][k], At[m][k], acc[ai][bj][m][n], 0, 0, 0); __builtin_amdgcn_s_setprio(0); } while (0)
; #define PG8_WAIT_V(n) asm volatile("s_waitcnt vmcnt(" #n ")" ::: "memory")
; #define PG8_WAIT_L(n) asm volatile("s_waitcnt lgkmcnt(" #n ")" ::: "memory")
; #define PG8_BAR __builtin_amdgcn_s_barrier()
; #define PG8_SCHED __builtin_amdgcn_sched_barrier(0)
; template <class Epi, class Sched, bool ALIGN_EPI = false, bool SP2 = false>
; __device__ __forceinline__ void gemm_phase(PG8_LAS unsigned char* lds, const Gemm g, const Sched& S, const Epi& E) {
;     ...
;             PG8_LDA(At, 1, 1); PG8_STAGE(PG8_SB(1, 0), b3, voffB); PG8_STAGE(PG8_SB(1, 1), b3 + hstep, voffB); PG8_STAGE(PG8_SA(1, 0), a3, voffA);
;             PG8_WAIT_V(8); PG8_WAIT_L(0); PG8_BAR; PG8_MMA(1, 0, At, B0); PG8_MMA(1, 1, At, B1); PG8_BAR; PG8_SCHED;
	s_add_i32 s11, s11, s29
	v_lshl_add_u64 v[170:171], v[244:245], 0, s[22:23]
	s_mov_b32 m0, s11
	ds_read_b128 v[210:213], v179 offset:49152
	ds_read_b128 v[216:219], v179 offset:50176
	ds_read_b128 v[220:223], v179 offset:51200
	ds_read_b128 v[224:227], v179 offset:52224
	ds_read_b128 v[228:231], v179 offset:53248
	ds_read_b128 v[232:235], v179 offset:54272
	ds_read_b128 v[236:239], v179 offset:55296
	ds_read_b128 v[240:243], v179 offset:56320
	global_load_lds_dwordx4 v[170:171], off
	v_lshl_add_u64 v[170:171], v[246:247], 0, s[22:23]
	s_add_i32 m0, s11, 0x2000
	s_add_i32 s11, s13, s29
	global_load_lds_dwordx4 v[170:171], off
	v_lshl_add_u64 v[170:171], v[248:249], 0, s[22:23]
	s_mov_b32 m0, s11
	s_nop 0
	global_load_lds_dwordx4 v[170:171], off
	v_lshl_add_u64 v[170:171], v[214:215], 0, s[22:23]
	s_add_i32 m0, s11, 0x2000
	s_nop 0
	global_load_lds_dwordx4 v[170:171], off
	v_lshl_add_u64 v[170:171], v[250:251], 0, s[22:23]
	s_mov_b32 m0, s50
	s_nop 0
	global_load_lds_dwordx4 v[170:171], off
	v_lshl_add_u64 v[170:171], v[252:253], 0, s[22:23]
	s_mov_b32 m0, s51
	s_nop 0
	global_load_lds_dwordx4 v[170:171], off
	s_waitcnt vmcnt(8)
	s_waitcnt lgkmcnt(0)
	s_barrier
	s_setprio 1
	s_waitcnt lgkmcnt(0)
	v_mfma_f32_16x16x32_bf16 v[60:63], v[162:165], v[210:213], v[60:63]
	v_mfma_f32_16x16x32_bf16 v[52:55], v[186:189], v[210:213], v[52:55]
	v_mfma_f32_16x16x32_bf16 v[44:47], v[162:165], v[220:223], v[44:47]
	v_mfma_f32_16x16x32_bf16 v[36:39], v[186:189], v[220:223], v[36:39]
	v_mfma_f32_16x16x32_bf16 v[28:31], v[162:165], v[228:231], v[28:31]
	v_mfma_f32_16x16x32_bf16 v[20:23], v[186:189], v[228:231], v[20:23]
	v_mfma_f32_16x16x32_bf16 v[12:15], v[162:165], v[236:239], v[12:15]
	v_mfma_f32_16x16x32_bf16 v[4:7], v[186:189], v[236:239], v[4:7]
	v_mfma_f32_16x16x32_bf16 v[60:63], v[182:185], v[216:219], v[60:63]
	v_mfma_f32_16x16x32_bf16 v[52:55], v[190:193], v[216:219], v[52:55]
	v_mfma_f32_16x16x32_bf16 v[44:47], v[182:185], v[224:227], v[44:47]
	v_mfma_f32_16x16x32_bf16 v[36:39], v[190:193], v[224:227], v[36:39]
	v_mfma_f32_16x16x32_bf16 v[28:31], v[182:185], v[232:235], v[28:31]
	v_mfma_f32_16x16x32_bf16 v[20:23], v[190:193], v[232:235], v[20:23]
	v_mfma_f32_16x16x32_bf16 v[12:15], v[182:185], v[240:243], v[12:15]
	v_mfma_f32_16x16x32_bf16 v[4:7], v[190:193], v[240:243], v[4:7]
	v_mfma_f32_16x16x32_bf16 v[56:59], v[194:197], v[210:213], v[56:59]
	v_mfma_f32_16x16x32_bf16 v[48:51], v[202:205], v[210:213], v[48:51]
	v_mfma_f32_16x16x32_bf16 v[40:43], v[194:197], v[220:223], v[40:43]
	v_mfma_f32_16x16x32_bf16 v[32:35], v[202:205], v[220:223], v[32:35]
	v_mfma_f32_16x16x32_bf16 v[24:27], v[194:197], v[228:231], v[24:27]
	v_mfma_f32_16x16x32_bf16 v[16:19], v[202:205], v[228:231], v[16:19]
	v_mfma_f32_16x16x32_bf16 v[8:11], v[194:197], v[236:239], v[8:11]
	v_mfma_f32_16x16x32_bf16 v[0:3], v[202:205], v[236:239], v[0:3]
	v_mfma_f32_16x16x32_bf16 v[56:59], v[198:201], v[216:219], v[56:59]
	v_mfma_f32_16x16x32_bf16 v[48:51], v[206:209], v[216:219], v[48:51]
	v_mfma_f32_16x16x32_bf16 v[40:43], v[198:201], v[224:227], v[40:43]
	v_mfma_f32_16x16x32_bf16 v[32:35], v[206:209], v[224:227], v[32:35]
	v_mfma_f32_16x16x32_bf16 v[24:27], v[198:201], v[232:235], v[24:27]
	v_mfma_f32_16x16x32_bf16 v[16:19], v[206:209], v[232:235], v[16:19]
	v_mfma_f32_16x16x32_bf16 v[8:11], v[198:201], v[240:243], v[8:11]
	v_mfma_f32_16x16x32_bf16 v[0:3], v[206:209], v[240:243], v[0:3]
	s_setprio 0
	s_barrier
	v_lshl_add_u64 v[158:159], v[158:159], 0, s[26:27]
	s_cmp_ge_i32 s10, s52
	v_lshl_add_u64 v[160:161], v[160:161], 0, s[26:27]
	s_cbranch_scc0 .LBB0_1776

; #define PG8_STAGE(bufoff, gbase, voff) do { _Pragma("unroll") for (int _i = 0; _i < 2; ++_i) \
;         __builtin_amdgcn_global_load_lds((const unsigned*)((const char*)(gbase) + (voff)[_i]), (PG8_LAS unsigned*)(lds + (bufoff) + ldsw + _i * 8192), 16, 0, 0); } while (0)
; #define PG8_LDA(dst, b, h) do { _Pragma("unroll") for (int m = 0; m < 4; ++m) _Pragma("unroll") for (int k = 0; k < 2; ++k) dst[m][k] = *(const PG8_LAS bf16x8*)(lds + PG8_SA(b, h) + aoff + m * 2048 + k * 1024); } while (0)
; #define PG8_LDB(dst, b, h) do { _Pragma("unroll") for (int n = 0; n < 2; ++n) _Pragma("unroll") for (int k = 0; k < 2; ++k) dst[n][k] = *(const PG8_LAS bf16x8*)(lds + PG8_SB(b, h) + boff + n * 2048 + k * 1024); } while (0)
; #define PG8_MMA(ai, bj, At, Bt) do { __builtin_amdgcn_s_setprio(1); _Pragma("unroll") for (int m = 0; m < 4; ++m) _Pragma("unroll") for (int n = 0; n < 2; ++n) _Pragma("unroll") for (int k = 0; k < 2; ++k) \
;         acc[ai][bj][m][n] = __builtin_amdgcn_mfma_f32_16x16x32_bf16(Bt[n][k], At[m][k], acc[ai][bj][m][n], 0, 0, 0); __builtin_amdgcn_s_setprio(0); } while (0)
; #define PG8_WAIT_V(n) asm volatile("s_waitcnt vmcnt(" #n ")" ::: "memory")
; #define PG8_WAIT_L(n) asm volatile("s_waitcnt lgkmcnt(" #n ")" ::: "memory")
; #define PG8_BAR __builtin_amdgcn_s_barrier()
; #define PG8_SCHED __builtin_amdgcn_sched_barrier(0)
; template <class Epi, class Sched, bool ALIGN_EPI = false, bool SP2 = false>
; __device__ __forceinline__ void gemm_phase(PG8_LAS unsigned char* lds, const Gemm g, const Sched& S, const Epi& E) {
;     ...
;         for (int t = 0; t < nt; t += 2) {
;             const bool last = (t == nt - 2);
;             const char* a1 = cA + (size_t)(t + 1) * kstep;
;             const char* a2 = last ? nA : cA + (size_t)(t + 2) * kstep; const char* b2 = last ? nB : cB + (size_t)(t + 2) * kstep;
;             const char* a3 = a2 + kstep; const char* b3 = b2 + kstep;
;             if (last && has_next) S.a_ready(nxt);
;             if constexpr (SP2) {
;             PG8_LDB(B0, 0, 0); PG8_LDB(B1, 0, 1); PG8_SCHED; PG8_LDA(At, 0, 0); PG8_STAGE(PG8_SA(1, 1), a1 + hstep, voffA);
;             PG8_WAIT_V(8); PG8_WAIT_L(0); PG8_BAR; PG8_MMA(0, 0, At, B0); PG8_MMA(0, 1, At, B1); PG8_BAR; PG8_SCHED;
;             PG8_LDA(At, 0, 1); PG8_STAGE(PG8_SB(0, 0), b2, voffB); PG8_STAGE(PG8_SB(0, 1), b2 + hstep, voffB); PG8_STAGE(PG8_SA(0, 0), a2, voffA);
.LBB0_1924:
	v_add_u32_e32 v192, s50, v161
	ds_read_b128 v[164:167], v162
	ds_read_b128 v[168:171], v162 offset:1024
	ds_read_b128 v[172:175], v162 offset:2048
	ds_read_b128 v[176:179], v162 offset:3072
	ds_read_b128 v[180:183], v192
	ds_read_b128 v[184:187], v192 offset:1024
	ds_read_b128 v[188:191], v192 offset:2048
	ds_read_b128 v[192:195], v192 offset:3072
	s_cmp_eq_u32 s49, s10
	v_lshl_add_u64 v[196:197], v[158:159], 0, s[24:25]
	s_cselect_b64 vcc, -1, 0
	s_add_i32 s10, s10, 2
	v_cndmask_b32_e32 v213, v197, v151, vcc
	v_cndmask_b32_e32 v212, v196, v150, vcc
	v_cndmask_b32_e32 v215, v155, v153, vcc
	v_cndmask_b32_e32 v214, v154, v152, vcc
	s_mov_b32 m0, s51
	v_lshl_add_u64 v[232:233], v[158:159], 0, v[146:147]
	ds_read_b128 v[196:199], v163
	ds_read_b128 v[200:203], v163 offset:1024
	ds_read_b128 v[204:207], v163 offset:2048
	ds_read_b128 v[208:211], v163 offset:3072
	ds_read_b128 v[216:219], v163 offset:4096
	ds_read_b128 v[220:223], v163 offset:5120
	ds_read_b128 v[224:227], v163 offset:6144
	ds_read_b128 v[228:231], v163 offset:7168
	global_load_lds_dwordx4 v[232:233], off
	v_lshl_add_u64 v[232:233], v[158:159], 0, v[144:145]
	s_mov_b32 m0, s52
	s_nop 0
	global_load_lds_dwordx4 v[232:233], off
	s_waitcnt vmcnt(8)
	s_waitcnt lgkmcnt(0)
	s_barrier
	s_setprio 1
	s_waitcnt lgkmcnt(0)
	v_mfma_f32_16x16x32_bf16 v[124:127], v[164:167], v[196:199], v[124:127]
	v_mfma_f32_16x16x32_bf16 v[120:123], v[172:175], v[196:199], v[120:123]
	v_mfma_f32_16x16x32_bf16 v[108:111], v[164:167], v[204:207], v[108:111]
	v_mfma_f32_16x16x32_bf16 v[104:107], v[172:175], v[204:207], v[104:107]
	v_mfma_f32_16x16x32_bf16 v[92:95], v[164:167], v[216:219], v[92:95]
	v_mfma_f32_16x16x32_bf16 v[88:91], v[172:175], v[216:219], v[88:91]
	v_mfma_f32_16x16x32_bf16 v[76:79], v[164:167], v[224:227], v[76:79]
	v_mfma_f32_16x16x32_bf16 v[72:75], v[172:175], v[224:227], v[72:75]
	v_mfma_f32_16x16x32_bf16 v[124:127], v[168:171], v[200:203], v[124:127]
	v_mfma_f32_16x16x32_bf16 v[120:123], v[176:179], v[200:203], v[120:123]
	v_mfma_f32_16x16x32_bf16 v[108:111], v[168:171], v[208:211], v[108:111]
	v_mfma_f32_16x16x32_bf16 v[104:107], v[176:179], v[208:211], v[104:107]
	v_mfma_f32_16x16x32_bf16 v[92:95], v[168:171], v[220:223], v[92:95]
	v_mfma_f32_16x16x32_bf16 v[88:91], v[176:179], v[220:223], v[88:91]
	v_mfma_f32_16x16x32_bf16 v[76:79], v[168:171], v[228:231], v[76:79]
	v_mfma_f32_16x16x32_bf16 v[72:75], v[176:179], v[228:231], v[72:75]
	v_mfma_f32_16x16x32_bf16 v[116:119], v[180:183], v[196:199], v[116:119]
	v_mfma_f32_16x16x32_bf16 v[112:115], v[188:191], v[196:199], v[112:115]
	v_mfma_f32_16x16x32_bf16 v[100:103], v[180:183], v[204:207], v[100:103]
	v_mfma_f32_16x16x32_bf16 v[96:99], v[188:191], v[204:207], v[96:99]
	v_mfma_f32_16x16x32_bf16 v[84:87], v[180:183], v[216:219], v[84:87]
	v_mfma_f32_16x16x32_bf16 v[80:83], v[188:191], v[216:219], v[80:83]
	v_mfma_f32_16x16x32_bf16 v[68:71], v[180:183], v[224:227], v[68:71]
	v_mfma_f32_16x16x32_bf16 v[64:67], v[188:191], v[224:227], v[64:67]
	v_mfma_f32_16x16x32_bf16 v[116:119], v[184:187], v[200:203], v[116:119]
	v_mfma_f32_16x16x32_bf16 v[112:115], v[192:195], v[200:203], v[112:115]
	v_mfma_f32_16x16x32_bf16 v[100:103], v[184:187], v[208:211], v[100:103]
	v_mfma_f32_16x16x32_bf16 v[96:99], v[192:195], v[208:211], v[96:99]
	v_mfma_f32_16x16x32_bf16 v[84:87], v[184:187], v[220:223], v[84:87]
	v_mfma_f32_16x16x32_bf16 v[80:83], v[192:195], v[220:223], v[80:83]
	v_mfma_f32_16x16x32_bf16 v[68:71], v[184:187], v[228:231], v[68:71]
	v_mfma_f32_16x16x32_bf16 v[64:67], v[192:195], v[228:231], v[64:67]
	s_setprio 0
	s_barrier
	s_mov_b32 m0, s53
	v_lshl_add_u64 v[232:233], v[214:215], 0, v[138:139]
	ds_read_b128 v[196:199], v163 offset:16384
	ds_read_b128 v[200:203], v163 offset:17408
	ds_read_b128 v[204:207], v163 offset:18432
	ds_read_b128 v[208:211], v163 offset:19456
	ds_read_b128 v[216:219], v163 offset:20480
	ds_read_b128 v[220:223], v163 offset:21504
	ds_read_b128 v[224:227], v163 offset:22528
	ds_read_b128 v[228:231], v163 offset:23552
	global_load_lds_dwordx4 v[232:233], off
	v_lshl_add_u64 v[234:235], v[214:215], 0, v[134:135]
	s_mov_b32 m0, s54
	v_lshl_add_u64 v[214:215], v[214:215], 0, s[14:15]
	global_load_lds_dwordx4 v[234:235], off
	v_lshl_add_u64 v[236:237], v[214:215], 0, v[138:139]
	s_mov_b32 m0, s55
	v_lshl_add_u64 v[214:215], v[214:215], 0, v[134:135]
	global_load_lds_dwordx4 v[236:237], off
	s_mov_b32 m0, s56
	v_lshl_add_u64 v[238:239], v[212:213], 0, v[140:141]
	global_load_lds_dwordx4 v[214:215], off
	s_mov_b32 m0, s37
	v_lshl_add_u64 v[240:241], v[212:213], 0, v[136:137]
	global_load_lds_dwordx4 v[238:239], off
	s_mov_b32 m0, s41
	s_nop 0
	global_load_lds_dwordx4 v[240:241], off
	s_waitcnt vmcnt(8)
	s_waitcnt lgkmcnt(0)
	s_barrier
; #define PG8_STAGE(bufoff, gbase, voff) do { _Pragma("unroll") for (int _i = 0; _i < 2; ++_i) \
;         __builtin_amdgcn_global_load_lds((const unsigned*)((const char*)(gbase) + (voff)[_i]), (PG8_LAS unsigned*)(lds + (bufoff) + ldsw + _i * 8192), 16, 0, 0); } while (0)
; #define PG8_LDA(dst, b, h) do { _Pragma("unroll") for (int m = 0; m < 4; ++m) _Pragma("unroll") for (int k = 0; k < 2; ++k) dst[m][k] = *(const PG8_LAS bf16x8*)(lds + PG8_SA(b, h) + aoff + m * 2048 + k * 1024); } while (0)
; #define PG8_LDB(dst, b, h) do { _Pragma("unroll") for (int n = 0; n < 2; ++n) _Pragma("unroll") for (int k = 0; k < 2; ++k) dst[n][k] = *(const PG8_LAS bf16x8*)(lds + PG8_SB(b, h) + boff + n * 2048 + k * 1024); } while (0)
; #define PG8_MMA(ai, bj, At, Bt) do { __builtin_amdgcn_s_setprio(1); _Pragma("unroll") for (int m = 0; m < 4; ++m) _Pragma("unroll") for (int n = 0; n < 2; ++n) _Pragma("unroll") for (int k = 0; k < 2; ++k) \
;         acc[ai][bj][m][n] = __builtin_amdgcn_mfma_f32_16x16x32_bf16(Bt[n][k], At[m][k], acc[ai][bj][m][n], 0, 0, 0); __builtin_amdgcn_s_setprio(0); } while (0)
; #define PG8_WAIT_V(n) asm volatile("s_waitcnt vmcnt(" #n ")" ::: "memory")
; #define PG8_WAIT_L(n) asm volatile("s_waitcnt lgkmcnt(" #n ")" ::: "memory")
; #define PG8_BAR __builtin_amdgcn_s_barrier()
; #define PG8_SCHED __builtin_amdgcn_sched_barrier(0)
; template <class Epi, class Sched, bool ALIGN_EPI = false, bool SP2 = false>
; __device__ __forceinline__ void gemm_phase(PG8_LAS unsigned char* lds, const Gemm g, const Sched& S, const Epi& E) {
;     ...
;             PG8_WAIT_V(8); PG8_WAIT_L(0); PG8_BAR; PG8_MMA(1, 0, At, B0); PG8_MMA(1, 1, At, B1); PG8_BAR; PG8_SCHED;
;             PG8_LDB(B0, 1, 0); PG8_LDB(B1, 1, 1); PG8_SCHED; PG8_LDA(At, 1, 0); PG8_STAGE(PG8_SA(0, 1), a2 + hstep, voffA);
;             PG8_WAIT_V(8); PG8_WAIT_L(0); PG8_BAR; PG8_MMA(0, 0, At, B0); PG8_MMA(0, 1, At, B1); PG8_BAR; PG8_SCHED;
	s_setprio 1
	s_waitcnt lgkmcnt(0)
	v_mfma_f32_16x16x32_bf16 v[60:63], v[164:167], v[196:199], v[60:63]
	v_mfma_f32_16x16x32_bf16 v[56:59], v[172:175], v[196:199], v[56:59]
	v_mfma_f32_16x16x32_bf16 v[44:47], v[164:167], v[204:207], v[44:47]
	v_mfma_f32_16x16x32_bf16 v[40:43], v[172:175], v[204:207], v[40:43]
	v_mfma_f32_16x16x32_bf16 v[28:31], v[164:167], v[216:219], v[28:31]
	v_mfma_f32_16x16x32_bf16 v[24:27], v[172:175], v[216:219], v[24:27]
	v_mfma_f32_16x16x32_bf16 v[12:15], v[164:167], v[224:227], v[12:15]
	v_mfma_f32_16x16x32_bf16 v[8:11], v[172:175], v[224:227], v[8:11]
	v_mfma_f32_16x16x32_bf16 v[60:63], v[168:171], v[200:203], v[60:63]
	v_mfma_f32_16x16x32_bf16 v[56:59], v[176:179], v[200:203], v[56:59]
	v_mfma_f32_16x16x32_bf16 v[44:47], v[168:171], v[208:211], v[44:47]
	v_mfma_f32_16x16x32_bf16 v[40:43], v[176:179], v[208:211], v[40:43]
	v_mfma_f32_16x16x32_bf16 v[28:31], v[168:171], v[220:223], v[28:31]
	v_mfma_f32_16x16x32_bf16 v[24:27], v[176:179], v[220:223], v[24:27]
	v_mfma_f32_16x16x32_bf16 v[12:15], v[168:171], v[228:231], v[12:15]
	v_mfma_f32_16x16x32_bf16 v[8:11], v[176:179], v[228:231], v[8:11]
	v_mfma_f32_16x16x32_bf16 v[52:55], v[180:183], v[196:199], v[52:55]
	v_mfma_f32_16x16x32_bf16 v[48:51], v[188:191], v[196:199], v[48:51]
	v_mfma_f32_16x16x32_bf16 v[36:39], v[180:183], v[204:207], v[36:39]
	v_mfma_f32_16x16x32_bf16 v[32:35], v[188:191], v[204:207], v[32:35]
	v_mfma_f32_16x16x32_bf16 v[20:23], v[180:183], v[216:219], v[20:23]
	v_mfma_f32_16x16x32_bf16 v[16:19], v[188:191], v[216:219], v[16:19]
	v_mfma_f32_16x16x32_bf16 v[4:7], v[180:183], v[224:227], v[4:7]
	v_mfma_f32_16x16x32_bf16 v[0:3], v[188:191], v[224:227], v[0:3]
	v_mfma_f32_16x16x32_bf16 v[52:55], v[184:187], v[200:203], v[52:55]
	v_mfma_f32_16x16x32_bf16 v[48:51], v[192:195], v[200:203], v[48:51]
	v_mfma_f32_16x16x32_bf16 v[36:39], v[184:187], v[208:211], v[36:39]
	v_mfma_f32_16x16x32_bf16 v[32:35], v[192:195], v[208:211], v[32:35]
	v_mfma_f32_16x16x32_bf16 v[20:23], v[184:187], v[220:223], v[20:23]
	v_mfma_f32_16x16x32_bf16 v[16:19], v[192:195], v[220:223], v[16:19]
	v_mfma_f32_16x16x32_bf16 v[4:7], v[184:187], v[228:231], v[4:7]
	v_mfma_f32_16x16x32_bf16 v[0:3], v[192:195], v[228:231], v[0:3]
	s_setprio 0
	s_barrier
	v_add_u32_e32 v176, s57, v161
	v_add_u32_e32 v192, s58, v161
	ds_read_b128 v[164:167], v176
	ds_read_b128 v[168:171], v176 offset:1024
	ds_read_b128 v[172:175], v176 offset:2048
	ds_read_b128 v[176:179], v176 offset:3072
	ds_read_b128 v[180:183], v192
	ds_read_b128 v[184:187], v192 offset:1024
	ds_read_b128 v[188:191], v192 offset:2048
	ds_read_b128 v[192:195], v192 offset:3072
	v_lshl_add_u64 v[212:213], v[212:213], 0, s[14:15]
	s_mov_b32 m0, s44
	v_lshl_add_u64 v[242:243], v[212:213], 0, v[140:141]
	ds_read_b128 v[196:199], v163 offset:32768
	ds_read_b128 v[200:203], v163 offset:33792
	ds_read_b128 v[204:207], v163 offset:34816
	ds_read_b128 v[208:211], v163 offset:35840
	ds_read_b128 v[216:219], v163 offset:36864
	ds_read_b128 v[220:223], v163 offset:37888
	ds_read_b128 v[224:227], v163 offset:38912
	ds_read_b128 v[228:231], v163 offset:39936
	global_load_lds_dwordx4 v[242:243], off
	v_lshl_add_u64 v[212:213], v[212:213], 0, v[136:137]
	s_mov_b32 m0, s45
	s_nop 0
	global_load_lds_dwordx4 v[212:213], off
	s_waitcnt vmcnt(8)
	s_waitcnt lgkmcnt(0)
	s_barrier
	s_setprio 1
	s_waitcnt lgkmcnt(0)
	v_mfma_f32_16x16x32_bf16 v[124:127], v[164:167], v[196:199], v[124:127]
	v_mfma_f32_16x16x32_bf16 v[120:123], v[172:175], v[196:199], v[120:123]
	v_mfma_f32_16x16x32_bf16 v[108:111], v[164:167], v[204:207], v[108:111]
	v_mfma_f32_16x16x32_bf16 v[104:107], v[172:175], v[204:207], v[104:107]
	v_mfma_f32_16x16x32_bf16 v[92:95], v[164:167], v[216:219], v[92:95]
	v_mfma_f32_16x16x32_bf16 v[88:91], v[172:175], v[216:219], v[88:91]
	v_mfma_f32_16x16x32_bf16 v[76:79], v[164:167], v[224:227], v[76:79]
	v_mfma_f32_16x16x32_bf16 v[72:75], v[172:175], v[224:227], v[72:75]
	v_mfma_f32_16x16x32_bf16 v[124:127], v[168:171], v[200:203], v[124:127]
	v_mfma_f32_16x16x32_bf16 v[120:123], v[176:179], v[200:203], v[120:123]
	v_mfma_f32_16x16x32_bf16 v[108:111], v[168:171], v[208:211], v[108:111]
	v_mfma_f32_16x16x32_bf16 v[104:107], v[176:179], v[208:211], v[104:107]
	v_mfma_f32_16x16x32_bf16 v[92:95], v[168:171], v[220:223], v[92:95]
	v_mfma_f32_16x16x32_bf16 v[88:91], v[176:179], v[220:223], v[88:91]
	v_mfma_f32_16x16x32_bf16 v[76:79], v[168:171], v[228:231], v[76:79]
	v_mfma_f32_16x16x32_bf16 v[72:75], v[176:179], v[228:231], v[72:75]
	v_mfma_f32_16x16x32_bf16 v[116:119], v[180:183], v[196:199], v[116:119]
	v_mfma_f32_16x16x32_bf16 v[112:115], v[188:191], v[196:199], v[112:115]
	v_mfma_f32_16x16x32_bf16 v[100:103], v[180:183], v[204:207], v[100:103]
	v_mfma_f32_16x16x32_bf16 v[96:99], v[188:191], v[204:207], v[96:99]
	v_mfma_f32_16x16x32_bf16 v[84:87], v[180:183], v[216:219], v[84:87]
	v_mfma_f32_16x16x32_bf16 v[80:83], v[188:191], v[216:219], v[80:83]
	v_mfma_f32_16x16x32_bf16 v[68:71], v[180:183], v[224:227], v[68:71]
	v_mfma_f32_16x16x32_bf16 v[64:67], v[188:191], v[224:227], v[64:67]
	v_mfma_f32_16x16x32_bf16 v[116:119], v[184:187], v[200:203], v[116:119]
	v_mfma_f32_16x16x32_bf16 v[112:115], v[192:195], v[200:203], v[112:115]
	v_mfma_f32_16x16x32_bf16 v[100:103], v[184:187], v[208:211], v[100:103]
	v_mfma_f32_16x16x32_bf16 v[96:99], v[192:195], v[208:211], v[96:99]
	v_mfma_f32_16x16x32_bf16 v[84:87], v[184:187], v[220:223], v[84:87]
	v_mfma_f32_16x16x32_bf16 v[80:83], v[192:195], v[220:223], v[80:83]
	v_mfma_f32_16x16x32_bf16 v[68:71], v[184:187], v[228:231], v[68:71]
	v_mfma_f32_16x16x32_bf16 v[64:67], v[192:195], v[228:231], v[64:67]
	s_setprio 0
	s_barrier
; #define PG8_STAGE(bufoff, gbase, voff) do { _Pragma("unroll") for (int _i = 0; _i < 2; ++_i) \
;         __builtin_amdgcn_global_load_lds((const unsigned*)((const char*)(gbase) + (voff)[_i]), (PG8_LAS unsigned*)(lds + (bufoff) + ldsw + _i * 8192), 16, 0, 0); } while (0)
; #define PG8_LDA(dst, b, h) do { _Pragma("unroll") for (int m = 0; m < 4; ++m) _Pragma("unroll") for (int k = 0; k < 2; ++k) dst[m][k] = *(const PG8_LAS bf16x8*)(lds + PG8_SA(b, h) + aoff + m * 2048 + k * 1024); } while (0)
; #define PG8_MMA(ai, bj, At, Bt) do { __builtin_amdgcn_s_setprio(1); _Pragma("unroll") for (int m = 0; m < 4; ++m) _Pragma("unroll") for (int n = 0; n < 2; ++n) _Pragma("unroll") for (int k = 0; k < 2; ++k) \
;         acc[ai][bj][m][n] = __builtin_amdgcn_mfma_f32_16x16x32_bf16(Bt[n][k], At[m][k], acc[ai][bj][m][n], 0, 0, 0); __builtin_amdgcn_s_setprio(0); } while (0)
; #define PG8_WAIT_V(n) asm volatile("s_waitcnt vmcnt(" #n ")" ::: "memory")
; #define PG8_WAIT_L(n) asm volatile("s_waitcnt lgkmcnt(" #n ")" ::: "memory")
; #define PG8_BAR __builtin_amdgcn_s_barrier()
; #define PG8_SCHED __builtin_amdgcn_sched_barrier(0)
; template <class Epi, class Sched, bool ALIGN_EPI = false, bool SP2 = false>
; __device__ __forceinline__ void gemm_phase(PG8_LAS unsigned char* lds, const Gemm g, const Sched& S, const Epi& E) {
;     ...
;             PG8_LDA(At, 1, 1); PG8_STAGE(PG8_SB(1, 0), b3, voffB); PG8_STAGE(PG8_SB(1, 1), b3 + hstep, voffB); PG8_STAGE(PG8_SA(1, 0), a3, voffA);
;             PG8_WAIT_V(8); PG8_WAIT_L(0); PG8_BAR; PG8_MMA(1, 0, At, B0); PG8_MMA(1, 1, At, B1); PG8_BAR; PG8_SCHED;
	s_mov_b32 m0, s59
	v_lshl_add_u64 v[212:213], v[232:233], 0, s[24:25]
	ds_read_b128 v[196:199], v163 offset:49152
	ds_read_b128 v[200:203], v163 offset:50176
	ds_read_b128 v[204:207], v163 offset:51200
	ds_read_b128 v[208:211], v163 offset:52224
	ds_read_b128 v[216:219], v163 offset:53248
	ds_read_b128 v[220:223], v163 offset:54272
	ds_read_b128 v[224:227], v163 offset:55296
	ds_read_b128 v[228:231], v163 offset:56320
	global_load_lds_dwordx4 v[212:213], off
	v_lshl_add_u64 v[212:213], v[234:235], 0, s[24:25]
	s_mov_b32 m0, s60
	s_nop 0
	global_load_lds_dwordx4 v[212:213], off
	v_lshl_add_u64 v[212:213], v[236:237], 0, s[24:25]
	s_mov_b32 m0, s61
	s_nop 0
	global_load_lds_dwordx4 v[212:213], off
	v_lshl_add_u64 v[212:213], v[214:215], 0, s[24:25]
	s_mov_b32 m0, s62
	s_nop 0
	global_load_lds_dwordx4 v[212:213], off
	v_lshl_add_u64 v[212:213], v[238:239], 0, s[24:25]
	s_mov_b32 m0, s46
	s_nop 0
	global_load_lds_dwordx4 v[212:213], off
	v_lshl_add_u64 v[212:213], v[240:241], 0, s[24:25]
	s_mov_b32 m0, s47
	s_nop 0
	global_load_lds_dwordx4 v[212:213], off
	s_waitcnt vmcnt(8)
	s_waitcnt lgkmcnt(0)
	s_barrier
	s_setprio 1
	s_waitcnt lgkmcnt(0)
	v_mfma_f32_16x16x32_bf16 v[60:63], v[164:167], v[196:199], v[60:63]
	v_mfma_f32_16x16x32_bf16 v[56:59], v[172:175], v[196:199], v[56:59]
	v_mfma_f32_16x16x32_bf16 v[44:47], v[164:167], v[204:207], v[44:47]
	v_mfma_f32_16x16x32_bf16 v[40:43], v[172:175], v[204:207], v[40:43]
	v_mfma_f32_16x16x32_bf16 v[28:31], v[164:167], v[216:219], v[28:31]
	v_mfma_f32_16x16x32_bf16 v[24:27], v[172:175], v[216:219], v[24:27]
	v_mfma_f32_16x16x32_bf16 v[12:15], v[164:167], v[224:227], v[12:15]
	v_mfma_f32_16x16x32_bf16 v[8:11], v[172:175], v[224:227], v[8:11]
	v_mfma_f32_16x16x32_bf16 v[60:63], v[168:171], v[200:203], v[60:63]
	v_mfma_f32_16x16x32_bf16 v[56:59], v[176:179], v[200:203], v[56:59]
	v_mfma_f32_16x16x32_bf16 v[44:47], v[168:171], v[208:211], v[44:47]
	v_mfma_f32_16x16x32_bf16 v[40:43], v[176:179], v[208:211], v[40:43]
	v_mfma_f32_16x16x32_bf16 v[28:31], v[168:171], v[220:223], v[28:31]
	v_mfma_f32_16x16x32_bf16 v[24:27], v[176:179], v[220:223], v[24:27]
	v_mfma_f32_16x16x32_bf16 v[12:15], v[168:171], v[228:231], v[12:15]
	v_mfma_f32_16x16x32_bf16 v[8:11], v[176:179], v[228:231], v[8:11]
	v_mfma_f32_16x16x32_bf16 v[52:55], v[180:183], v[196:199], v[52:55]
	v_mfma_f32_16x16x32_bf16 v[48:51], v[188:191], v[196:199], v[48:51]
	v_mfma_f32_16x16x32_bf16 v[36:39], v[180:183], v[204:207], v[36:39]
	v_mfma_f32_16x16x32_bf16 v[32:35], v[188:191], v[204:207], v[32:35]
	v_mfma_f32_16x16x32_bf16 v[20:23], v[180:183], v[216:219], v[20:23]
	v_mfma_f32_16x16x32_bf16 v[16:19], v[188:191], v[216:219], v[16:19]
	v_mfma_f32_16x16x32_bf16 v[4:7], v[180:183], v[224:227], v[4:7]
	v_mfma_f32_16x16x32_bf16 v[0:3], v[188:191], v[224:227], v[0:3]
	v_mfma_f32_16x16x32_bf16 v[52:55], v[184:187], v[200:203], v[52:55]
	v_mfma_f32_16x16x32_bf16 v[48:51], v[192:195], v[200:203], v[48:51]
	v_mfma_f32_16x16x32_bf16 v[36:39], v[184:187], v[208:211], v[36:39]
	v_mfma_f32_16x16x32_bf16 v[32:35], v[192:195], v[208:211], v[32:35]
	v_mfma_f32_16x16x32_bf16 v[20:23], v[184:187], v[220:223], v[20:23]
	v_mfma_f32_16x16x32_bf16 v[16:19], v[192:195], v[220:223], v[16:19]
	v_mfma_f32_16x16x32_bf16 v[4:7], v[184:187], v[228:231], v[4:7]
	v_mfma_f32_16x16x32_bf16 v[0:3], v[192:195], v[228:231], v[0:3]
	s_setprio 0
	s_barrier
	v_lshl_add_u64 v[154:155], v[154:155], 0, s[28:29]
	s_cmp_ge_i32 s10, s48
	v_lshl_add_u64 v[158:159], v[158:159], 0, s[28:29]
	s_cbranch_scc0 .LBB0_1924

; #define PG8_STAGE(bufoff, gbase, voff) do { _Pragma("unroll") for (int _i = 0; _i < 2; ++_i) \
;         __builtin_amdgcn_global_load_lds((const unsigned*)((const char*)(gbase) + (voff)[_i]), (PG8_LAS unsigned*)(lds + (bufoff) + ldsw + _i * 8192), 16, 0, 0); } while (0)
; #define PG8_LDA(dst, b, h) do { _Pragma("unroll") for (int m = 0; m < 4; ++m) _Pragma("unroll") for (int k = 0; k < 2; ++k) dst[m][k] = *(const PG8_LAS bf16x8*)(lds + PG8_SA(b, h) + aoff + m * 2048 + k * 1024); } while (0)
; #define PG8_LDB(dst, b, h) do { _Pragma("unroll") for (int n = 0; n < 2; ++n) _Pragma("unroll") for (int k = 0; k < 2; ++k) dst[n][k] = *(const PG8_LAS bf16x8*)(lds + PG8_SB(b, h) + boff + n * 2048 + k * 1024); } while (0)
; #define PG8_MMA(ai, bj, At, Bt) do { __builtin_amdgcn_s_setprio(1); _Pragma("unroll") for (int m = 0; m < 4; ++m) _Pragma("unroll") for (int n = 0; n < 2; ++n) _Pragma("unroll") for (int k = 0; k < 2; ++k) \
;         acc[ai][bj][m][n] = __builtin_amdgcn_mfma_f32_16x16x32_bf16(Bt[n][k], At[m][k], acc[ai][bj][m][n], 0, 0, 0); __builtin_amdgcn_s_setprio(0); } while (0)
; #define PG8_WAIT_V(n) asm volatile("s_waitcnt vmcnt(" #n ")" ::: "memory")
; #define PG8_WAIT_L(n) asm volatile("s_waitcnt lgkmcnt(" #n ")" ::: "memory")
; #define PG8_BAR __builtin_amdgcn_s_barrier()
; #define PG8_SCHED __builtin_amdgcn_sched_barrier(0)
; template <class Epi, class Sched, bool ALIGN_EPI = false, bool SP2 = false>
; __device__ __forceinline__ void gemm_phase(PG8_LAS unsigned char* lds, const Gemm g, const Sched& S, const Epi& E) {
;     ...
;         for (int t = 0; t < nt; t += 2) {
;             const bool last = (t == nt - 2);
;             const char* a1 = cA + (size_t)(t + 1) * kstep;
;             const char* a2 = last ? nA : cA + (size_t)(t + 2) * kstep; const char* b2 = last ? nB : cB + (size_t)(t + 2) * kstep;
;             const char* a3 = a2 + kstep; const char* b3 = b2 + kstep;
;             if (last && has_next) S.a_ready(nxt);
;             if constexpr (SP2) {
;             PG8_LDB(B0, 0, 0); PG8_LDB(B1, 0, 1); PG8_SCHED; PG8_LDA(At, 0, 0); PG8_STAGE(PG8_SA(1, 1), a1 + hstep, voffA);
;             PG8_WAIT_V(8); PG8_WAIT_L(0); PG8_BAR; PG8_MMA(0, 0, At, B0); PG8_MMA(0, 1, At, B1); PG8_BAR; PG8_SCHED;
;             PG8_LDA(At, 0, 1); PG8_STAGE(PG8_SB(0, 0), b2, voffB); PG8_STAGE(PG8_SB(0, 1), b2 + hstep, voffB); PG8_STAGE(PG8_SA(0, 0), a2, voffA);
.LBB0_1947:
	v_add_u32_e32 v178, s53, v216
	v_add_u32_e32 v194, s54, v216
	ds_read_b128 v[138:141], v178
	ds_read_b128 v[142:145], v178 offset:1024
	ds_read_b128 v[146:149], v178 offset:2048
	ds_read_b128 v[178:181], v178 offset:3072
	ds_read_b128 v[182:185], v194
	ds_read_b128 v[186:189], v194 offset:1024
	ds_read_b128 v[190:193], v194 offset:2048
	ds_read_b128 v[194:197], v194 offset:3072
	s_cmp_eq_u32 s47, s10
	v_lshl_add_u64 v[198:199], v[136:137], 0, s[20:21]
	s_cselect_b64 vcc, -1, 0
	s_add_i32 s10, s10, 2
	v_cndmask_b32_e32 v215, v199, v175, vcc
	v_cndmask_b32_e32 v214, v198, v174, vcc
	v_cndmask_b32_e32 v237, v135, v177, vcc
	v_cndmask_b32_e32 v236, v134, v176, vcc
	v_lshl_add_u64 v[238:239], v[136:137], 0, v[168:169]
	s_add_i32 m0, s34, 0xc000
	ds_read_b128 v[198:201], v218
	ds_read_b128 v[202:205], v218 offset:1024
	ds_read_b128 v[206:209], v218 offset:2048
	ds_read_b128 v[210:213], v218 offset:3072
	ds_read_b128 v[220:223], v218 offset:4096
	ds_read_b128 v[224:227], v218 offset:5120
	ds_read_b128 v[228:231], v218 offset:6144
	ds_read_b128 v[232:235], v218 offset:7168
	global_load_lds_dwordx4 v[238:239], off
	v_lshl_add_u64 v[238:239], v[136:137], 0, v[166:167]
	s_add_i32 m0, s34, 0xe000
	s_nop 0
	global_load_lds_dwordx4 v[238:239], off
	s_waitcnt vmcnt(8)
	s_waitcnt lgkmcnt(0)
	s_barrier
	s_setprio 1
	s_waitcnt lgkmcnt(0)
	v_mfma_f32_16x16x32_bf16 v[130:133], v[138:141], v[198:201], v[130:133]
	v_mfma_f32_16x16x32_bf16 v[126:129], v[146:149], v[198:201], v[126:129]
	v_mfma_f32_16x16x32_bf16 v[114:117], v[138:141], v[206:209], v[114:117]
	v_mfma_f32_16x16x32_bf16 v[110:113], v[146:149], v[206:209], v[110:113]
	v_mfma_f32_16x16x32_bf16 v[98:101], v[138:141], v[220:223], v[98:101]
	v_mfma_f32_16x16x32_bf16 v[94:97], v[146:149], v[220:223], v[94:97]
	v_mfma_f32_16x16x32_bf16 v[82:85], v[138:141], v[228:231], v[82:85]
	v_mfma_f32_16x16x32_bf16 v[78:81], v[146:149], v[228:231], v[78:81]
	v_mfma_f32_16x16x32_bf16 v[130:133], v[142:145], v[202:205], v[130:133]
	v_mfma_f32_16x16x32_bf16 v[126:129], v[178:181], v[202:205], v[126:129]
	v_mfma_f32_16x16x32_bf16 v[114:117], v[142:145], v[210:213], v[114:117]
	v_mfma_f32_16x16x32_bf16 v[110:113], v[178:181], v[210:213], v[110:113]
	v_mfma_f32_16x16x32_bf16 v[98:101], v[142:145], v[224:227], v[98:101]
	v_mfma_f32_16x16x32_bf16 v[94:97], v[178:181], v[224:227], v[94:97]
	v_mfma_f32_16x16x32_bf16 v[82:85], v[142:145], v[232:235], v[82:85]
	v_mfma_f32_16x16x32_bf16 v[78:81], v[178:181], v[232:235], v[78:81]
	v_mfma_f32_16x16x32_bf16 v[122:125], v[182:185], v[198:201], v[122:125]
	v_mfma_f32_16x16x32_bf16 v[118:121], v[190:193], v[198:201], v[118:121]
	v_mfma_f32_16x16x32_bf16 v[106:109], v[182:185], v[206:209], v[106:109]
	v_mfma_f32_16x16x32_bf16 v[102:105], v[190:193], v[206:209], v[102:105]
	v_mfma_f32_16x16x32_bf16 v[90:93], v[182:185], v[220:223], v[90:93]
	v_mfma_f32_16x16x32_bf16 v[86:89], v[190:193], v[220:223], v[86:89]
	v_mfma_f32_16x16x32_bf16 v[74:77], v[182:185], v[228:231], v[74:77]
	v_mfma_f32_16x16x32_bf16 v[70:73], v[190:193], v[228:231], v[70:73]
	v_mfma_f32_16x16x32_bf16 v[122:125], v[186:189], v[202:205], v[122:125]
	v_mfma_f32_16x16x32_bf16 v[118:121], v[194:197], v[202:205], v[118:121]
	v_mfma_f32_16x16x32_bf16 v[106:109], v[186:189], v[210:213], v[106:109]
	v_mfma_f32_16x16x32_bf16 v[102:105], v[194:197], v[210:213], v[102:105]
	v_mfma_f32_16x16x32_bf16 v[90:93], v[186:189], v[224:227], v[90:93]
	v_mfma_f32_16x16x32_bf16 v[86:89], v[194:197], v[224:227], v[86:89]
	v_mfma_f32_16x16x32_bf16 v[74:77], v[186:189], v[232:235], v[74:77]
	v_mfma_f32_16x16x32_bf16 v[70:73], v[194:197], v[232:235], v[70:73]
	s_setprio 0
	s_barrier
	s_add_i32 s11, s53, s29
	v_lshl_add_u64 v[238:239], v[236:237], 0, v[158:159]
	s_mov_b32 m0, s11
	ds_read_b128 v[198:201], v218 offset:16384
	ds_read_b128 v[202:205], v218 offset:17408
	ds_read_b128 v[206:209], v218 offset:18432
	ds_read_b128 v[210:213], v218 offset:19456
	ds_read_b128 v[220:223], v218 offset:20480
	ds_read_b128 v[224:227], v218 offset:21504
	ds_read_b128 v[228:231], v218 offset:22528
	ds_read_b128 v[232:235], v218 offset:23552
	global_load_lds_dwordx4 v[238:239], off
	v_lshl_add_u64 v[240:241], v[236:237], 0, v[162:163]
	s_add_i32 m0, s11, 0x2000
	v_lshl_add_u64 v[236:237], v[236:237], 0, s[12:13]
	s_add_i32 s11, s54, s29
	global_load_lds_dwordx4 v[240:241], off
	v_lshl_add_u64 v[242:243], v[236:237], 0, v[158:159]
	s_mov_b32 m0, s11
	v_lshl_add_u64 v[236:237], v[236:237], 0, v[162:163]
	global_load_lds_dwordx4 v[242:243], off
	s_add_i32 m0, s11, 0x2000
	v_lshl_add_u64 v[244:245], v[214:215], 0, v[154:155]
	global_load_lds_dwordx4 v[236:237], off
	s_mov_b32 m0, s34
	v_lshl_add_u64 v[246:247], v[214:215], 0, v[160:161]
	global_load_lds_dwordx4 v[244:245], off
	s_mov_b32 m0, s35
	s_nop 0
	global_load_lds_dwordx4 v[246:247], off
	s_waitcnt vmcnt(8)
	s_waitcnt lgkmcnt(0)
	s_barrier
; #define PG8_STAGE(bufoff, gbase, voff) do { _Pragma("unroll") for (int _i = 0; _i < 2; ++_i) \
;         __builtin_amdgcn_global_load_lds((const unsigned*)((const char*)(gbase) + (voff)[_i]), (PG8_LAS unsigned*)(lds + (bufoff) + ldsw + _i * 8192), 16, 0, 0); } while (0)
; #define PG8_LDA(dst, b, h) do { _Pragma("unroll") for (int m = 0; m < 4; ++m) _Pragma("unroll") for (int k = 0; k < 2; ++k) dst[m][k] = *(const PG8_LAS bf16x8*)(lds + PG8_SA(b, h) + aoff + m * 2048 + k * 1024); } while (0)
; #define PG8_LDB(dst, b, h) do { _Pragma("unroll") for (int n = 0; n < 2; ++n) _Pragma("unroll") for (int k = 0; k < 2; ++k) dst[n][k] = *(const PG8_LAS bf16x8*)(lds + PG8_SB(b, h) + boff + n * 2048 + k * 1024); } while (0)
; #define PG8_MMA(ai, bj, At, Bt) do { __builtin_amdgcn_s_setprio(1); _Pragma("unroll") for (int m = 0; m < 4; ++m) _Pragma("unroll") for (int n = 0; n < 2; ++n) _Pragma("unroll") for (int k = 0; k < 2; ++k) \
;         acc[ai][bj][m][n] = __builtin_amdgcn_mfma_f32_16x16x32_bf16(Bt[n][k], At[m][k], acc[ai][bj][m][n], 0, 0, 0); __builtin_amdgcn_s_setprio(0); } while (0)
; #define PG8_WAIT_V(n) asm volatile("s_waitcnt vmcnt(" #n ")" ::: "memory")
; #define PG8_WAIT_L(n) asm volatile("s_waitcnt lgkmcnt(" #n ")" ::: "memory")
; #define PG8_BAR __builtin_amdgcn_s_barrier()
; #define PG8_SCHED __builtin_amdgcn_sched_barrier(0)
; template <class Epi, class Sched, bool ALIGN_EPI = false, bool SP2 = false>
; __device__ __forceinline__ void gemm_phase(PG8_LAS unsigned char* lds, const Gemm g, const Sched& S, const Epi& E) {
;     ...
;             PG8_WAIT_V(8); PG8_WAIT_L(0); PG8_BAR; PG8_MMA(1, 0, At, B0); PG8_MMA(1, 1, At, B1); PG8_BAR; PG8_SCHED;
;             PG8_LDB(B0, 1, 0); PG8_LDB(B1, 1, 1); PG8_SCHED; PG8_LDA(At, 1, 0); PG8_STAGE(PG8_SA(0, 1), a2 + hstep, voffA);
;             PG8_WAIT_V(8); PG8_WAIT_L(0); PG8_BAR; PG8_MMA(0, 0, At, B0); PG8_MMA(0, 1, At, B1); PG8_BAR; PG8_SCHED;
	s_setprio 1
	s_waitcnt lgkmcnt(0)
	v_mfma_f32_16x16x32_bf16 v[66:69], v[138:141], v[198:201], v[66:69]
	v_mfma_f32_16x16x32_bf16 v[62:65], v[146:149], v[198:201], v[62:65]
	v_mfma_f32_16x16x32_bf16 v[50:53], v[138:141], v[206:209], v[50:53]
	v_mfma_f32_16x16x32_bf16 v[46:49], v[146:149], v[206:209], v[46:49]
	v_mfma_f32_16x16x32_bf16 v[34:37], v[138:141], v[220:223], v[34:37]
	v_mfma_f32_16x16x32_bf16 v[30:33], v[146:149], v[220:223], v[30:33]
	v_mfma_f32_16x16x32_bf16 v[18:21], v[138:141], v[228:231], v[18:21]
	v_mfma_f32_16x16x32_bf16 v[14:17], v[146:149], v[228:231], v[14:17]
	v_mfma_f32_16x16x32_bf16 v[66:69], v[142:145], v[202:205], v[66:69]
	v_mfma_f32_16x16x32_bf16 v[62:65], v[178:181], v[202:205], v[62:65]
	v_mfma_f32_16x16x32_bf16 v[50:53], v[142:145], v[210:213], v[50:53]
	v_mfma_f32_16x16x32_bf16 v[46:49], v[178:181], v[210:213], v[46:49]
	v_mfma_f32_16x16x32_bf16 v[34:37], v[142:145], v[224:227], v[34:37]
	v_mfma_f32_16x16x32_bf16 v[30:33], v[178:181], v[224:227], v[30:33]
	v_mfma_f32_16x16x32_bf16 v[18:21], v[142:145], v[232:235], v[18:21]
	v_mfma_f32_16x16x32_bf16 v[14:17], v[178:181], v[232:235], v[14:17]
	v_mfma_f32_16x16x32_bf16 v[58:61], v[182:185], v[198:201], v[58:61]
	v_mfma_f32_16x16x32_bf16 v[54:57], v[190:193], v[198:201], v[54:57]
	v_mfma_f32_16x16x32_bf16 v[42:45], v[182:185], v[206:209], v[42:45]
	v_mfma_f32_16x16x32_bf16 v[38:41], v[190:193], v[206:209], v[38:41]
	v_mfma_f32_16x16x32_bf16 v[26:29], v[182:185], v[220:223], v[26:29]
	v_mfma_f32_16x16x32_bf16 v[22:25], v[190:193], v[220:223], v[22:25]
	v_mfma_f32_16x16x32_bf16 v[10:13], v[182:185], v[228:231], v[10:13]
	v_mfma_f32_16x16x32_bf16 v[6:9], v[190:193], v[228:231], v[6:9]
	v_mfma_f32_16x16x32_bf16 v[58:61], v[186:189], v[202:205], v[58:61]
	v_mfma_f32_16x16x32_bf16 v[54:57], v[194:197], v[202:205], v[54:57]
	v_mfma_f32_16x16x32_bf16 v[42:45], v[186:189], v[210:213], v[42:45]
	v_mfma_f32_16x16x32_bf16 v[38:41], v[194:197], v[210:213], v[38:41]
	v_mfma_f32_16x16x32_bf16 v[26:29], v[186:189], v[224:227], v[26:29]
	v_mfma_f32_16x16x32_bf16 v[22:25], v[194:197], v[224:227], v[22:25]
	v_mfma_f32_16x16x32_bf16 v[10:13], v[186:189], v[232:235], v[10:13]
	v_mfma_f32_16x16x32_bf16 v[6:9], v[194:197], v[232:235], v[6:9]
	s_setprio 0
	s_barrier
	s_add_i32 s11, 0, 0x18000
	s_add_i32 s31, 0, 0x1c000
	v_add_u32_e32 v178, s11, v216
	v_add_u32_e32 v194, s31, v216
	ds_read_b128 v[138:141], v178
	ds_read_b128 v[142:145], v178 offset:1024
	ds_read_b128 v[146:149], v178 offset:2048
	ds_read_b128 v[178:181], v178 offset:3072
	ds_read_b128 v[182:185], v194
	ds_read_b128 v[186:189], v194 offset:1024
	ds_read_b128 v[190:193], v194 offset:2048
	ds_read_b128 v[194:197], v194 offset:3072
	v_lshl_add_u64 v[214:215], v[214:215], 0, s[12:13]
	s_mov_b32 m0, s36
	v_lshl_add_u64 v[248:249], v[214:215], 0, v[154:155]
	ds_read_b128 v[198:201], v218 offset:32768
	ds_read_b128 v[202:205], v218 offset:33792
	ds_read_b128 v[206:209], v218 offset:34816
	ds_read_b128 v[210:213], v218 offset:35840
	ds_read_b128 v[220:223], v218 offset:36864
	ds_read_b128 v[224:227], v218 offset:37888
	ds_read_b128 v[228:231], v218 offset:38912
	ds_read_b128 v[232:235], v218 offset:39936
	global_load_lds_dwordx4 v[248:249], off
	v_lshl_add_u64 v[214:215], v[214:215], 0, v[160:161]
	s_mov_b32 m0, s37
	s_nop 0
	global_load_lds_dwordx4 v[214:215], off
	s_waitcnt vmcnt(8)
	s_waitcnt lgkmcnt(0)
	s_barrier
	s_setprio 1
	s_waitcnt lgkmcnt(0)
	v_mfma_f32_16x16x32_bf16 v[130:133], v[138:141], v[198:201], v[130:133]
	v_mfma_f32_16x16x32_bf16 v[126:129], v[146:149], v[198:201], v[126:129]
	v_mfma_f32_16x16x32_bf16 v[114:117], v[138:141], v[206:209], v[114:117]
	v_mfma_f32_16x16x32_bf16 v[110:113], v[146:149], v[206:209], v[110:113]
	v_mfma_f32_16x16x32_bf16 v[98:101], v[138:141], v[220:223], v[98:101]
	v_mfma_f32_16x16x32_bf16 v[94:97], v[146:149], v[220:223], v[94:97]
	v_mfma_f32_16x16x32_bf16 v[82:85], v[138:141], v[228:231], v[82:85]
	v_mfma_f32_16x16x32_bf16 v[78:81], v[146:149], v[228:231], v[78:81]
	v_mfma_f32_16x16x32_bf16 v[130:133], v[142:145], v[202:205], v[130:133]
	v_mfma_f32_16x16x32_bf16 v[126:129], v[178:181], v[202:205], v[126:129]
	v_mfma_f32_16x16x32_bf16 v[114:117], v[142:145], v[210:213], v[114:117]
	v_mfma_f32_16x16x32_bf16 v[110:113], v[178:181], v[210:213], v[110:113]
	v_mfma_f32_16x16x32_bf16 v[98:101], v[142:145], v[224:227], v[98:101]
	v_mfma_f32_16x16x32_bf16 v[94:97], v[178:181], v[224:227], v[94:97]
	v_mfma_f32_16x16x32_bf16 v[82:85], v[142:145], v[232:235], v[82:85]
	v_mfma_f32_16x16x32_bf16 v[78:81], v[178:181], v[232:235], v[78:81]
	v_mfma_f32_16x16x32_bf16 v[122:125], v[182:185], v[198:201], v[122:125]
	v_mfma_f32_16x16x32_bf16 v[118:121], v[190:193], v[198:201], v[118:121]
	v_mfma_f32_16x16x32_bf16 v[106:109], v[182:185], v[206:209], v[106:109]
	v_mfma_f32_16x16x32_bf16 v[102:105], v[190:193], v[206:209], v[102:105]
	v_mfma_f32_16x16x32_bf16 v[90:93], v[182:185], v[220:223], v[90:93]
	v_mfma_f32_16x16x32_bf16 v[86:89], v[190:193], v[220:223], v[86:89]
	v_mfma_f32_16x16x32_bf16 v[74:77], v[182:185], v[228:231], v[74:77]
	v_mfma_f32_16x16x32_bf16 v[70:73], v[190:193], v[228:231], v[70:73]
	v_mfma_f32_16x16x32_bf16 v[122:125], v[186:189], v[202:205], v[122:125]
	v_mfma_f32_16x16x32_bf16 v[118:121], v[194:197], v[202:205], v[118:121]
	v_mfma_f32_16x16x32_bf16 v[106:109], v[186:189], v[210:213], v[106:109]
	v_mfma_f32_16x16x32_bf16 v[102:105], v[194:197], v[210:213], v[102:105]
	v_mfma_f32_16x16x32_bf16 v[90:93], v[186:189], v[224:227], v[90:93]
	v_mfma_f32_16x16x32_bf16 v[86:89], v[194:197], v[224:227], v[86:89]
	v_mfma_f32_16x16x32_bf16 v[74:77], v[186:189], v[232:235], v[74:77]
	v_mfma_f32_16x16x32_bf16 v[70:73], v[194:197], v[232:235], v[70:73]
	s_setprio 0
	s_barrier
; #define PG8_STAGE(bufoff, gbase, voff) do { _Pragma("unroll") for (int _i = 0; _i < 2; ++_i) \
;         __builtin_amdgcn_global_load_lds((const unsigned*)((const char*)(gbase) + (voff)[_i]), (PG8_LAS unsigned*)(lds + (bufoff) + ldsw + _i * 8192), 16, 0, 0); } while (0)
; #define PG8_LDA(dst, b, h) do { _Pragma("unroll") for (int m = 0; m < 4; ++m) _Pragma("unroll") for (int k = 0; k < 2; ++k) dst[m][k] = *(const PG8_LAS bf16x8*)(lds + PG8_SA(b, h) + aoff + m * 2048 + k * 1024); } while (0)
; #define PG8_MMA(ai, bj, At, Bt) do { __builtin_amdgcn_s_setprio(1); _Pragma("unroll") for (int m = 0; m < 4; ++m) _Pragma("unroll") for (int n = 0; n < 2; ++n) _Pragma("unroll") for (int k = 0; k < 2; ++k) \
;         acc[ai][bj][m][n] = __builtin_amdgcn_mfma_f32_16x16x32_bf16(Bt[n][k], At[m][k], acc[ai][bj][m][n], 0, 0, 0); __builtin_amdgcn_s_setprio(0); } while (0)
; #define PG8_WAIT_V(n) asm volatile("s_waitcnt vmcnt(" #n ")" ::: "memory")
; #define PG8_WAIT_L(n) asm volatile("s_waitcnt lgkmcnt(" #n ")" ::: "memory")
; #define PG8_BAR __builtin_amdgcn_s_barrier()
; #define PG8_SCHED __builtin_amdgcn_sched_barrier(0)
; template <class Epi, class Sched, bool ALIGN_EPI = false, bool SP2 = false>
; __device__ __forceinline__ void gemm_phase(PG8_LAS unsigned char* lds, const Gemm g, const Sched& S, const Epi& E) {
;     ...
;             PG8_LDA(At, 1, 1); PG8_STAGE(PG8_SB(1, 0), b3, voffB); PG8_STAGE(PG8_SB(1, 1), b3 + hstep, voffB); PG8_STAGE(PG8_SA(1, 0), a3, voffA);
;             PG8_WAIT_V(8); PG8_WAIT_L(0); PG8_BAR; PG8_MMA(1, 0, At, B0); PG8_MMA(1, 1, At, B1); PG8_BAR; PG8_SCHED;
	s_add_i32 s11, s11, s29
	v_lshl_add_u64 v[214:215], v[238:239], 0, s[20:21]
	s_mov_b32 m0, s11
	ds_read_b128 v[198:201], v218 offset:49152
	ds_read_b128 v[202:205], v218 offset:50176
	ds_read_b128 v[206:209], v218 offset:51200
	ds_read_b128 v[210:213], v218 offset:52224
	ds_read_b128 v[220:223], v218 offset:53248
	ds_read_b128 v[224:227], v218 offset:54272
	ds_read_b128 v[228:231], v218 offset:55296
	ds_read_b128 v[232:235], v218 offset:56320
	global_load_lds_dwordx4 v[214:215], off
	v_lshl_add_u64 v[214:215], v[240:241], 0, s[20:21]
	s_add_i32 m0, s11, 0x2000
	s_add_i32 s11, s31, s29
	global_load_lds_dwordx4 v[214:215], off
	v_lshl_add_u64 v[214:215], v[242:243], 0, s[20:21]
	s_mov_b32 m0, s11
	s_nop 0
	global_load_lds_dwordx4 v[214:215], off
	v_lshl_add_u64 v[214:215], v[236:237], 0, s[20:21]
	s_add_i32 m0, s11, 0x2000
	s_nop 0
	global_load_lds_dwordx4 v[214:215], off
	v_lshl_add_u64 v[214:215], v[244:245], 0, s[20:21]
	s_mov_b32 m0, s41
	s_nop 0
	global_load_lds_dwordx4 v[214:215], off
	v_lshl_add_u64 v[214:215], v[246:247], 0, s[20:21]
	s_mov_b32 m0, s44
	s_nop 0
	global_load_lds_dwordx4 v[214:215], off
	s_waitcnt vmcnt(8)
	s_waitcnt lgkmcnt(0)
	s_barrier
	s_setprio 1
	s_waitcnt lgkmcnt(0)
	v_mfma_f32_16x16x32_bf16 v[66:69], v[138:141], v[198:201], v[66:69]
	v_mfma_f32_16x16x32_bf16 v[62:65], v[146:149], v[198:201], v[62:65]
	v_mfma_f32_16x16x32_bf16 v[50:53], v[138:141], v[206:209], v[50:53]
	v_mfma_f32_16x16x32_bf16 v[46:49], v[146:149], v[206:209], v[46:49]
	v_mfma_f32_16x16x32_bf16 v[34:37], v[138:141], v[220:223], v[34:37]
	v_mfma_f32_16x16x32_bf16 v[30:33], v[146:149], v[220:223], v[30:33]
	v_mfma_f32_16x16x32_bf16 v[18:21], v[138:141], v[228:231], v[18:21]
	v_mfma_f32_16x16x32_bf16 v[14:17], v[146:149], v[228:231], v[14:17]
	v_mfma_f32_16x16x32_bf16 v[66:69], v[142:145], v[202:205], v[66:69]
	v_mfma_f32_16x16x32_bf16 v[62:65], v[178:181], v[202:205], v[62:65]
	v_mfma_f32_16x16x32_bf16 v[50:53], v[142:145], v[210:213], v[50:53]
	v_mfma_f32_16x16x32_bf16 v[46:49], v[178:181], v[210:213], v[46:49]
	v_mfma_f32_16x16x32_bf16 v[34:37], v[142:145], v[224:227], v[34:37]
	v_mfma_f32_16x16x32_bf16 v[30:33], v[178:181], v[224:227], v[30:33]
	v_mfma_f32_16x16x32_bf16 v[18:21], v[142:145], v[232:235], v[18:21]
	v_mfma_f32_16x16x32_bf16 v[14:17], v[178:181], v[232:235], v[14:17]
	v_mfma_f32_16x16x32_bf16 v[58:61], v[182:185], v[198:201], v[58:61]
	v_mfma_f32_16x16x32_bf16 v[54:57], v[190:193], v[198:201], v[54:57]
	v_mfma_f32_16x16x32_bf16 v[42:45], v[182:185], v[206:209], v[42:45]
	v_mfma_f32_16x16x32_bf16 v[38:41], v[190:193], v[206:209], v[38:41]
	v_mfma_f32_16x16x32_bf16 v[26:29], v[182:185], v[220:223], v[26:29]
	v_mfma_f32_16x16x32_bf16 v[22:25], v[190:193], v[220:223], v[22:25]
	v_mfma_f32_16x16x32_bf16 v[10:13], v[182:185], v[228:231], v[10:13]
	v_mfma_f32_16x16x32_bf16 v[6:9], v[190:193], v[228:231], v[6:9]
	v_mfma_f32_16x16x32_bf16 v[58:61], v[186:189], v[202:205], v[58:61]
	v_mfma_f32_16x16x32_bf16 v[54:57], v[194:197], v[202:205], v[54:57]
	v_mfma_f32_16x16x32_bf16 v[42:45], v[186:189], v[210:213], v[42:45]
	v_mfma_f32_16x16x32_bf16 v[38:41], v[194:197], v[210:213], v[38:41]
	v_mfma_f32_16x16x32_bf16 v[26:29], v[186:189], v[224:227], v[26:29]
	v_mfma_f32_16x16x32_bf16 v[22:25], v[194:197], v[224:227], v[22:25]
	v_mfma_f32_16x16x32_bf16 v[10:13], v[186:189], v[232:235], v[10:13]
	v_mfma_f32_16x16x32_bf16 v[6:9], v[194:197], v[232:235], v[6:9]
	s_setprio 0
	s_barrier
	v_lshl_add_u64 v[134:135], v[134:135], 0, s[26:27]
	s_cmp_ge_i32 s10, s46
	v_lshl_add_u64 v[136:137], v[136:137], 0, s[26:27]
	s_cbranch_scc0 .LBB0_1947
